# r3 chunk-state fragments prefetched before the score barrier; all flat_* accesses (global memory only) converted to global_* so LDS waits no longer stall on global loads
# speedup vs baseline: 1.0019x; 1.0012x over previous
; __device__ __forceinline__ unsigned f2bf(float f) { unsigned u = __builtin_bit_cast(unsigned, f); return (u + 0x7fffu + ((u >> 16) & 1u)) >> 16; }
; __device__ __forceinline__ float siluf(float x) { return x * __builtin_amdgcn_rcpf(1.f + __expf(-x)); }
; __device__ __forceinline__ void conv_phase(const Args& a, int L) {
;     ...
;     for (int idx = blockIdx.x * NTHR + tid; idx < NTILE * 256; idx += gridDim.x * NTHR) {
;         const int tile = idx >> 8, side = (idx >> 7) & 1, lc = idx & 127, pm = tile / NTN, pn = tile % NTN, ch = pn * 128 + lc;
;         const float* hb = HB + (size_t)tile * 1024;
;         float pa = hb[(2 + side) * 256 + lc], pg = hb[(2 + side) * 256 + 128 + lc];
;         if (side == 0 && (pm & 15) != 0) { const float* nb = HB + (size_t)(tile - NTN) * 1024 + 256; pa += cw[ch] * nb[lc]; pg += cw[DFF + ch] * nb[128 + lc]; }
;         if (side == 1 && (pm & 15) != 15) { const float* nb = HB + (size_t)(tile + NTN) * 1024; pa += cw[2 * UPW + ch] * nb[lc]; pg += cw[2 * UPW + DFF + ch] * nb[128 + lc]; }
;         act[(size_t)(pm * 256 + (side ? 255 : 0)) * DFF + ch] = (bf16_t)f2bf(pa * siluf(pg));
;     }
.LBB0_39:
	s_andn2_saveexec_b64 s[28:29], s[28:29]
	s_or_b64 exec, exec, s[28:29]
	s_waitcnt vmcnt(0) lgkmcnt(0)
	v_mul_f32_e32 v3, 0xbfb8aa3b, v9
	v_exp_f32_e32 v3, v3
	v_add_u32_e32 v14, s88, v14
	v_add_f32_e32 v3, 1.0, v3
	v_rcp_f32_e32 v3, v3
	s_nop 0
	v_mul_f32_e32 v3, v9, v3
	v_mul_f32_e32 v3, v8, v3
	v_bfe_u32 v8, v3, 16, 1
	v_add3_u32 v3, v3, v8, s91
	v_mov_b32_e32 v8, 0xff
	v_cndmask_b32_e64 v8, v8, 0, s[0:1]
	v_lshl_or_b32 v0, v0, 8, v8
	v_mov_b64_e32 v[8:9], s[12:13]
	s_movk_i32 s0, 0x2c00
	v_mad_i64_i32 v[8:9], s[0:1], v0, s0, v[8:9]
	s_mov_b32 s0, 0x57fff
	s_nop 0
	v_cmp_lt_i32_e32 vcc, s0, v14
	v_lshl_add_u64 v[6:7], v[6:7], 1, v[8:9]
	s_or_b64 s[14:15], vcc, s[14:15]
	global_store_short_d16_hi v[6:7], v3, off
	s_andn2_b64 exec, exec, s[14:15]
	s_cbranch_execz .LBB0_45
.LBB0_40:
	v_ashrrev_i32_e32 v10, 8, v14
	v_ashrrev_i32_e32 v11, 31, v10
	v_bfe_u32 v3, v14, 7, 1
	v_lshlrev_b64 v[12:13], 12, v[10:11]
	v_lshl_add_u64 v[6:7], s[6:7], 0, v[12:13]
	v_lshl_or_b32 v0, v3, 10, v2
	v_lshl_add_u64 v[6:7], v[6:7], 0, v[0:1]
	global_load_dword v8, v[6:7], off offset:2048
	global_load_dword v9, v[6:7], off offset:2560
	s_mov_b32 s0, 0x2e8ba2e9
	v_mul_hi_i32 v0, v10, s0
	v_lshrrev_b32_e32 v6, 31, v0
	v_ashrrev_i32_e32 v0, 3, v0
	v_add_u32_e32 v0, v0, v6
	v_mul_lo_u32 v6, v0, 44
	v_sub_u32_e32 v6, v10, v6
	v_and_b32_e32 v16, 15, v0
	v_lshl_or_b32 v6, v6, 7, v15
	v_cmp_eq_u32_e32 vcc, 0, v3
	v_cmp_ne_u32_e64 s[0:1], 0, v16
	s_and_b64 s[28:29], vcc, s[0:1]
	v_ashrrev_i32_e32 v7, 31, v6
	s_and_saveexec_b64 s[0:1], s[28:29]
	s_cbranch_execz .LBB0_42
	v_readlane_b32 s28, v254, 53
	v_readlane_b32 s29, v254, 54
	v_lshl_add_u64 v[12:13], v[4:5], 0, v[12:13]
	s_nop 0
	v_lshl_add_u64 v[18:19], v[6:7], 2, s[28:29]
	global_load_dword v20, v[18:19], off
	s_mov_b32 s28, 0xfffd4000
	v_add_co_u32_e32 v18, vcc, 0x5000, v18
	s_mov_b32 s29, -1
	s_nop 0
	v_addc_co_u32_e32 v19, vcc, 0, v19, vcc
	v_lshl_add_u64 v[12:13], v[12:13], 0, s[28:29]
	global_load_dword v21, v[18:19], off offset:2048
	s_nop 0
	global_load_dword v18, v[12:13], off offset:1024
	global_load_dword v19, v[12:13], off offset:1536
	s_waitcnt vmcnt(0) lgkmcnt(0)
	v_pk_fma_f32 v[8:9], v[20:21], v[18:19], v[8:9]
.LBB0_42:
	s_or_b64 exec, exec, s[0:1]
	v_cmp_ne_u32_e32 vcc, 0, v3
	v_cmp_ne_u32_e64 s[38:39], 15, v16
	v_cmp_eq_u32_e64 s[0:1], 0, v3
	s_and_b64 s[28:29], vcc, s[38:39]
	s_and_saveexec_b64 s[30:31], s[28:29]
	s_xor_b64 s[28:29], exec, s[30:31]
	s_cbranch_execz .LBB0_39
	v_readlane_b32 s30, v254, 53
	v_readlane_b32 s31, v254, 54
	v_lshlrev_b64 v[10:11], 12, v[10:11]
	v_lshl_add_u64 v[10:11], v[4:5], 0, v[10:11]
	v_lshl_add_u64 v[12:13], v[6:7], 2, s[30:31]
	v_add_co_u32_e32 v16, vcc, 0x16000, v12
	s_mov_b64 s[30:31], 0x2c000
	s_nop 0
	v_addc_co_u32_e32 v17, vcc, 0, v13, vcc
	v_lshl_add_u64 v[18:19], v[10:11], 0, s[30:31]
	v_add_co_u32_e32 v10, vcc, 0x2c000, v10
	global_load_dword v16, v[16:17], off
	s_nop 0
	v_addc_co_u32_e32 v11, vcc, 0, v11, vcc
	v_add_co_u32_e32 v12, vcc, 0x1b000, v12
	s_nop 1
	v_addc_co_u32_e32 v13, vcc, 0, v13, vcc
	global_load_dword v17, v[12:13], off offset:2048
	s_nop 0
	global_load_dword v10, v[10:11], off
	s_nop 0
	global_load_dword v11, v[18:19], off offset:512
	s_waitcnt vmcnt(0) lgkmcnt(0)
	v_pk_fma_f32 v[8:9], v[16:17], v[10:11], v[8:9]
	s_branch .LBB0_39

; __device__ __forceinline__ float ss_rstd(const u64_t* ss, int row) { return __builtin_amdgcn_rsqf((float)ss[row] * (SS_IFX / (float)2048) + 1e-6f); }
;     __device__ __forceinline__ void operator()(f32x4 (&acc)[2][2][4][2], const Unit& u, int wr, int wc, int fr_in, int fq_in) const {
;     ...
;         if (wv < 4) { const int cl = wv * 64 + fq * 16 + fr, ch = ((cl >> 7) ? DFF : 0) + u.pn * 128 + (cl & 127);
;             WL[cl] = cw[ch]; WL[256 + cl] = cw[UPW + ch]; WL[512 + cl] = cw[2 * UPW + ch]; WL[768 + cl] = cb[ch]; }
; #pragma unroll
;         for (int ai = 0; ai < 2; ++ai)
; #pragma unroll
;             for (int m = 0; m < 4; ++m) { asm volatile("" : "+v"(fr)); const float sc = ss_rstd(ss, u.pm * BM + ai * HALF + wr * 64 + m * 16 + fr);
; #pragma unroll
;                 for (int bj = 0; bj < 2; ++bj)
; #pragma unroll
;                     for (int n = 0; n < 2; ++n) acc[ai][bj][m][n] *= sc; }
.LBB0_59:
	v_mov_b32_e32 v171, v167
	v_mov_b32_e32 v170, v166
	v_readlane_b32 s40, v255, 10
	v_readlane_b32 s41, v255, 11
	v_lshlrev_b32_e32 v140, 4, v171
	v_readlane_b32 s1, v255, 9
	s_andn2_b64 vcc, exec, s[40:41]
	s_nop 0
	v_add3_u32 v140, v170, s1, v140
	s_cbranch_vccnz .LBB0_61
	s_movk_i32 s1, 0x80
	v_cmp_gt_u32_e32 vcc, s1, v140
	v_mov_b32_e32 v141, 0x1600
	s_movk_i32 s1, 0x7f
	v_cndmask_b32_e64 v141, v141, 0, vcc
	v_lshl_add_u32 v141, s81, 7, v141
	v_and_or_b32 v142, v140, s1, v141
	v_ashrrev_i32_e32 v143, 31, v142
	v_readlane_b32 s40, v254, 53
	v_lshlrev_b64 v[142:143], 2, v[142:143]
	v_readlane_b32 s41, v254, 54
	v_lshl_add_u32 v146, v140, 2, 0
	v_add_u32_e32 v148, 0x24d00, v146
	v_lshl_add_u64 v[144:145], s[40:41], 0, v[142:143]
	global_load_dword v141, v[144:145], off
	v_add_co_u32_e32 v146, vcc, 0xb000, v144
	v_readlane_b32 s40, v255, 5
	s_nop 0
	v_addc_co_u32_e32 v147, vcc, 0, v145, vcc
	v_add_co_u32_e32 v144, vcc, 0x16000, v144
	v_readlane_b32 s41, v255, 6
	s_nop 0
	v_addc_co_u32_e32 v145, vcc, 0, v145, vcc
	v_lshl_add_u64 v[142:143], s[40:41], 0, v[142:143]
	global_load_dword v222, v[146:147], off
	global_load_dword v223, v[144:145], off
	global_load_dword v224, v[142:143], off
	s_waitcnt vmcnt(0) lgkmcnt(0)
	ds_write_b32 v148, v141
	ds_write_b32 v148, v222 offset:1024
	ds_write_b32 v148, v223 offset:2048
	ds_write_b32 v148, v224 offset:3072
.LBB0_61:
	v_readlane_b32 s1, v253, 16
	s_lshl_b32 s29, s0, 8
	s_mul_i32 s0, s0, 44
	v_lshl_add_u32 v172, v140, 4, s1
	v_readlane_b32 s1, v255, 4
	s_add_i32 s29, s29, s1
	v_add_u32_e32 v140, s29, v170
	v_ashrrev_i32_e32 v141, 31, v140
	v_lshl_add_u64 v[140:141], v[140:141], 3, s[14:15]
	global_load_dwordx2 v[192:193], v[140:141], off offset:128
	global_load_dwordx2 v[194:195], v[140:141], off offset:256
	global_load_dwordx2 v[196:197], v[140:141], off offset:384
	global_load_dwordx2 v[198:199], v[140:141], off offset:1024
	global_load_dwordx2 v[200:201], v[140:141], off offset:1152
	global_load_dwordx2 v[202:203], v[140:141], off offset:1280
	global_load_dwordx2 v[204:205], v[140:141], off offset:1408
	global_load_dwordx2 v[140:141], v[140:141], off
	s_add_i32 s11, s29, 0x80
	s_add_i32 s1, s29, 0x90
	s_add_i32 s0, s0, s81
	v_readlane_b32 s48, v255, 12
	s_waitcnt vmcnt(0) lgkmcnt(0)
	v_ffbh_u32_e32 v142, v141
	v_min_u32_e32 v142, 32, v142
	v_lshlrev_b64 v[140:141], v142, v[140:141]
	v_min_u32_e32 v140, 1, v140
	v_or_b32_e32 v140, v141, v140
	v_cvt_f32_u32_e32 v140, v140
	v_sub_u32_e32 v141, 32, v142
	v_ldexp_f32 v140, v140, v141
	v_fmamk_f32 v140, v140, 0x2e000000, v207
	v_rsq_f32_e32 v140, v140
	s_nop 0
	v_pk_mul_f32 v[124:125], v[124:125], v[140:141] op_sel_hi:[1,0]
	v_pk_mul_f32 v[122:123], v[122:123], v[140:141] op_sel_hi:[1,0]
	v_pk_mul_f32 v[116:117], v[116:117], v[140:141] op_sel_hi:[1,0]
	v_pk_mul_f32 v[114:115], v[114:115], v[140:141] op_sel_hi:[1,0]
	v_pk_mul_f32 v[108:109], v[108:109], v[140:141] op_sel_hi:[1,0]
	v_pk_mul_f32 v[106:107], v[106:107], v[140:141] op_sel_hi:[1,0]
	v_pk_mul_f32 v[88:89], v[88:89], v[140:141] op_sel_hi:[1,0]
	v_pk_mul_f32 v[86:87], v[86:87], v[140:141] op_sel_hi:[1,0]
	v_add3_u32 v140, v170, s29, 16
	v_ashrrev_i32_e32 v141, 31, v140
	v_lshl_add_u64 v[140:141], v[140:141], 3, s[14:15]
	v_mov_b32_e32 v142, v192
	v_mov_b32_e32 v143, v193
	s_nop 0
	v_add3_u32 v140, v170, s29, 32
	v_ashrrev_i32_e32 v141, 31, v140
	v_lshl_add_u64 v[140:141], v[140:141], 3, s[14:15]
	v_mov_b32_e32 v140, v194
	v_mov_b32_e32 v141, v195
	s_nop 0
	v_add3_u32 v144, v170, s29, 48
	v_ashrrev_i32_e32 v145, 31, v144
	v_lshl_add_u64 v[144:145], v[144:145], 3, s[14:15]
	v_mov_b32_e32 v144, v196
	v_mov_b32_e32 v145, v197
	s_waitcnt vmcnt(0) lgkmcnt(0)
	v_ffbh_u32_e32 v146, v145
	v_min_u32_e32 v146, 32, v146
	v_lshlrev_b64 v[144:145], v146, v[144:145]
	v_min_u32_e32 v144, 1, v144
	v_or_b32_e32 v144, v145, v144
	v_cvt_f32_u32_e32 v144, v144
	v_sub_u32_e32 v145, 32, v146
	v_ldexp_f32 v144, v144, v145
	v_fmamk_f32 v144, v144, 0x2e000000, v207
	v_rsq_f32_e32 v144, v144
	s_nop 0
	v_pk_mul_f32 v[128:129], v[128:129], v[144:145] op_sel_hi:[1,0]
	v_pk_mul_f32 v[126:127], v[126:127], v[144:145] op_sel_hi:[1,0]
	v_pk_mul_f32 v[120:121], v[120:121], v[144:145] op_sel_hi:[1,0]
	v_pk_mul_f32 v[118:119], v[118:119], v[144:145] op_sel_hi:[1,0]
	v_pk_mul_f32 v[112:113], v[112:113], v[144:145] op_sel_hi:[1,0]
	v_pk_mul_f32 v[110:111], v[110:111], v[144:145] op_sel_hi:[1,0]
	v_pk_mul_f32 v[92:93], v[92:93], v[144:145] op_sel_hi:[1,0]
	v_pk_mul_f32 v[90:91], v[90:91], v[144:145] op_sel_hi:[1,0]
	v_add_u32_e32 v144, s11, v170
	v_ashrrev_i32_e32 v145, 31, v144
	v_lshl_add_u64 v[144:145], v[144:145], 3, s[14:15]
	v_mov_b32_e32 v144, v198
	v_mov_b32_e32 v145, v199
	s_waitcnt vmcnt(0) lgkmcnt(0)
	v_ffbh_u32_e32 v146, v145
	v_min_u32_e32 v146, 32, v146
	v_lshlrev_b64 v[144:145], v146, v[144:145]
	v_min_u32_e32 v144, 1, v144
	v_or_b32_e32 v144, v145, v144
	v_cvt_f32_u32_e32 v144, v144
	v_sub_u32_e32 v145, 32, v146
	v_ldexp_f32 v144, v144, v145
	v_fmamk_f32 v144, v144, 0x2e000000, v207
	v_rsq_f32_e32 v144, v144
	s_nop 0
	v_pk_mul_f32 v[28:29], v[28:29], v[144:145] op_sel_hi:[1,0]
	v_pk_mul_f32 v[26:27], v[26:27], v[144:145] op_sel_hi:[1,0]
	v_pk_mul_f32 v[20:21], v[20:21], v[144:145] op_sel_hi:[1,0]
	v_pk_mul_f32 v[18:19], v[18:19], v[144:145] op_sel_hi:[1,0]
	v_pk_mul_f32 v[12:13], v[12:13], v[144:145] op_sel_hi:[1,0]
	v_pk_mul_f32 v[10:11], v[10:11], v[144:145] op_sel_hi:[1,0]
	v_pk_mul_f32 v[4:5], v[4:5], v[144:145] op_sel_hi:[1,0]
	v_pk_mul_f32 v[2:3], v[2:3], v[144:145] op_sel_hi:[1,0]
	v_add_u32_e32 v144, s1, v170
	v_ashrrev_i32_e32 v145, 31, v144
	v_lshl_add_u64 v[144:145], v[144:145], 3, s[14:15]
	s_add_i32 s1, s29, 0xa0
	v_mov_b32_e32 v146, v200
	v_mov_b32_e32 v147, v201
	s_nop 0
	v_add_u32_e32 v144, s1, v170
	v_ashrrev_i32_e32 v145, 31, v144
	v_lshl_add_u64 v[144:145], v[144:145], 3, s[14:15]
	s_add_i32 s1, s29, 0xb0
	v_mov_b32_e32 v144, v202
	v_mov_b32_e32 v145, v203
	s_nop 0
	v_add_u32_e32 v148, s1, v170
	v_ashrrev_i32_e32 v149, 31, v148
	v_lshl_add_u64 v[148:149], v[148:149], 3, s[14:15]
	v_mov_b32_e32 v148, v204
	v_mov_b32_e32 v149, v205
	s_ashr_i32 s1, s0, 31
	s_lshl_b64 s[40:41], s[0:1], 12
	v_cmp_eq_u32_e64 s[0:1], 0, v170
	v_cmp_eq_u32_e32 vcc, 15, v170
	s_waitcnt vmcnt(0) lgkmcnt(0)
; #define LAS __attribute__((address_space(3)))
; __device__ __forceinline__ float ss_rstd(const u64_t* ss, int row) { return __builtin_amdgcn_rsqf((float)ss[row] * (SS_IFX / (float)2048) + 1e-6f); }
;     __device__ __forceinline__ void operator()(f32x4 (&acc)[2][2][4][2], const Unit& u, int wr, int wc, int fr_in, int fq_in) const {
;     ...
;             for (int m = 0; m < 4; ++m) { asm volatile("" : "+v"(fr)); const float sc = ss_rstd(ss, u.pm * BM + ai * HALF + wr * 64 + m * 16 + fr);
; #pragma unroll
;                 for (int bj = 0; bj < 2; ++bj)
; #pragma unroll
;                     for (int n = 0; n < 2; ++n) acc[ai][bj][m][n] *= sc; }
;         float* hb = HB + (size_t)(u.pm * (UPW / 256) + u.pn) * 1024;
; #pragma unroll
;         for (int ai = 0; ai < 2; ++ai) { const int blk = 2 * ai + wr;
;             asm volatile("" : "+v"(fr), "+v"(fq)); const int lc0 = wc * 32 + 8 * fq;
; #pragma unroll
;             for (int bj = 0; bj < 2; ++bj)
; #pragma unroll
;                 for (int n = 0; n < 2; ++n) {
;                     LAS float* d0 = fr == 0 ? HL + (blk * 2 + 0) * 256 + bj * 128 + lc0 + 4 * n : DMP;
;                     LAS float* d1 = fr == 15 ? HL + (blk * 2 + 1) * 256 + bj * 128 + lc0 + 4 * n : DMP;
;                     *(LAS f32x4*)d0 = acc[ai][bj][0][n]; *(LAS f32x4*)d1 = acc[ai][bj][3][n]; }
;         }
;         asm volatile("s_waitcnt lgkmcnt(0)" ::: "memory"); __builtin_amdgcn_s_barrier(); asm volatile("" ::: "memory");
;         if (wv == 0) { const int l4 = (fq * 16 + fr) * 4;
;             *(f32x4*)(hb + l4) = *(const LAS f32x4*)(HL + l4); *(f32x4*)(hb + 256 + l4) = *(const LAS f32x4*)(HL + 7 * 256 + l4); }
	v_ffbh_u32_e32 v150, v149
	v_min_u32_e32 v150, 32, v150
	v_lshlrev_b64 v[148:149], v150, v[148:149]
	v_min_u32_e32 v148, 1, v148
	v_or_b32_e32 v148, v149, v148
	v_cvt_f32_u32_e32 v148, v148
	v_sub_u32_e32 v149, 32, v150
	v_ldexp_f32 v148, v148, v149
	v_fmamk_f32 v148, v148, 0x2e000000, v207
	v_rsq_f32_e32 v148, v148
	s_nop 0
	v_pk_mul_f32 v[32:33], v[32:33], v[148:149] op_sel_hi:[1,0]
	v_pk_mul_f32 v[30:31], v[30:31], v[148:149] op_sel_hi:[1,0]
	v_pk_mul_f32 v[24:25], v[24:25], v[148:149] op_sel_hi:[1,0]
	v_pk_mul_f32 v[22:23], v[22:23], v[148:149] op_sel_hi:[1,0]
	v_pk_mul_f32 v[16:17], v[16:17], v[148:149] op_sel_hi:[1,0]
	v_pk_mul_f32 v[14:15], v[14:15], v[148:149] op_sel_hi:[1,0]
	v_pk_mul_f32 v[8:9], v[8:9], v[148:149] op_sel_hi:[1,0]
	v_pk_mul_f32 v[6:7], v[6:7], v[148:149] op_sel_hi:[1,0]
	v_lshl_add_u32 v148, v171, 3, s68
	v_lshl_add_u32 v148, v148, 2, s48
	v_cndmask_b32_e64 v149, v172, v148, s[0:1]
	v_add_u32_e32 v150, 0x400, v148
	v_cndmask_b32_e32 v150, v172, v150, vcc
	ds_write_b128 v149, v[122:125]
	ds_write_b128 v150, v[126:129]
	v_add_u32_e32 v149, 16, v148
	v_cndmask_b32_e64 v149, v172, v149, s[0:1]
	v_add_u32_e32 v150, 0x410, v148
	v_cndmask_b32_e32 v150, v172, v150, vcc
	ds_write_b128 v149, v[114:117]
	ds_write_b128 v150, v[118:121]
	v_add_u32_e32 v149, 0x200, v148
	v_cndmask_b32_e64 v149, v172, v149, s[0:1]
	v_add_u32_e32 v150, 0x600, v148
	v_cndmask_b32_e32 v150, v172, v150, vcc
	ds_write_b128 v149, v[106:109]
	ds_write_b128 v150, v[110:113]
	v_add_u32_e32 v149, 0x210, v148
	v_add_u32_e32 v148, 0x610, v148
	v_cndmask_b32_e64 v149, v172, v149, s[0:1]
	v_cndmask_b32_e32 v148, v172, v148, vcc
	ds_write_b128 v149, v[86:89]
	ds_write_b128 v148, v[90:93]
	v_readlane_b32 s48, v255, 13
	v_lshl_add_u32 v148, v171, 3, s68
	v_cmp_eq_u32_e32 vcc, 0, v170
	v_lshl_add_u32 v148, v148, 2, s48
	v_cmp_eq_u32_e64 s[0:1], 15, v170
	v_cndmask_b32_e32 v149, v172, v148, vcc
	v_add_u32_e32 v150, 0x400, v148
	v_cndmask_b32_e64 v150, v172, v150, s[0:1]
	ds_write_b128 v149, v[26:29]
	ds_write_b128 v150, v[30:33]
	v_add_u32_e32 v149, 16, v148
	v_cndmask_b32_e32 v149, v172, v149, vcc
	v_add_u32_e32 v150, 0x410, v148
	v_cndmask_b32_e64 v150, v172, v150, s[0:1]
	ds_write_b128 v149, v[18:21]
	ds_write_b128 v150, v[22:25]
	v_add_u32_e32 v149, 0x200, v148
	v_cndmask_b32_e32 v149, v172, v149, vcc
	v_add_u32_e32 v150, 0x600, v148
	v_cndmask_b32_e64 v150, v172, v150, s[0:1]
	ds_write_b128 v149, v[10:13]
	ds_write_b128 v150, v[14:17]
	v_add_u32_e32 v149, 0x210, v148
	v_cndmask_b32_e32 v149, v172, v149, vcc
	v_add_u32_e32 v148, 0x610, v148
	v_cndmask_b32_e64 v148, v172, v148, s[0:1]
	ds_write_b128 v149, v[2:5]
	ds_write_b128 v148, v[6:9]
	s_waitcnt lgkmcnt(0)
	s_barrier
	s_add_u32 s0, s6, s40
	v_cndmask_b32_e64 v148, 0, 1, s[4:5]
	s_addc_u32 s1, s7, s41
	v_cmp_ne_u32_e64 s[40:41], 1, v148
	s_andn2_b64 vcc, exec, s[4:5]
	s_cbranch_vccnz .LBB0_63
	v_lshlrev_b32_e32 v148, 6, v171
	v_lshl_add_u32 v152, v170, 2, v148
	v_lshl_add_u32 v154, v152, 2, 0
	v_add_u32_e32 v148, 0x20100, v154
	ds_read_b128 v[148:151], v148
	v_ashrrev_i32_e32 v153, 31, v152
	v_lshl_add_u64 v[152:153], v[152:153], 2, s[0:1]
	s_waitcnt lgkmcnt(0)
	global_store_dwordx4 v[152:153], v[148:151], off
	s_nop 1
	v_add_u32_e32 v148, 0x21d00, v154
	ds_read_b128 v[148:151], v148
	s_waitcnt lgkmcnt(0)
	global_store_dwordx4 v[152:153], v[148:151], off offset:1024
.LBB0_63:
	s_nop 1
	v_ffbh_u32_e32 v148, v143
	v_min_u32_e32 v148, 32, v148
	v_lshlrev_b64 v[142:143], v148, v[142:143]
	v_min_u32_e32 v142, 1, v142
	v_or_b32_e32 v142, v143, v142
	v_cvt_f32_u32_e32 v142, v142
	v_sub_u32_e32 v143, 32, v148
	s_add_i32 s50, 0, 0x24d00
	v_ldexp_f32 v142, v142, v143
	v_fmamk_f32 v142, v142, 0x2e000000, v207
	v_rsq_f32_e32 v150, v142
	v_ffbh_u32_e32 v142, v141
	v_min_u32_e32 v148, 32, v142
	v_lshlrev_b64 v[140:141], v148, v[140:141]
	v_pk_mul_f32 v[152:153], v[100:101], v[150:151] op_sel_hi:[1,0]
	v_min_u32_e32 v100, 1, v140
	v_or_b32_e32 v100, v141, v100
	v_cvt_f32_u32_e32 v100, v100
	v_pk_mul_f32 v[142:143], v[84:85], v[150:151] op_sel_hi:[1,0]
	v_sub_u32_e32 v84, 32, v148
	v_pk_mul_f32 v[156:157], v[98:99], v[150:151] op_sel_hi:[1,0]
	v_ldexp_f32 v84, v100, v84
	v_pk_mul_f32 v[100:101], v[74:75], v[150:151] op_sel_hi:[1,0]
	v_ffbh_u32_e32 v74, v147
	v_pk_mul_f32 v[98:99], v[76:77], v[150:151] op_sel_hi:[1,0]
	v_min_u32_e32 v76, 32, v74
	v_lshlrev_b64 v[74:75], v76, v[146:147]
	v_fmamk_f32 v84, v84, 0x2e000000, v207
	v_min_u32_e32 v74, 1, v74
	v_rsq_f32_e32 v84, v84
	v_or_b32_e32 v74, v75, v74
	v_cvt_f32_u32_e32 v74, v74
	v_readlane_b32 s54, v253, 17
	v_pk_mul_f32 v[140:141], v[72:73], v[84:85] op_sel_hi:[1,0]
	v_sub_u32_e32 v72, 32, v76
	v_ldexp_f32 v72, v74, v72
	v_fmamk_f32 v72, v72, 0x2e000000, v207
	v_rsq_f32_e32 v72, v72
	v_pk_mul_f32 v[158:159], v[94:95], v[84:85] op_sel_hi:[1,0]
	v_pk_mul_f32 v[94:95], v[66:67], v[84:85] op_sel_hi:[1,0]
	v_pk_mul_f32 v[154:155], v[78:79], v[84:85] op_sel_hi:[1,0]
	v_pk_mul_f32 v[66:67], v[60:61], v[72:73] op_sel_hi:[1,0]
	v_ffbh_u32_e32 v60, v145
	v_pk_mul_f32 v[74:75], v[64:65], v[72:73] op_sel_hi:[1,0]
	v_min_u32_e32 v64, 32, v60
	v_lshlrev_b64 v[60:61], v64, v[144:145]
	v_min_u32_e32 v60, 1, v60
	v_or_b32_e32 v60, v61, v60
	v_cvt_f32_u32_e32 v60, v60
	v_pk_mul_f32 v[76:77], v[62:63], v[72:73] op_sel_hi:[1,0]
	v_pk_mul_f32 v[62:63], v[48:49], v[72:73] op_sel_hi:[1,0]
	v_sub_u32_e32 v48, 32, v64
	v_ldexp_f32 v48, v60, v48
	v_fmamk_f32 v48, v48, 0x2e000000, v207
	v_rsq_f32_e32 v78, v48
	v_pk_mul_f32 v[64:65], v[46:47], v[72:73] op_sel_hi:[1,0]
	v_readlane_b32 s62, v253, 18
	v_pk_mul_f32 v[160:161], v[96:97], v[84:85] op_sel_hi:[1,0]
	v_pk_mul_f32 v[46:47], v[34:35], v[78:79] op_sel_hi:[1,0]
; #define LAS __attribute__((address_space(3)))
; __device__ __forceinline__ f32x4 dpp4_shr1(f32x4 o, f32x4 v) { return (f32x4){DPPF(o[0], v[0], 0x111), DPPF(o[1], v[1], 0x111), DPPF(o[2], v[2], 0x111), DPPF(o[3], v[3], 0x111)}; }
; __device__ __forceinline__ f32x4 dpp4_shl1(f32x4 o, f32x4 v) { return (f32x4){DPPF(o[0], v[0], 0x101), DPPF(o[1], v[1], 0x101), DPPF(o[2], v[2], 0x101), DPPF(o[3], v[3], 0x101)}; }
; __device__ __forceinline__ f32x4 dpp4_ror1(f32x4 v) { return (f32x4){DPPF(v[0], v[0], 0x121), DPPF(v[1], v[1], 0x121), DPPF(v[2], v[2], 0x121), DPPF(v[3], v[3], 0x121)}; }
; __device__ __forceinline__ f32x4 dpp4_ror15(f32x4 v) { return (f32x4){DPPF(v[0], v[0], 0x12f), DPPF(v[1], v[1], 0x12f), DPPF(v[2], v[2], 0x12f), DPPF(v[3], v[3], 0x12f)}; }
;     __device__ __forceinline__ void operator()(f32x4 (&acc)[2][2][4][2], const Unit& u, int wr, int wc, int fr_in, int fq_in) const {
;     ...
;         for (int ai = 0; ai < 2; ++ai) { const int blk = 2 * ai + wr;
;             const int upslot = blk > 0 ? (blk - 1) * 2 + 1 : 8, dnslot = blk < 3 ? (blk + 1) * 2 : 8;
; #pragma unroll
;             for (int q = 0; q < 4; ++q) { const int bj = q >> 1, n = q & 1;
;                 asm volatile("" : "+v"(fr), "+v"(fq)); const int lc0 = wc * 32 + 8 * fq;
;                 const int cl = bj * 128 + lc0 + 4 * n;
;                 const f32x4 w0 = *(const LAS f32x4*)(WL + cl), w1 = *(const LAS f32x4*)(WL + 256 + cl), w2 = *(const LAS f32x4*)(WL + 512 + cl), bb = *(const LAS f32x4*)(WL + 768 + cl);
;                 f32x4 carry = *(const LAS f32x4*)(HL + upslot * 256 + bj * 128 + lc0 + 4 * n);
;                 const f32x4 hdn = *(const LAS f32x4*)(HL + dnslot * 256 + bj * 128 + lc0 + 4 * n);
; #pragma unroll
;                 for (int m = 0; m < 4; ++m) { const f32x4 cur = acc[ai][bj][m][n];
;                     const f32x4 up = dpp4_shr1(carry, cur);
;                     const f32x4 nf = m < 3 ? dpp4_ror15(acc[ai][bj][m < 3 ? m + 1 : 3][n]) : hdn;
;                     const f32x4 dn = dpp4_shl1(nf, cur);
;                     carry = dpp4_ror1(cur);
;                     acc[ai][bj][m][n] = w0 * up + w1 * cur + w2 * dn + bb; }
	v_lshlrev_b32_e32 v34, 3, v171
	v_add_lshl_u32 v173, v34, s68, 2
	v_add_u32_e32 v34, s50, v173
	v_pk_mul_f32 v[146:147], v[70:71], v[84:85] op_sel_hi:[1,0]
	v_pk_mul_f32 v[96:97], v[68:69], v[84:85] op_sel_hi:[1,0]
	v_pk_mul_f32 v[68:69], v[58:59], v[72:73] op_sel_hi:[1,0]
	v_pk_mul_f32 v[58:59], v[44:45], v[72:73] op_sel_hi:[1,0]
	v_pk_mul_f32 v[60:61], v[42:43], v[72:73] op_sel_hi:[1,0]
	v_pk_mul_f32 v[72:73], v[56:57], v[78:79] op_sel_hi:[1,0]
	v_pk_mul_f32 v[70:71], v[54:55], v[78:79] op_sel_hi:[1,0]
	v_pk_mul_f32 v[56:57], v[52:53], v[78:79] op_sel_hi:[1,0]
	v_pk_mul_f32 v[54:55], v[50:51], v[78:79] op_sel_hi:[1,0]
	v_pk_mul_f32 v[52:53], v[40:41], v[78:79] op_sel_hi:[1,0]
	v_pk_mul_f32 v[50:51], v[38:39], v[78:79] op_sel_hi:[1,0]
	v_pk_mul_f32 v[48:49], v[36:37], v[78:79] op_sel_hi:[1,0]
	v_add_u32_e32 v35, s54, v173
	ds_read_b128 v[38:41], v34
	ds_read_b128 v[42:45], v35
	v_add_u32_e32 v78, s62, v173
	v_readlane_b32 s75, v253, 19
	v_add_u32_e32 v34, s67, v173
	v_pk_mul_f32 v[162:163], v[104:105], v[150:151] op_sel_hi:[1,0]
	v_pk_mul_f32 v[164:165], v[102:103], v[150:151] op_sel_hi:[1,0]
	v_pk_mul_f32 v[148:149], v[82:83], v[150:151] op_sel_hi:[1,0]
	v_pk_mul_f32 v[150:151], v[80:81], v[84:85] op_sel_hi:[1,0]
	v_add_u32_e32 v82, s75, v173
	ds_read_b128 v[34:37], v34
	ds_read_b128 v[78:81], v78
	ds_read_b128 v[174:177], v82
	v_add_u32_e32 v82, s78, v173
	ds_read_b128 v[186:189], v82
	s_waitcnt lgkmcnt(0)
	v_mov_b32_dpp v34, v122 row_shr:1 row_mask:0xf bank_mask:0xf
	v_mov_b32_dpp v35, v123 row_shr:1 row_mask:0xf bank_mask:0xf
	v_mov_b32_e32 v82, v164
	v_mov_b32_e32 v83, v165
	v_mov_b32_dpp v36, v124 row_shr:1 row_mask:0xf bank_mask:0xf
	v_mov_b32_dpp v37, v125 row_shr:1 row_mask:0xf bank_mask:0xf
	v_mov_b32_dpp v82, v82 row_ror:15 row_mask:0xf bank_mask:0xf
	v_mov_b32_dpp v83, v83 row_ror:15 row_mask:0xf bank_mask:0xf
	v_mov_b32_e32 v84, v162
	v_mov_b32_e32 v85, v163
	v_mov_b32_e32 v102, v122
	v_mov_b32_e32 v103, v123
	v_pk_mul_f32 v[34:35], v[38:39], v[34:35]
	v_mov_b32_dpp v84, v84 row_ror:15 row_mask:0xf bank_mask:0xf
	v_mov_b32_dpp v85, v85 row_ror:15 row_mask:0xf bank_mask:0xf
	v_mov_b32_dpp v82, v122 row_shl:1 row_mask:0xf bank_mask:0xf
	v_mov_b32_dpp v83, v123 row_shl:1 row_mask:0xf bank_mask:0xf
	v_mov_b32_dpp v102, v102 row_ror:1 row_mask:0xf bank_mask:0xf
	v_mov_b32_dpp v103, v103 row_ror:1 row_mask:0xf bank_mask:0xf
	v_mov_b32_e32 v104, v124
	v_mov_b32_e32 v105, v125
	v_pk_mul_f32 v[36:37], v[40:41], v[36:37]
	v_pk_fma_f32 v[34:35], v[122:123], v[42:43], v[34:35]
	v_mov_b32_dpp v84, v124 row_shl:1 row_mask:0xf bank_mask:0xf
	v_mov_b32_dpp v85, v125 row_shl:1 row_mask:0xf bank_mask:0xf
	v_mov_b32_dpp v104, v104 row_ror:1 row_mask:0xf bank_mask:0xf
	v_mov_b32_dpp v105, v105 row_ror:1 row_mask:0xf bank_mask:0xf
	v_pk_fma_f32 v[36:37], v[124:125], v[44:45], v[36:37]
	v_pk_fma_f32 v[34:35], v[78:79], v[82:83], v[34:35]
	v_mov_b32_dpp v102, v164 row_shr:1 row_mask:0xf bank_mask:0xf
	v_mov_b32_dpp v103, v165 row_shr:1 row_mask:0xf bank_mask:0xf
	v_mov_b32_e32 v82, v158
	v_mov_b32_e32 v83, v159
	v_pk_fma_f32 v[36:37], v[80:81], v[84:85], v[36:37]
	v_mov_b32_dpp v104, v162 row_shr:1 row_mask:0xf bank_mask:0xf
	v_mov_b32_dpp v105, v163 row_shr:1 row_mask:0xf bank_mask:0xf
	v_mov_b32_dpp v82, v82 row_ror:15 row_mask:0xf bank_mask:0xf
	v_mov_b32_dpp v83, v83 row_ror:15 row_mask:0xf bank_mask:0xf
	v_mov_b32_e32 v84, v160
	v_mov_b32_e32 v85, v161
	v_pk_mul_f32 v[102:103], v[38:39], v[102:103]
	v_mov_b32_dpp v84, v84 row_ror:15 row_mask:0xf bank_mask:0xf
	v_mov_b32_dpp v85, v85 row_ror:15 row_mask:0xf bank_mask:0xf
	v_mov_b32_dpp v82, v164 row_shl:1 row_mask:0xf bank_mask:0xf
	v_mov_b32_dpp v83, v165 row_shl:1 row_mask:0xf bank_mask:0xf
	v_mov_b32_e32 v122, v164
	v_pk_mul_f32 v[104:105], v[40:41], v[104:105]
	v_pk_fma_f32 v[102:103], v[164:165], v[42:43], v[102:103]
	v_mov_b32_dpp v165, v165 row_ror:1 row_mask:0xf bank_mask:0xf
	v_mov_b32_dpp v84, v162 row_shl:1 row_mask:0xf bank_mask:0xf
	v_mov_b32_dpp v85, v163 row_shl:1 row_mask:0xf bank_mask:0xf
	v_mov_b32_dpp v122, v122 row_ror:1 row_mask:0xf bank_mask:0xf
	v_mov_b32_e32 v124, v162
	v_pk_fma_f32 v[104:105], v[162:163], v[44:45], v[104:105]
	v_mov_b32_dpp v163, v163 row_ror:1 row_mask:0xf bank_mask:0xf
	v_pk_fma_f32 v[82:83], v[78:79], v[82:83], v[102:103]
	v_mov_b32_dpp v165, v159 row_shr:1 row_mask:0xf bank_mask:0xf
	v_mov_b32_dpp v124, v124 row_ror:1 row_mask:0xf bank_mask:0xf
	v_pk_fma_f32 v[84:85], v[80:81], v[84:85], v[104:105]
	v_pk_add_f32 v[104:105], v[174:175], v[82:83]
	v_mov_b32_dpp v122, v158 row_shr:1 row_mask:0xf bank_mask:0xf
	v_mov_b32_dpp v163, v161 row_shr:1 row_mask:0xf bank_mask:0xf
	v_mov_b32_e32 v83, v127
	v_mov_b32_e32 v123, v165
	v_pk_add_f32 v[102:103], v[176:177], v[84:85]
	v_mov_b32_dpp v124, v160 row_shr:1 row_mask:0xf bank_mask:0xf
	v_mov_b32_dpp v83, v83 row_ror:15 row_mask:0xf bank_mask:0xf
	v_mov_b32_e32 v85, v129
	v_pk_mul_f32 v[122:123], v[38:39], v[122:123]
	v_mov_b32_e32 v125, v163
	v_mov_b32_dpp v85, v85 row_ror:15 row_mask:0xf bank_mask:0xf
	v_mov_b32_dpp v83, v159 row_shl:1 row_mask:0xf bank_mask:0xf
	v_mov_b32_e32 v144, v158
	v_pk_mul_f32 v[124:125], v[40:41], v[124:125]
	v_pk_fma_f32 v[122:123], v[158:159], v[42:43], v[122:123]
	v_mov_b32_dpp v159, v159 row_ror:1 row_mask:0xf bank_mask:0xf
	v_mov_b32_dpp v85, v161 row_shl:1 row_mask:0xf bank_mask:0xf
	v_mov_b32_dpp v144, v144 row_ror:1 row_mask:0xf bank_mask:0xf
	v_mov_b32_e32 v162, v160
	v_pk_fma_f32 v[124:125], v[160:161], v[44:45], v[124:125]
	v_mov_b32_dpp v161, v161 row_ror:1 row_mask:0xf bank_mask:0xf
	v_mov_b32_dpp v159, v127 row_shr:1 row_mask:0xf bank_mask:0xf
; #define LAS __attribute__((address_space(3)))
; __device__ __forceinline__ f32x4 dpp4_shr1(f32x4 o, f32x4 v) { return (f32x4){DPPF(o[0], v[0], 0x111), DPPF(o[1], v[1], 0x111), DPPF(o[2], v[2], 0x111), DPPF(o[3], v[3], 0x111)}; }
; __device__ __forceinline__ f32x4 dpp4_shl1(f32x4 o, f32x4 v) { return (f32x4){DPPF(o[0], v[0], 0x101), DPPF(o[1], v[1], 0x101), DPPF(o[2], v[2], 0x101), DPPF(o[3], v[3], 0x101)}; }
; __device__ __forceinline__ f32x4 dpp4_ror1(f32x4 v) { return (f32x4){DPPF(v[0], v[0], 0x121), DPPF(v[1], v[1], 0x121), DPPF(v[2], v[2], 0x121), DPPF(v[3], v[3], 0x121)}; }
; __device__ __forceinline__ f32x4 dpp4_ror15(f32x4 v) { return (f32x4){DPPF(v[0], v[0], 0x12f), DPPF(v[1], v[1], 0x12f), DPPF(v[2], v[2], 0x12f), DPPF(v[3], v[3], 0x12f)}; }
;     __device__ __forceinline__ void operator()(f32x4 (&acc)[2][2][4][2], const Unit& u, int wr, int wc, int fr_in, int fq_in) const {
;     ...
;             for (int q = 0; q < 4; ++q) { const int bj = q >> 1, n = q & 1;
;                 asm volatile("" : "+v"(fr), "+v"(fq)); const int lc0 = wc * 32 + 8 * fq;
;                 const int cl = bj * 128 + lc0 + 4 * n;
;                 const f32x4 w0 = *(const LAS f32x4*)(WL + cl), w1 = *(const LAS f32x4*)(WL + 256 + cl), w2 = *(const LAS f32x4*)(WL + 512 + cl), bb = *(const LAS f32x4*)(WL + 768 + cl);
;                 f32x4 carry = *(const LAS f32x4*)(HL + upslot * 256 + bj * 128 + lc0 + 4 * n);
;                 const f32x4 hdn = *(const LAS f32x4*)(HL + dnslot * 256 + bj * 128 + lc0 + 4 * n);
; #pragma unroll
;                 for (int m = 0; m < 4; ++m) { const f32x4 cur = acc[ai][bj][m][n];
;                     const f32x4 up = dpp4_shr1(carry, cur);
;                     const f32x4 nf = m < 3 ? dpp4_ror15(acc[ai][bj][m < 3 ? m + 1 : 3][n]) : hdn;
;                     const f32x4 dn = dpp4_shl1(nf, cur);
;                     carry = dpp4_ror1(cur);
;                     acc[ai][bj][m][n] = w0 * up + w1 * cur + w2 * dn + bb; }
;                 if (ai == 0) { LAS float* d0 = ((wr == 0) & (fr == 0)) ? PAL + bj * 128 + lc0 + 4 * n : DMP; *(LAS f32x4*)d0 = acc[ai][bj][0][n]; }
;                 if (ai == 1) { LAS float* d1 = ((wr == 1) & (fr == 15)) ? PAL + 256 + bj * 128 + lc0 + 4 * n : DMP; *(LAS f32x4*)d1 = acc[ai][bj][3][n]; }
;                 asm volatile("s_waitcnt lgkmcnt(0)" ::: "memory");
	v_mov_b32_dpp v162, v162 row_ror:1 row_mask:0xf bank_mask:0xf
	v_mov_b32_dpp v144, v126 row_shr:1 row_mask:0xf bank_mask:0xf
	v_mov_b32_dpp v161, v129 row_shr:1 row_mask:0xf bank_mask:0xf
	v_mov_b32_e32 v145, v159
	v_mov_b32_e32 v82, v126
	v_mov_b32_e32 v84, v128
	v_mov_b32_dpp v162, v128 row_shr:1 row_mask:0xf bank_mask:0xf
	v_mov_b32_e32 v163, v161
	v_pk_mul_f32 v[38:39], v[38:39], v[144:145]
	v_mov_b32_dpp v82, v82 row_ror:15 row_mask:0xf bank_mask:0xf
	v_mov_b32_dpp v84, v84 row_ror:15 row_mask:0xf bank_mask:0xf
	v_mov_b32_dpp v186, v126 row_shl:1 row_mask:0xf bank_mask:0xf
	v_mov_b32_dpp v187, v127 row_shl:1 row_mask:0xf bank_mask:0xf
	v_pk_mul_f32 v[40:41], v[40:41], v[162:163]
	v_pk_fma_f32 v[38:39], v[126:127], v[42:43], v[38:39]
	v_mov_b32_dpp v82, v158 row_shl:1 row_mask:0xf bank_mask:0xf
	v_mov_b32_dpp v84, v160 row_shl:1 row_mask:0xf bank_mask:0xf
	v_mov_b32_dpp v188, v128 row_shl:1 row_mask:0xf bank_mask:0xf
	v_mov_b32_dpp v189, v129 row_shl:1 row_mask:0xf bank_mask:0xf
	v_pk_fma_f32 v[40:41], v[128:129], v[44:45], v[40:41]
	v_pk_fma_f32 v[38:39], v[78:79], v[186:187], v[38:39]
	v_pk_fma_f32 v[122:123], v[78:79], v[82:83], v[122:123]
	v_pk_fma_f32 v[82:83], v[80:81], v[84:85], v[124:125]
	v_pk_fma_f32 v[40:41], v[80:81], v[188:189], v[40:41]
	v_pk_add_f32 v[80:81], v[174:175], v[38:39]
	v_or_b32_e32 v38, s3, v170
	v_readlane_b32 s51, v253, 20
	v_cmp_eq_u32_e32 vcc, 0, v38
	v_pk_add_f32 v[36:37], v[176:177], v[36:37]
	v_add_u32_e32 v39, s51, v173
	v_pk_add_f32 v[34:35], v[174:175], v[34:35]
	v_cndmask_b32_e32 v38, v172, v39, vcc
	ds_write_b128 v38, v[34:37]
	s_waitcnt lgkmcnt(0)
	v_pk_add_f32 v[84:85], v[174:175], v[122:123]
	v_lshlrev_b32_e32 v38, 3, v171
	v_add_lshl_u32 v173, v38, s68, 2
	v_or_b32_e32 v38, 16, v173
	v_pk_add_f32 v[78:79], v[176:177], v[40:41]
	v_add_u32_e32 v39, s50, v38
	v_add_u32_e32 v40, s54, v38
	v_add_u32_e32 v122, s62, v38
	v_add_u32_e32 v123, s75, v38
	v_add_u32_e32 v38, s67, v173
	v_pk_add_f32 v[82:83], v[176:177], v[82:83]
	ds_read_b128 v[42:45], v39
	ds_read_b128 v[158:161], v40
	ds_read_b128 v[38:41], v38 offset:16
	ds_read_b128 v[162:165], v122
	ds_read_b128 v[174:177], v123
	v_add_u32_e32 v122, s78, v173
	ds_read_b128 v[186:189], v122 offset:16
	s_waitcnt lgkmcnt(0)
	v_mov_b32_dpp v38, v114 row_shr:1 row_mask:0xf bank_mask:0xf
	v_mov_b32_dpp v39, v115 row_shr:1 row_mask:0xf bank_mask:0xf
	v_mov_b32_e32 v122, v156
	v_mov_b32_e32 v123, v157
	v_mov_b32_e32 v126, v114
	v_mov_b32_e32 v127, v115
	v_mov_b32_dpp v40, v116 row_shr:1 row_mask:0xf bank_mask:0xf
	v_mov_b32_dpp v41, v117 row_shr:1 row_mask:0xf bank_mask:0xf
	v_mov_b32_dpp v122, v122 row_ror:15 row_mask:0xf bank_mask:0xf
	v_mov_b32_dpp v123, v123 row_ror:15 row_mask:0xf bank_mask:0xf
	v_mov_b32_e32 v124, v152
	v_mov_b32_e32 v125, v153
	v_mov_b32_dpp v126, v126 row_ror:1 row_mask:0xf bank_mask:0xf
	v_mov_b32_dpp v127, v127 row_ror:1 row_mask:0xf bank_mask:0xf
	v_mov_b32_e32 v128, v116
	v_mov_b32_e32 v129, v117
	v_pk_mul_f32 v[38:39], v[42:43], v[38:39]
	v_mov_b32_dpp v124, v124 row_ror:15 row_mask:0xf bank_mask:0xf
	v_mov_b32_dpp v125, v125 row_ror:15 row_mask:0xf bank_mask:0xf
	v_mov_b32_dpp v122, v114 row_shl:1 row_mask:0xf bank_mask:0xf
	v_mov_b32_dpp v123, v115 row_shl:1 row_mask:0xf bank_mask:0xf
	v_mov_b32_dpp v128, v128 row_ror:1 row_mask:0xf bank_mask:0xf
	v_mov_b32_dpp v129, v129 row_ror:1 row_mask:0xf bank_mask:0xf
	v_pk_mul_f32 v[40:41], v[44:45], v[40:41]
	v_pk_fma_f32 v[38:39], v[114:115], v[158:159], v[38:39]
	v_mov_b32_dpp v126, v156 row_shr:1 row_mask:0xf bank_mask:0xf
	v_mov_b32_dpp v127, v157 row_shr:1 row_mask:0xf bank_mask:0xf
	v_mov_b32_e32 v114, v154
	v_mov_b32_e32 v115, v155
	v_mov_b32_dpp v124, v116 row_shl:1 row_mask:0xf bank_mask:0xf
	v_mov_b32_dpp v125, v117 row_shl:1 row_mask:0xf bank_mask:0xf
	v_pk_fma_f32 v[40:41], v[116:117], v[160:161], v[40:41]
	v_mov_b32_dpp v128, v152 row_shr:1 row_mask:0xf bank_mask:0xf
	v_mov_b32_dpp v129, v153 row_shr:1 row_mask:0xf bank_mask:0xf
	v_mov_b32_dpp v114, v114 row_ror:15 row_mask:0xf bank_mask:0xf
	v_mov_b32_dpp v115, v115 row_ror:15 row_mask:0xf bank_mask:0xf
	v_mov_b32_e32 v116, v150
	v_mov_b32_e32 v117, v151
	v_pk_mul_f32 v[126:127], v[42:43], v[126:127]
	v_pk_fma_f32 v[38:39], v[162:163], v[122:123], v[38:39]
	v_mov_b32_dpp v116, v116 row_ror:15 row_mask:0xf bank_mask:0xf
	v_mov_b32_dpp v117, v117 row_ror:15 row_mask:0xf bank_mask:0xf
	v_mov_b32_dpp v114, v156 row_shl:1 row_mask:0xf bank_mask:0xf
	v_mov_b32_dpp v115, v157 row_shl:1 row_mask:0xf bank_mask:0xf
	v_mov_b32_e32 v122, v156
	v_pk_mul_f32 v[128:129], v[44:45], v[128:129]
	v_pk_fma_f32 v[126:127], v[156:157], v[158:159], v[126:127]
	v_mov_b32_dpp v157, v157 row_ror:1 row_mask:0xf bank_mask:0xf
	v_mov_b32_dpp v116, v152 row_shl:1 row_mask:0xf bank_mask:0xf
	v_mov_b32_dpp v117, v153 row_shl:1 row_mask:0xf bank_mask:0xf
	v_mov_b32_dpp v122, v122 row_ror:1 row_mask:0xf bank_mask:0xf
	v_pk_fma_f32 v[128:129], v[152:153], v[160:161], v[128:129]
	v_pk_fma_f32 v[114:115], v[162:163], v[114:115], v[126:127]
	v_mov_b32_dpp v157, v155 row_shr:1 row_mask:0xf bank_mask:0xf
	v_pk_fma_f32 v[116:117], v[164:165], v[116:117], v[128:129]
	v_pk_add_f32 v[128:129], v[174:175], v[114:115]
	v_mov_b32_dpp v122, v154 row_shr:1 row_mask:0xf bank_mask:0xf
	v_mov_b32_e32 v115, v119
	v_mov_b32_e32 v123, v157
	v_pk_mul_f32 v[122:123], v[42:43], v[122:123]
	v_mov_b32_dpp v115, v115 row_ror:15 row_mask:0xf bank_mask:0xf
	v_pk_fma_f32 v[40:41], v[164:165], v[124:125], v[40:41]
	v_mov_b32_e32 v124, v152
	v_mov_b32_dpp v153, v153 row_ror:1 row_mask:0xf bank_mask:0xf
	v_mov_b32_dpp v115, v155 row_shl:1 row_mask:0xf bank_mask:0xf
	v_mov_b32_e32 v144, v154
; #define LAS __attribute__((address_space(3)))
; __device__ __forceinline__ f32x4 dpp4_shr1(f32x4 o, f32x4 v) { return (f32x4){DPPF(o[0], v[0], 0x111), DPPF(o[1], v[1], 0x111), DPPF(o[2], v[2], 0x111), DPPF(o[3], v[3], 0x111)}; }
; __device__ __forceinline__ f32x4 dpp4_shl1(f32x4 o, f32x4 v) { return (f32x4){DPPF(o[0], v[0], 0x101), DPPF(o[1], v[1], 0x101), DPPF(o[2], v[2], 0x101), DPPF(o[3], v[3], 0x101)}; }
; __device__ __forceinline__ f32x4 dpp4_ror1(f32x4 v) { return (f32x4){DPPF(v[0], v[0], 0x121), DPPF(v[1], v[1], 0x121), DPPF(v[2], v[2], 0x121), DPPF(v[3], v[3], 0x121)}; }
; __device__ __forceinline__ f32x4 dpp4_ror15(f32x4 v) { return (f32x4){DPPF(v[0], v[0], 0x12f), DPPF(v[1], v[1], 0x12f), DPPF(v[2], v[2], 0x12f), DPPF(v[3], v[3], 0x12f)}; }
;     __device__ __forceinline__ void operator()(f32x4 (&acc)[2][2][4][2], const Unit& u, int wr, int wc, int fr_in, int fq_in) const {
;     ...
;             for (int q = 0; q < 4; ++q) { const int bj = q >> 1, n = q & 1;
;                 asm volatile("" : "+v"(fr), "+v"(fq)); const int lc0 = wc * 32 + 8 * fq;
;                 const int cl = bj * 128 + lc0 + 4 * n;
;                 const f32x4 w0 = *(const LAS f32x4*)(WL + cl), w1 = *(const LAS f32x4*)(WL + 256 + cl), w2 = *(const LAS f32x4*)(WL + 512 + cl), bb = *(const LAS f32x4*)(WL + 768 + cl);
;                 f32x4 carry = *(const LAS f32x4*)(HL + upslot * 256 + bj * 128 + lc0 + 4 * n);
;                 const f32x4 hdn = *(const LAS f32x4*)(HL + dnslot * 256 + bj * 128 + lc0 + 4 * n);
; #pragma unroll
;                 for (int m = 0; m < 4; ++m) { const f32x4 cur = acc[ai][bj][m][n];
;                     const f32x4 up = dpp4_shr1(carry, cur);
;                     const f32x4 nf = m < 3 ? dpp4_ror15(acc[ai][bj][m < 3 ? m + 1 : 3][n]) : hdn;
;                     const f32x4 dn = dpp4_shl1(nf, cur);
;                     carry = dpp4_ror1(cur);
;                     acc[ai][bj][m][n] = w0 * up + w1 * cur + w2 * dn + bb; }
;                 if (ai == 0) { LAS float* d0 = ((wr == 0) & (fr == 0)) ? PAL + bj * 128 + lc0 + 4 * n : DMP; *(LAS f32x4*)d0 = acc[ai][bj][0][n]; }
;                 if (ai == 1) { LAS float* d1 = ((wr == 1) & (fr == 15)) ? PAL + 256 + bj * 128 + lc0 + 4 * n : DMP; *(LAS f32x4*)d1 = acc[ai][bj][3][n]; }
;                 asm volatile("s_waitcnt lgkmcnt(0)" ::: "memory");
	v_pk_fma_f32 v[122:123], v[154:155], v[158:159], v[122:123]
	v_mov_b32_dpp v155, v155 row_ror:1 row_mask:0xf bank_mask:0xf
	v_mov_b32_dpp v124, v124 row_ror:1 row_mask:0xf bank_mask:0xf
	v_mov_b32_dpp v153, v151 row_shr:1 row_mask:0xf bank_mask:0xf
	v_mov_b32_dpp v144, v144 row_ror:1 row_mask:0xf bank_mask:0xf
	v_mov_b32_dpp v155, v119 row_shr:1 row_mask:0xf bank_mask:0xf
	v_pk_add_f32 v[126:127], v[176:177], v[116:117]
	v_mov_b32_dpp v124, v150 row_shr:1 row_mask:0xf bank_mask:0xf
	v_mov_b32_e32 v116, v120
	v_mov_b32_e32 v117, v121
	v_mov_b32_e32 v125, v153
	v_mov_b32_dpp v144, v118 row_shr:1 row_mask:0xf bank_mask:0xf
	v_mov_b32_e32 v145, v155
	v_mov_b32_e32 v114, v118
	v_mov_b32_dpp v116, v116 row_ror:15 row_mask:0xf bank_mask:0xf
	v_mov_b32_dpp v117, v117 row_ror:15 row_mask:0xf bank_mask:0xf
	v_pk_mul_f32 v[124:125], v[44:45], v[124:125]
	v_pk_mul_f32 v[42:43], v[42:43], v[144:145]
	v_mov_b32_dpp v114, v114 row_ror:15 row_mask:0xf bank_mask:0xf
	v_mov_b32_dpp v116, v150 row_shl:1 row_mask:0xf bank_mask:0xf
	v_mov_b32_dpp v117, v151 row_shl:1 row_mask:0xf bank_mask:0xf
	v_pk_fma_f32 v[124:125], v[150:151], v[160:161], v[124:125]
	v_mov_b32_dpp v186, v118 row_shl:1 row_mask:0xf bank_mask:0xf
	v_mov_b32_dpp v187, v119 row_shl:1 row_mask:0xf bank_mask:0xf
	v_pk_fma_f32 v[42:43], v[118:119], v[158:159], v[42:43]
	v_mov_b32_dpp v114, v154 row_shl:1 row_mask:0xf bank_mask:0xf
	v_pk_fma_f32 v[116:117], v[164:165], v[116:117], v[124:125]
	v_pk_fma_f32 v[42:43], v[162:163], v[186:187], v[42:43]
	v_mov_b32_e32 v152, v150
	v_mov_b32_dpp v151, v151 row_ror:1 row_mask:0xf bank_mask:0xf
	v_pk_fma_f32 v[114:115], v[162:163], v[114:115], v[122:123]
	v_pk_add_f32 v[122:123], v[176:177], v[116:117]
	v_pk_add_f32 v[116:117], v[174:175], v[42:43]
	v_or_b32_e32 v42, s3, v170
	v_mov_b32_dpp v152, v152 row_ror:1 row_mask:0xf bank_mask:0xf
	v_mov_b32_dpp v151, v121 row_shr:1 row_mask:0xf bank_mask:0xf
	v_add3_u32 v43, s51, v173, 16
	v_cmp_eq_u32_e32 vcc, 0, v42
	v_pk_add_f32 v[40:41], v[176:177], v[40:41]
	v_pk_add_f32 v[38:39], v[174:175], v[38:39]
	v_mov_b32_dpp v152, v120 row_shr:1 row_mask:0xf bank_mask:0xf
	v_mov_b32_e32 v153, v151
	v_cndmask_b32_e32 v42, v172, v43, vcc
	v_pk_mul_f32 v[44:45], v[44:45], v[152:153]
	ds_write_b128 v42, v[38:41]
	v_mov_b32_dpp v188, v120 row_shl:1 row_mask:0xf bank_mask:0xf
	v_mov_b32_dpp v189, v121 row_shl:1 row_mask:0xf bank_mask:0xf
	v_pk_fma_f32 v[44:45], v[120:121], v[160:161], v[44:45]
	s_waitcnt lgkmcnt(0)
	v_pk_add_f32 v[124:125], v[174:175], v[114:115]
	v_lshlrev_b32_e32 v42, 3, v171
	v_pk_fma_f32 v[44:45], v[164:165], v[188:189], v[44:45]
	v_add_lshl_u32 v164, v42, s68, 2
	v_add_u32_e32 v42, 0x200, v164
	v_pk_add_f32 v[114:115], v[176:177], v[44:45]
	v_add_u32_e32 v43, s50, v42
	v_add_u32_e32 v44, s54, v42
	v_add_u32_e32 v118, s62, v42
	v_add_u32_e32 v119, s75, v42
	v_add_u32_e32 v42, s67, v164
	ds_read_b128 v[152:155], v43
	ds_read_b128 v[156:159], v44
	ds_read_b128 v[42:45], v42 offset:512
	ds_read_b128 v[160:163], v118
	ds_read_b128 v[174:177], v119
	v_add_u32_e32 v118, s78, v164
	ds_read_b128 v[186:189], v118 offset:512
	s_waitcnt lgkmcnt(0)
	v_mov_b32_dpp v42, v106 row_shr:1 row_mask:0xf bank_mask:0xf
	v_mov_b32_dpp v43, v107 row_shr:1 row_mask:0xf bank_mask:0xf
	v_mov_b32_e32 v118, v148
	v_mov_b32_e32 v119, v149
	v_mov_b32_e32 v144, v106
	v_mov_b32_e32 v145, v107
	v_mov_b32_dpp v44, v108 row_shr:1 row_mask:0xf bank_mask:0xf
	v_mov_b32_dpp v45, v109 row_shr:1 row_mask:0xf bank_mask:0xf
	v_mov_b32_dpp v118, v118 row_ror:15 row_mask:0xf bank_mask:0xf
	v_mov_b32_dpp v119, v119 row_ror:15 row_mask:0xf bank_mask:0xf
	v_mov_b32_e32 v120, v142
	v_mov_b32_e32 v121, v143
	v_mov_b32_dpp v144, v144 row_ror:1 row_mask:0xf bank_mask:0xf
	v_mov_b32_dpp v145, v145 row_ror:1 row_mask:0xf bank_mask:0xf
	v_mov_b32_e32 v150, v108
	v_mov_b32_e32 v151, v109
	v_pk_mul_f32 v[42:43], v[152:153], v[42:43]
	v_mov_b32_dpp v120, v120 row_ror:15 row_mask:0xf bank_mask:0xf
	v_mov_b32_dpp v121, v121 row_ror:15 row_mask:0xf bank_mask:0xf
	v_mov_b32_dpp v118, v106 row_shl:1 row_mask:0xf bank_mask:0xf
	v_mov_b32_dpp v119, v107 row_shl:1 row_mask:0xf bank_mask:0xf
	v_mov_b32_dpp v150, v150 row_ror:1 row_mask:0xf bank_mask:0xf
	v_mov_b32_dpp v151, v151 row_ror:1 row_mask:0xf bank_mask:0xf
	v_pk_mul_f32 v[44:45], v[154:155], v[44:45]
	v_pk_fma_f32 v[42:43], v[106:107], v[156:157], v[42:43]
	v_mov_b32_dpp v144, v148 row_shr:1 row_mask:0xf bank_mask:0xf
	v_mov_b32_dpp v145, v149 row_shr:1 row_mask:0xf bank_mask:0xf
	v_mov_b32_e32 v106, v146
	v_mov_b32_e32 v107, v147
	v_mov_b32_dpp v120, v108 row_shl:1 row_mask:0xf bank_mask:0xf
	v_mov_b32_dpp v121, v109 row_shl:1 row_mask:0xf bank_mask:0xf
	v_pk_fma_f32 v[44:45], v[108:109], v[158:159], v[44:45]
	v_mov_b32_dpp v150, v142 row_shr:1 row_mask:0xf bank_mask:0xf
	v_mov_b32_dpp v151, v143 row_shr:1 row_mask:0xf bank_mask:0xf
	v_mov_b32_dpp v106, v106 row_ror:15 row_mask:0xf bank_mask:0xf
	v_mov_b32_dpp v107, v107 row_ror:15 row_mask:0xf bank_mask:0xf
	v_mov_b32_e32 v108, v140
	v_mov_b32_e32 v109, v141
	v_pk_mul_f32 v[144:145], v[152:153], v[144:145]
	v_pk_fma_f32 v[42:43], v[160:161], v[118:119], v[42:43]
	v_mov_b32_dpp v108, v108 row_ror:15 row_mask:0xf bank_mask:0xf
	v_mov_b32_dpp v109, v109 row_ror:15 row_mask:0xf bank_mask:0xf
	v_mov_b32_dpp v106, v148 row_shl:1 row_mask:0xf bank_mask:0xf
	v_mov_b32_dpp v107, v149 row_shl:1 row_mask:0xf bank_mask:0xf
	v_mov_b32_e32 v118, v148
	v_pk_mul_f32 v[150:151], v[154:155], v[150:151]
	v_pk_fma_f32 v[144:145], v[148:149], v[156:157], v[144:145]
	v_mov_b32_dpp v149, v149 row_ror:1 row_mask:0xf bank_mask:0xf
	v_pk_fma_f32 v[44:45], v[162:163], v[120:121], v[44:45]
; #define LAS __attribute__((address_space(3)))
; __device__ __forceinline__ f32x4 dpp4_shr1(f32x4 o, f32x4 v) { return (f32x4){DPPF(o[0], v[0], 0x111), DPPF(o[1], v[1], 0x111), DPPF(o[2], v[2], 0x111), DPPF(o[3], v[3], 0x111)}; }
; __device__ __forceinline__ f32x4 dpp4_shl1(f32x4 o, f32x4 v) { return (f32x4){DPPF(o[0], v[0], 0x101), DPPF(o[1], v[1], 0x101), DPPF(o[2], v[2], 0x101), DPPF(o[3], v[3], 0x101)}; }
; __device__ __forceinline__ f32x4 dpp4_ror1(f32x4 v) { return (f32x4){DPPF(v[0], v[0], 0x121), DPPF(v[1], v[1], 0x121), DPPF(v[2], v[2], 0x121), DPPF(v[3], v[3], 0x121)}; }
; __device__ __forceinline__ f32x4 dpp4_ror15(f32x4 v) { return (f32x4){DPPF(v[0], v[0], 0x12f), DPPF(v[1], v[1], 0x12f), DPPF(v[2], v[2], 0x12f), DPPF(v[3], v[3], 0x12f)}; }
;     __device__ __forceinline__ void operator()(f32x4 (&acc)[2][2][4][2], const Unit& u, int wr, int wc, int fr_in, int fq_in) const {
;     ...
;             for (int q = 0; q < 4; ++q) { const int bj = q >> 1, n = q & 1;
;                 asm volatile("" : "+v"(fr), "+v"(fq)); const int lc0 = wc * 32 + 8 * fq;
;                 const int cl = bj * 128 + lc0 + 4 * n;
;                 const f32x4 w0 = *(const LAS f32x4*)(WL + cl), w1 = *(const LAS f32x4*)(WL + 256 + cl), w2 = *(const LAS f32x4*)(WL + 512 + cl), bb = *(const LAS f32x4*)(WL + 768 + cl);
;                 f32x4 carry = *(const LAS f32x4*)(HL + upslot * 256 + bj * 128 + lc0 + 4 * n);
;                 const f32x4 hdn = *(const LAS f32x4*)(HL + dnslot * 256 + bj * 128 + lc0 + 4 * n);
; #pragma unroll
;                 for (int m = 0; m < 4; ++m) { const f32x4 cur = acc[ai][bj][m][n];
;                     const f32x4 up = dpp4_shr1(carry, cur);
;                     const f32x4 nf = m < 3 ? dpp4_ror15(acc[ai][bj][m < 3 ? m + 1 : 3][n]) : hdn;
;                     const f32x4 dn = dpp4_shl1(nf, cur);
;                     carry = dpp4_ror1(cur);
;                     acc[ai][bj][m][n] = w0 * up + w1 * cur + w2 * dn + bb; }
;                 if (ai == 0) { LAS float* d0 = ((wr == 0) & (fr == 0)) ? PAL + bj * 128 + lc0 + 4 * n : DMP; *(LAS f32x4*)d0 = acc[ai][bj][0][n]; }
;                 if (ai == 1) { LAS float* d1 = ((wr == 1) & (fr == 15)) ? PAL + 256 + bj * 128 + lc0 + 4 * n : DMP; *(LAS f32x4*)d1 = acc[ai][bj][3][n]; }
;                 asm volatile("s_waitcnt lgkmcnt(0)" ::: "memory");
	v_mov_b32_dpp v108, v142 row_shl:1 row_mask:0xf bank_mask:0xf
	v_mov_b32_dpp v109, v143 row_shl:1 row_mask:0xf bank_mask:0xf
	v_mov_b32_dpp v118, v118 row_ror:1 row_mask:0xf bank_mask:0xf
	v_mov_b32_e32 v120, v142
	v_pk_fma_f32 v[150:151], v[142:143], v[158:159], v[150:151]
	v_mov_b32_dpp v143, v143 row_ror:1 row_mask:0xf bank_mask:0xf
	v_pk_fma_f32 v[106:107], v[160:161], v[106:107], v[144:145]
	v_mov_b32_dpp v149, v147 row_shr:1 row_mask:0xf bank_mask:0xf
	v_mov_b32_dpp v120, v120 row_ror:1 row_mask:0xf bank_mask:0xf
	v_pk_fma_f32 v[108:109], v[162:163], v[108:109], v[150:151]
	v_pk_add_f32 v[150:151], v[174:175], v[106:107]
	v_mov_b32_dpp v118, v146 row_shr:1 row_mask:0xf bank_mask:0xf
	v_mov_b32_dpp v143, v141 row_shr:1 row_mask:0xf bank_mask:0xf
	v_mov_b32_e32 v107, v111
	v_mov_b32_e32 v119, v149
	v_pk_add_f32 v[144:145], v[176:177], v[108:109]
	v_mov_b32_dpp v120, v140 row_shr:1 row_mask:0xf bank_mask:0xf
	v_mov_b32_dpp v107, v107 row_ror:15 row_mask:0xf bank_mask:0xf
	v_mov_b32_e32 v108, v112
	v_mov_b32_e32 v109, v113
	v_pk_mul_f32 v[118:119], v[152:153], v[118:119]
	v_mov_b32_e32 v121, v143
	v_mov_b32_e32 v106, v110
	v_mov_b32_dpp v108, v108 row_ror:15 row_mask:0xf bank_mask:0xf
	v_mov_b32_dpp v109, v109 row_ror:15 row_mask:0xf bank_mask:0xf
	v_mov_b32_dpp v107, v147 row_shl:1 row_mask:0xf bank_mask:0xf
	v_mov_b32_e32 v142, v146
	v_pk_mul_f32 v[120:121], v[154:155], v[120:121]
	v_pk_fma_f32 v[118:119], v[146:147], v[156:157], v[118:119]
	v_mov_b32_dpp v147, v147 row_ror:1 row_mask:0xf bank_mask:0xf
	v_mov_b32_dpp v106, v106 row_ror:15 row_mask:0xf bank_mask:0xf
	v_mov_b32_dpp v108, v140 row_shl:1 row_mask:0xf bank_mask:0xf
	v_mov_b32_dpp v109, v141 row_shl:1 row_mask:0xf bank_mask:0xf
	v_mov_b32_dpp v142, v142 row_ror:1 row_mask:0xf bank_mask:0xf
	v_pk_fma_f32 v[120:121], v[140:141], v[158:159], v[120:121]
	v_mov_b32_dpp v147, v111 row_shr:1 row_mask:0xf bank_mask:0xf
	v_mov_b32_dpp v106, v146 row_shl:1 row_mask:0xf bank_mask:0xf
	v_pk_fma_f32 v[108:109], v[162:163], v[108:109], v[120:121]
	v_mov_b32_dpp v142, v110 row_shr:1 row_mask:0xf bank_mask:0xf
	v_mov_b32_e32 v143, v147
	v_pk_fma_f32 v[106:107], v[160:161], v[106:107], v[118:119]
	v_pk_add_f32 v[118:119], v[176:177], v[108:109]
	v_pk_mul_f32 v[108:109], v[152:153], v[142:143]
	v_mov_b32_dpp v186, v110 row_shl:1 row_mask:0xf bank_mask:0xf
	v_pk_fma_f32 v[108:109], v[110:111], v[156:157], v[108:109]
	v_or_b32_e32 v110, s3, v170
	v_readlane_b32 s51, v253, 21
	v_mov_b32_dpp v187, v111 row_shl:1 row_mask:0xf bank_mask:0xf
	v_cmp_eq_u32_e32 vcc, 0, v110
	v_add_u32_e32 v111, s51, v164
	v_pk_add_f32 v[44:45], v[176:177], v[44:45]
	v_pk_add_f32 v[42:43], v[174:175], v[42:43]
	v_cndmask_b32_e32 v110, v172, v111, vcc
	v_mov_b32_e32 v148, v140
	v_mov_b32_dpp v141, v141 row_ror:1 row_mask:0xf bank_mask:0xf
	ds_write_b128 v110, v[42:45]
	v_mov_b32_dpp v148, v148 row_ror:1 row_mask:0xf bank_mask:0xf
	v_mov_b32_dpp v141, v113 row_shr:1 row_mask:0xf bank_mask:0xf
	s_waitcnt lgkmcnt(0)
	v_mov_b32_e32 v149, v141
	v_lshlrev_b32_e32 v110, 3, v171
	v_mov_b32_dpp v148, v112 row_shr:1 row_mask:0xf bank_mask:0xf
	v_add_lshl_u32 v173, v110, s68, 2
	v_pk_add_f32 v[120:121], v[174:175], v[106:107]
	v_pk_mul_f32 v[106:107], v[154:155], v[148:149]
	v_add_u32_e32 v110, 0x210, v173
	v_mov_b32_dpp v188, v112 row_shl:1 row_mask:0xf bank_mask:0xf
	v_pk_fma_f32 v[106:107], v[112:113], v[158:159], v[106:107]
	v_add_u32_e32 v111, s50, v110
	v_add_u32_e32 v112, s54, v110
	v_add_u32_e32 v152, s62, v110
	v_add_u32_e32 v156, s75, v110
	v_add_u32_e32 v110, s67, v173
	v_mov_b32_dpp v189, v113 row_shl:1 row_mask:0xf bank_mask:0xf
	ds_read_b128 v[140:143], v111
	ds_read_b128 v[146:149], v112
	ds_read_b128 v[110:113], v110 offset:528
	ds_read_b128 v[152:155], v152
	ds_read_b128 v[156:159], v156
	v_pk_fma_f32 v[108:109], v[160:161], v[186:187], v[108:109]
	v_mov_b32_e32 v164, v100
	s_waitcnt lgkmcnt(0)
	v_mov_b32_dpp v110, v86 row_shr:1 row_mask:0xf bank_mask:0xf
	v_mov_b32_dpp v111, v87 row_shr:1 row_mask:0xf bank_mask:0xf
	v_mov_b32_e32 v165, v101
	v_pk_add_f32 v[108:109], v[174:175], v[108:109]
	v_mov_b32_dpp v112, v88 row_shr:1 row_mask:0xf bank_mask:0xf
	v_mov_b32_dpp v113, v89 row_shr:1 row_mask:0xf bank_mask:0xf
	v_mov_b32_dpp v164, v164 row_ror:15 row_mask:0xf bank_mask:0xf
	v_mov_b32_dpp v165, v165 row_ror:15 row_mask:0xf bank_mask:0xf
	v_mov_b32_e32 v174, v98
	v_mov_b32_e32 v175, v99
	v_pk_mul_f32 v[110:111], v[140:141], v[110:111]
	v_mov_b32_dpp v174, v174 row_ror:15 row_mask:0xf bank_mask:0xf
	v_mov_b32_dpp v175, v175 row_ror:15 row_mask:0xf bank_mask:0xf
	v_mov_b32_dpp v164, v86 row_shl:1 row_mask:0xf bank_mask:0xf
	v_mov_b32_dpp v165, v87 row_shl:1 row_mask:0xf bank_mask:0xf
	v_mov_b32_e32 v186, v86
	v_mov_b32_e32 v187, v87
	v_pk_mul_f32 v[112:113], v[142:143], v[112:113]
	v_pk_fma_f32 v[86:87], v[86:87], v[146:147], v[110:111]
	v_pk_fma_f32 v[106:107], v[162:163], v[188:189], v[106:107]
	v_mov_b32_dpp v174, v88 row_shl:1 row_mask:0xf bank_mask:0xf
	v_mov_b32_dpp v175, v89 row_shl:1 row_mask:0xf bank_mask:0xf
	v_mov_b32_dpp v186, v186 row_ror:1 row_mask:0xf bank_mask:0xf
	v_mov_b32_dpp v187, v187 row_ror:1 row_mask:0xf bank_mask:0xf
	v_mov_b32_e32 v188, v88
	v_mov_b32_e32 v189, v89
	v_pk_fma_f32 v[88:89], v[88:89], v[148:149], v[112:113]
	v_pk_fma_f32 v[86:87], v[152:153], v[164:165], v[86:87]
	v_mov_b32_dpp v188, v188 row_ror:1 row_mask:0xf bank_mask:0xf
	v_mov_b32_dpp v189, v189 row_ror:1 row_mask:0xf bank_mask:0xf
	v_pk_fma_f32 v[88:89], v[154:155], v[174:175], v[88:89]
	v_pk_add_f32 v[174:175], v[156:157], v[86:87]
	v_mov_b32_dpp v186, v100 row_shr:1 row_mask:0xf bank_mask:0xf
; #define LAS __attribute__((address_space(3)))
; __device__ __forceinline__ unsigned cvt_pk_bf16(float lo, float hi) { unsigned r; asm volatile("v_cvt_pk_bf16_f32 %0, %1, %2" : "=v"(r) : "v"(lo), "v"(hi)); return r; }
; __device__ __forceinline__ float siluf(float x) { return x * __builtin_amdgcn_rcpf(1.f + __expf(-x)); }
;     __device__ __forceinline__ void operator()(f32x4 (&acc)[2][2][4][2], const Unit& u, int wr, int wc, int fr_in, int fq_in) const {
;     ...
;             for (int q = 0; q < 4; ++q) { const int bj = q >> 1, n = q & 1;
;                 asm volatile("" : "+v"(fr), "+v"(fq)); const int lc0 = wc * 32 + 8 * fq;
;                 const int cl = bj * 128 + lc0 + 4 * n;
;                 const f32x4 w0 = *(const LAS f32x4*)(WL + cl), w1 = *(const LAS f32x4*)(WL + 256 + cl), w2 = *(const LAS f32x4*)(WL + 512 + cl), bb = *(const LAS f32x4*)(WL + 768 + cl);
;                 f32x4 carry = *(const LAS f32x4*)(HL + upslot * 256 + bj * 128 + lc0 + 4 * n);
;                 const f32x4 hdn = *(const LAS f32x4*)(HL + dnslot * 256 + bj * 128 + lc0 + 4 * n);
; #pragma unroll
;                 for (int m = 0; m < 4; ++m) { const f32x4 cur = acc[ai][bj][m][n];
;                     const f32x4 up = dpp4_shr1(carry, cur);
;                     const f32x4 nf = m < 3 ? dpp4_ror15(acc[ai][bj][m < 3 ? m + 1 : 3][n]) : hdn;
;                     const f32x4 dn = dpp4_shl1(nf, cur);
;                     carry = dpp4_ror1(cur);
;                     acc[ai][bj][m][n] = w0 * up + w1 * cur + w2 * dn + bb; }
;                 if (ai == 0) { LAS float* d0 = ((wr == 0) & (fr == 0)) ? PAL + bj * 128 + lc0 + 4 * n : DMP; *(LAS f32x4*)d0 = acc[ai][bj][0][n]; }
;                 if (ai == 1) { LAS float* d1 = ((wr == 1) & (fr == 15)) ? PAL + 256 + bj * 128 + lc0 + 4 * n : DMP; *(LAS f32x4*)d1 = acc[ai][bj][3][n]; }
;                 asm volatile("s_waitcnt lgkmcnt(0)" ::: "memory");
;             }
;             asm volatile("" : "+v"(fr), "+v"(fq));
; #pragma unroll
;             for (int m = 0; m < 4; ++m) { const int row = u.pm * BM + ai * HALF + wr * 64 + m * 16 + fr;
;                 const f32x4 a0 = acc[ai][0][m][0], a1 = acc[ai][0][m][1], g0 = acc[ai][1][m][0], g1 = acc[ai][1][m][1];
;                 u32x4 w; w.x = cvt_pk_bf16(a0[0] * siluf(g0[0]), a0[1] * siluf(g0[1])); w.y = cvt_pk_bf16(a0[2] * siluf(g0[2]), a0[3] * siluf(g0[3]));
	v_mov_b32_dpp v187, v101 row_shr:1 row_mask:0xf bank_mask:0xf
	v_mov_b32_e32 v86, v94
	v_mov_b32_e32 v87, v95
	v_pk_add_f32 v[106:107], v[176:177], v[106:107]
	v_pk_add_f32 v[176:177], v[158:159], v[88:89]
	v_mov_b32_dpp v188, v98 row_shr:1 row_mask:0xf bank_mask:0xf
	v_mov_b32_dpp v189, v99 row_shr:1 row_mask:0xf bank_mask:0xf
	v_mov_b32_dpp v86, v86 row_ror:15 row_mask:0xf bank_mask:0xf
	v_mov_b32_dpp v87, v87 row_ror:15 row_mask:0xf bank_mask:0xf
	v_mov_b32_e32 v88, v96
	v_mov_b32_e32 v89, v97
	v_pk_mul_f32 v[112:113], v[140:141], v[186:187]
	v_mov_b32_dpp v88, v88 row_ror:15 row_mask:0xf bank_mask:0xf
	v_mov_b32_dpp v89, v89 row_ror:15 row_mask:0xf bank_mask:0xf
	v_mov_b32_dpp v86, v100 row_shl:1 row_mask:0xf bank_mask:0xf
	v_mov_b32_dpp v87, v101 row_shl:1 row_mask:0xf bank_mask:0xf
	v_mov_b32_e32 v164, v100
	v_pk_mul_f32 v[110:111], v[142:143], v[188:189]
	v_pk_fma_f32 v[112:113], v[100:101], v[146:147], v[112:113]
	v_mov_b32_dpp v101, v101 row_ror:1 row_mask:0xf bank_mask:0xf
	v_mov_b32_dpp v88, v98 row_shl:1 row_mask:0xf bank_mask:0xf
	v_mov_b32_dpp v89, v99 row_shl:1 row_mask:0xf bank_mask:0xf
	v_mov_b32_dpp v164, v164 row_ror:1 row_mask:0xf bank_mask:0xf
	v_mov_b32_e32 v190, v98
	v_pk_fma_f32 v[110:111], v[98:99], v[148:149], v[110:111]
	v_mov_b32_dpp v99, v99 row_ror:1 row_mask:0xf bank_mask:0xf
	v_pk_fma_f32 v[86:87], v[152:153], v[86:87], v[112:113]
	v_mov_b32_dpp v101, v95 row_shr:1 row_mask:0xf bank_mask:0xf
	v_add_u32_e32 v160, s78, v173
	v_mov_b32_dpp v190, v190 row_ror:1 row_mask:0xf bank_mask:0xf
	v_pk_fma_f32 v[88:89], v[154:155], v[88:89], v[110:111]
	v_pk_add_f32 v[112:113], v[156:157], v[86:87]
	v_mov_b32_dpp v164, v94 row_shr:1 row_mask:0xf bank_mask:0xf
	v_mov_b32_dpp v99, v97 row_shr:1 row_mask:0xf bank_mask:0xf
	v_mov_b32_e32 v87, v91
	v_mov_b32_e32 v165, v101
	ds_read_b128 v[160:163], v160 offset:528
	v_pk_add_f32 v[110:111], v[158:159], v[88:89]
	v_mov_b32_dpp v190, v96 row_shr:1 row_mask:0xf bank_mask:0xf
	v_mov_b32_dpp v87, v87 row_ror:15 row_mask:0xf bank_mask:0xf
	v_mov_b32_e32 v88, v92
	v_mov_b32_e32 v89, v93
	v_pk_mul_f32 v[100:101], v[140:141], v[164:165]
	v_mov_b32_e32 v191, v99
	v_mov_b32_dpp v88, v88 row_ror:15 row_mask:0xf bank_mask:0xf
	v_mov_b32_dpp v89, v89 row_ror:15 row_mask:0xf bank_mask:0xf
	v_mov_b32_dpp v87, v95 row_shl:1 row_mask:0xf bank_mask:0xf
	v_mov_b32_e32 v186, v94
	v_pk_mul_f32 v[98:99], v[142:143], v[190:191]
	v_pk_fma_f32 v[100:101], v[94:95], v[146:147], v[100:101]
	v_mov_b32_dpp v95, v95 row_ror:1 row_mask:0xf bank_mask:0xf
	v_mov_b32_dpp v88, v96 row_shl:1 row_mask:0xf bank_mask:0xf
	v_mov_b32_dpp v89, v97 row_shl:1 row_mask:0xf bank_mask:0xf
	v_mov_b32_dpp v186, v186 row_ror:1 row_mask:0xf bank_mask:0xf
	v_pk_fma_f32 v[98:99], v[96:97], v[148:149], v[98:99]
	v_mov_b32_dpp v95, v91 row_shr:1 row_mask:0xf bank_mask:0xf
	v_pk_fma_f32 v[88:89], v[154:155], v[88:89], v[98:99]
	v_mov_b32_dpp v186, v90 row_shr:1 row_mask:0xf bank_mask:0xf
	v_mov_b32_e32 v187, v95
	v_pk_add_f32 v[98:99], v[158:159], v[88:89]
	v_pk_mul_f32 v[88:89], v[140:141], v[186:187]
	v_readlane_b32 s51, v253, 15
	v_mov_b32_e32 v86, v90
	s_waitcnt lgkmcnt(0)
	v_mov_b32_dpp v160, v90 row_shl:1 row_mask:0xf bank_mask:0xf
	v_mov_b32_dpp v161, v91 row_shl:1 row_mask:0xf bank_mask:0xf
	v_pk_fma_f32 v[88:89], v[90:91], v[146:147], v[88:89]
	v_or_b32_e32 v90, s3, v170
	v_add_u32_e32 v91, s51, v173
	v_mov_b32_dpp v86, v86 row_ror:15 row_mask:0xf bank_mask:0xf
	v_mov_b32_e32 v188, v96
	v_mov_b32_dpp v97, v97 row_ror:1 row_mask:0xf bank_mask:0xf
	v_add_u32_e32 v91, 0x2610, v91
	v_cmp_eq_u32_e32 vcc, 0, v90
	v_mov_b32_dpp v86, v94 row_shl:1 row_mask:0xf bank_mask:0xf
	v_mov_b32_dpp v188, v188 row_ror:1 row_mask:0xf bank_mask:0xf
	v_mov_b32_dpp v97, v93 row_shr:1 row_mask:0xf bank_mask:0xf
	v_cndmask_b32_e32 v90, v172, v91, vcc
	v_pk_fma_f32 v[86:87], v[152:153], v[86:87], v[100:101]
	v_mov_b32_dpp v188, v92 row_shr:1 row_mask:0xf bank_mask:0xf
	v_mov_b32_e32 v189, v97
	ds_write_b128 v90, v[174:177]
	v_mul_f32_e32 v90, 0xbfb8aa3b, v42
	v_pk_add_f32 v[100:101], v[156:157], v[86:87]
	v_pk_mul_f32 v[86:87], v[142:143], v[188:189]
	v_exp_f32_e32 v91, v90
	v_mul_f32_e32 v90, 0xbfb8aa3b, v43
	v_mov_b32_dpp v163, v93 row_shl:1 row_mask:0xf bank_mask:0xf
	v_pk_fma_f32 v[86:87], v[92:93], v[148:149], v[86:87]
	v_exp_f32_e32 v93, v90
	v_add_f32_e32 v91, 1.0, v91
	v_rcp_f32_e32 v94, v91
	s_waitcnt lgkmcnt(0)
; __device__ __forceinline__ unsigned cvt_pk_bf16(float lo, float hi) { unsigned r; asm volatile("v_cvt_pk_bf16_f32 %0, %1, %2" : "=v"(r) : "v"(lo), "v"(hi)); return r; }
; __device__ __forceinline__ float siluf(float x) { return x * __builtin_amdgcn_rcpf(1.f + __expf(-x)); }
;     __device__ __forceinline__ void operator()(f32x4 (&acc)[2][2][4][2], const Unit& u, int wr, int wc, int fr_in, int fq_in) const {
;     ...
;             for (int m = 0; m < 4; ++m) { const int row = u.pm * BM + ai * HALF + wr * 64 + m * 16 + fr;
;                 const f32x4 a0 = acc[ai][0][m][0], a1 = acc[ai][0][m][1], g0 = acc[ai][1][m][0], g1 = acc[ai][1][m][1];
;                 u32x4 w; w.x = cvt_pk_bf16(a0[0] * siluf(g0[0]), a0[1] * siluf(g0[1])); w.y = cvt_pk_bf16(a0[2] * siluf(g0[2]), a0[3] * siluf(g0[3]));
;                 w.z = cvt_pk_bf16(a1[0] * siluf(g1[0]), a1[1] * siluf(g1[1])); w.w = cvt_pk_bf16(a1[2] * siluf(g1[2]), a1[3] * siluf(g1[3]));
;                 *(u32x4*)(ACT + (size_t)row * DFF + u.pn * 128 + wc * 32 + 8 * fq) = w;
;                 asm volatile("" ::: "memory"); }
	v_add_f32_e32 v91, 1.0, v93
	v_rcp_f32_e32 v93, v91
	v_mul_f32_e32 v42, v42, v94
	v_mul_f32_e32 v34, v34, v42
	v_mul_f32_e32 v42, v43, v93
	v_mul_f32_e32 v43, 0xbfb8aa3b, v44
	v_exp_f32_e32 v43, v43
	v_mul_f32_e32 v93, 0xbfb8aa3b, v45
	v_exp_f32_e32 v93, v93
	v_mul_f32_e32 v35, v35, v42
	v_add_f32_e32 v42, 1.0, v43
	v_rcp_f32_e32 v43, v42
	v_add_f32_e32 v42, 1.0, v93
	v_rcp_f32_e32 v93, v42
	v_cvt_pk_bf16_f32 v42, v34, v35
	v_mul_f32_e32 v34, v44, v43
	v_mul_f32_e32 v34, v36, v34
	v_mul_f32_e32 v36, 0xbfb8aa3b, v174
	v_mul_f32_e32 v43, 0xbfb8aa3b, v175
	v_exp_f32_e32 v36, v36
	v_exp_f32_e32 v43, v43
	v_mul_f32_e32 v35, v45, v93
	v_mul_f32_e32 v35, v37, v35
	v_add_f32_e32 v36, 1.0, v36
	v_add_f32_e32 v37, 1.0, v43
	v_rcp_f32_e32 v36, v36
	v_rcp_f32_e32 v37, v37
	v_cvt_pk_bf16_f32 v43, v34, v35
	s_lshl_b32 s48, s81, 7
	v_mul_f32_e32 v34, v174, v36
	v_mul_f32_e32 v35, v175, v37
	v_mul_f32_e32 v36, 0xbfb8aa3b, v176
	v_mul_f32_e32 v37, 0xbfb8aa3b, v177
	v_exp_f32_e32 v36, v36
	v_exp_f32_e32 v37, v37
	v_mul_f32_e32 v34, v38, v34
	v_mul_f32_e32 v35, v39, v35
	v_add_f32_e32 v36, 1.0, v36
	v_add_f32_e32 v37, 1.0, v37
	v_rcp_f32_e32 v36, v36
	v_rcp_f32_e32 v37, v37
	v_cvt_pk_bf16_f32 v44, v34, v35
	s_ashr_i32 s49, s48, 31
	v_mul_f32_e32 v34, v176, v36
	v_mul_f32_e32 v35, v177, v37
	v_mul_f32_e32 v34, v40, v34
	v_mul_f32_e32 v35, v41, v35
	v_mov_b32_dpp v162, v92 row_shl:1 row_mask:0xf bank_mask:0xf
	v_add_u32_e32 v92, s29, v170
	v_cvt_pk_bf16_f32 v45, v34, v35
	v_mov_b64_e32 v[34:35], s[12:13]
	s_movk_i32 s29, 0x2c00
	v_lshlrev_b32_e32 v90, 3, v171
	v_mad_i64_i32 v[36:37], s[96:97], v92, s29, v[34:35]
	s_lshl_b64 s[48:49], s[48:49], 1
	v_ashrrev_i32_e32 v91, 31, v90
	v_lshl_add_u64 v[36:37], v[36:37], 0, s[48:49]
	v_lshl_add_u64 v[38:39], v[36:37], 0, s[24:25]
	v_lshlrev_b64 v[36:37], 1, v[90:91]
	v_lshl_add_u64 v[38:39], v[38:39], 0, v[36:37]
	global_store_dwordx4 v[38:39], v[42:45], off
	v_mul_f32_e32 v38, 0xbfb8aa3b, v150
	v_mul_f32_e32 v39, 0xbfb8aa3b, v151
	v_exp_f32_e32 v38, v38
	v_exp_f32_e32 v39, v39
	v_mul_f32_e32 v40, 0xbfb8aa3b, v144
	v_mul_f32_e32 v41, 0xbfb8aa3b, v145
	v_exp_f32_e32 v40, v40
	v_exp_f32_e32 v41, v41
	v_add_f32_e32 v38, 1.0, v38
	v_add_f32_e32 v39, 1.0, v39
	v_rcp_f32_e32 v38, v38
	v_rcp_f32_e32 v39, v39
	v_add_f32_e32 v40, 1.0, v40
	v_add_f32_e32 v41, 1.0, v41
	v_rcp_f32_e32 v40, v40
	v_rcp_f32_e32 v41, v41
	v_mul_f32_e32 v38, v150, v38
	v_mul_f32_e32 v39, v151, v39
	v_mul_f32_e32 v38, v104, v38
	v_mul_f32_e32 v39, v105, v39
	v_cvt_pk_bf16_f32 v38, v38, v39
	v_mul_f32_e32 v39, v144, v40
	v_mul_f32_e32 v40, v145, v41
	v_mul_f32_e32 v41, 0xbfb8aa3b, v112
	v_mul_f32_e32 v43, 0xbfb8aa3b, v113
	v_exp_f32_e32 v41, v41
	v_exp_f32_e32 v43, v43
	v_mul_f32_e32 v39, v102, v39
	v_mul_f32_e32 v40, v103, v40
	v_add_f32_e32 v41, 1.0, v41
	v_add_f32_e32 v43, 1.0, v43
	v_rcp_f32_e32 v41, v41
	v_rcp_f32_e32 v43, v43
	v_cvt_pk_bf16_f32 v39, v39, v40
	v_mul_f32_e32 v44, 0xbfb8aa3b, v111
	v_mul_f32_e32 v40, v112, v41
	v_mul_f32_e32 v41, v113, v43
	v_mul_f32_e32 v43, 0xbfb8aa3b, v110
	v_exp_f32_e32 v43, v43
	v_exp_f32_e32 v44, v44
	v_mul_f32_e32 v40, v128, v40
	v_mul_f32_e32 v41, v129, v41
	v_add_f32_e32 v43, 1.0, v43
	v_add_f32_e32 v44, 1.0, v44
	v_rcp_f32_e32 v43, v43
	v_rcp_f32_e32 v44, v44
	v_cvt_pk_bf16_f32 v40, v40, v41
	v_add_u32_e32 v42, 16, v92
	v_mul_f32_e32 v41, v110, v43
	v_mul_f32_e32 v43, v111, v44
	v_mul_f32_e32 v41, v126, v41
	v_mul_f32_e32 v43, v127, v43
	v_cvt_pk_bf16_f32 v41, v41, v43
	v_mad_i64_i32 v[42:43], s[96:97], v42, s29, v[34:35]
	v_lshl_add_u64 v[42:43], v[42:43], 0, s[48:49]
	v_lshl_add_u64 v[42:43], v[42:43], 0, s[24:25]
	v_lshl_add_u64 v[42:43], v[42:43], 0, v[36:37]
	global_store_dwordx4 v[42:43], v[38:41], off
	v_mul_f32_e32 v43, 0xbfb8aa3b, v101
	v_exp_f32_e32 v43, v43
	v_mul_f32_e32 v38, 0xbfb8aa3b, v120
	v_mul_f32_e32 v39, 0xbfb8aa3b, v121
	v_exp_f32_e32 v38, v38
	v_exp_f32_e32 v39, v39
	v_mul_f32_e32 v40, 0xbfb8aa3b, v118
	v_mul_f32_e32 v41, 0xbfb8aa3b, v119
	v_exp_f32_e32 v40, v40
	v_exp_f32_e32 v41, v41
	v_add_f32_e32 v38, 1.0, v38
	v_add_f32_e32 v39, 1.0, v39
	v_rcp_f32_e32 v38, v38
	v_rcp_f32_e32 v39, v39
	v_add_f32_e32 v40, 1.0, v40
	v_add_f32_e32 v41, 1.0, v41
	v_rcp_f32_e32 v40, v40
	v_rcp_f32_e32 v41, v41
	v_mul_f32_e32 v38, v120, v38
	v_mul_f32_e32 v39, v121, v39
	v_mul_f32_e32 v38, v84, v38
	v_mul_f32_e32 v39, v85, v39
	v_cvt_pk_bf16_f32 v38, v38, v39
	v_mul_f32_e32 v39, v118, v40
	v_mul_f32_e32 v40, v119, v41
	v_mul_f32_e32 v41, 0xbfb8aa3b, v100
	v_exp_f32_e32 v41, v41
	v_add_f32_e32 v43, 1.0, v43
	v_rcp_f32_e32 v43, v43
	v_mul_f32_e32 v39, v82, v39
	v_add_f32_e32 v41, 1.0, v41
	v_rcp_f32_e32 v41, v41
	v_mul_f32_e32 v40, v83, v40
	v_cvt_pk_bf16_f32 v39, v39, v40
	v_mul_f32_e32 v44, 0xbfb8aa3b, v99
	v_mul_f32_e32 v40, v100, v41
	v_mul_f32_e32 v41, v101, v43
	v_mul_f32_e32 v43, 0xbfb8aa3b, v98
	v_exp_f32_e32 v43, v43
	v_exp_f32_e32 v44, v44
	v_mul_f32_e32 v40, v124, v40
	v_mul_f32_e32 v41, v125, v41
	v_add_f32_e32 v43, 1.0, v43
	v_add_f32_e32 v44, 1.0, v44
	v_rcp_f32_e32 v43, v43
	v_rcp_f32_e32 v44, v44
	v_cvt_pk_bf16_f32 v40, v40, v41
	v_add_u32_e32 v42, 32, v92
	v_mul_f32_e32 v41, v98, v43
	v_mul_f32_e32 v43, v99, v44
	v_mul_f32_e32 v41, v122, v41
	v_mul_f32_e32 v43, v123, v43
	v_cvt_pk_bf16_f32 v41, v41, v43
	v_mad_i64_i32 v[42:43], s[96:97], v42, s29, v[34:35]
	v_lshl_add_u64 v[42:43], v[42:43], 0, s[48:49]
	v_lshl_add_u64 v[42:43], v[42:43], 0, s[24:25]
	v_lshl_add_u64 v[42:43], v[42:43], 0, v[36:37]
	global_store_dwordx4 v[42:43], v[38:41], off
	v_pk_fma_f32 v[88:89], v[152:153], v[160:161], v[88:89]
	v_pk_fma_f32 v[86:87], v[154:155], v[162:163], v[86:87]
	v_mul_f32_e32 v38, 0xbfb8aa3b, v108
; #define LAS __attribute__((address_space(3)))
; __device__ __forceinline__ unsigned cvt_pk_bf16(float lo, float hi) { unsigned r; asm volatile("v_cvt_pk_bf16_f32 %0, %1, %2" : "=v"(r) : "v"(lo), "v"(hi)); return r; }
; __device__ __forceinline__ float siluf(float x) { return x * __builtin_amdgcn_rcpf(1.f + __expf(-x)); }
;     __device__ __forceinline__ void operator()(f32x4 (&acc)[2][2][4][2], const Unit& u, int wr, int wc, int fr_in, int fq_in) const {
;     ...
;         for (int ai = 0; ai < 2; ++ai) { const int blk = 2 * ai + wr;
;             const int upslot = blk > 0 ? (blk - 1) * 2 + 1 : 8, dnslot = blk < 3 ? (blk + 1) * 2 : 8;
; #pragma unroll
;             for (int q = 0; q < 4; ++q) { const int bj = q >> 1, n = q & 1;
;                 asm volatile("" : "+v"(fr), "+v"(fq)); const int lc0 = wc * 32 + 8 * fq;
;                 const int cl = bj * 128 + lc0 + 4 * n;
;                 const f32x4 w0 = *(const LAS f32x4*)(WL + cl), w1 = *(const LAS f32x4*)(WL + 256 + cl), w2 = *(const LAS f32x4*)(WL + 512 + cl), bb = *(const LAS f32x4*)(WL + 768 + cl);
;                 f32x4 carry = *(const LAS f32x4*)(HL + upslot * 256 + bj * 128 + lc0 + 4 * n);
;                 const f32x4 hdn = *(const LAS f32x4*)(HL + dnslot * 256 + bj * 128 + lc0 + 4 * n);
; #pragma unroll
;                 for (int m = 0; m < 4; ++m) { const f32x4 cur = acc[ai][bj][m][n];
;                     const f32x4 up = dpp4_shr1(carry, cur);
;                     const f32x4 nf = m < 3 ? dpp4_ror15(acc[ai][bj][m < 3 ? m + 1 : 3][n]) : hdn;
;                     const f32x4 dn = dpp4_shl1(nf, cur);
;                     carry = dpp4_ror1(cur);
;                     acc[ai][bj][m][n] = w0 * up + w1 * cur + w2 * dn + bb; }
;     ...
;             for (int m = 0; m < 4; ++m) { const int row = u.pm * BM + ai * HALF + wr * 64 + m * 16 + fr;
;                 const f32x4 a0 = acc[ai][0][m][0], a1 = acc[ai][0][m][1], g0 = acc[ai][1][m][0], g1 = acc[ai][1][m][1];
;                 u32x4 w; w.x = cvt_pk_bf16(a0[0] * siluf(g0[0]), a0[1] * siluf(g0[1])); w.y = cvt_pk_bf16(a0[2] * siluf(g0[2]), a0[3] * siluf(g0[3]));
;                 w.z = cvt_pk_bf16(a1[0] * siluf(g1[0]), a1[1] * siluf(g1[1])); w.w = cvt_pk_bf16(a1[2] * siluf(g1[2]), a1[3] * siluf(g1[3]));
;                 *(u32x4*)(ACT + (size_t)row * DFF + u.pn * 128 + wc * 32 + 8 * fq) = w;
;                 asm volatile("" ::: "memory"); }
	v_mul_f32_e32 v39, 0xbfb8aa3b, v109
	v_exp_f32_e32 v38, v38
	v_exp_f32_e32 v39, v39
	v_mul_f32_e32 v40, 0xbfb8aa3b, v106
	v_mul_f32_e32 v41, 0xbfb8aa3b, v107
	v_exp_f32_e32 v40, v40
	v_exp_f32_e32 v41, v41
	v_add_f32_e32 v38, 1.0, v38
	v_add_f32_e32 v39, 1.0, v39
	v_rcp_f32_e32 v38, v38
	v_rcp_f32_e32 v39, v39
	v_add_f32_e32 v40, 1.0, v40
	v_add_f32_e32 v41, 1.0, v41
	v_rcp_f32_e32 v40, v40
	v_rcp_f32_e32 v41, v41
	v_mul_f32_e32 v38, v108, v38
	v_mul_f32_e32 v39, v109, v39
	v_pk_add_f32 v[88:89], v[156:157], v[88:89]
	v_mul_f32_e32 v38, v80, v38
	v_mul_f32_e32 v39, v81, v39
	v_cvt_pk_bf16_f32 v38, v38, v39
	v_mul_f32_e32 v39, v106, v40
	v_mul_f32_e32 v40, v107, v41
	v_mul_f32_e32 v41, 0xbfb8aa3b, v88
	v_mul_f32_e32 v43, 0xbfb8aa3b, v89
	v_exp_f32_e32 v41, v41
	v_exp_f32_e32 v43, v43
	v_pk_add_f32 v[86:87], v[158:159], v[86:87]
	v_mul_f32_e32 v39, v78, v39
	v_add_f32_e32 v41, 1.0, v41
	v_add_f32_e32 v43, 1.0, v43
	v_rcp_f32_e32 v41, v41
	v_rcp_f32_e32 v43, v43
	v_mul_f32_e32 v40, v79, v40
	v_cvt_pk_bf16_f32 v39, v39, v40
	v_mul_f32_e32 v40, v88, v41
	v_mul_f32_e32 v41, v89, v43
	v_mul_f32_e32 v43, 0xbfb8aa3b, v86
	v_mul_f32_e32 v44, 0xbfb8aa3b, v87
	v_exp_f32_e32 v43, v43
	v_exp_f32_e32 v44, v44
	v_mul_f32_e32 v40, v116, v40
	v_mul_f32_e32 v41, v117, v41
	v_add_f32_e32 v43, 1.0, v43
	v_add_f32_e32 v44, 1.0, v44
	v_rcp_f32_e32 v43, v43
	v_rcp_f32_e32 v44, v44
	v_cvt_pk_bf16_f32 v40, v40, v41
	v_add_u32_e32 v42, 48, v92
	v_mul_f32_e32 v41, v86, v43
	v_mul_f32_e32 v43, v87, v44
	v_mul_f32_e32 v41, v114, v41
	v_mul_f32_e32 v43, v115, v43
	v_cvt_pk_bf16_f32 v41, v41, v43
	v_mad_i64_i32 v[42:43], s[96:97], v42, s29, v[34:35]
	v_lshl_add_u64 v[42:43], v[42:43], 0, s[48:49]
	v_lshl_add_u64 v[42:43], v[42:43], 0, s[24:25]
	v_lshl_add_u64 v[36:37], v[42:43], 0, v[36:37]
	global_store_dwordx4 v[36:37], v[38:41], off
	v_mov_b32_e32 v42, v74
	v_lshlrev_b32_e32 v36, 3, v171
	v_add_lshl_u32 v104, v36, s68, 2
	v_add_u32_e32 v36, s50, v104
	v_add_u32_e32 v37, s54, v104
	ds_read_b128 v[80:83], v36
	ds_read_b128 v[84:87], v37
	v_add_u32_e32 v36, s70, v104
	v_add_u32_e32 v40, s62, v104
	v_add_u32_e32 v41, s75, v104
	ds_read_b128 v[36:39], v36
	ds_read_b128 v[88:91], v40
	ds_read_b128 v[92:95], v41
	v_add_u32_e32 v40, s80, v104
	ds_read_b128 v[96:99], v40
	s_waitcnt lgkmcnt(0)
	v_mov_b32_dpp v36, v26 row_shr:1 row_mask:0xf bank_mask:0xf
	v_mov_b32_dpp v37, v27 row_shr:1 row_mask:0xf bank_mask:0xf
	v_mov_b32_dpp v38, v28 row_shr:1 row_mask:0xf bank_mask:0xf
	v_mov_b32_dpp v39, v29 row_shr:1 row_mask:0xf bank_mask:0xf
	v_mov_b32_e32 v40, v76
	v_mov_b32_e32 v41, v77
	v_mov_b32_e32 v43, v75
	v_mov_b32_dpp v40, v40 row_ror:15 row_mask:0xf bank_mask:0xf
	v_mov_b32_dpp v41, v41 row_ror:15 row_mask:0xf bank_mask:0xf
	v_mov_b32_dpp v42, v42 row_ror:15 row_mask:0xf bank_mask:0xf
	v_mov_b32_dpp v43, v43 row_ror:15 row_mask:0xf bank_mask:0xf
	v_pk_mul_f32 v[36:37], v[80:81], v[36:37]
	v_pk_mul_f32 v[38:39], v[82:83], v[38:39]
	v_mov_b32_dpp v40, v26 row_shl:1 row_mask:0xf bank_mask:0xf
	v_mov_b32_dpp v41, v27 row_shl:1 row_mask:0xf bank_mask:0xf
	v_mov_b32_dpp v42, v28 row_shl:1 row_mask:0xf bank_mask:0xf
	v_mov_b32_dpp v43, v29 row_shl:1 row_mask:0xf bank_mask:0xf
	v_mov_b32_e32 v100, v26
	v_mov_b32_e32 v101, v27
	v_mov_b32_e32 v102, v28
	v_mov_b32_e32 v103, v29
	v_pk_fma_f32 v[28:29], v[28:29], v[86:87], v[38:39]
	v_pk_fma_f32 v[26:27], v[26:27], v[84:85], v[36:37]
	v_mov_b32_dpp v100, v100 row_ror:1 row_mask:0xf bank_mask:0xf
	v_mov_b32_dpp v101, v101 row_ror:1 row_mask:0xf bank_mask:0xf
	v_mov_b32_dpp v102, v102 row_ror:1 row_mask:0xf bank_mask:0xf
	v_mov_b32_dpp v103, v103 row_ror:1 row_mask:0xf bank_mask:0xf
	v_pk_fma_f32 v[26:27], v[88:89], v[40:41], v[26:27]
	v_pk_fma_f32 v[28:29], v[90:91], v[42:43], v[28:29]
	v_pk_add_f32 v[78:79], v[92:93], v[26:27]
	v_pk_add_f32 v[44:45], v[94:95], v[28:29]
	v_mov_b32_dpp v100, v76 row_shr:1 row_mask:0xf bank_mask:0xf
	v_mov_b32_dpp v101, v77 row_shr:1 row_mask:0xf bank_mask:0xf
	v_mov_b32_dpp v102, v74 row_shr:1 row_mask:0xf bank_mask:0xf
	v_mov_b32_dpp v103, v75 row_shr:1 row_mask:0xf bank_mask:0xf
	v_mov_b32_e32 v26, v70
	v_mov_b32_e32 v27, v71
	v_mov_b32_e32 v28, v72
	v_mov_b32_e32 v29, v73
	v_mov_b32_dpp v26, v26 row_ror:15 row_mask:0xf bank_mask:0xf
	v_mov_b32_dpp v27, v27 row_ror:15 row_mask:0xf bank_mask:0xf
	v_mov_b32_dpp v28, v28 row_ror:15 row_mask:0xf bank_mask:0xf
	v_mov_b32_dpp v29, v29 row_ror:15 row_mask:0xf bank_mask:0xf
	v_pk_mul_f32 v[40:41], v[82:83], v[102:103]
	v_pk_mul_f32 v[42:43], v[80:81], v[100:101]
	v_mov_b32_dpp v26, v76 row_shl:1 row_mask:0xf bank_mask:0xf
	v_mov_b32_dpp v27, v77 row_shl:1 row_mask:0xf bank_mask:0xf
	v_mov_b32_dpp v28, v74 row_shl:1 row_mask:0xf bank_mask:0xf
	v_mov_b32_dpp v29, v75 row_shl:1 row_mask:0xf bank_mask:0xf
	v_mov_b32_e32 v36, v76
	v_mov_b32_e32 v38, v74
	v_pk_fma_f32 v[40:41], v[74:75], v[86:87], v[40:41]
	v_mov_b32_dpp v75, v75 row_ror:1 row_mask:0xf bank_mask:0xf
	v_pk_fma_f32 v[42:43], v[76:77], v[84:85], v[42:43]
	v_mov_b32_dpp v77, v77 row_ror:1 row_mask:0xf bank_mask:0xf
	v_mov_b32_dpp v36, v36 row_ror:1 row_mask:0xf bank_mask:0xf
	v_mov_b32_dpp v38, v38 row_ror:1 row_mask:0xf bank_mask:0xf
	v_pk_fma_f32 v[28:29], v[90:91], v[28:29], v[40:41]
	v_pk_fma_f32 v[26:27], v[88:89], v[26:27], v[42:43]
	v_mov_b32_dpp v77, v71 row_shr:1 row_mask:0xf bank_mask:0xf
	v_mov_b32_dpp v75, v73 row_shr:1 row_mask:0xf bank_mask:0xf
	v_pk_add_f32 v[40:41], v[94:95], v[28:29]
	v_pk_add_f32 v[42:43], v[92:93], v[26:27]
	v_mov_b32_dpp v36, v70 row_shr:1 row_mask:0xf bank_mask:0xf
	v_mov_b32_dpp v38, v72 row_shr:1 row_mask:0xf bank_mask:0xf
	v_mov_b32_e32 v27, v31
	v_mov_b32_e32 v29, v33
; #define LAS __attribute__((address_space(3)))
; __device__ __forceinline__ f32x4 dpp4_shr1(f32x4 o, f32x4 v) { return (f32x4){DPPF(o[0], v[0], 0x111), DPPF(o[1], v[1], 0x111), DPPF(o[2], v[2], 0x111), DPPF(o[3], v[3], 0x111)}; }
; __device__ __forceinline__ f32x4 dpp4_shl1(f32x4 o, f32x4 v) { return (f32x4){DPPF(o[0], v[0], 0x101), DPPF(o[1], v[1], 0x101), DPPF(o[2], v[2], 0x101), DPPF(o[3], v[3], 0x101)}; }
; __device__ __forceinline__ f32x4 dpp4_ror1(f32x4 v) { return (f32x4){DPPF(v[0], v[0], 0x121), DPPF(v[1], v[1], 0x121), DPPF(v[2], v[2], 0x121), DPPF(v[3], v[3], 0x121)}; }
;     __device__ __forceinline__ void operator()(f32x4 (&acc)[2][2][4][2], const Unit& u, int wr, int wc, int fr_in, int fq_in) const {
;     ...
;         for (int ai = 0; ai < 2; ++ai) { const int blk = 2 * ai + wr;
;             const int upslot = blk > 0 ? (blk - 1) * 2 + 1 : 8, dnslot = blk < 3 ? (blk + 1) * 2 : 8;
; #pragma unroll
;             for (int q = 0; q < 4; ++q) { const int bj = q >> 1, n = q & 1;
;                 asm volatile("" : "+v"(fr), "+v"(fq)); const int lc0 = wc * 32 + 8 * fq;
;                 const int cl = bj * 128 + lc0 + 4 * n;
;                 const f32x4 w0 = *(const LAS f32x4*)(WL + cl), w1 = *(const LAS f32x4*)(WL + 256 + cl), w2 = *(const LAS f32x4*)(WL + 512 + cl), bb = *(const LAS f32x4*)(WL + 768 + cl);
;                 f32x4 carry = *(const LAS f32x4*)(HL + upslot * 256 + bj * 128 + lc0 + 4 * n);
;                 const f32x4 hdn = *(const LAS f32x4*)(HL + dnslot * 256 + bj * 128 + lc0 + 4 * n);
; #pragma unroll
;                 for (int m = 0; m < 4; ++m) { const f32x4 cur = acc[ai][bj][m][n];
;                     const f32x4 up = dpp4_shr1(carry, cur);
;                     const f32x4 nf = m < 3 ? dpp4_ror15(acc[ai][bj][m < 3 ? m + 1 : 3][n]) : hdn;
;                     const f32x4 dn = dpp4_shl1(nf, cur);
;                     carry = dpp4_ror1(cur);
;                     acc[ai][bj][m][n] = w0 * up + w1 * cur + w2 * dn + bb; }
;                 if (ai == 0) { LAS float* d0 = ((wr == 0) & (fr == 0)) ? PAL + bj * 128 + lc0 + 4 * n : DMP; *(LAS f32x4*)d0 = acc[ai][bj][0][n]; }
;                 if (ai == 1) { LAS float* d1 = ((wr == 1) & (fr == 15)) ? PAL + 256 + bj * 128 + lc0 + 4 * n : DMP; *(LAS f32x4*)d1 = acc[ai][bj][3][n]; }
	v_mov_b32_e32 v37, v77
	v_mov_b32_e32 v39, v75
	v_mov_b32_e32 v26, v30
	v_mov_b32_dpp v27, v27 row_ror:15 row_mask:0xf bank_mask:0xf
	v_mov_b32_e32 v28, v32
	v_mov_b32_dpp v29, v29 row_ror:15 row_mask:0xf bank_mask:0xf
	v_pk_mul_f32 v[36:37], v[80:81], v[36:37]
	v_pk_mul_f32 v[38:39], v[82:83], v[38:39]
	v_mov_b32_dpp v26, v26 row_ror:15 row_mask:0xf bank_mask:0xf
	v_mov_b32_dpp v28, v28 row_ror:15 row_mask:0xf bank_mask:0xf
	v_mov_b32_dpp v27, v71 row_shl:1 row_mask:0xf bank_mask:0xf
	v_mov_b32_dpp v29, v73 row_shl:1 row_mask:0xf bank_mask:0xf
	v_mov_b32_e32 v74, v70
	v_mov_b32_e32 v76, v72
	v_pk_fma_f32 v[38:39], v[72:73], v[86:87], v[38:39]
	v_mov_b32_dpp v73, v73 row_ror:1 row_mask:0xf bank_mask:0xf
	v_pk_fma_f32 v[36:37], v[70:71], v[84:85], v[36:37]
	v_mov_b32_dpp v71, v71 row_ror:1 row_mask:0xf bank_mask:0xf
	v_mov_b32_dpp v26, v70 row_shl:1 row_mask:0xf bank_mask:0xf
	v_mov_b32_dpp v28, v72 row_shl:1 row_mask:0xf bank_mask:0xf
	v_mov_b32_dpp v74, v74 row_ror:1 row_mask:0xf bank_mask:0xf
	v_mov_b32_dpp v76, v76 row_ror:1 row_mask:0xf bank_mask:0xf
	v_mov_b32_dpp v71, v31 row_shr:1 row_mask:0xf bank_mask:0xf
	v_mov_b32_dpp v73, v33 row_shr:1 row_mask:0xf bank_mask:0xf
	v_pk_fma_f32 v[26:27], v[88:89], v[26:27], v[36:37]
	v_pk_fma_f32 v[28:29], v[90:91], v[28:29], v[38:39]
	v_mov_b32_dpp v74, v30 row_shr:1 row_mask:0xf bank_mask:0xf
	v_mov_b32_dpp v76, v32 row_shr:1 row_mask:0xf bank_mask:0xf
	v_mov_b32_e32 v77, v73
	v_mov_b32_e32 v75, v71
	v_pk_add_f32 v[36:37], v[94:95], v[28:29]
	v_pk_add_f32 v[38:39], v[92:93], v[26:27]
	v_pk_mul_f32 v[26:27], v[82:83], v[76:77]
	v_pk_mul_f32 v[28:29], v[80:81], v[74:75]
	v_mov_b32_dpp v96, v30 row_shl:1 row_mask:0xf bank_mask:0xf
	v_mov_b32_dpp v97, v31 row_shl:1 row_mask:0xf bank_mask:0xf
	v_mov_b32_dpp v98, v32 row_shl:1 row_mask:0xf bank_mask:0xf
	v_mov_b32_dpp v99, v33 row_shl:1 row_mask:0xf bank_mask:0xf
	v_pk_fma_f32 v[26:27], v[32:33], v[86:87], v[26:27]
	v_pk_fma_f32 v[28:29], v[30:31], v[84:85], v[28:29]
	v_pk_fma_f32 v[26:27], v[90:91], v[98:99], v[26:27]
	v_pk_fma_f32 v[30:31], v[88:89], v[96:97], v[28:29]
	v_cmp_eq_u32_e32 vcc, 15, v170
	v_readlane_b32 s81, v253, 22
	v_pk_add_f32 v[28:29], v[94:95], v[26:27]
	v_pk_add_f32 v[26:27], v[92:93], v[30:31]
	v_add_u32_e32 v30, s81, v104
	s_and_b64 vcc, s[82:83], vcc
	v_cndmask_b32_e32 v30, v172, v30, vcc
	ds_write_b128 v30, v[26:29]
	s_waitcnt lgkmcnt(0)
	v_mov_b32_e32 v72, v66
	v_lshlrev_b32_e32 v30, 3, v171
	v_add_lshl_u32 v104, v30, s68, 2
	v_or_b32_e32 v30, 16, v104
	v_add_u32_e32 v31, s50, v30
	v_add_u32_e32 v32, s54, v30
	v_add_u32_e32 v70, s62, v30
	v_add_u32_e32 v71, s75, v30
	v_add_u32_e32 v30, s70, v104
	ds_read_b128 v[80:83], v31
	ds_read_b128 v[84:87], v32
	ds_read_b128 v[30:33], v30 offset:16
	ds_read_b128 v[88:91], v70
	ds_read_b128 v[92:95], v71
	v_add_u32_e32 v70, s80, v104
	ds_read_b128 v[96:99], v70 offset:16
	s_waitcnt lgkmcnt(0)
	v_mov_b32_dpp v30, v18 row_shr:1 row_mask:0xf bank_mask:0xf
	v_mov_b32_dpp v31, v19 row_shr:1 row_mask:0xf bank_mask:0xf
	v_mov_b32_dpp v32, v20 row_shr:1 row_mask:0xf bank_mask:0xf
	v_mov_b32_dpp v33, v21 row_shr:1 row_mask:0xf bank_mask:0xf
	v_mov_b32_e32 v70, v68
	v_mov_b32_e32 v71, v69
	v_mov_b32_e32 v73, v67
	v_mov_b32_dpp v70, v70 row_ror:15 row_mask:0xf bank_mask:0xf
	v_mov_b32_dpp v71, v71 row_ror:15 row_mask:0xf bank_mask:0xf
	v_mov_b32_dpp v72, v72 row_ror:15 row_mask:0xf bank_mask:0xf
	v_mov_b32_dpp v73, v73 row_ror:15 row_mask:0xf bank_mask:0xf
	v_pk_mul_f32 v[30:31], v[80:81], v[30:31]
	v_pk_mul_f32 v[32:33], v[82:83], v[32:33]
	v_mov_b32_dpp v70, v18 row_shl:1 row_mask:0xf bank_mask:0xf
	v_mov_b32_dpp v71, v19 row_shl:1 row_mask:0xf bank_mask:0xf
	v_mov_b32_dpp v72, v20 row_shl:1 row_mask:0xf bank_mask:0xf
	v_mov_b32_dpp v73, v21 row_shl:1 row_mask:0xf bank_mask:0xf
	v_mov_b32_e32 v100, v18
	v_mov_b32_e32 v101, v19
	v_mov_b32_e32 v102, v20
	v_mov_b32_e32 v103, v21
	v_pk_fma_f32 v[20:21], v[20:21], v[86:87], v[32:33]
	v_pk_fma_f32 v[18:19], v[18:19], v[84:85], v[30:31]
	v_mov_b32_dpp v100, v100 row_ror:1 row_mask:0xf bank_mask:0xf
	v_mov_b32_dpp v101, v101 row_ror:1 row_mask:0xf bank_mask:0xf
	v_mov_b32_dpp v102, v102 row_ror:1 row_mask:0xf bank_mask:0xf
	v_mov_b32_dpp v103, v103 row_ror:1 row_mask:0xf bank_mask:0xf
	v_pk_fma_f32 v[18:19], v[88:89], v[70:71], v[18:19]
	v_pk_fma_f32 v[20:21], v[90:91], v[72:73], v[20:21]
	v_pk_add_f32 v[76:77], v[92:93], v[18:19]
	v_pk_add_f32 v[74:75], v[94:95], v[20:21]
	v_mov_b32_dpp v100, v68 row_shr:1 row_mask:0xf bank_mask:0xf
	v_mov_b32_dpp v101, v69 row_shr:1 row_mask:0xf bank_mask:0xf
	v_mov_b32_dpp v102, v66 row_shr:1 row_mask:0xf bank_mask:0xf
	v_mov_b32_dpp v103, v67 row_shr:1 row_mask:0xf bank_mask:0xf
	v_mov_b32_e32 v18, v54
	v_mov_b32_e32 v19, v55
	v_mov_b32_e32 v20, v56
	v_mov_b32_e32 v21, v57
	v_mov_b32_dpp v18, v18 row_ror:15 row_mask:0xf bank_mask:0xf
	v_mov_b32_dpp v19, v19 row_ror:15 row_mask:0xf bank_mask:0xf
	v_mov_b32_dpp v20, v20 row_ror:15 row_mask:0xf bank_mask:0xf
	v_mov_b32_dpp v21, v21 row_ror:15 row_mask:0xf bank_mask:0xf
	v_pk_mul_f32 v[70:71], v[82:83], v[102:103]
	v_pk_mul_f32 v[72:73], v[80:81], v[100:101]
	v_mov_b32_dpp v18, v68 row_shl:1 row_mask:0xf bank_mask:0xf
	v_mov_b32_dpp v19, v69 row_shl:1 row_mask:0xf bank_mask:0xf
	v_mov_b32_dpp v20, v66 row_shl:1 row_mask:0xf bank_mask:0xf
	v_mov_b32_dpp v21, v67 row_shl:1 row_mask:0xf bank_mask:0xf
	v_mov_b32_e32 v30, v68
	v_mov_b32_e32 v32, v66
	v_pk_fma_f32 v[70:71], v[66:67], v[86:87], v[70:71]
	v_mov_b32_dpp v67, v67 row_ror:1 row_mask:0xf bank_mask:0xf
	v_pk_fma_f32 v[72:73], v[68:69], v[84:85], v[72:73]
	v_mov_b32_dpp v69, v69 row_ror:1 row_mask:0xf bank_mask:0xf
; #define LAS __attribute__((address_space(3)))
; __device__ __forceinline__ f32x4 dpp4_shr1(f32x4 o, f32x4 v) { return (f32x4){DPPF(o[0], v[0], 0x111), DPPF(o[1], v[1], 0x111), DPPF(o[2], v[2], 0x111), DPPF(o[3], v[3], 0x111)}; }
; __device__ __forceinline__ f32x4 dpp4_shl1(f32x4 o, f32x4 v) { return (f32x4){DPPF(o[0], v[0], 0x101), DPPF(o[1], v[1], 0x101), DPPF(o[2], v[2], 0x101), DPPF(o[3], v[3], 0x101)}; }
; __device__ __forceinline__ f32x4 dpp4_ror1(f32x4 v) { return (f32x4){DPPF(v[0], v[0], 0x121), DPPF(v[1], v[1], 0x121), DPPF(v[2], v[2], 0x121), DPPF(v[3], v[3], 0x121)}; }
;     __device__ __forceinline__ void operator()(f32x4 (&acc)[2][2][4][2], const Unit& u, int wr, int wc, int fr_in, int fq_in) const {
;     ...
;         for (int ai = 0; ai < 2; ++ai) { const int blk = 2 * ai + wr;
;             const int upslot = blk > 0 ? (blk - 1) * 2 + 1 : 8, dnslot = blk < 3 ? (blk + 1) * 2 : 8;
; #pragma unroll
;             for (int q = 0; q < 4; ++q) { const int bj = q >> 1, n = q & 1;
;                 asm volatile("" : "+v"(fr), "+v"(fq)); const int lc0 = wc * 32 + 8 * fq;
;                 const int cl = bj * 128 + lc0 + 4 * n;
;                 const f32x4 w0 = *(const LAS f32x4*)(WL + cl), w1 = *(const LAS f32x4*)(WL + 256 + cl), w2 = *(const LAS f32x4*)(WL + 512 + cl), bb = *(const LAS f32x4*)(WL + 768 + cl);
;                 f32x4 carry = *(const LAS f32x4*)(HL + upslot * 256 + bj * 128 + lc0 + 4 * n);
;                 const f32x4 hdn = *(const LAS f32x4*)(HL + dnslot * 256 + bj * 128 + lc0 + 4 * n);
; #pragma unroll
;                 for (int m = 0; m < 4; ++m) { const f32x4 cur = acc[ai][bj][m][n];
;                     const f32x4 up = dpp4_shr1(carry, cur);
;                     const f32x4 nf = m < 3 ? dpp4_ror15(acc[ai][bj][m < 3 ? m + 1 : 3][n]) : hdn;
;                     const f32x4 dn = dpp4_shl1(nf, cur);
;                     carry = dpp4_ror1(cur);
;                     acc[ai][bj][m][n] = w0 * up + w1 * cur + w2 * dn + bb; }
;                 if (ai == 0) { LAS float* d0 = ((wr == 0) & (fr == 0)) ? PAL + bj * 128 + lc0 + 4 * n : DMP; *(LAS f32x4*)d0 = acc[ai][bj][0][n]; }
;                 if (ai == 1) { LAS float* d1 = ((wr == 1) & (fr == 15)) ? PAL + 256 + bj * 128 + lc0 + 4 * n : DMP; *(LAS f32x4*)d1 = acc[ai][bj][3][n]; }
	v_mov_b32_dpp v30, v30 row_ror:1 row_mask:0xf bank_mask:0xf
	v_mov_b32_dpp v32, v32 row_ror:1 row_mask:0xf bank_mask:0xf
	v_pk_fma_f32 v[20:21], v[90:91], v[20:21], v[70:71]
	v_pk_fma_f32 v[18:19], v[88:89], v[18:19], v[72:73]
	v_mov_b32_dpp v69, v55 row_shr:1 row_mask:0xf bank_mask:0xf
	v_mov_b32_dpp v67, v57 row_shr:1 row_mask:0xf bank_mask:0xf
	v_pk_add_f32 v[70:71], v[94:95], v[20:21]
	v_pk_add_f32 v[72:73], v[92:93], v[18:19]
	v_mov_b32_dpp v30, v54 row_shr:1 row_mask:0xf bank_mask:0xf
	v_mov_b32_dpp v32, v56 row_shr:1 row_mask:0xf bank_mask:0xf
	v_mov_b32_e32 v19, v23
	v_mov_b32_e32 v21, v25
	v_mov_b32_e32 v31, v69
	v_mov_b32_e32 v33, v67
	v_mov_b32_e32 v18, v22
	v_mov_b32_dpp v19, v19 row_ror:15 row_mask:0xf bank_mask:0xf
	v_mov_b32_e32 v20, v24
	v_mov_b32_dpp v21, v21 row_ror:15 row_mask:0xf bank_mask:0xf
	v_pk_mul_f32 v[30:31], v[80:81], v[30:31]
	v_pk_mul_f32 v[32:33], v[82:83], v[32:33]
	v_mov_b32_dpp v18, v18 row_ror:15 row_mask:0xf bank_mask:0xf
	v_mov_b32_dpp v20, v20 row_ror:15 row_mask:0xf bank_mask:0xf
	v_mov_b32_dpp v19, v55 row_shl:1 row_mask:0xf bank_mask:0xf
	v_mov_b32_dpp v21, v57 row_shl:1 row_mask:0xf bank_mask:0xf
	v_mov_b32_e32 v66, v54
	v_mov_b32_e32 v68, v56
	v_pk_fma_f32 v[32:33], v[56:57], v[86:87], v[32:33]
	v_mov_b32_dpp v57, v57 row_ror:1 row_mask:0xf bank_mask:0xf
	v_pk_fma_f32 v[30:31], v[54:55], v[84:85], v[30:31]
	v_mov_b32_dpp v55, v55 row_ror:1 row_mask:0xf bank_mask:0xf
	v_mov_b32_dpp v18, v54 row_shl:1 row_mask:0xf bank_mask:0xf
	v_mov_b32_dpp v20, v56 row_shl:1 row_mask:0xf bank_mask:0xf
	v_mov_b32_dpp v66, v66 row_ror:1 row_mask:0xf bank_mask:0xf
	v_mov_b32_dpp v68, v68 row_ror:1 row_mask:0xf bank_mask:0xf
	v_mov_b32_dpp v55, v23 row_shr:1 row_mask:0xf bank_mask:0xf
	v_mov_b32_dpp v57, v25 row_shr:1 row_mask:0xf bank_mask:0xf
	v_pk_fma_f32 v[18:19], v[88:89], v[18:19], v[30:31]
	v_pk_fma_f32 v[20:21], v[90:91], v[20:21], v[32:33]
	v_mov_b32_dpp v66, v22 row_shr:1 row_mask:0xf bank_mask:0xf
	v_mov_b32_dpp v68, v24 row_shr:1 row_mask:0xf bank_mask:0xf
	v_mov_b32_e32 v69, v57
	v_mov_b32_e32 v67, v55
	v_pk_add_f32 v[30:31], v[94:95], v[20:21]
	v_pk_add_f32 v[32:33], v[92:93], v[18:19]
	v_pk_mul_f32 v[18:19], v[82:83], v[68:69]
	v_pk_mul_f32 v[20:21], v[80:81], v[66:67]
	v_mov_b32_dpp v96, v22 row_shl:1 row_mask:0xf bank_mask:0xf
	v_mov_b32_dpp v97, v23 row_shl:1 row_mask:0xf bank_mask:0xf
	v_mov_b32_dpp v98, v24 row_shl:1 row_mask:0xf bank_mask:0xf
	v_mov_b32_dpp v99, v25 row_shl:1 row_mask:0xf bank_mask:0xf
	v_pk_fma_f32 v[18:19], v[24:25], v[86:87], v[18:19]
	v_pk_fma_f32 v[20:21], v[22:23], v[84:85], v[20:21]
	v_pk_fma_f32 v[18:19], v[90:91], v[98:99], v[18:19]
	v_pk_fma_f32 v[22:23], v[88:89], v[96:97], v[20:21]
	v_cmp_eq_u32_e32 vcc, 15, v170
	v_pk_add_f32 v[20:21], v[94:95], v[18:19]
	v_pk_add_f32 v[18:19], v[92:93], v[22:23]
	v_add3_u32 v22, s81, v104, 16
	s_and_b64 vcc, s[82:83], vcc
	v_cndmask_b32_e32 v22, v172, v22, vcc
	ds_write_b128 v22, v[18:21]
	s_waitcnt lgkmcnt(0)
	v_mov_b32_e32 v56, v62
	v_lshlrev_b32_e32 v22, 3, v171
	v_add_lshl_u32 v104, v22, s68, 2
	v_add_u32_e32 v22, 0x200, v104
	v_add_u32_e32 v23, s50, v22
	v_add_u32_e32 v24, s54, v22
	v_add_u32_e32 v54, s62, v22
	v_add_u32_e32 v55, s75, v22
	v_add_u32_e32 v22, s70, v104
	ds_read_b128 v[80:83], v23
	ds_read_b128 v[84:87], v24
	ds_read_b128 v[22:25], v22 offset:512
	ds_read_b128 v[88:91], v54
	ds_read_b128 v[92:95], v55
	v_add_u32_e32 v54, s80, v104
	ds_read_b128 v[96:99], v54 offset:512
	s_waitcnt lgkmcnt(0)
	v_mov_b32_dpp v22, v10 row_shr:1 row_mask:0xf bank_mask:0xf
	v_mov_b32_dpp v23, v11 row_shr:1 row_mask:0xf bank_mask:0xf
	v_mov_b32_dpp v24, v12 row_shr:1 row_mask:0xf bank_mask:0xf
	v_mov_b32_dpp v25, v13 row_shr:1 row_mask:0xf bank_mask:0xf
	v_mov_b32_e32 v54, v64
	v_mov_b32_e32 v55, v65
	v_mov_b32_e32 v57, v63
	v_mov_b32_dpp v54, v54 row_ror:15 row_mask:0xf bank_mask:0xf
	v_mov_b32_dpp v55, v55 row_ror:15 row_mask:0xf bank_mask:0xf
	v_mov_b32_dpp v56, v56 row_ror:15 row_mask:0xf bank_mask:0xf
	v_mov_b32_dpp v57, v57 row_ror:15 row_mask:0xf bank_mask:0xf
	v_pk_mul_f32 v[22:23], v[80:81], v[22:23]
	v_pk_mul_f32 v[24:25], v[82:83], v[24:25]
	v_mov_b32_dpp v54, v10 row_shl:1 row_mask:0xf bank_mask:0xf
	v_mov_b32_dpp v55, v11 row_shl:1 row_mask:0xf bank_mask:0xf
	v_mov_b32_dpp v56, v12 row_shl:1 row_mask:0xf bank_mask:0xf
	v_mov_b32_dpp v57, v13 row_shl:1 row_mask:0xf bank_mask:0xf
	v_mov_b32_e32 v100, v10
	v_mov_b32_e32 v101, v11
	v_mov_b32_e32 v102, v12
	v_mov_b32_e32 v103, v13
	v_pk_fma_f32 v[12:13], v[12:13], v[86:87], v[24:25]
	v_pk_fma_f32 v[10:11], v[10:11], v[84:85], v[22:23]
	v_mov_b32_dpp v100, v100 row_ror:1 row_mask:0xf bank_mask:0xf
	v_mov_b32_dpp v101, v101 row_ror:1 row_mask:0xf bank_mask:0xf
	v_mov_b32_dpp v102, v102 row_ror:1 row_mask:0xf bank_mask:0xf
	v_mov_b32_dpp v103, v103 row_ror:1 row_mask:0xf bank_mask:0xf
	v_pk_fma_f32 v[10:11], v[88:89], v[54:55], v[10:11]
	v_pk_fma_f32 v[12:13], v[90:91], v[56:57], v[12:13]
	v_pk_add_f32 v[68:69], v[92:93], v[10:11]
	v_pk_add_f32 v[66:67], v[94:95], v[12:13]
	v_mov_b32_dpp v100, v64 row_shr:1 row_mask:0xf bank_mask:0xf
	v_mov_b32_dpp v101, v65 row_shr:1 row_mask:0xf bank_mask:0xf
	v_mov_b32_dpp v102, v62 row_shr:1 row_mask:0xf bank_mask:0xf
	v_mov_b32_dpp v103, v63 row_shr:1 row_mask:0xf bank_mask:0xf
	v_mov_b32_e32 v10, v50
	v_mov_b32_e32 v11, v51
	v_mov_b32_e32 v12, v52
	v_mov_b32_e32 v13, v53
	v_mov_b32_dpp v10, v10 row_ror:15 row_mask:0xf bank_mask:0xf
	v_mov_b32_dpp v11, v11 row_ror:15 row_mask:0xf bank_mask:0xf
	v_mov_b32_dpp v12, v12 row_ror:15 row_mask:0xf bank_mask:0xf
	v_mov_b32_dpp v13, v13 row_ror:15 row_mask:0xf bank_mask:0xf
; #define LAS __attribute__((address_space(3)))
; __device__ __forceinline__ f32x4 dpp4_shr1(f32x4 o, f32x4 v) { return (f32x4){DPPF(o[0], v[0], 0x111), DPPF(o[1], v[1], 0x111), DPPF(o[2], v[2], 0x111), DPPF(o[3], v[3], 0x111)}; }
; __device__ __forceinline__ f32x4 dpp4_shl1(f32x4 o, f32x4 v) { return (f32x4){DPPF(o[0], v[0], 0x101), DPPF(o[1], v[1], 0x101), DPPF(o[2], v[2], 0x101), DPPF(o[3], v[3], 0x101)}; }
; __device__ __forceinline__ f32x4 dpp4_ror1(f32x4 v) { return (f32x4){DPPF(v[0], v[0], 0x121), DPPF(v[1], v[1], 0x121), DPPF(v[2], v[2], 0x121), DPPF(v[3], v[3], 0x121)}; }
;     __device__ __forceinline__ void operator()(f32x4 (&acc)[2][2][4][2], const Unit& u, int wr, int wc, int fr_in, int fq_in) const {
;     ...
;         for (int ai = 0; ai < 2; ++ai) { const int blk = 2 * ai + wr;
;             const int upslot = blk > 0 ? (blk - 1) * 2 + 1 : 8, dnslot = blk < 3 ? (blk + 1) * 2 : 8;
; #pragma unroll
;             for (int q = 0; q < 4; ++q) { const int bj = q >> 1, n = q & 1;
;                 asm volatile("" : "+v"(fr), "+v"(fq)); const int lc0 = wc * 32 + 8 * fq;
;                 const int cl = bj * 128 + lc0 + 4 * n;
;                 const f32x4 w0 = *(const LAS f32x4*)(WL + cl), w1 = *(const LAS f32x4*)(WL + 256 + cl), w2 = *(const LAS f32x4*)(WL + 512 + cl), bb = *(const LAS f32x4*)(WL + 768 + cl);
;                 f32x4 carry = *(const LAS f32x4*)(HL + upslot * 256 + bj * 128 + lc0 + 4 * n);
;                 const f32x4 hdn = *(const LAS f32x4*)(HL + dnslot * 256 + bj * 128 + lc0 + 4 * n);
; #pragma unroll
;                 for (int m = 0; m < 4; ++m) { const f32x4 cur = acc[ai][bj][m][n];
;                     const f32x4 up = dpp4_shr1(carry, cur);
;                     const f32x4 nf = m < 3 ? dpp4_ror15(acc[ai][bj][m < 3 ? m + 1 : 3][n]) : hdn;
;                     const f32x4 dn = dpp4_shl1(nf, cur);
;                     carry = dpp4_ror1(cur);
;                     acc[ai][bj][m][n] = w0 * up + w1 * cur + w2 * dn + bb; }
;                 if (ai == 0) { LAS float* d0 = ((wr == 0) & (fr == 0)) ? PAL + bj * 128 + lc0 + 4 * n : DMP; *(LAS f32x4*)d0 = acc[ai][bj][0][n]; }
;                 if (ai == 1) { LAS float* d1 = ((wr == 1) & (fr == 15)) ? PAL + 256 + bj * 128 + lc0 + 4 * n : DMP; *(LAS f32x4*)d1 = acc[ai][bj][3][n]; }
	v_pk_mul_f32 v[54:55], v[82:83], v[102:103]
	v_pk_mul_f32 v[56:57], v[80:81], v[100:101]
	v_mov_b32_dpp v10, v64 row_shl:1 row_mask:0xf bank_mask:0xf
	v_mov_b32_dpp v11, v65 row_shl:1 row_mask:0xf bank_mask:0xf
	v_mov_b32_dpp v12, v62 row_shl:1 row_mask:0xf bank_mask:0xf
	v_mov_b32_dpp v13, v63 row_shl:1 row_mask:0xf bank_mask:0xf
	v_mov_b32_e32 v22, v64
	v_mov_b32_e32 v24, v62
	v_pk_fma_f32 v[54:55], v[62:63], v[86:87], v[54:55]
	v_mov_b32_dpp v63, v63 row_ror:1 row_mask:0xf bank_mask:0xf
	v_pk_fma_f32 v[56:57], v[64:65], v[84:85], v[56:57]
	v_mov_b32_dpp v65, v65 row_ror:1 row_mask:0xf bank_mask:0xf
	v_mov_b32_dpp v22, v22 row_ror:1 row_mask:0xf bank_mask:0xf
	v_mov_b32_dpp v24, v24 row_ror:1 row_mask:0xf bank_mask:0xf
	v_pk_fma_f32 v[12:13], v[90:91], v[12:13], v[54:55]
	v_pk_fma_f32 v[10:11], v[88:89], v[10:11], v[56:57]
	v_mov_b32_dpp v65, v51 row_shr:1 row_mask:0xf bank_mask:0xf
	v_mov_b32_dpp v63, v53 row_shr:1 row_mask:0xf bank_mask:0xf
	v_pk_add_f32 v[54:55], v[94:95], v[12:13]
	v_pk_add_f32 v[56:57], v[92:93], v[10:11]
	v_mov_b32_dpp v22, v50 row_shr:1 row_mask:0xf bank_mask:0xf
	v_mov_b32_dpp v24, v52 row_shr:1 row_mask:0xf bank_mask:0xf
	v_mov_b32_e32 v11, v15
	v_mov_b32_e32 v13, v17
	v_mov_b32_e32 v23, v65
	v_mov_b32_e32 v25, v63
	v_mov_b32_e32 v10, v14
	v_mov_b32_dpp v11, v11 row_ror:15 row_mask:0xf bank_mask:0xf
	v_mov_b32_e32 v12, v16
	v_mov_b32_dpp v13, v13 row_ror:15 row_mask:0xf bank_mask:0xf
	v_pk_mul_f32 v[22:23], v[80:81], v[22:23]
	v_pk_mul_f32 v[24:25], v[82:83], v[24:25]
	v_mov_b32_dpp v10, v10 row_ror:15 row_mask:0xf bank_mask:0xf
	v_mov_b32_dpp v12, v12 row_ror:15 row_mask:0xf bank_mask:0xf
	v_mov_b32_dpp v11, v51 row_shl:1 row_mask:0xf bank_mask:0xf
	v_mov_b32_dpp v13, v53 row_shl:1 row_mask:0xf bank_mask:0xf
	v_mov_b32_e32 v62, v50
	v_mov_b32_e32 v64, v52
	v_pk_fma_f32 v[24:25], v[52:53], v[86:87], v[24:25]
	v_mov_b32_dpp v53, v53 row_ror:1 row_mask:0xf bank_mask:0xf
	v_pk_fma_f32 v[22:23], v[50:51], v[84:85], v[22:23]
	v_mov_b32_dpp v51, v51 row_ror:1 row_mask:0xf bank_mask:0xf
	v_mov_b32_dpp v10, v50 row_shl:1 row_mask:0xf bank_mask:0xf
	v_mov_b32_dpp v12, v52 row_shl:1 row_mask:0xf bank_mask:0xf
	v_mov_b32_dpp v62, v62 row_ror:1 row_mask:0xf bank_mask:0xf
	v_mov_b32_dpp v64, v64 row_ror:1 row_mask:0xf bank_mask:0xf
	v_mov_b32_dpp v51, v15 row_shr:1 row_mask:0xf bank_mask:0xf
	v_mov_b32_dpp v53, v17 row_shr:1 row_mask:0xf bank_mask:0xf
	v_pk_fma_f32 v[10:11], v[88:89], v[10:11], v[22:23]
	v_pk_fma_f32 v[12:13], v[90:91], v[12:13], v[24:25]
	v_mov_b32_dpp v62, v14 row_shr:1 row_mask:0xf bank_mask:0xf
	v_mov_b32_dpp v64, v16 row_shr:1 row_mask:0xf bank_mask:0xf
	v_mov_b32_e32 v65, v53
	v_mov_b32_e32 v63, v51
	v_pk_add_f32 v[22:23], v[94:95], v[12:13]
	v_pk_add_f32 v[24:25], v[92:93], v[10:11]
	v_pk_mul_f32 v[10:11], v[82:83], v[64:65]
	v_pk_mul_f32 v[12:13], v[80:81], v[62:63]
	v_mov_b32_dpp v96, v14 row_shl:1 row_mask:0xf bank_mask:0xf
	v_mov_b32_dpp v97, v15 row_shl:1 row_mask:0xf bank_mask:0xf
	v_mov_b32_dpp v98, v16 row_shl:1 row_mask:0xf bank_mask:0xf
	v_mov_b32_dpp v99, v17 row_shl:1 row_mask:0xf bank_mask:0xf
	v_pk_fma_f32 v[10:11], v[16:17], v[86:87], v[10:11]
	v_pk_fma_f32 v[12:13], v[14:15], v[84:85], v[12:13]
	v_pk_fma_f32 v[10:11], v[90:91], v[98:99], v[10:11]
	v_pk_fma_f32 v[14:15], v[88:89], v[96:97], v[12:13]
	v_cmp_eq_u32_e32 vcc, 15, v170
	v_readlane_b32 s81, v253, 23
	v_pk_add_f32 v[12:13], v[94:95], v[10:11]
	v_pk_add_f32 v[10:11], v[92:93], v[14:15]
	v_add_u32_e32 v14, s81, v104
	s_and_b64 vcc, s[82:83], vcc
	v_cndmask_b32_e32 v14, v172, v14, vcc
	ds_write_b128 v14, v[10:13]
	s_waitcnt lgkmcnt(0)
	v_mov_b32_e32 v52, v58
	v_lshlrev_b32_e32 v14, 3, v171
	v_add_lshl_u32 v102, v14, s68, 2
	v_add_u32_e32 v14, 0x210, v102
	v_add_u32_e32 v15, s50, v14
	v_add_u32_e32 v16, s54, v14
	v_add_u32_e32 v50, s62, v14
	v_add_u32_e32 v51, s75, v14
	v_add_u32_e32 v14, s70, v102
	ds_read_b128 v[62:65], v15
	ds_read_b128 v[80:83], v16
	ds_read_b128 v[14:17], v14 offset:528
	ds_read_b128 v[84:87], v50
	ds_read_b128 v[88:91], v51
	v_add_u32_e32 v50, s80, v102
	ds_read_b128 v[92:95], v50 offset:528
	s_waitcnt lgkmcnt(0)
	v_mov_b32_dpp v14, v2 row_shr:1 row_mask:0xf bank_mask:0xf
	v_mov_b32_dpp v15, v3 row_shr:1 row_mask:0xf bank_mask:0xf
	v_mov_b32_dpp v16, v4 row_shr:1 row_mask:0xf bank_mask:0xf
	v_mov_b32_dpp v17, v5 row_shr:1 row_mask:0xf bank_mask:0xf
	v_mov_b32_e32 v50, v60
	v_mov_b32_e32 v51, v61
	v_mov_b32_e32 v53, v59
	v_mov_b32_dpp v50, v50 row_ror:15 row_mask:0xf bank_mask:0xf
	v_mov_b32_dpp v51, v51 row_ror:15 row_mask:0xf bank_mask:0xf
	v_mov_b32_dpp v52, v52 row_ror:15 row_mask:0xf bank_mask:0xf
	v_mov_b32_dpp v53, v53 row_ror:15 row_mask:0xf bank_mask:0xf
	v_pk_mul_f32 v[14:15], v[62:63], v[14:15]
	v_pk_mul_f32 v[16:17], v[64:65], v[16:17]
	v_mov_b32_dpp v50, v2 row_shl:1 row_mask:0xf bank_mask:0xf
	v_mov_b32_dpp v51, v3 row_shl:1 row_mask:0xf bank_mask:0xf
	v_mov_b32_dpp v52, v4 row_shl:1 row_mask:0xf bank_mask:0xf
	v_mov_b32_dpp v53, v5 row_shl:1 row_mask:0xf bank_mask:0xf
	v_mov_b32_e32 v96, v2
	v_mov_b32_e32 v97, v3
	v_mov_b32_e32 v98, v4
	v_mov_b32_e32 v99, v5
	v_pk_fma_f32 v[4:5], v[4:5], v[82:83], v[16:17]
	v_pk_fma_f32 v[2:3], v[2:3], v[80:81], v[14:15]
	v_mov_b32_dpp v96, v96 row_ror:1 row_mask:0xf bank_mask:0xf
	v_mov_b32_dpp v97, v97 row_ror:1 row_mask:0xf bank_mask:0xf
	v_mov_b32_dpp v98, v98 row_ror:1 row_mask:0xf bank_mask:0xf
	v_mov_b32_dpp v99, v99 row_ror:1 row_mask:0xf bank_mask:0xf
	v_pk_fma_f32 v[2:3], v[84:85], v[50:51], v[2:3]
	v_pk_fma_f32 v[4:5], v[86:87], v[52:53], v[4:5]
	v_pk_add_f32 v[100:101], v[88:89], v[2:3]
	v_pk_add_f32 v[52:53], v[90:91], v[4:5]
; #define LAS __attribute__((address_space(3)))
; __device__ __forceinline__ unsigned cvt_pk_bf16(float lo, float hi) { unsigned r; asm volatile("v_cvt_pk_bf16_f32 %0, %1, %2" : "=v"(r) : "v"(lo), "v"(hi)); return r; }
; __device__ __forceinline__ float siluf(float x) { return x * __builtin_amdgcn_rcpf(1.f + __expf(-x)); }
;     __device__ __forceinline__ void operator()(f32x4 (&acc)[2][2][4][2], const Unit& u, int wr, int wc, int fr_in, int fq_in) const {
;     ...
;             for (int q = 0; q < 4; ++q) { const int bj = q >> 1, n = q & 1;
;                 asm volatile("" : "+v"(fr), "+v"(fq)); const int lc0 = wc * 32 + 8 * fq;
;                 const int cl = bj * 128 + lc0 + 4 * n;
;                 const f32x4 w0 = *(const LAS f32x4*)(WL + cl), w1 = *(const LAS f32x4*)(WL + 256 + cl), w2 = *(const LAS f32x4*)(WL + 512 + cl), bb = *(const LAS f32x4*)(WL + 768 + cl);
;                 f32x4 carry = *(const LAS f32x4*)(HL + upslot * 256 + bj * 128 + lc0 + 4 * n);
;                 const f32x4 hdn = *(const LAS f32x4*)(HL + dnslot * 256 + bj * 128 + lc0 + 4 * n);
; #pragma unroll
;                 for (int m = 0; m < 4; ++m) { const f32x4 cur = acc[ai][bj][m][n];
;                     const f32x4 up = dpp4_shr1(carry, cur);
;                     const f32x4 nf = m < 3 ? dpp4_ror15(acc[ai][bj][m < 3 ? m + 1 : 3][n]) : hdn;
;                     const f32x4 dn = dpp4_shl1(nf, cur);
;                     carry = dpp4_ror1(cur);
;                     acc[ai][bj][m][n] = w0 * up + w1 * cur + w2 * dn + bb; }
;                 if (ai == 0) { LAS float* d0 = ((wr == 0) & (fr == 0)) ? PAL + bj * 128 + lc0 + 4 * n : DMP; *(LAS f32x4*)d0 = acc[ai][bj][0][n]; }
;                 if (ai == 1) { LAS float* d1 = ((wr == 1) & (fr == 15)) ? PAL + 256 + bj * 128 + lc0 + 4 * n : DMP; *(LAS f32x4*)d1 = acc[ai][bj][3][n]; }
;                 asm volatile("s_waitcnt lgkmcnt(0)" ::: "memory");
;             }
;             asm volatile("" : "+v"(fr), "+v"(fq));
; #pragma unroll
;             for (int m = 0; m < 4; ++m) { const int row = u.pm * BM + ai * HALF + wr * 64 + m * 16 + fr;
;                 const f32x4 a0 = acc[ai][0][m][0], a1 = acc[ai][0][m][1], g0 = acc[ai][1][m][0], g1 = acc[ai][1][m][1];
;                 u32x4 w; w.x = cvt_pk_bf16(a0[0] * siluf(g0[0]), a0[1] * siluf(g0[1])); w.y = cvt_pk_bf16(a0[2] * siluf(g0[2]), a0[3] * siluf(g0[3]));
	v_mov_b32_dpp v96, v60 row_shr:1 row_mask:0xf bank_mask:0xf
	v_mov_b32_dpp v97, v61 row_shr:1 row_mask:0xf bank_mask:0xf
	v_mov_b32_dpp v98, v58 row_shr:1 row_mask:0xf bank_mask:0xf
	v_mov_b32_dpp v99, v59 row_shr:1 row_mask:0xf bank_mask:0xf
	v_mov_b32_e32 v2, v46
	v_mov_b32_e32 v3, v47
	v_mov_b32_e32 v4, v48
	v_mov_b32_e32 v5, v49
	v_mov_b32_dpp v2, v2 row_ror:15 row_mask:0xf bank_mask:0xf
	v_mov_b32_dpp v3, v3 row_ror:15 row_mask:0xf bank_mask:0xf
	v_mov_b32_dpp v4, v4 row_ror:15 row_mask:0xf bank_mask:0xf
	v_mov_b32_dpp v5, v5 row_ror:15 row_mask:0xf bank_mask:0xf
	v_pk_mul_f32 v[50:51], v[64:65], v[98:99]
	v_pk_mul_f32 v[96:97], v[62:63], v[96:97]
	v_mov_b32_dpp v2, v60 row_shl:1 row_mask:0xf bank_mask:0xf
	v_mov_b32_dpp v3, v61 row_shl:1 row_mask:0xf bank_mask:0xf
	v_mov_b32_dpp v4, v58 row_shl:1 row_mask:0xf bank_mask:0xf
	v_mov_b32_dpp v5, v59 row_shl:1 row_mask:0xf bank_mask:0xf
	v_mov_b32_e32 v14, v60
	v_mov_b32_e32 v16, v58
	v_pk_fma_f32 v[50:51], v[58:59], v[82:83], v[50:51]
	v_mov_b32_dpp v59, v59 row_ror:1 row_mask:0xf bank_mask:0xf
	v_pk_fma_f32 v[96:97], v[60:61], v[80:81], v[96:97]
	v_mov_b32_dpp v61, v61 row_ror:1 row_mask:0xf bank_mask:0xf
	v_mov_b32_dpp v14, v14 row_ror:1 row_mask:0xf bank_mask:0xf
	v_mov_b32_dpp v16, v16 row_ror:1 row_mask:0xf bank_mask:0xf
	v_pk_fma_f32 v[4:5], v[86:87], v[4:5], v[50:51]
	v_pk_fma_f32 v[2:3], v[84:85], v[2:3], v[96:97]
	v_mov_b32_dpp v61, v47 row_shr:1 row_mask:0xf bank_mask:0xf
	v_mov_b32_dpp v59, v49 row_shr:1 row_mask:0xf bank_mask:0xf
	v_pk_add_f32 v[50:51], v[90:91], v[4:5]
	v_pk_add_f32 v[96:97], v[88:89], v[2:3]
	v_mov_b32_dpp v14, v46 row_shr:1 row_mask:0xf bank_mask:0xf
	v_mov_b32_dpp v16, v48 row_shr:1 row_mask:0xf bank_mask:0xf
	v_mov_b32_e32 v3, v7
	v_mov_b32_e32 v5, v9
	v_mov_b32_e32 v15, v61
	v_mov_b32_e32 v17, v59
	v_mov_b32_e32 v2, v6
	v_mov_b32_dpp v3, v3 row_ror:15 row_mask:0xf bank_mask:0xf
	v_mov_b32_e32 v4, v8
	v_mov_b32_dpp v5, v5 row_ror:15 row_mask:0xf bank_mask:0xf
	v_pk_mul_f32 v[14:15], v[62:63], v[14:15]
	v_pk_mul_f32 v[16:17], v[64:65], v[16:17]
	v_mov_b32_dpp v2, v2 row_ror:15 row_mask:0xf bank_mask:0xf
	v_mov_b32_dpp v4, v4 row_ror:15 row_mask:0xf bank_mask:0xf
	v_mov_b32_dpp v3, v47 row_shl:1 row_mask:0xf bank_mask:0xf
	v_mov_b32_dpp v5, v49 row_shl:1 row_mask:0xf bank_mask:0xf
	v_mov_b32_e32 v58, v46
	v_mov_b32_e32 v60, v48
	v_pk_fma_f32 v[16:17], v[48:49], v[82:83], v[16:17]
	v_mov_b32_dpp v49, v49 row_ror:1 row_mask:0xf bank_mask:0xf
	v_pk_fma_f32 v[14:15], v[46:47], v[80:81], v[14:15]
	v_mov_b32_dpp v47, v47 row_ror:1 row_mask:0xf bank_mask:0xf
	v_mov_b32_dpp v2, v46 row_shl:1 row_mask:0xf bank_mask:0xf
	v_mov_b32_dpp v4, v48 row_shl:1 row_mask:0xf bank_mask:0xf
	v_mov_b32_dpp v58, v58 row_ror:1 row_mask:0xf bank_mask:0xf
	v_mov_b32_dpp v60, v60 row_ror:1 row_mask:0xf bank_mask:0xf
	v_mov_b32_dpp v47, v7 row_shr:1 row_mask:0xf bank_mask:0xf
	v_mov_b32_dpp v49, v9 row_shr:1 row_mask:0xf bank_mask:0xf
	v_pk_fma_f32 v[2:3], v[84:85], v[2:3], v[14:15]
	v_pk_fma_f32 v[4:5], v[86:87], v[4:5], v[16:17]
	v_mov_b32_dpp v58, v6 row_shr:1 row_mask:0xf bank_mask:0xf
	v_mov_b32_dpp v60, v8 row_shr:1 row_mask:0xf bank_mask:0xf
	v_mov_b32_e32 v61, v49
	v_mov_b32_e32 v59, v47
	v_pk_add_f32 v[14:15], v[90:91], v[4:5]
	v_pk_add_f32 v[16:17], v[88:89], v[2:3]
	v_pk_mul_f32 v[2:3], v[64:65], v[60:61]
	v_pk_mul_f32 v[4:5], v[62:63], v[58:59]
	v_mov_b32_dpp v92, v6 row_shl:1 row_mask:0xf bank_mask:0xf
	v_mov_b32_dpp v93, v7 row_shl:1 row_mask:0xf bank_mask:0xf
	v_mov_b32_dpp v94, v8 row_shl:1 row_mask:0xf bank_mask:0xf
	v_mov_b32_dpp v95, v9 row_shl:1 row_mask:0xf bank_mask:0xf
	v_pk_fma_f32 v[2:3], v[8:9], v[82:83], v[2:3]
	v_pk_fma_f32 v[4:5], v[6:7], v[80:81], v[4:5]
	v_pk_fma_f32 v[2:3], v[86:87], v[94:95], v[2:3]
	v_pk_fma_f32 v[6:7], v[84:85], v[92:93], v[4:5]
	v_pk_add_f32 v[4:5], v[90:91], v[2:3]
	v_pk_add_f32 v[2:3], v[88:89], v[6:7]
	v_cmp_eq_u32_e32 vcc, 15, v170
	v_add_u32_e32 v6, s51, v102
	v_add_u32_e32 v6, 0x2a10, v6
	s_and_b64 vcc, s[82:83], vcc
	v_cndmask_b32_e32 v6, v172, v6, vcc
	ds_write_b128 v6, v[2:5]
	v_mul_f32_e32 v6, 0xbfb8aa3b, v68
	v_exp_f32_e32 v7, v6
	v_mul_f32_e32 v6, 0xbfb8aa3b, v69
	v_exp_f32_e32 v8, v6
	v_mul_f32_e32 v46, 0xbfb8aa3b, v66
	v_exp_f32_e32 v46, v46
	v_mul_f32_e32 v47, 0xbfb8aa3b, v67
	v_add_f32_e32 v7, 1.0, v7
	v_exp_f32_e32 v47, v47
	v_rcp_f32_e32 v9, v7
	v_add_f32_e32 v7, 1.0, v8
	v_rcp_f32_e32 v8, v7
	v_add_f32_e32 v46, 1.0, v46
	v_rcp_f32_e32 v48, v46
	v_add_f32_e32 v46, 1.0, v47
	v_rcp_f32_e32 v47, v46
	v_mul_f32_e32 v8, v69, v8
	v_mul_f32_e32 v9, v68, v9
	v_mul_f32_e32 v8, v79, v8
	s_waitcnt lgkmcnt(0)
; __device__ __forceinline__ unsigned cvt_pk_bf16(float lo, float hi) { unsigned r; asm volatile("v_cvt_pk_bf16_f32 %0, %1, %2" : "=v"(r) : "v"(lo), "v"(hi)); return r; }
; __device__ __forceinline__ float siluf(float x) { return x * __builtin_amdgcn_rcpf(1.f + __expf(-x)); }
;     __device__ __forceinline__ void operator()(f32x4 (&acc)[2][2][4][2], const Unit& u, int wr, int wc, int fr_in, int fq_in) const {
;     ...
;             for (int m = 0; m < 4; ++m) { const int row = u.pm * BM + ai * HALF + wr * 64 + m * 16 + fr;
;                 const f32x4 a0 = acc[ai][0][m][0], a1 = acc[ai][0][m][1], g0 = acc[ai][1][m][0], g1 = acc[ai][1][m][1];
;                 u32x4 w; w.x = cvt_pk_bf16(a0[0] * siluf(g0[0]), a0[1] * siluf(g0[1])); w.y = cvt_pk_bf16(a0[2] * siluf(g0[2]), a0[3] * siluf(g0[3]));
;                 w.z = cvt_pk_bf16(a1[0] * siluf(g1[0]), a1[1] * siluf(g1[1])); w.w = cvt_pk_bf16(a1[2] * siluf(g1[2]), a1[3] * siluf(g1[3]));
;                 *(u32x4*)(ACT + (size_t)row * DFF + u.pn * 128 + wc * 32 + 8 * fq) = w;
;                 asm volatile("" ::: "memory"); }
;         }
;         asm volatile("s_waitcnt lgkmcnt(0)" ::: "memory"); __builtin_amdgcn_s_barrier(); asm volatile("" ::: "memory");
	v_mul_f32_e32 v9, v78, v9
	v_cvt_pk_bf16_f32 v46, v9, v8
	v_mul_f32_e32 v8, v66, v48
	v_mul_f32_e32 v8, v44, v8
	v_mul_f32_e32 v9, v67, v47
	v_mul_f32_e32 v44, 0xbfb8aa3b, v100
	v_mul_f32_e32 v47, 0xbfb8aa3b, v101
	v_exp_f32_e32 v44, v44
	v_exp_f32_e32 v47, v47
	v_mul_f32_e32 v9, v45, v9
	v_add_u32_e32 v58, s11, v170
	v_add_f32_e32 v44, 1.0, v44
	v_add_f32_e32 v45, 1.0, v47
	v_rcp_f32_e32 v44, v44
	v_rcp_f32_e32 v45, v45
	v_cvt_pk_bf16_f32 v47, v8, v9
	v_lshlrev_b32_e32 v6, 3, v171
	v_mul_f32_e32 v8, v100, v44
	v_mul_f32_e32 v9, v101, v45
	v_mul_f32_e32 v44, 0xbfb8aa3b, v52
	v_mul_f32_e32 v45, 0xbfb8aa3b, v53
	v_exp_f32_e32 v44, v44
	v_exp_f32_e32 v45, v45
	v_mul_f32_e32 v8, v76, v8
	v_mul_f32_e32 v9, v77, v9
	v_add_f32_e32 v44, 1.0, v44
	v_add_f32_e32 v45, 1.0, v45
	v_rcp_f32_e32 v44, v44
	v_rcp_f32_e32 v45, v45
	v_cvt_pk_bf16_f32 v48, v8, v9
	v_ashrrev_i32_e32 v7, 31, v6
	v_mul_f32_e32 v8, v52, v44
	v_mul_f32_e32 v9, v53, v45
	v_mul_f32_e32 v8, v74, v8
	v_mul_f32_e32 v9, v75, v9
	v_cvt_pk_bf16_f32 v49, v8, v9
	v_mad_i64_i32 v[8:9], s[50:51], v58, s29, v[34:35]
	v_lshl_add_u64 v[8:9], v[8:9], 0, s[48:49]
	v_lshl_add_u64 v[8:9], v[8:9], 0, s[24:25]
	v_lshlrev_b64 v[6:7], 1, v[6:7]
	v_lshl_add_u64 v[8:9], v[8:9], 0, v[6:7]
	global_store_dwordx4 v[8:9], v[46:49], off
	v_mul_f32_e32 v8, 0xbfb8aa3b, v56
	v_exp_f32_e32 v8, v8
	v_mul_f32_e32 v9, 0xbfb8aa3b, v57
	v_exp_f32_e32 v9, v9
	v_mul_f32_e32 v44, 0xbfb8aa3b, v55
	v_add_f32_e32 v8, 1.0, v8
	v_rcp_f32_e32 v8, v8
	v_add_f32_e32 v9, 1.0, v9
	v_rcp_f32_e32 v9, v9
	v_exp_f32_e32 v44, v44
	v_mul_f32_e32 v8, v56, v8
	v_mul_f32_e32 v8, v42, v8
	v_mul_f32_e32 v42, 0xbfb8aa3b, v54
	v_exp_f32_e32 v42, v42
	v_mul_f32_e32 v9, v57, v9
	v_mul_f32_e32 v9, v43, v9
	v_add_f32_e32 v42, 1.0, v42
	v_rcp_f32_e32 v43, v42
	v_add_f32_e32 v42, 1.0, v44
	v_rcp_f32_e32 v44, v42
	v_cvt_pk_bf16_f32 v42, v8, v9
	v_mul_f32_e32 v8, v54, v43
	v_mul_f32_e32 v8, v40, v8
	v_mul_f32_e32 v40, 0xbfb8aa3b, v96
	v_mul_f32_e32 v43, 0xbfb8aa3b, v97
	v_exp_f32_e32 v40, v40
	v_exp_f32_e32 v43, v43
	v_mul_f32_e32 v9, v55, v44
	v_mul_f32_e32 v9, v41, v9
	v_add_f32_e32 v40, 1.0, v40
	v_add_f32_e32 v41, 1.0, v43
	v_rcp_f32_e32 v40, v40
	v_rcp_f32_e32 v41, v41
	v_cvt_pk_bf16_f32 v43, v8, v9
	v_add_u32_e32 v46, 16, v58
	v_mul_f32_e32 v8, v96, v40
	v_mul_f32_e32 v9, v97, v41
	v_mul_f32_e32 v40, 0xbfb8aa3b, v50
	v_mul_f32_e32 v41, 0xbfb8aa3b, v51
	v_exp_f32_e32 v40, v40
	v_exp_f32_e32 v41, v41
	v_mul_f32_e32 v8, v72, v8
	v_mul_f32_e32 v9, v73, v9
	v_add_f32_e32 v40, 1.0, v40
	v_add_f32_e32 v41, 1.0, v41
	v_rcp_f32_e32 v40, v40
	v_rcp_f32_e32 v41, v41
	v_cvt_pk_bf16_f32 v44, v8, v9
	s_and_b64 vcc, exec, s[40:41]
	v_mul_f32_e32 v8, v50, v40
	v_mul_f32_e32 v9, v51, v41
	v_mul_f32_e32 v8, v70, v8
	v_mul_f32_e32 v9, v71, v9
	v_cvt_pk_bf16_f32 v45, v8, v9
	v_mad_i64_i32 v[8:9], s[50:51], v46, s29, v[34:35]
	v_lshl_add_u64 v[8:9], v[8:9], 0, s[48:49]
	v_lshl_add_u64 v[8:9], v[8:9], 0, s[24:25]
	v_lshl_add_u64 v[8:9], v[8:9], 0, v[6:7]
	global_store_dwordx4 v[8:9], v[42:45], off
	v_mul_f32_e32 v8, 0xbfb8aa3b, v24
	v_mul_f32_e32 v9, 0xbfb8aa3b, v25
	v_exp_f32_e32 v8, v8
	v_exp_f32_e32 v9, v9
	v_add_u32_e32 v42, 32, v58
	v_add_f32_e32 v8, 1.0, v8
	v_add_f32_e32 v9, 1.0, v9
	v_rcp_f32_e32 v8, v8
	v_rcp_f32_e32 v9, v9
	v_mul_f32_e32 v8, v24, v8
	v_mul_f32_e32 v9, v25, v9
	v_mul_f32_e32 v24, 0xbfb8aa3b, v22
	v_mul_f32_e32 v25, 0xbfb8aa3b, v23
	v_exp_f32_e32 v24, v24
	v_exp_f32_e32 v25, v25
	v_mul_f32_e32 v8, v38, v8
	v_mul_f32_e32 v9, v39, v9
	v_add_f32_e32 v24, 1.0, v24
	v_add_f32_e32 v25, 1.0, v25
	v_rcp_f32_e32 v24, v24
	v_rcp_f32_e32 v25, v25
	v_cvt_pk_bf16_f32 v38, v8, v9
	v_mul_f32_e32 v8, v22, v24
	v_mul_f32_e32 v9, v23, v25
	v_mul_f32_e32 v22, 0xbfb8aa3b, v16
	v_mul_f32_e32 v23, 0xbfb8aa3b, v17
	v_exp_f32_e32 v22, v22
	v_exp_f32_e32 v23, v23
	v_mul_f32_e32 v8, v36, v8
	v_mul_f32_e32 v9, v37, v9
	v_add_f32_e32 v22, 1.0, v22
	v_add_f32_e32 v23, 1.0, v23
	v_rcp_f32_e32 v22, v22
	v_rcp_f32_e32 v23, v23
	v_cvt_pk_bf16_f32 v39, v8, v9
	v_mul_f32_e32 v8, v16, v22
	v_mul_f32_e32 v9, v17, v23
	v_mul_f32_e32 v16, 0xbfb8aa3b, v14
	v_mul_f32_e32 v17, 0xbfb8aa3b, v15
	v_exp_f32_e32 v16, v16
	v_exp_f32_e32 v17, v17
	v_mul_f32_e32 v8, v32, v8
	v_mul_f32_e32 v9, v33, v9
	v_add_f32_e32 v16, 1.0, v16
	v_add_f32_e32 v17, 1.0, v17
	v_rcp_f32_e32 v16, v16
	v_rcp_f32_e32 v17, v17
	v_cvt_pk_bf16_f32 v40, v8, v9
	v_mul_f32_e32 v8, v14, v16
	v_mul_f32_e32 v9, v15, v17
	v_mul_f32_e32 v8, v30, v8
	v_mul_f32_e32 v9, v31, v9
	v_cvt_pk_bf16_f32 v41, v8, v9
	v_mad_i64_i32 v[8:9], s[50:51], v42, s29, v[34:35]
	v_lshl_add_u64 v[8:9], v[8:9], 0, s[48:49]
	v_lshl_add_u64 v[8:9], v[8:9], 0, s[24:25]
	v_lshl_add_u64 v[8:9], v[8:9], 0, v[6:7]
	global_store_dwordx4 v[8:9], v[38:41], off
	v_mul_f32_e32 v8, 0xbfb8aa3b, v10
	v_mul_f32_e32 v9, 0xbfb8aa3b, v11
	v_exp_f32_e32 v8, v8
	v_exp_f32_e32 v9, v9
	v_add_u32_e32 v14, 48, v58
	v_add_f32_e32 v8, 1.0, v8
	v_add_f32_e32 v9, 1.0, v9
	v_rcp_f32_e32 v8, v8
	v_rcp_f32_e32 v9, v9
	v_mul_f32_e32 v8, v10, v8
	v_mul_f32_e32 v9, v11, v9
	v_mul_f32_e32 v10, 0xbfb8aa3b, v12
	v_mul_f32_e32 v11, 0xbfb8aa3b, v13
	v_exp_f32_e32 v10, v10
	v_exp_f32_e32 v11, v11
	v_mul_f32_e32 v8, v26, v8
	v_mul_f32_e32 v9, v27, v9
	v_add_f32_e32 v10, 1.0, v10
	v_add_f32_e32 v11, 1.0, v11
	v_rcp_f32_e32 v10, v10
	v_rcp_f32_e32 v11, v11
	v_cvt_pk_bf16_f32 v8, v8, v9
	v_mul_f32_e32 v9, v12, v10
	v_mul_f32_e32 v10, v13, v11
	v_mul_f32_e32 v11, 0xbfb8aa3b, v2
	v_exp_f32_e32 v11, v11
	v_mul_f32_e32 v12, 0xbfb8aa3b, v3
	v_exp_f32_e32 v12, v12
	v_mul_f32_e32 v9, v28, v9
	v_add_f32_e32 v11, 1.0, v11
	v_rcp_f32_e32 v11, v11
	v_mul_f32_e32 v10, v29, v10
	v_cvt_pk_bf16_f32 v9, v9, v10
	v_mul_f32_e32 v10, 0xbfb8aa3b, v4
	v_add_f32_e32 v12, 1.0, v12
	v_mul_f32_e32 v2, v2, v11
	v_exp_f32_e32 v10, v10
	v_mul_f32_e32 v11, 0xbfb8aa3b, v5
	v_rcp_f32_e32 v12, v12
	v_exp_f32_e32 v11, v11
	v_add_f32_e32 v10, 1.0, v10
	v_mul_f32_e32 v2, v18, v2
	v_mul_f32_e32 v3, v3, v12
	v_rcp_f32_e32 v12, v10
	v_add_f32_e32 v10, 1.0, v11
	v_rcp_f32_e32 v11, v10
	v_mul_f32_e32 v3, v19, v3
	v_cvt_pk_bf16_f32 v10, v2, v3
	v_mul_f32_e32 v2, v4, v12
	v_mul_f32_e32 v3, v5, v11
	v_mul_f32_e32 v2, v20, v2
	v_mul_f32_e32 v3, v21, v3
	v_cvt_pk_bf16_f32 v11, v2, v3
	v_mad_i64_i32 v[2:3], s[50:51], v14, s29, v[34:35]
	v_lshl_add_u64 v[2:3], v[2:3], 0, s[48:49]
	v_lshl_add_u64 v[2:3], v[2:3], 0, s[24:25]
	v_lshl_add_u64 v[2:3], v[2:3], 0, v[6:7]
	global_store_dwordx4 v[2:3], v[8:11], off
	s_waitcnt lgkmcnt(0)
	s_barrier
	s_cbranch_vccz .LBB0_65
	s_andn2_b64 vcc, exec, s[38:39]
	s_mov_b64 s[0:1], -1
	s_cbranch_vccnz .LBB0_52
	s_branch .LBB0_66
; #define LAS __attribute__((address_space(3)))
;     __device__ __forceinline__ void operator()(f32x4 (&acc)[2][2][4][2], const Unit& u, int wr, int wc, int fr_in, int fq_in) const {
;     ...
;         if (wv == 0) { const int l4 = (fq * 16 + fr) * 4;
;             *(f32x4*)(hb + 512 + l4) = *(const LAS f32x4*)(PAL + l4); *(f32x4*)(hb + 768 + l4) = *(const LAS f32x4*)(PAL + 256 + l4);
;             asm volatile("s_waitcnt lgkmcnt(0)" ::: "memory"); }
.LBB0_65:
	v_lshlrev_b32_e32 v2, 6, v171
	v_lshl_add_u32 v6, v170, 2, v2
	v_lshl_add_u32 v8, v6, 2, 0
	v_add_u32_e32 v2, 0x22500, v8
	ds_read_b128 v[2:5], v2
	v_ashrrev_i32_e32 v7, 31, v6
	v_lshl_add_u64 v[6:7], v[6:7], 2, s[0:1]
	s_waitcnt lgkmcnt(0)
	global_store_dwordx4 v[6:7], v[2:5], off offset:2048
	s_nop 1
	v_add_u32_e32 v2, 0x22900, v8
	ds_read_b128 v[2:5], v2
	s_waitcnt lgkmcnt(0)
	global_store_dwordx4 v[6:7], v[2:5], off offset:3072
	s_waitcnt lgkmcnt(0)
	s_andn2_b64 vcc, exec, s[38:39]
	s_mov_b64 s[0:1], -1
	s_cbranch_vccnz .LBB0_52

; #define LAS __attribute__((address_space(3)))
; __device__ __forceinline__ u32x4 pack8(const float (&v)[8]) { u32x4 w; w.x = cvt_pk_bf16(v[0], v[1]); w.y = cvt_pk_bf16(v[2], v[3]); w.z = cvt_pk_bf16(v[4], v[5]); w.w = cvt_pk_bf16(v[6], v[7]); return w; }
; __device__ __forceinline__ void r3_item(const Args& a, int L, int item, LAS unsigned char* lds) {
;     ...
;     { const int mat = tid >> 8, i = (tid >> 2) & 63, g = tid & 3;
;         const int col = mat == 0 ? (hl < 4 ? GQ + hl * 64 : RQ + (hl - 4) * 64) : (hl < 4 ? GK + hl * 64 : RK + (hl - 4) * 64);
;         float va[8], vb[8]; load_qk16(a, proj + (R0 + i) * LD + col, hl, c * 64 + i, g, va, vb);
;         const float sg = mat == 0 ? 1.f : -1.f;
; #pragma unroll
;         for (int dir = 0; dir < 2; ++dir) { float ta[8], tb[8];
; #pragma unroll
;             for (int e = 0; e < 8; ++e) { ta[e] = va[e] * __expf(sg * cum[(dir * 64 + i) * 64 + g * 8 + e]); tb[e] = vb[e] * __expf(sg * cum[(dir * 64 + i) * 64 + 32 + g * 8 + e]); }
;             LAS bf16_t* dst = QK + ((dir * 2 + mat) * 64 + i) * PT;
;             *(LAS u32x4*)(dst + g * 8) = pack8(ta); *(LAS u32x4*)(dst + 32 + g * 8) = pack8(tb); } }
;     { const int j = tid >> 3, vg = tid & 7; const int vcol = hl < 4 ? GV + hl * 128 : RV + (hl - 4) * 128;
;         const bf16_t* vp = proj + (R0 + j) * LD + vcol + vg * 16;
; #pragma unroll
;         for (int q = 0; q < 2; ++q) { const u32x4 w = *(const u32x4*)(vp + q * 8); const int v0 = vg * 16 + q * 8;
;             VT[(v0 + 0) * PT + j] = (bf16_t)(w.x & 0xffff); VT[(v0 + 1) * PT + j] = (bf16_t)(w.x >> 16); VT[(v0 + 2) * PT + j] = (bf16_t)(w.y & 0xffff); VT[(v0 + 3) * PT + j] = (bf16_t)(w.y >> 16);
;             VT[(v0 + 4) * PT + j] = (bf16_t)(w.z & 0xffff); VT[(v0 + 5) * PT + j] = (bf16_t)(w.z >> 16); VT[(v0 + 6) * PT + j] = (bf16_t)(w.w & 0xffff); VT[(v0 + 7) * PT + j] = (bf16_t)(w.w >> 16); } }
;     __syncthreads();
.LBB0_116:
	v_lshlrev_b32_e32 v16, 8, v21
	v_lshlrev_b32_e32 v17, 2, v22
	v_add3_u32 v16, 0, v16, v17
	ds_read_b128 v[26:29], v16
	ds_read_b128 v[30:33], v16 offset:16
	ds_read_b128 v[34:37], v16 offset:128
	ds_read_b128 v[38:41], v16 offset:144
	v_lshrrev_b32_e32 v17, 2, v24
	s_mov_b32 s5, 0xfffffc0
	s_waitcnt lgkmcnt(3)
	v_mul_f32_e32 v22, v20, v26
	s_waitcnt lgkmcnt(1)
	v_mul_f32_e32 v26, v20, v35
	v_mul_f32_e32 v26, 0x3fb8aa3b, v26
	v_exp_f32_e32 v26, v26
	v_mul_f32_e32 v23, v20, v34
	v_mul_f32_e32 v25, v20, v27
	v_mul_f32_e32 v27, v20, v36
	v_mul_f32_e32 v34, v11, v26
	v_mul_f32_e32 v26, v20, v28
	v_mul_f32_e32 v28, v20, v29
	v_mul_f32_e32 v29, v20, v37
	v_mul_f32_e32 v26, 0x3fb8aa3b, v26
	v_mul_f32_e32 v27, 0x3fb8aa3b, v27
	v_mul_f32_e32 v28, 0x3fb8aa3b, v28
	v_mul_f32_e32 v29, 0x3fb8aa3b, v29
	v_exp_f32_e32 v26, v26
	v_exp_f32_e32 v27, v27
	v_exp_f32_e32 v28, v28
	v_exp_f32_e32 v29, v29
	v_mul_f32_e32 v35, v14, v26
	v_mul_f32_e32 v36, v8, v27
	v_mul_f32_e32 v27, v15, v28
	v_mul_f32_e32 v37, v9, v29
	v_mul_f32_e32 v26, v20, v30
	s_waitcnt lgkmcnt(0)
	v_mul_f32_e32 v28, v20, v38
	v_mul_f32_e32 v29, v20, v31
	v_mul_f32_e32 v26, 0x3fb8aa3b, v26
	v_mul_f32_e32 v28, 0x3fb8aa3b, v28
	v_mul_f32_e32 v29, 0x3fb8aa3b, v29
	v_exp_f32_e32 v26, v26
	v_exp_f32_e32 v28, v28
	v_exp_f32_e32 v29, v29
	v_mul_f32_e32 v22, 0x3fb8aa3b, v22
	v_mul_f32_e32 v31, v12, v26
	v_mul_f32_e32 v38, v2, v28
	v_mul_f32_e32 v28, v13, v29
	v_mul_f32_e32 v26, v20, v32
	v_mul_f32_e32 v29, v20, v40
	v_mul_f32_e32 v32, v20, v33
	v_mul_f32_e32 v29, 0x3fb8aa3b, v29
	v_mul_f32_e32 v32, 0x3fb8aa3b, v32
	v_mul_f32_e32 v25, 0x3fb8aa3b, v25
	v_mul_f32_e32 v30, v20, v39
	v_mul_f32_e32 v26, 0x3fb8aa3b, v26
	v_exp_f32_e32 v29, v29
	v_exp_f32_e32 v32, v32
	v_mul_f32_e32 v33, v20, v41
	v_exp_f32_e32 v22, v22
	v_mul_f32_e32 v23, 0x3fb8aa3b, v23
	v_exp_f32_e32 v25, v25
	v_mul_f32_e32 v30, 0x3fb8aa3b, v30
	v_exp_f32_e32 v26, v26
	v_mul_f32_e32 v33, 0x3fb8aa3b, v33
	v_exp_f32_e32 v23, v23
	v_exp_f32_e32 v30, v30
	v_exp_f32_e32 v33, v33
	v_and_or_b32 v21, v17, s5, v21
	v_mul_f32_e32 v40, v6, v29
	v_mul_f32_e32 v29, v5, v32
	v_mul_lo_u32 v21, v21, s81
	v_mul_f32_e32 v22, v18, v22
	v_mul_f32_e32 v25, v19, v25
	v_mul_f32_e32 v39, v4, v26
	v_cvt_pk_bf16_f32 v26, v22, v25
	v_cvt_pk_bf16_f32 v27, v35, v27
	v_cvt_pk_bf16_f32 v28, v31, v28
	v_cvt_pk_bf16_f32 v29, v39, v29
	v_add3_u32 v0, 0, v21, v0
	v_mul_f32_e32 v23, v10, v23
	v_mul_f32_e32 v30, v3, v30
	v_mul_f32_e32 v32, v7, v33
	ds_write_b128 v0, v[26:29] offset:51200
	v_cvt_pk_bf16_f32 v26, v23, v34
	v_cvt_pk_bf16_f32 v27, v36, v37
	v_cvt_pk_bf16_f32 v28, v38, v30
	v_cvt_pk_bf16_f32 v29, v40, v32
	ds_write_b128 v0, v[26:29] offset:51264
	ds_read_b128 v[26:29], v16 offset:16384
	ds_read_b128 v[30:33], v16 offset:16400
	ds_read_b128 v[34:37], v16 offset:16512
	ds_read_b128 v[38:41], v16 offset:16528
	v_add_u32_e32 v0, 0xc800, v0
	s_lshl_b32 s5, s28, 7
	s_waitcnt lgkmcnt(3)
	v_mul_f32_e32 v21, v20, v26
	s_waitcnt lgkmcnt(1)
	v_mul_f32_e32 v16, v20, v34
	v_mul_f32_e32 v22, v20, v27
	v_mul_f32_e32 v23, v20, v35
	v_mul_f32_e32 v21, 0x3fb8aa3b, v21
	v_mul_f32_e32 v16, 0x3fb8aa3b, v16
	v_mul_f32_e32 v22, 0x3fb8aa3b, v22
	v_mul_f32_e32 v23, 0x3fb8aa3b, v23
	v_exp_f32_e32 v21, v21
	v_exp_f32_e32 v16, v16
	v_exp_f32_e32 v22, v22
	v_exp_f32_e32 v23, v23
	v_mul_f32_e32 v18, v18, v21
	v_mul_f32_e32 v10, v10, v16
	v_mul_f32_e32 v16, v19, v22
	v_mul_f32_e32 v11, v11, v23
	v_mul_f32_e32 v19, v20, v28
	v_mul_f32_e32 v21, v20, v36
	v_mul_f32_e32 v22, v20, v29
	v_mul_f32_e32 v23, v20, v37
	v_mul_f32_e32 v19, 0x3fb8aa3b, v19
	v_mul_f32_e32 v21, 0x3fb8aa3b, v21
	v_mul_f32_e32 v22, 0x3fb8aa3b, v22
	v_mul_f32_e32 v23, 0x3fb8aa3b, v23
	v_exp_f32_e32 v19, v19
	v_exp_f32_e32 v21, v21
	v_exp_f32_e32 v22, v22
	v_exp_f32_e32 v23, v23
	v_mul_f32_e32 v14, v14, v19
	v_mul_f32_e32 v8, v8, v21
	v_mul_f32_e32 v15, v15, v22
	v_mul_f32_e32 v9, v9, v23
	v_mul_f32_e32 v19, v20, v30
	s_waitcnt lgkmcnt(0)
	v_mul_f32_e32 v21, v20, v38
	v_mul_f32_e32 v22, v20, v31
	v_mul_f32_e32 v23, v20, v39
	v_mul_f32_e32 v19, 0x3fb8aa3b, v19
	v_mul_f32_e32 v21, 0x3fb8aa3b, v21
	v_mul_f32_e32 v22, 0x3fb8aa3b, v22
	v_mul_f32_e32 v23, 0x3fb8aa3b, v23
	v_exp_f32_e32 v19, v19
	v_exp_f32_e32 v21, v21
	v_exp_f32_e32 v22, v22
	v_exp_f32_e32 v23, v23
	v_mul_f32_e32 v12, v12, v19
	v_mul_f32_e32 v19, v2, v21
	v_mul_f32_e32 v13, v13, v22
	v_mul_f32_e32 v21, v3, v23
	v_mul_f32_e32 v2, v20, v32
	v_mul_f32_e32 v3, v20, v40
	v_mul_f32_e32 v22, v20, v33
	v_mul_f32_e32 v20, v20, v41
	v_mul_f32_e32 v2, 0x3fb8aa3b, v2
	v_mul_f32_e32 v3, 0x3fb8aa3b, v3
	v_mul_f32_e32 v22, 0x3fb8aa3b, v22
	v_mul_f32_e32 v20, 0x3fb8aa3b, v20
	v_exp_f32_e32 v2, v2
	v_exp_f32_e32 v3, v3
	v_exp_f32_e32 v22, v22
	v_exp_f32_e32 v20, v20
	v_mul_f32_e32 v23, v4, v2
	v_mul_f32_e32 v6, v6, v3
	v_mul_f32_e32 v5, v5, v22
	v_mul_f32_e32 v7, v7, v20
	v_cvt_pk_bf16_f32 v2, v18, v16
	v_cvt_pk_bf16_f32 v3, v14, v15
	v_cvt_pk_bf16_f32 v4, v12, v13
	v_ashrrev_i32_e32 v20, 3, v24
	v_cvt_pk_bf16_f32 v5, v23, v5
	ds_write_b128 v0, v[2:5] offset:18432
	v_cvt_pk_bf16_f32 v2, v10, v11
	v_cvt_pk_bf16_f32 v3, v8, v9
	v_cvt_pk_bf16_f32 v4, v19, v21
	v_ashrrev_i32_e32 v21, 31, v20
	v_cvt_pk_bf16_f32 v5, v6, v7
	ds_write_b128 v0, v[2:5] offset:18496
	v_lshl_add_u64 v[18:19], s[0:1], 0, v[20:21]
	v_mov_b64_e32 v[2:3], s[22:23]
	s_or_b32 s7, s5, 0xe00
	s_add_i32 s24, s5, 0x1200
	v_mad_u64_u32 v[22:23], s[0:1], v18, s79, v[2:3]
	s_and_b64 s[10:11], s[2:3], exec
	v_mov_b32_e32 v0, v23
	s_cselect_b32 s7, s7, s24
	v_mad_u64_u32 v[2:3], s[0:1], v19, s79, v[0:1]
	v_lshlrev_b32_e32 v0, 4, v24
	v_mov_b32_e32 v23, v2
	s_lshl_b32 s24, s7, 1
	v_and_b32_e32 v21, 0x70, v0
	v_lshl_add_u64 v[2:3], v[22:23], 0, s[24:25]
	v_lshlrev_b32_e32 v0, 1, v21
	v_lshl_add_u64 v[6:7], v[2:3], 0, v[0:1]
	global_load_dwordx4 v[2:5], v[6:7], off
	global_load_dwordx4 v[112:115], v[6:7], off offset:16
	v_mul_u32_u24_e32 v8, 0x90, v21
	v_lshlrev_b32_e32 v9, 1, v20
	v_add3_u32 v8, 0, v8, v9
	s_waitcnt vmcnt(0) lgkmcnt(0)
	ds_write_b16 v8, v2 offset:32768
	ds_write_b16_d16_hi v8, v2 offset:32912
	ds_write_b16 v8, v3 offset:33056
	ds_write_b16_d16_hi v8, v3 offset:33200
	ds_write_b16 v8, v4 offset:33344
	ds_write_b16_d16_hi v8, v4 offset:33488
	ds_write_b16 v8, v5 offset:33632
	ds_write_b16_d16_hi v8, v5 offset:33776
	v_ashrrev_i32_e32 v42, 6, v24
	v_and_b32_e32 v44, 1, v42
	v_and_b32_e32 v66, 31, v24
	v_lshlrev_b32_e32 v45, 5, v44
	v_bfe_u32 v25, v24, 5, 1
	ds_write_b16 v8, v112 offset:33920
	ds_write_b16_d16_hi v8, v112 offset:34064
	ds_write_b16 v8, v113 offset:34208
	ds_write_b16_d16_hi v8, v113 offset:34352
	ds_write_b16 v8, v114 offset:34496
	ds_write_b16_d16_hi v8, v114 offset:34640
	ds_write_b16 v8, v115 offset:34784
	ds_write_b16_d16_hi v8, v115 offset:34928
	v_ashrrev_i32_e32 v43, 8, v24
	s_movk_i32 s0, 0x4800
	v_or_b32_e32 v2, v45, v66
	v_mad_i32_i24 v6, v43, s0, 0
	v_mul_u32_u24_e32 v2, 0x90, v2
	v_lshlrev_b32_e32 v24, 4, v25
	v_add3_u32 v34, v6, v2, v24
	s_waitcnt lgkmcnt(0)
	s_barrier
; #define LAS __attribute__((address_space(3)))
; __device__ __forceinline__ unsigned cvt_pk_bf16(float lo, float hi) { unsigned r; asm volatile("v_cvt_pk_bf16_f32 %0, %1, %2" : "=v"(r) : "v"(lo), "v"(hi)); return r; }
; __device__ __forceinline__ void r3_item(const Args& a, int L, int item, LAS unsigned char* lds) {
;     ...
;     { const int dir = wid >> 2, it = (wid >> 1) & 1, jt = wid & 1; f32x16 sc = f32x16{};
;         const LAS bf16_t* Qt = QK + ((dir * 2 + 0) * 64) * PT; const LAS bf16_t* Kt = QK + ((dir * 2 + 1) * 64) * PT;
; #pragma unroll
;         for (int ks = 0; ks < 4; ++ks) { const bf16x8 av = *(const LAS bf16x8*)(Kt + (jt * 32 + r32) * PT + ks * 16 + hi * 8), bv = *(const LAS bf16x8*)(Qt + (it * 32 + r32) * PT + ks * 16 + hi * 8);
;             sc = __builtin_amdgcn_mfma_f32_32x32x16_bf16(av, bv, sc, 0, 0, 0); }
;         const int i = it * 32 + r32;
; #pragma unroll
;         for (int g4 = 0; g4 < 4; ++g4) { float v[4];
; #pragma unroll
;             for (int e = 0; e < 4; ++e) { const int j = jt * 32 + 8 * g4 + 4 * hi + e; const bool keep = dir == 0 ? (j <= i) : (j >= i); v[e] = keep ? sc[g4 * 4 + e] : 0.f; }
;             u32x2 w; w.x = cvt_pk_bf16(v[0], v[1]); w.y = cvt_pk_bf16(v[2], v[3]);
;             *(LAS u32x2*)(P + (dir * 64 + i) * PT + jt * 32 + 8 * g4 + 4 * hi) = w; } }
	ds_read_b128 v[2:5], v34 offset:60416
	v_and_or_b32 v46, v17, 32, v66
	v_mul_u32_u24_e32 v7, 0x90, v46
	v_add3_u32 v38, v6, v7, v24
	ds_read_b128 v[6:9], v38 offset:51200
	ds_read_b128 v[26:29], v34 offset:60448
	ds_read_b128 v[30:33], v38 offset:51232
	s_waitcnt lgkmcnt(2)
	v_mfma_f32_32x32x16_bf16 v[2:17], v[2:5], v[6:9], 0
	v_lshlrev_b32_e32 v67, 2, v25
	v_readlane_b32 s7, v253, 24
	v_and_b32_e32 v68, 3, v42
	s_lshl_b32 s0, s4, 10
	s_or_b32 s0, s5, s0
	v_lshlrev_b32_e32 v69, 5, v43
	s_or_b32 s0, s0, s6
	s_waitcnt lgkmcnt(0)
	v_mfma_f32_32x32x16_bf16 v[2:17], v[26:29], v[30:33], v[2:17]
	ds_read_b128 v[26:29], v34 offset:60480
	ds_read_b128 v[30:33], v38 offset:51264
	ds_read_b128 v[34:37], v34 offset:60512
	ds_read_b128 v[38:41], v38 offset:51296
	s_ashr_i32 s1, s0, 31
	s_movk_i32 s4, 0x210
	s_waitcnt lgkmcnt(2)
	v_mfma_f32_32x32x16_bf16 v[2:17], v[26:29], v[30:33], v[2:17]
	v_lshl_or_b32 v27, v43, 6, v46
	v_lshlrev_b32_e32 v26, 3, v25
	v_or_b32_e32 v25, v45, v67
	v_mul_lo_u32 v27, v27, s81
	v_add_u32_e32 v27, s7, v27
	v_lshlrev_b32_e32 v28, 6, v44
	v_cmp_le_u32_e32 vcc, v25, v46
	s_waitcnt lgkmcnt(0)
	v_mfma_f32_32x32x16_bf16 v[2:17], v[34:37], v[38:41], v[2:17]
	v_add3_u32 v26, v27, v28, v26
	v_cndmask_b32_e64 v27, 0, 1, vcc
	v_cmp_ge_u32_e32 vcc, v25, v46
	s_nop 1
	v_cndmask_b32_e64 v28, 0, 1, vcc
	v_cndmask_b32_e64 v27, v28, v27, s[38:39]
	v_and_b32_e32 v27, 1, v27
	v_cmp_eq_u32_e32 vcc, 1, v27
	v_or_b32_e32 v27, 1, v25
	s_nop 1
	v_cndmask_b32_e32 v2, 0, v2, vcc
	v_cmp_lt_u32_e32 vcc, v25, v46
	s_nop 1
	v_cndmask_b32_e64 v28, 0, 1, vcc
	v_cmp_ge_u32_e32 vcc, v27, v46
	s_nop 1
	v_cndmask_b32_e64 v27, 0, 1, vcc
	v_cndmask_b32_e64 v27, v27, v28, s[38:39]
	v_and_b32_e32 v27, 1, v27
	v_cmp_eq_u32_e32 vcc, 1, v27
	v_or_b32_e32 v27, 2, v25
	s_nop 0
	v_cndmask_b32_e32 v3, 0, v3, vcc
	v_cmp_le_u32_e32 vcc, v27, v46
	v_cvt_pk_bf16_f32 v2, v2, v3
	s_nop 1
	v_cndmask_b32_e64 v28, 0, 1, vcc
	v_cmp_ge_u32_e32 vcc, v27, v46
	s_nop 1
	v_cndmask_b32_e64 v27, 0, 1, vcc
	v_cndmask_b32_e64 v27, v27, v28, s[38:39]
	v_and_b32_e32 v27, 1, v27
	v_cmp_eq_u32_e32 vcc, 1, v27
	v_or_b32_e32 v27, 3, v25
	s_nop 0
	v_cndmask_b32_e32 v4, 0, v4, vcc
	v_cmp_le_u32_e32 vcc, v27, v46
	s_nop 1
	v_cndmask_b32_e64 v28, 0, 1, vcc
	v_cmp_ge_u32_e32 vcc, v27, v46
	s_nop 1
	v_cndmask_b32_e64 v27, 0, 1, vcc
	v_cndmask_b32_e64 v27, v27, v28, s[38:39]
	v_and_b32_e32 v27, 1, v27
	v_cmp_eq_u32_e32 vcc, 1, v27
	s_nop 1
	v_cndmask_b32_e32 v5, 0, v5, vcc
	v_cvt_pk_bf16_f32 v3, v4, v5
	ds_write_b64 v26, v[2:3]
	v_or_b32_e32 v2, 8, v25
	v_cmp_le_u32_e32 vcc, v2, v46
	s_nop 1
	v_cndmask_b32_e64 v3, 0, 1, vcc
	v_cmp_ge_u32_e32 vcc, v2, v46
	s_nop 1
	v_cndmask_b32_e64 v2, 0, 1, vcc
	v_cndmask_b32_e64 v2, v2, v3, s[38:39]
	v_and_b32_e32 v2, 1, v2
	v_cmp_eq_u32_e32 vcc, 1, v2
	v_or_b32_e32 v3, 9, v25
	s_nop 0
	v_cndmask_b32_e32 v2, 0, v6, vcc
	v_cmp_le_u32_e32 vcc, v3, v46
	s_nop 1
	v_cndmask_b32_e64 v4, 0, 1, vcc
	v_cmp_ge_u32_e32 vcc, v3, v46
	s_nop 1
	v_cndmask_b32_e64 v3, 0, 1, vcc
	v_cndmask_b32_e64 v3, v3, v4, s[38:39]
	v_and_b32_e32 v3, 1, v3
	v_cmp_eq_u32_e32 vcc, 1, v3
	v_or_b32_e32 v4, 10, v25
	s_nop 0
	v_cndmask_b32_e32 v3, 0, v7, vcc
	v_cmp_le_u32_e32 vcc, v4, v46
	v_cvt_pk_bf16_f32 v2, v2, v3
	s_nop 1
	v_cndmask_b32_e64 v5, 0, 1, vcc
	v_cmp_ge_u32_e32 vcc, v4, v46
	s_nop 1
	v_cndmask_b32_e64 v4, 0, 1, vcc
	v_cndmask_b32_e64 v4, v4, v5, s[38:39]
	v_and_b32_e32 v4, 1, v4
	v_cmp_eq_u32_e32 vcc, 1, v4
	v_or_b32_e32 v5, 11, v25
	s_nop 0
	v_cndmask_b32_e32 v4, 0, v8, vcc
	v_cmp_le_u32_e32 vcc, v5, v46
	s_nop 1
	v_cndmask_b32_e64 v6, 0, 1, vcc
	v_cmp_ge_u32_e32 vcc, v5, v46
	s_nop 1
	v_cndmask_b32_e64 v5, 0, 1, vcc
	v_cndmask_b32_e64 v5, v5, v6, s[38:39]
	v_and_b32_e32 v5, 1, v5
	v_cmp_eq_u32_e32 vcc, 1, v5
	s_nop 1
	v_cndmask_b32_e32 v5, 0, v9, vcc
	v_cvt_pk_bf16_f32 v3, v4, v5
	ds_write_b64 v26, v[2:3] offset:16
	v_or_b32_e32 v2, 16, v25
	v_cmp_le_u32_e32 vcc, v2, v46
	s_nop 1
	v_cndmask_b32_e64 v3, 0, 1, vcc
	v_cmp_ge_u32_e32 vcc, v2, v46
	s_nop 1
	v_cndmask_b32_e64 v2, 0, 1, vcc
	v_cndmask_b32_e64 v2, v2, v3, s[38:39]
	v_and_b32_e32 v2, 1, v2
	v_cmp_eq_u32_e32 vcc, 1, v2
	v_or_b32_e32 v3, 17, v25
	s_nop 0
	v_cndmask_b32_e32 v2, 0, v10, vcc
	v_cmp_le_u32_e32 vcc, v3, v46
	s_nop 1
	v_cndmask_b32_e64 v4, 0, 1, vcc
	v_cmp_ge_u32_e32 vcc, v3, v46
	s_nop 1
	v_cndmask_b32_e64 v3, 0, 1, vcc
	v_cndmask_b32_e64 v3, v3, v4, s[38:39]
	v_and_b32_e32 v3, 1, v3
	v_cmp_eq_u32_e32 vcc, 1, v3
	v_or_b32_e32 v4, 18, v25
	s_nop 0
	v_cndmask_b32_e32 v3, 0, v11, vcc
	v_cmp_le_u32_e32 vcc, v4, v46
	v_cvt_pk_bf16_f32 v2, v2, v3
	s_nop 1
	v_cndmask_b32_e64 v5, 0, 1, vcc
	v_cmp_ge_u32_e32 vcc, v4, v46
	s_nop 1
	v_cndmask_b32_e64 v4, 0, 1, vcc
	v_cndmask_b32_e64 v4, v4, v5, s[38:39]
	v_and_b32_e32 v4, 1, v4
	v_cmp_eq_u32_e32 vcc, 1, v4
	v_or_b32_e32 v5, 19, v25
	s_nop 0
	v_cndmask_b32_e32 v4, 0, v12, vcc
	v_cmp_le_u32_e32 vcc, v5, v46
	s_nop 1
	v_cndmask_b32_e64 v6, 0, 1, vcc
	v_cmp_ge_u32_e32 vcc, v5, v46
	s_nop 1
	v_cndmask_b32_e64 v5, 0, 1, vcc
	v_cndmask_b32_e64 v5, v5, v6, s[38:39]
	v_and_b32_e32 v5, 1, v5
	v_cmp_eq_u32_e32 vcc, 1, v5
	s_nop 1
	v_cndmask_b32_e32 v5, 0, v13, vcc
	v_cvt_pk_bf16_f32 v3, v4, v5
	ds_write_b64 v26, v[2:3] offset:32
	v_or_b32_e32 v2, 24, v25
	v_cmp_le_u32_e32 vcc, v2, v46
	s_nop 1
	v_cndmask_b32_e64 v3, 0, 1, vcc
	v_cmp_ge_u32_e32 vcc, v2, v46
	s_nop 1
	v_cndmask_b32_e64 v2, 0, 1, vcc
	v_cndmask_b32_e64 v2, v2, v3, s[38:39]
	v_and_b32_e32 v2, 1, v2
	v_cmp_eq_u32_e32 vcc, 1, v2
	v_or_b32_e32 v3, 25, v25
	s_nop 0
	v_cndmask_b32_e32 v2, 0, v14, vcc
	v_cmp_le_u32_e32 vcc, v3, v46
	s_nop 1
	v_cndmask_b32_e64 v4, 0, 1, vcc
	v_cmp_ge_u32_e32 vcc, v3, v46
	s_nop 1
; #define LAS __attribute__((address_space(3)))
; __device__ __forceinline__ unsigned cvt_pk_bf16(float lo, float hi) { unsigned r; asm volatile("v_cvt_pk_bf16_f32 %0, %1, %2" : "=v"(r) : "v"(lo), "v"(hi)); return r; }
; __device__ __forceinline__ int crow(int r, int hi) { return (r & 3) + 8 * (r >> 2) + 4 * hi; }
; __device__ __forceinline__ int crow(int r, int hi) { return (r & 3) + 8 * (r >> 2) + 4 * hi; }
; __device__ __forceinline__ int seqidx(int b, int hl, int dir, int c) { return ((b * 8 + hl) * 2 + dir) * 64 + c; }
; __device__ __forceinline__ void r3_item(const Args& a, int L, int item, LAS unsigned char* lds) {
;     ...
;         for (int g4 = 0; g4 < 4; ++g4) { float v[4];
; #pragma unroll
;             for (int e = 0; e < 4; ++e) { const int j = jt * 32 + 8 * g4 + 4 * hi + e; const bool keep = dir == 0 ? (j <= i) : (j >= i); v[e] = keep ? sc[g4 * 4 + e] : 0.f; }
;             u32x2 w; w.x = cvt_pk_bf16(v[0], v[1]); w.y = cvt_pk_bf16(v[2], v[3]);
;             *(LAS u32x2*)(P + (dir * 64 + i) * PT + jt * 32 + 8 * g4 + 4 * hi) = w; } }
;     __syncthreads();
;     { const int it = wid >> 2, vt = wid & 3; f32x16 acc = f32x16{};
;         bf16x8 stf[2][4];
; #pragma unroll
;         for (int dir = 0; dir < 2; ++dir) { const bf16_t* stp = (const bf16_t*)(a.ws + WS_ST) + (size_t)seqidx(b, hl, dir, c) * 8192 + (vt * 32 + r32) * 64 + hi * 8;
; #pragma unroll
;             for (int ks = 0; ks < 4; ++ks) stf[dir][ks] = *(const bf16x8*)(stp + ks * 16); }
; #pragma unroll
;         for (int dir = 0; dir < 2; ++dir) { const LAS bf16_t* Qt = QK + ((dir * 2 + 0) * 64) * PT;
; #pragma unroll
;             for (int ks = 0; ks < 4; ++ks) { const bf16x8 av = *(const LAS bf16x8*)(P + (dir * 64 + it * 32 + r32) * PT + ks * 16 + hi * 8), bv = *(const LAS bf16x8*)(VT + (vt * 32 + r32) * PT + ks * 16 + hi * 8);
;                 acc = __builtin_amdgcn_mfma_f32_32x32x16_bf16(av, bv, acc, 0, 0, 0); }
; #pragma unroll
;             for (int ks = 0; ks < 4; ++ks) { const bf16x8 av = *(const LAS bf16x8*)(Qt + (it * 32 + r32) * PT + ks * 16 + hi * 8), bv = stf[dir][ks];
;                 acc = __builtin_amdgcn_mfma_f32_32x32x16_bf16(av, bv, acc, 0, 0, 0); } }
;         __syncthreads();
;         LAS float* OL = (LAS float*)(lds + L_OL);
; #pragma unroll
;         for (int r = 0; r < 16; ++r) OL[(it * 32 + crow(r, hi)) * OLP + vt * 32 + r32] = acc[r]; }
	v_cndmask_b32_e64 v3, 0, 1, vcc
	v_cndmask_b32_e64 v3, v3, v4, s[38:39]
	v_and_b32_e32 v3, 1, v3
	v_cmp_eq_u32_e32 vcc, 1, v3
	v_or_b32_e32 v4, 26, v25
	s_nop 0
	v_cndmask_b32_e32 v3, 0, v15, vcc
	v_cmp_le_u32_e32 vcc, v4, v46
	v_cvt_pk_bf16_f32 v2, v2, v3
	s_nop 1
	v_cndmask_b32_e64 v5, 0, 1, vcc
	v_cmp_ge_u32_e32 vcc, v4, v46
	s_nop 1
	v_cndmask_b32_e64 v4, 0, 1, vcc
	v_cndmask_b32_e64 v4, v4, v5, s[38:39]
	v_and_b32_e32 v4, 1, v4
	v_cmp_eq_u32_e32 vcc, 1, v4
	v_or_b32_e32 v5, 27, v25
	v_mov_b32_e32 v25, v1
	v_cndmask_b32_e32 v4, 0, v16, vcc
	v_cmp_le_u32_e32 vcc, v5, v46
	s_nop 1
	v_cndmask_b32_e64 v6, 0, 1, vcc
	v_cmp_ge_u32_e32 vcc, v5, v46
	s_nop 1
	v_cndmask_b32_e64 v5, 0, 1, vcc
	v_cndmask_b32_e64 v5, v5, v6, s[38:39]
	v_and_b32_e32 v5, 1, v5
	v_cmp_eq_u32_e32 vcc, 1, v5
	v_lshl_or_b32 v6, v68, 5, v66
	v_mul_u32_u24_e32 v6, 0x90, v6
	v_cndmask_b32_e32 v5, 0, v17, vcc
	v_cvt_pk_bf16_f32 v3, v4, v5
	ds_write_b64 v26, v[2:3] offset:48
	v_lshlrev_b32_e32 v2, 7, v66
	v_lshl_or_b32 v2, v68, 12, v2
	v_mov_b32_e32 v3, v1
	v_lshl_add_u64 v[2:3], s[8:9], 0, v[2:3]
	v_lshl_add_u64 v[62:63], v[2:3], 0, v[24:25]
	v_or_b32_e32 v2, v69, v66
	v_mul_lo_u32 v25, v2, s81
	v_add3_u32 v70, s7, v24, v25
	s_lshl_b64 s[6:7], s[0:1], 14
	v_add3_u32 v50, 0, v6, v24
	v_lshl_add_u64 v[64:65], v[62:63], 0, s[6:7]
	s_or_b32 s100, s0, 64
	s_ashr_i32 s101, s100, 31
	s_lshl_b64 s[100:101], s[100:101], 14
	v_lshl_add_u64 v[104:105], v[62:63], 0, s[100:101]
	global_load_dwordx4 v[72:75], v[64:65], off
	global_load_dwordx4 v[76:79], v[64:65], off offset:32
	global_load_dwordx4 v[80:83], v[64:65], off offset:64
	global_load_dwordx4 v[84:87], v[64:65], off offset:96
	global_load_dwordx4 v[88:91], v[104:105], off
	global_load_dwordx4 v[92:95], v[104:105], off offset:32
	global_load_dwordx4 v[96:99], v[104:105], off offset:64
	global_load_dwordx4 v[100:103], v[104:105], off offset:96
	s_waitcnt lgkmcnt(0)
	s_barrier
	ds_read_b128 v[2:5], v70
	ds_read_b128 v[26:29], v50 offset:32768
	ds_read_b128 v[30:33], v70 offset:32
	ds_read_b128 v[34:37], v50 offset:32800
	s_waitcnt lgkmcnt(0)
	v_mfma_f32_32x32x16_bf16 v[2:17], v[2:5], v[26:29], 0
	v_add3_u32 v71, 0, v25, v24
	s_or_b32 s0, s0, 64
	s_ashr_i32 s1, s0, 31
	s_lshl_b64 s[0:1], s[0:1], 14
	v_mfma_f32_32x32x16_bf16 v[2:17], v[30:33], v[34:37], v[2:17]
	ds_read_b128 v[30:33], v70 offset:64
	ds_read_b128 v[42:45], v50 offset:32832
	ds_read_b128 v[46:49], v70 offset:96
	ds_read_b128 v[50:53], v50 offset:32864
	ds_read_b128 v[54:57], v71 offset:51200
	ds_read_b128 v[58:61], v71 offset:51232
	s_waitcnt lgkmcnt(0)
	v_mfma_f32_32x32x16_bf16 v[2:17], v[30:33], v[42:45], v[2:17]
	v_mfma_f32_32x32x16_bf16 v[2:17], v[46:49], v[50:53], v[2:17]
	s_waitcnt vmcnt(0)
	v_mfma_f32_32x32x16_bf16 v[2:17], v[54:57], v[72:75], v[2:17]
	s_waitcnt lgkmcnt(0)
	v_mfma_f32_32x32x16_bf16 v[2:17], v[58:61], v[76:79], v[2:17]
	ds_read_b128 v[30:33], v71 offset:51264
	ds_read_b128 v[54:57], v71 offset:51296
	s_waitcnt lgkmcnt(0)
	v_mfma_f32_32x32x16_bf16 v[2:17], v[30:33], v[80:83], v[2:17]
	ds_read_b128 v[30:33], v70 offset:9216
	v_lshl_add_u64 v[46:47], v[62:63], 0, s[0:1]
	s_and_b64 s[0:1], s[2:3], exec
	s_movk_i32 s0, 0x1400
	s_cselect_b32 s0, 0x1000, s0
	s_or_b32 s0, s0, s5
	s_waitcnt vmcnt(0)
	v_mfma_f32_32x32x16_bf16 v[2:17], v[54:57], v[84:87], v[2:17]
	ds_read_b128 v[38:41], v70 offset:9248
	s_waitcnt lgkmcnt(1)
	v_mfma_f32_32x32x16_bf16 v[2:17], v[30:33], v[26:29], v[2:17]
	s_waitcnt lgkmcnt(0)
	v_mfma_f32_32x32x16_bf16 v[2:17], v[38:41], v[34:37], v[2:17]
	ds_read_b128 v[28:31], v70 offset:9280
	ds_read_b128 v[32:35], v70 offset:9312
	s_waitcnt lgkmcnt(0)
	v_mfma_f32_32x32x16_bf16 v[2:17], v[28:31], v[42:45], v[2:17]
	v_add_u32_e32 v44, 0xc800, v71
	ds_read_b128 v[36:39], v44 offset:18432
	ds_read_b128 v[40:43], v44 offset:18464
	v_mfma_f32_32x32x16_bf16 v[2:17], v[32:35], v[50:53], v[2:17]
	s_waitcnt vmcnt(0) lgkmcnt(0)
	v_mfma_f32_32x32x16_bf16 v[2:17], v[36:39], v[88:91], v[2:17]
	v_mfma_f32_32x32x16_bf16 v[2:17], v[40:43], v[92:95], v[2:17]
	ds_read_b128 v[28:31], v44 offset:18496
	ds_read_b128 v[36:39], v44 offset:18528
	s_waitcnt lgkmcnt(0)
	s_barrier
	v_mfma_f32_32x32x16_bf16 v[2:17], v[28:31], v[96:99], v[2:17]
	s_waitcnt vmcnt(0)
	v_mfma_f32_32x32x16_bf16 v[2:17], v[36:39], v[100:103], v[2:17]
	v_or_b32_e32 v24, v67, v69
	v_lshl_add_u32 v25, v68, 7, 0
	v_lshlrev_b32_e32 v26, 2, v66
	v_mul_lo_u32 v24, v24, s4
	v_add3_u32 v24, v25, v26, v24
	v_add_u32_e32 v25, 0xc800, v24
	s_nop 5
	ds_write2_b32 v25, v2, v3 offset1:132
	v_add_u32_e32 v2, 0xcc00, v24
	ds_write2_b32 v2, v4, v5 offset0:8 offset1:140
	v_add_u32_e32 v2, 0xd800, v24
	ds_write2_b32 v2, v6, v7 offset0:32 offset1:164
	v_add_u32_e32 v2, 0xdc00, v24
	ds_write2_b32 v2, v8, v9 offset0:40 offset1:172
	v_add_u32_e32 v2, 0xe800, v24
	ds_write2_b32 v2, v10, v11 offset0:64 offset1:196
	v_add_u32_e32 v2, 0xec00, v24
	ds_write2_b32 v2, v12, v13 offset0:72 offset1:204
	v_add_u32_e32 v2, 0xf800, v24
	ds_write2_b32 v2, v14, v15 offset0:96 offset1:228
	v_add_u32_e32 v2, 0xfc00, v24
	ds_write2_b32 v2, v16, v17 offset0:104 offset1:236
	v_or_b32_e32 v2, s0, v21
	v_lshlrev_b32_e32 v2, 1, v2
	v_mov_b32_e32 v3, v1
	v_lshl_add_u64 v[2:3], v[22:23], 0, v[2:3]
	s_waitcnt lgkmcnt(0)
	s_barrier
; #define LAS __attribute__((address_space(3)))
; __device__ __forceinline__ float siluf(float x) { return x * __builtin_amdgcn_rcpf(1.f + __expf(-x)); }
; __device__ __forceinline__ void r3_item(const Args& a, int L, int item, LAS unsigned char* lds) {
;     ...
;     { const int row = tid >> 3, seg = tid & 7; const LAS float* op = (const LAS float*)(lds + L_OL) + row * OLP + seg * 16; float ov[16]; float s = 0.f;
; #pragma unroll
;         for (int e = 0; e < 16; ++e) { ov[e] = op[e]; s += ov[e] * ov[e]; }
;         s += __shfl_xor(s, 1); s += __shfl_xor(s, 2); s += __shfl_xor(s, 4);
;         const float rs = rsqrtf(s * (1.0f / 128.0f) + EPS);
;         const int gcol = (hl < 4 ? GR + hl * 128 : RG + (hl - 4) * 128) + seg * 16;
;         const bf16_t* gp = proj + (R0 + row) * LD + gcol; const u32x4 g0 = *(const u32x4*)gp, g1 = *(const u32x4*)(gp + 8);
;         float gt[16] = {bflo(g0.x), bfhi(g0.x), bflo(g0.y), bfhi(g0.y), bflo(g0.z), bfhi(g0.z), bflo(g0.w), bfhi(g0.w), bflo(g1.x), bfhi(g1.x), bflo(g1.y), bfhi(g1.y), bflo(g1.z), bfhi(g1.z), bflo(g1.w), bfhi(g1.w)};
;         const float* hg = a.head_gain + (size_t)L * D + 1024 + hl * 128 + seg * 16;
;         float res[16];
; #pragma unroll
;         for (int e = 0; e < 16; ++e) res[e] = ov[e] * rs * hg[e] * siluf(gt[e]);
	global_load_dwordx4 v[22:25], v[2:3], off
	s_lshl_b32 s0, s28, 9
	s_add_u32 s0, s12, s0
	v_mul_lo_u32 v4, v20, s4
	v_lshlrev_b32_e32 v20, 2, v21
	s_addc_u32 s1, s13, 0
	v_mov_b32_e32 v21, v1
	v_add3_u32 v4, 0, v4, v20
	v_lshl_add_u64 v[38:39], s[0:1], 0, v[20:21]
	ds_read_b128 v[14:17], v4 offset:51200
	ds_read_b128 v[10:13], v4 offset:51216
	global_load_dwordx4 v[26:29], v[2:3], off offset:16
	ds_read_b128 v[6:9], v4 offset:51232
	ds_read_b128 v[2:5], v4 offset:51248
	global_load_dwordx4 v[30:33], v[38:39], off
	s_waitcnt lgkmcnt(0)
	v_mul_f32_e32 v34, v15, v15
	v_fmac_f32_e32 v34, v14, v14
	v_fmac_f32_e32 v34, v16, v16
	v_fmac_f32_e32 v34, v17, v17
	v_fmac_f32_e32 v34, v10, v10
	v_fmac_f32_e32 v34, v11, v11
	v_fmac_f32_e32 v34, v12, v12
	v_fmac_f32_e32 v34, v13, v13
	v_pk_mul_f32 v[20:21], v[6:7], v[6:7]
	s_lshl_b32 s24, s28, 8
	v_add_f32_e32 v20, v34, v20
	v_add_f32_e32 v34, v20, v21
	v_pk_mul_f32 v[20:21], v[8:9], v[8:9]
	s_mov_b64 s[0:1], 0x21300800
	v_add_f32_e32 v20, v34, v20
	v_add_f32_e32 v34, v20, v21
	v_pk_mul_f32 v[20:21], v[2:3], v[2:3]
	s_add_i32 s15, s15, s87
	v_add_f32_e32 v20, v34, v20
	v_add_f32_e32 v34, v20, v21
	v_pk_mul_f32 v[20:21], v[4:5], v[4:5]
	s_add_i32 s14, s14, s87
	v_add_f32_e32 v20, v34, v20
	v_and_b32_e32 v34, 64, v208
	v_add_f32_e32 v20, v20, v21
	v_xor_b32_e32 v21, 1, v208
	v_add_u32_e32 v40, 64, v34
	v_cmp_lt_i32_e32 vcc, v21, v40
	global_load_dwordx4 v[34:37], v[38:39], off offset:16
	s_cmpk_gt_i32 s15, 0x3ff
	v_cndmask_b32_e32 v21, v208, v21, vcc
	v_lshlrev_b32_e32 v21, 2, v21
	ds_bpermute_b32 v21, v21, v20
	s_waitcnt lgkmcnt(0)
	v_add_f32_e32 v20, v20, v21
	v_xor_b32_e32 v21, 2, v208
	v_cmp_lt_i32_e32 vcc, v21, v40
	s_waitcnt vmcnt(0)
	v_and_b32_e32 v42, 0xffff0000, v22
	v_cndmask_b32_e32 v21, v208, v21, vcc
	v_lshlrev_b32_e32 v21, 2, v21
	ds_bpermute_b32 v21, v21, v20
	v_lshlrev_b32_e32 v44, 16, v23
	v_and_b32_e32 v46, 0xffff0000, v23
	v_lshlrev_b32_e32 v48, 16, v24
	v_and_b32_e32 v50, 0xffff0000, v24
	s_waitcnt lgkmcnt(0)
	v_add_f32_e32 v20, v20, v21
	v_xor_b32_e32 v21, 4, v208
	v_cmp_lt_i32_e32 vcc, v21, v40
	v_lshlrev_b32_e32 v40, 16, v22
	v_mul_f32_e32 v24, 0xbfb8aa3b, v40
	v_cndmask_b32_e32 v21, v208, v21, vcc
	v_lshlrev_b32_e32 v21, 2, v21
	ds_bpermute_b32 v21, v21, v20
	v_exp_f32_e32 v24, v24
	v_lshlrev_b32_e32 v52, 16, v25
	v_and_b32_e32 v54, 0xffff0000, v25
	v_mov_b32_e32 v25, v30
	s_waitcnt lgkmcnt(0)
	v_add_f32_e32 v20, v20, v21
	v_fmamk_f32 v20, v20, 0x3c000000, v207
	v_mul_f32_e32 v21, 0x4b800000, v20
	v_cmp_gt_f32_e32 vcc, s34, v20
	v_lshlrev_b32_e32 v56, 16, v26
	v_and_b32_e32 v58, 0xffff0000, v26
	v_cndmask_b32_e32 v20, v20, v21, vcc
	v_rsq_f32_e32 v20, v20
	v_lshlrev_b32_e32 v60, 16, v27
	v_and_b32_e32 v62, 0xffff0000, v27
	v_lshlrev_b32_e32 v64, 16, v28
	v_mul_f32_e32 v21, 0x45800000, v20
	v_cndmask_b32_e32 v69, v20, v21, vcc
	global_load_dwordx4 v[20:23], v[38:39], off offset:32
	v_mul_f32_e32 v41, v14, v69
	v_add_f32_e32 v14, 1.0, v24
	v_rcp_f32_e32 v24, v14
	v_mul_f32_e32 v14, 0xbfb8aa3b, v42
	v_exp_f32_e32 v14, v14
	v_mul_f32_e32 v43, v15, v69
	v_pk_mul_f32 v[24:25], v[24:25], v[40:41]
	v_mul_f32_e32 v45, v16, v69
	v_add_f32_e32 v14, 1.0, v14
	v_rcp_f32_e32 v30, v14
	v_mul_f32_e32 v14, 0xbfb8aa3b, v44
	v_mul_f32_e32 v40, v24, v25
	v_exp_f32_e32 v24, v14
	v_pk_mul_f32 v[14:15], v[30:31], v[42:43]
	v_mul_f32_e32 v47, v17, v69
	v_mul_f32_e32 v30, v14, v15
	v_add_f32_e32 v14, 1.0, v24
	global_load_dwordx4 v[24:27], v[38:39], off offset:48
	v_rcp_f32_e32 v14, v14
	v_mul_f32_e32 v15, 0xbfb8aa3b, v46
	v_exp_f32_e32 v16, v15
	v_mov_b32_e32 v15, v32
	v_pk_mul_f32 v[14:15], v[14:15], v[44:45]
	v_mul_f32_e32 v49, v10, v69
	v_mul_f32_e32 v31, v14, v15
	v_add_f32_e32 v14, 1.0, v16
	v_rcp_f32_e32 v32, v14
	v_mul_f32_e32 v14, 0xbfb8aa3b, v48
	v_exp_f32_e32 v16, v14
	v_mul_f32_e32 v51, v11, v69
	v_pk_mul_f32 v[14:15], v[32:33], v[46:47]
	v_mul_f32_e32 v53, v12, v69
	v_add_f32_e32 v10, 1.0, v16
	v_mul_f32_e32 v17, v14, v15
	v_rcp_f32_e32 v14, v10
	v_mul_f32_e32 v10, 0xbfb8aa3b, v50
	v_exp_f32_e32 v10, v10
	v_mov_b32_e32 v15, v34
	v_pk_mul_f32 v[14:15], v[14:15], v[48:49]
	v_mul_f32_e32 v12, 0xbfb8aa3b, v54
	v_add_f32_e32 v10, 1.0, v10
	v_rcp_f32_e32 v34, v10
	v_mul_f32_e32 v10, 0xbfb8aa3b, v52
	v_mul_f32_e32 v14, v14, v15
	v_exp_f32_e32 v15, v10
	v_pk_mul_f32 v[10:11], v[34:35], v[50:51]
	v_exp_f32_e32 v12, v12
	v_mul_f32_e32 v16, v10, v11
	v_add_f32_e32 v10, 1.0, v15
	v_rcp_f32_e32 v10, v10
	v_mov_b32_e32 v11, v36
	v_mov_b32_e32 v55, v37
	v_mul_f32_e32 v7, v7, v69
	v_pk_mul_f32 v[10:11], v[10:11], v[52:53]
	v_and_b32_e32 v28, 0xffff0000, v28
	v_mul_f32_e32 v15, v10, v11
	v_add_f32_e32 v10, 1.0, v12
	v_rcp_f32_e32 v10, v10
	v_mul_f32_e32 v12, 0xbfb8aa3b, v56
	v_exp_f32_e32 v12, v12
	v_mul_f32_e32 v11, v13, v69
	v_pk_mul_f32 v[10:11], v[10:11], v[54:55]
	v_lshlrev_b32_e32 v66, 16, v29
	v_mul_f32_e32 v32, v10, v11
	v_mul_f32_e32 v11, v6, v69
	v_add_f32_e32 v6, 1.0, v12
	v_rcp_f32_e32 v10, v6
	v_mul_f32_e32 v6, 0xbfb8aa3b, v58
	v_exp_f32_e32 v6, v6
	v_and_b32_e32 v68, 0xffff0000, v29
	v_mul_f32_e32 v3, v3, v69
	v_mul_f32_e32 v5, v5, v69
	v_add_f32_e32 v6, 1.0, v6
	v_rcp_f32_e32 v6, v6
	s_waitcnt vmcnt(0) lgkmcnt(0)
; __device__ __forceinline__ unsigned cvt_pk_bf16(float lo, float hi) { unsigned r; asm volatile("v_cvt_pk_bf16_f32 %0, %1, %2" : "=v"(r) : "v"(lo), "v"(hi)); return r; }
; __device__ __forceinline__ float logsigmoidf(float x) { return fminf(x, 0.f) - __logf(1.f + __expf(-fabsf(x))); }
; __device__ __forceinline__ float siluf(float x) { return x * __builtin_amdgcn_rcpf(1.f + __expf(-x)); }
; __device__ __forceinline__ void build_cum(const Args& a, int L, int hl, long R0, const bf16_t* __restrict__ proj, LAS unsigned char* lds) {
;     ...
;     } else {
;         const float lg = logsigmoidf(a.decay_logit[(L * 2 + dir) * 4 + (hl - 4)]);
; #pragma unroll 4
;         for (int it = 0; it < 16; ++it) cum[(dir * 64 + isub + 4 * it) * 64 + k] = lg;
; __device__ __forceinline__ void r3_item(const Args& a, int L, int item, LAS unsigned char* lds) {
;     ...
;         for (int e = 0; e < 16; ++e) res[e] = ov[e] * rs * hg[e] * siluf(gt[e]);
;         bf16_t* mp = (bf16_t*)(a.ws + WS_MRG) + (R0 + row) * D + 1024 + hl * 128 + seg * 16;
;         u32x4 w0, w1; w0.x = cvt_pk_bf16(res[0], res[1]); w0.y = cvt_pk_bf16(res[2], res[3]); w0.z = cvt_pk_bf16(res[4], res[5]); w0.w = cvt_pk_bf16(res[6], res[7]);
;         w1.x = cvt_pk_bf16(res[8], res[9]); w1.y = cvt_pk_bf16(res[10], res[11]); w1.z = cvt_pk_bf16(res[12], res[13]); w1.w = cvt_pk_bf16(res[14], res[15]);
;         *(u32x4*)mp = w0; *(u32x4*)(mp + 8) = w1; }
	v_mov_b32_e32 v57, v20
	v_pk_mul_f32 v[10:11], v[10:11], v[56:57]
	v_mov_b32_e32 v59, v21
	v_mul_f32_e32 v20, v10, v11
	v_mul_f32_e32 v10, 0xbfb8aa3b, v60
	v_exp_f32_e32 v10, v10
	v_pk_mul_f32 v[6:7], v[6:7], v[58:59]
	v_mov_b32_e32 v61, v22
	v_mul_f32_e32 v21, v6, v7
	v_add_f32_e32 v6, 1.0, v10
	v_mul_f32_e32 v7, v8, v69
	v_rcp_f32_e32 v6, v6
	v_mul_f32_e32 v8, 0xbfb8aa3b, v62
	v_exp_f32_e32 v8, v8
	v_mov_b32_e32 v63, v23
	v_pk_mul_f32 v[6:7], v[6:7], v[60:61]
	v_mov_b32_e32 v65, v24
	v_mul_f32_e32 v22, v6, v7
	v_add_f32_e32 v6, 1.0, v8
	v_rcp_f32_e32 v6, v6
	v_mul_f32_e32 v8, 0xbfb8aa3b, v64
	v_exp_f32_e32 v8, v8
	v_mul_f32_e32 v7, v9, v69
	v_pk_mul_f32 v[6:7], v[6:7], v[62:63]
	v_mov_b32_e32 v29, v25
	v_mul_f32_e32 v9, v6, v7
	v_mul_f32_e32 v7, v2, v69
	v_add_f32_e32 v2, 1.0, v8
	v_rcp_f32_e32 v6, v2
	v_mul_f32_e32 v2, 0xbfb8aa3b, v28
	v_exp_f32_e32 v2, v2
	v_mov_b32_e32 v67, v26
	v_pk_mul_f32 v[6:7], v[6:7], v[64:65]
	v_add_f32_e32 v2, 1.0, v2
	v_rcp_f32_e32 v2, v2
	v_mul_f32_e32 v8, v6, v7
	v_mul_f32_e32 v6, 0xbfb8aa3b, v66
	v_exp_f32_e32 v6, v6
	v_pk_mul_f32 v[2:3], v[2:3], v[28:29]
	s_nop 0
	v_mul_f32_e32 v23, v2, v3
	v_mul_f32_e32 v3, 0xbfb8aa3b, v68
	v_add_f32_e32 v2, 1.0, v6
	v_exp_f32_e32 v6, v3
	v_rcp_f32_e32 v2, v2
	v_mul_f32_e32 v3, v4, v69
	v_mov_b32_e32 v69, v27
	v_add_f32_e32 v4, 1.0, v6
	v_rcp_f32_e32 v4, v4
	v_pk_mul_f32 v[2:3], v[2:3], v[66:67]
	s_nop 0
	v_mul_f32_e32 v24, v2, v3
	v_pk_mul_f32 v[2:3], v[4:5], v[68:69]
	s_nop 0
	v_mul_f32_e32 v25, v2, v3
	v_lshlrev_b64 v[2:3], 12, v[18:19]
	v_lshl_add_u64 v[2:3], s[98:99], 0, v[2:3]
	v_lshl_add_u64 v[2:3], v[2:3], 0, s[24:25]
	v_lshl_add_u64 v[10:11], v[2:3], 0, v[0:1]
	v_lshl_add_u64 v[12:13], v[10:11], 0, s[0:1]
	v_add_co_u32_e32 v10, vcc, 0x21300000, v10
	v_cvt_pk_bf16_f32 v2, v40, v30
	v_cvt_pk_bf16_f32 v3, v31, v17
	v_cvt_pk_bf16_f32 v4, v14, v16
	v_cvt_pk_bf16_f32 v5, v15, v32
	s_nop 1
	v_addc_co_u32_e32 v11, vcc, 0, v11, vcc
	v_cvt_pk_bf16_f32 v6, v20, v21
	v_cvt_pk_bf16_f32 v7, v22, v9
	v_cvt_pk_bf16_f32 v8, v8, v23
	v_cvt_pk_bf16_f32 v9, v24, v25
	global_store_dwordx4 v[10:11], v[2:5], off offset:2048
	global_store_dwordx4 v[12:13], v[6:9], off offset:16
	s_cbranch_scc1 .LBB0_144
.LBB0_117:
	s_bfe_u32 s28, s15, 0x30006
	s_cmp_lt_u32 s28, 4
	v_mov_b32_e32 v24, v206
	v_mov_b32_e32 v20, v206
	s_cselect_b64 s[2:3], -1, 0
	s_cmp_gt_u32 s28, 3
	s_waitcnt lgkmcnt(0)
	s_barrier
	s_cselect_b64 s[6:7], -1, 0
	v_and_b32_e32 v21, 63, v20
	v_ashrrev_i32_e32 v18, 7, v20
	v_bfe_u32 v19, v20, 6, 1
	s_mov_b64 s[0:1], -1
	s_and_b64 vcc, exec, s[6:7]
	v_lshlrev_b32_e32 v23, 8, v18
	v_lshlrev_b32_e32 v0, 2, v21
	s_cbranch_vccz .LBB0_121
	v_readlane_b32 s0, v254, 42
	s_add_i32 s0, s0, s28
	s_mov_b32 s1, 1
	v_lshl_add_u32 v2, v19, 2, s0
	v_ashrrev_i32_e32 v3, 31, v2
	v_lshl_add_u64 v[2:3], v[2:3], 2, s[50:51]
	global_load_dword v3, v[2:3], off
	s_mov_b32 s0, 0
	s_mov_b32 s4, 16
	s_waitcnt vmcnt(0) lgkmcnt(0)
	v_mul_f32_e64 v2, |v3|, s95
	v_exp_f32_e32 v4, v2
	v_max_f32_e32 v3, v3, v3
	v_lshl_add_u32 v2, v19, 14, 0
	v_min_f32_e32 v3, 0, v3
	v_add_f32_e32 v4, 1.0, v4
	v_cmp_gt_f32_e32 vcc, s34, v4
	v_add3_u32 v2, v2, v23, v0
	s_nop 0
	v_cndmask_b32_e64 v5, 0, 32, vcc
	v_ldexp_f32 v4, v4, v5
	v_log_f32_e32 v4, v4
	v_cndmask_b32_e32 v5, 0, v210, vcc
	v_mul_f32_e32 v6, 0x3f317217, v4
	v_fma_f32 v6, v4, s35, -v6
	v_fmac_f32_e32 v6, 0x3377d1cf, v4
	v_fmac_f32_e32 v6, 0x3f317217, v4
	v_cmp_lt_f32_e64 vcc, |v4|, s73
	s_nop 1
	v_cndmask_b32_e32 v4, v4, v6, vcc
	v_sub_f32_e32 v4, v4, v5
	v_sub_f32_e32 v3, v3, v4

; __device__ __forceinline__ float logsigmoidf(float x) { return fminf(x, 0.f) - __logf(1.f + __expf(-fabsf(x))); }
; __device__ __forceinline__ void build_cum(const Args& a, int L, int hl, long R0, const bf16_t* __restrict__ proj, LAS unsigned char* lds) {
;     ...
;     if (hl < 4) {
;         float gw[16];
; #pragma unroll
;         for (int r = 0; r < 16; ++r) gw[r] = a.gate_w[((size_t)(L * 2 + dir) * 16 + r) * 256 + hl * 64 + k];
;         const float gb = a.gate_b[(L * 2 + dir) * 256 + hl * 64 + k];
; #pragma unroll 4
;         for (int it = 0; it < 16; ++it) { const int i = isub + 4 * it; const bf16_t* ga = proj + (R0 + i) * LD + GAF + dir * 16;
;             const u32x4 g0 = *(const u32x4*)ga, g1 = *(const u32x4*)(ga + 8);
;             float x = gb;
;             x += gw[0] * bflo(g0.x) + gw[1] * bfhi(g0.x) + gw[2] * bflo(g0.y) + gw[3] * bfhi(g0.y) + gw[4] * bflo(g0.z) + gw[5] * bfhi(g0.z) + gw[6] * bflo(g0.w) + gw[7] * bfhi(g0.w);
;             x += gw[8] * bflo(g1.x) + gw[9] * bfhi(g1.x) + gw[10] * bflo(g1.y) + gw[11] * bfhi(g1.y) + gw[12] * bflo(g1.z) + gw[13] * bfhi(g1.z) + gw[14] * bflo(g1.w) + gw[15] * bfhi(g1.w);
;             cum[(dir * 64 + i) * 64 + k] = logsigmoidf(x) * (1.0f / 16.0f); }
.LBB0_121:
	s_ashr_i32 s4, s15, 9
	s_ashr_i32 s5, s4, 31
	s_and_b64 vcc, exec, s[0:1]
	s_cbranch_vccz .LBB0_124
	v_readlane_b32 s0, v254, 43
	s_lshl_b32 s24, s28, 8
	v_readlane_b32 s1, v254, 44
	v_or_b32_e32 v2, s0, v19
	v_ashrrev_i32_e32 v3, 31, v2
	v_lshlrev_b64 v[2:3], 14, v[2:3]
	v_lshl_add_u64 v[2:3], s[48:49], 0, v[2:3]
	v_lshl_add_u64 v[2:3], v[2:3], 0, s[24:25]
	v_lshl_add_u64 v[26:27], v[2:3], 0, v[0:1]
	v_add_co_u32_e32 v16, vcc, s94, v26
	s_lshl_b32 s0, s28, 6
	s_nop 0
	v_addc_co_u32_e32 v17, vcc, 0, v27, vcc
	v_add_co_u32_e32 v28, vcc, s17, v26
	global_load_dword v2, v[26:27], off
	global_load_dword v4, v[26:27], off offset:1024
	global_load_dword v6, v[26:27], off offset:2048
	global_load_dword v8, v[26:27], off offset:3072
	global_load_dword v10, v[16:17], off
	global_load_dword v12, v[16:17], off offset:1024
	global_load_dword v14, v[16:17], off offset:2048
	s_nop 0
	global_load_dword v16, v[16:17], off offset:3072
	v_addc_co_u32_e32 v29, vcc, 0, v27, vcc
	v_add_co_u32_e32 v26, vcc, s59, v26
	v_lshl_or_b32 v22, v19, 8, s1
	s_nop 0
	v_addc_co_u32_e32 v27, vcc, 0, v27, vcc
	global_load_dword v3, v[28:29], off
	global_load_dword v5, v[28:29], off offset:1024
	global_load_dword v7, v[28:29], off offset:2048
	global_load_dword v9, v[28:29], off offset:3072
	s_waitcnt vmcnt(0)
	global_load_dword v11, v[26:27], off
	global_load_dword v13, v[26:27], off offset:1024
	global_load_dword v15, v[26:27], off offset:2048
	global_load_dword v17, v[26:27], off offset:3072
	v_or3_b32 v26, v22, s0, v21
	v_ashrrev_i32_e32 v27, 31, v26
	v_lshl_add_u64 v[26:27], v[26:27], 2, s[66:67]
	global_load_dword v22, v[26:27], off
	s_and_b32 s0, s14, 63
	s_mul_i32 s0, s0, 0xc8000
	s_mul_i32 s10, s4, 0x3200000
	s_mul_hi_i32 s1, s4, 0x3200000
	s_add_u32 s0, s10, s0
	s_addc_u32 s1, s1, 0
	v_lshl_add_u32 v19, v19, 14, v23
	v_mov_b64_e32 v[26:27], s[0:1]
	v_or_b32_e32 v0, v19, v0
	v_mad_i64_i32 v[18:19], s[0:1], v18, s79, v[26:27]
	v_lshrrev_b32_e32 v23, 1, v20
	v_and_or_b32 v18, v23, 32, v18
	v_add_u32_e32 v0, 0, v0
	v_lshl_add_u64 v[18:19], s[98:99], 0, v[18:19]
	s_mov_b64 s[10:11], 0

; __device__ __forceinline__ void load_qk16(const Args& a, const bf16_t* __restrict__ src, int hl, int pos, int g, float (&va)[8], float (&vb)[8]) {
;     const u32x4 wa = *(const u32x4*)(src + g * 8), wb = *(const u32x4*)(src + 32 + g * 8);
;     va[0] = bflo(wa.x); va[1] = bfhi(wa.x); va[2] = bflo(wa.y); va[3] = bfhi(wa.y); va[4] = bflo(wa.z); va[5] = bfhi(wa.z); va[6] = bflo(wa.w); va[7] = bfhi(wa.w);
;     vb[0] = bflo(wb.x); vb[1] = bfhi(wb.x); vb[2] = bflo(wb.y); vb[3] = bfhi(wb.y); vb[4] = bflo(wb.z); vb[5] = bfhi(wb.z); vb[6] = bflo(wb.w); vb[7] = bfhi(wb.w);
;     if (hl >= 4) { const f32x2* rp = (const f32x2*)(a.ws + WS_ROPE) + pos * 32 + g * 8;
; #pragma unroll
;         for (int e = 0; e < 8; ++e) { const f32x2 cs = rp[e]; const float x1 = va[e], x2 = vb[e]; va[e] = x1 * cs.x - x2 * cs.y; vb[e] = x1 * cs.y + x2 * cs.x; } }
.LBB0_142:
	s_or_b64 exec, exec, s[0:1]
	s_and_b32 s6, s15, 63
	s_lshl_b64 s[0:1], s[4:5], 12
	s_lshl_b32 s5, s6, 6
	v_bfe_u32 v21, v24, 2, 6
	s_or_b32 s0, s0, s5
	v_or_b32_e32 v4, s0, v21
	v_mov_b64_e32 v[2:3], s[22:23]
	v_mad_u64_u32 v[2:3], s[10:11], v4, s79, v[2:3]
	v_mad_i32_i24 v3, s1, v211, v3
	v_lshl_add_u64 v[2:3], v[0:1], 1, v[2:3]
	v_lshlrev_b32_e32 v0, 3, v24
	v_and_b32_e32 v22, 24, v0
	v_lshlrev_b32_e32 v0, 1, v22
	v_lshl_add_u64 v[6:7], v[2:3], 0, v[0:1]
	global_load_dwordx4 v[2:5], v[6:7], off
	global_load_dwordx4 v[26:29], v[6:7], off offset:64
	s_cmp_lt_u32 s28, 4
	s_waitcnt vmcnt(0) lgkmcnt(0)
	v_lshlrev_b32_e32 v18, 16, v2
	v_and_b32_e32 v19, 0xffff0000, v2
	v_lshlrev_b32_e32 v10, 16, v26
	v_and_b32_e32 v11, 0xffff0000, v26
	v_lshlrev_b32_e32 v14, 16, v3
	v_and_b32_e32 v15, 0xffff0000, v3
	v_lshlrev_b32_e32 v8, 16, v27
	v_and_b32_e32 v9, 0xffff0000, v27
	v_lshlrev_b32_e32 v12, 16, v4
	v_and_b32_e32 v13, 0xffff0000, v4
	v_lshlrev_b32_e32 v2, 16, v28
	v_and_b32_e32 v3, 0xffff0000, v28
	v_lshlrev_b32_e32 v4, 16, v5
	v_and_b32_e32 v5, 0xffff0000, v5
	v_lshlrev_b32_e32 v6, 16, v29
	v_and_b32_e32 v7, 0xffff0000, v29
	s_cbranch_scc1 .LBB0_116
	v_or_b32_e32 v16, s5, v21
	v_readlane_b32 s10, v254, 28
	v_lshlrev_b32_e32 v16, 8, v16
	v_mov_b32_e32 v17, v1
	v_readlane_b32 s11, v254, 29
	v_lshlrev_b32_e32 v26, 3, v22
	v_mov_b32_e32 v27, v1
	v_lshl_add_u64 v[16:17], s[10:11], 0, v[16:17]
	v_lshl_add_u64 v[30:31], v[16:17], 0, v[26:27]
	global_load_dwordx4 v[26:29], v[30:31], off
	global_load_dwordx4 v[112:115], v[30:31], off offset:16
	global_load_dwordx4 v[116:119], v[30:31], off offset:32
	global_load_dwordx4 v[120:123], v[30:31], off offset:48
	s_waitcnt vmcnt(0) lgkmcnt(0)
	v_mov_b32_e32 v32, v26
	v_mov_b32_e32 v33, v28
	v_mov_b32_e32 v28, v27
	v_pk_mul_f32 v[16:17], v[28:29], v[10:11]
	v_pk_mul_f32 v[10:11], v[32:33], v[10:11]
	v_pk_fma_f32 v[16:17], v[32:33], v[18:19], v[16:17] neg_lo:[0,0,1] neg_hi:[0,0,1]
	v_pk_fma_f32 v[10:11], v[28:29], v[18:19], v[10:11]
	v_mov_b32_e32 v26, v112
	v_mov_b32_e32 v27, v113
	v_mov_b32_e32 v28, v114
	v_mov_b32_e32 v29, v115
	v_mov_b32_e32 v18, v26
	v_mov_b32_e32 v19, v28
	v_mov_b32_e32 v28, v27
	v_pk_mul_f32 v[26:27], v[28:29], v[8:9]
	v_pk_mul_f32 v[8:9], v[18:19], v[8:9]
	v_pk_fma_f32 v[32:33], v[18:19], v[14:15], v[26:27] neg_lo:[0,0,1] neg_hi:[0,0,1]
	v_pk_fma_f32 v[8:9], v[28:29], v[14:15], v[8:9]
	v_mov_b32_e32 v26, v116
	v_mov_b32_e32 v27, v117
	v_mov_b32_e32 v28, v118
	v_mov_b32_e32 v29, v119
	v_mov_b32_e32 v14, v26
	v_mov_b32_e32 v15, v28
	v_mov_b32_e32 v28, v27
	v_pk_mul_f32 v[18:19], v[28:29], v[2:3]
	v_pk_mul_f32 v[2:3], v[14:15], v[2:3]
	v_pk_fma_f32 v[26:27], v[14:15], v[12:13], v[18:19] neg_lo:[0,0,1] neg_hi:[0,0,1]
	v_pk_fma_f32 v[2:3], v[28:29], v[12:13], v[2:3]
	v_mov_b32_e32 v12, v120
	v_mov_b32_e32 v13, v121
	v_mov_b32_e32 v14, v122
	v_mov_b32_e32 v15, v123
	v_mov_b32_e32 v30, v5
	v_mov_b32_e32 v31, v7
	v_mov_b32_e32 v28, v13
	v_pk_mul_f32 v[18:19], v[12:13], v[4:5]
	v_pk_mul_f32 v[28:29], v[28:29], v[6:7]
	v_pk_mul_f32 v[30:31], v[14:15], v[30:31]
	s_nop 0
	v_mov_b32_e32 v19, v30
	v_mov_b32_e32 v29, v31
	v_pk_add_f32 v[28:29], v[18:19], v[28:29] neg_lo:[0,1] neg_hi:[0,1]
	v_mov_b32_e32 v18, v13
	v_mov_b32_e32 v13, v14
	v_mov_b32_e32 v19, v15
	v_pk_mul_f32 v[6:7], v[12:13], v[6:7]
	v_mov_b32_e32 v14, v32
	v_pk_fma_f32 v[6:7], v[18:19], v[4:5], v[6:7]
	v_mov_b32_e32 v18, v16
	v_mov_b32_e32 v19, v17
	v_mov_b32_e32 v15, v33
	v_mov_b32_e32 v12, v26
	v_mov_b32_e32 v13, v27
	v_mov_b32_e32 v4, v28
	v_mov_b32_e32 v5, v29
	s_branch .LBB0_116

; __device__ __forceinline__ float logsigmoidf(float x) { return fminf(x, 0.f) - __logf(1.f + __expf(-fabsf(x))); }
; __device__ __forceinline__ void build_cum(const Args& a, int L, int hl, long R0, const bf16_t* __restrict__ proj, LAS unsigned char* lds) {
;     ...
;     } else {
;         const float lg = logsigmoidf(a.decay_logit[(L * 2 + dir) * 4 + (hl - 4)]);
; #pragma unroll 4
;         for (int it = 0; it < 16; ++it) cum[(dir * 64 + isub + 4 * it) * 64 + k] = lg;
.LBB0_158:
	v_mov_b32_e32 v34, v206
	s_bfe_u32 s14, s13, 0x30006
	v_mov_b32_e32 v20, v206
	s_waitcnt lgkmcnt(0)
	s_barrier
	s_cmp_lt_u32 s14, 4
	v_and_b32_e32 v21, 63, v20
	v_ashrrev_i32_e32 v18, 7, v20
	v_bfe_u32 v19, v20, 6, 1
	s_cselect_b64 s[8:9], -1, 0
	s_cmp_gt_u32 s14, 3
	s_mov_b64 s[0:1], -1
	v_lshlrev_b32_e32 v23, 8, v18
	v_lshlrev_b32_e32 v0, 2, v21
	s_cbranch_scc0 .LBB0_162
	v_readlane_b32 s0, v254, 42
	s_add_i32 s0, s0, s14
	s_mov_b32 s1, 1
	v_lshl_add_u32 v2, v19, 2, s0
	v_ashrrev_i32_e32 v3, 31, v2
	v_lshl_add_u64 v[2:3], v[2:3], 2, s[50:51]
	global_load_dword v3, v[2:3], off
	s_mov_b32 s0, 0
	s_mov_b32 s4, 16
	s_waitcnt vmcnt(0) lgkmcnt(0)
	v_mul_f32_e64 v2, |v3|, s95
	v_exp_f32_e32 v4, v2
	v_max_f32_e32 v3, v3, v3
	v_lshl_add_u32 v2, v19, 14, 0
	v_min_f32_e32 v3, 0, v3
	v_add_f32_e32 v4, 1.0, v4
	v_cmp_gt_f32_e32 vcc, s34, v4
	v_add3_u32 v2, v2, v23, v0
	s_nop 0
	v_cndmask_b32_e64 v5, 0, 32, vcc
	v_ldexp_f32 v4, v4, v5
	v_log_f32_e32 v4, v4
	v_cndmask_b32_e32 v5, 0, v210, vcc
	v_mul_f32_e32 v6, 0x3f317217, v4
	v_fma_f32 v6, v4, s35, -v6
	v_fmac_f32_e32 v6, 0x3377d1cf, v4
	v_fmac_f32_e32 v6, 0x3f317217, v4
	v_cmp_lt_f32_e64 vcc, |v4|, s73
	s_nop 1
	v_cndmask_b32_e32 v4, v4, v6, vcc
	v_sub_f32_e32 v4, v4, v5
	v_sub_f32_e32 v3, v3, v4

; __device__ __forceinline__ float logsigmoidf(float x) { return fminf(x, 0.f) - __logf(1.f + __expf(-fabsf(x))); }
; __device__ __forceinline__ void build_cum(const Args& a, int L, int hl, long R0, const bf16_t* __restrict__ proj, LAS unsigned char* lds) {
;     ...
;     if (hl < 4) {
;         float gw[16];
; #pragma unroll
;         for (int r = 0; r < 16; ++r) gw[r] = a.gate_w[((size_t)(L * 2 + dir) * 16 + r) * 256 + hl * 64 + k];
;         const float gb = a.gate_b[(L * 2 + dir) * 256 + hl * 64 + k];
; #pragma unroll 4
;         for (int it = 0; it < 16; ++it) { const int i = isub + 4 * it; const bf16_t* ga = proj + (R0 + i) * LD + GAF + dir * 16;
;             const u32x4 g0 = *(const u32x4*)ga, g1 = *(const u32x4*)(ga + 8);
;             float x = gb;
;             x += gw[0] * bflo(g0.x) + gw[1] * bfhi(g0.x) + gw[2] * bflo(g0.y) + gw[3] * bfhi(g0.y) + gw[4] * bflo(g0.z) + gw[5] * bfhi(g0.z) + gw[6] * bflo(g0.w) + gw[7] * bfhi(g0.w);
;             x += gw[8] * bflo(g1.x) + gw[9] * bfhi(g1.x) + gw[10] * bflo(g1.y) + gw[11] * bfhi(g1.y) + gw[12] * bflo(g1.z) + gw[13] * bfhi(g1.z) + gw[14] * bflo(g1.w) + gw[15] * bfhi(g1.w);
;             cum[(dir * 64 + i) * 64 + k] = logsigmoidf(x) * (1.0f / 16.0f); }
.LBB0_162:
	s_ashr_i32 s4, s13, 9
	s_ashr_i32 s5, s4, 31
	s_and_b64 vcc, exec, s[0:1]
	s_cbranch_vccz .LBB0_165
	v_readlane_b32 s0, v254, 43
	s_lshl_b32 s24, s14, 8
	v_readlane_b32 s1, v254, 44
	v_or_b32_e32 v2, s0, v19
	v_ashrrev_i32_e32 v3, 31, v2
	v_lshlrev_b64 v[2:3], 14, v[2:3]
	v_lshl_add_u64 v[2:3], s[48:49], 0, v[2:3]
	v_lshl_add_u64 v[2:3], v[2:3], 0, s[24:25]
	v_lshl_add_u64 v[24:25], v[2:3], 0, v[0:1]
	v_add_co_u32_e32 v16, vcc, s94, v24
	s_lshl_b32 s0, s14, 6
	s_nop 0
	v_addc_co_u32_e32 v17, vcc, 0, v25, vcc
	v_add_co_u32_e32 v26, vcc, s17, v24
	global_load_dword v2, v[24:25], off
	global_load_dword v4, v[24:25], off offset:1024
	global_load_dword v6, v[24:25], off offset:2048
	global_load_dword v8, v[24:25], off offset:3072
	global_load_dword v10, v[16:17], off
	global_load_dword v12, v[16:17], off offset:1024
	global_load_dword v14, v[16:17], off offset:2048
	s_nop 0
	global_load_dword v16, v[16:17], off offset:3072
	v_addc_co_u32_e32 v27, vcc, 0, v25, vcc
	v_add_co_u32_e32 v24, vcc, s59, v24
	v_lshl_or_b32 v22, v19, 8, s1
	s_nop 0
	v_addc_co_u32_e32 v25, vcc, 0, v25, vcc
	global_load_dword v3, v[26:27], off
	global_load_dword v5, v[26:27], off offset:1024
	global_load_dword v7, v[26:27], off offset:2048
	global_load_dword v9, v[26:27], off offset:3072
	s_waitcnt vmcnt(0)
	global_load_dword v11, v[24:25], off
	global_load_dword v13, v[24:25], off offset:1024
	global_load_dword v15, v[24:25], off offset:2048
	global_load_dword v17, v[24:25], off offset:3072
	v_or3_b32 v24, v22, s0, v21
	v_ashrrev_i32_e32 v25, 31, v24
	v_lshl_add_u64 v[24:25], v[24:25], 2, s[66:67]
	global_load_dword v22, v[24:25], off
	s_and_b32 s0, s12, 63
	s_mul_i32 s0, s0, 0xc8000
	s_mul_i32 s10, s4, 0x3200000
	s_mul_hi_i32 s1, s4, 0x3200000
	s_add_u32 s0, s10, s0
	s_addc_u32 s1, s1, 0
	v_lshl_add_u32 v19, v19, 14, v23
	v_mov_b64_e32 v[24:25], s[0:1]
	v_or_b32_e32 v0, v19, v0
	v_mad_i64_i32 v[18:19], s[0:1], v18, s79, v[24:25]
	v_lshrrev_b32_e32 v23, 1, v20
	v_and_or_b32 v18, v23, 32, v18
	v_add_u32_e32 v0, 0, v0
	v_lshl_add_u64 v[18:19], s[98:99], 0, v[18:19]
	s_mov_b64 s[10:11], 0

; __device__ __forceinline__ unsigned f2bf(float f) { unsigned u = __builtin_bit_cast(unsigned, f); return (u + 0x7fffu + ((u >> 16) & 1u)) >> 16; }
; __device__ __forceinline__ void r1_item(const Args& a, int L, int item, LAS unsigned char* lds) {
;     ...
;     if (tid < 256) { const int i = (tid >> 2) & 63, g = tid & 3; const int kcol = hl < 4 ? GK + hl * 64 : RK + (hl - 4) * 64;
;         float va[8], vb[8]; load_qk16(a, proj + (R0 + i) * LD + kcol, hl, c * 64 + i, g, va, vb);
; #pragma unroll
;         for (int dir = 0; dir < 2; ++dir) { const int lastrow = dir == 0 ? 63 : 64;
; #pragma unroll
;             for (int e = 0; e < 8; ++e) { const int ka = g * 8 + e, kb = 32 + g * 8 + e;
;                 const float wa = __expf(cum[lastrow * 64 + ka] - cum[(dir * 64 + i) * 64 + ka]), wb = __expf(cum[lastrow * 64 + kb] - cum[(dir * 64 + i) * 64 + kb]);
;                 KeT[(dir * 64 + ka) * PT + i] = (bf16_t)f2bf(va[e] * wa); KeT[(dir * 64 + kb) * PT + i] = (bf16_t)f2bf(vb[e] * wb); } }
;     } else { const int t2 = tid - 256, j = t2 >> 2, vg = t2 & 3; const int vcol = hl < 4 ? GV + hl * 128 : RV + (hl - 4) * 128;
;         const bf16_t* vp = proj + (R0 + j) * LD + vcol + vg * 32;
; #pragma unroll
;         for (int q = 0; q < 4; ++q) { const u32x4 w = *(const u32x4*)(vp + q * 8); const int v0 = vg * 32 + q * 8;
;             VT[(v0 + 0) * PT + j] = (bf16_t)(w.x & 0xffff); VT[(v0 + 1) * PT + j] = (bf16_t)(w.x >> 16); VT[(v0 + 2) * PT + j] = (bf16_t)(w.y & 0xffff); VT[(v0 + 3) * PT + j] = (bf16_t)(w.y >> 16);
;             VT[(v0 + 4) * PT + j] = (bf16_t)(w.z & 0xffff); VT[(v0 + 5) * PT + j] = (bf16_t)(w.z >> 16); VT[(v0 + 6) * PT + j] = (bf16_t)(w.w & 0xffff); VT[(v0 + 7) * PT + j] = (bf16_t)(w.w >> 16); } }
.LBB0_172:
	s_or_b64 exec, exec, s[0:1]
	s_and_b32 s15, s13, 63
	s_lshl_b64 s[10:11], s[4:5], 12
	s_lshl_b32 s5, s15, 6
	s_movk_i32 s0, 0xff
	s_or_b32 s10, s10, s5
	v_cmp_lt_i32_e32 vcc, s0, v34
	s_waitcnt lgkmcnt(0)
	s_barrier
	s_and_saveexec_b64 s[0:1], vcc
	s_xor_b64 s[0:1], exec, s[0:1]
	s_cbranch_execz .LBB0_174
	v_add_u32_e32 v0, 0xffffff00, v34
	v_lshrrev_b32_e32 v0, 2, v0
	s_lshl_b32 s24, s14, 7
	v_lshl_add_u64 v[2:3], s[10:11], 0, v[0:1]
	v_mov_b64_e32 v[4:5], s[22:23]
	s_or_b32 s30, s24, 0xe00
	s_addk_i32 s24, 0x1200
	v_mad_u64_u32 v[4:5], s[28:29], v2, s79, v[4:5]
	s_and_b64 s[28:29], s[8:9], exec
	v_mov_b32_e32 v2, v5
	s_cselect_b32 s24, s30, s24
	v_mad_u64_u32 v[2:3], s[28:29], v3, s79, v[2:3]
	v_mov_b32_e32 v5, v2
	s_lshl_b32 s24, s24, 1
	v_lshl_add_u64 v[2:3], v[4:5], 0, s[24:25]
	v_lshlrev_b32_e32 v4, 5, v34
	v_and_b32_e32 v8, 0x60, v4
	v_lshlrev_b32_e32 v4, 1, v8
	v_mov_b32_e32 v5, v1
	v_lshl_add_u64 v[6:7], v[2:3], 0, v[4:5]
	v_mul_u32_u24_e32 v2, 0x90, v8
	v_lshlrev_b32_e32 v0, 1, v0
	v_add3_u32 v0, 0, v2, v0
	global_load_dwordx4 v[2:5], v[6:7], off
	global_load_dwordx4 v[112:115], v[6:7], off offset:16
	global_load_dwordx4 v[116:119], v[6:7], off offset:32
	global_load_dwordx4 v[120:123], v[6:7], off offset:48
	s_waitcnt vmcnt(0) lgkmcnt(0)
	ds_write_b16 v0, v2 offset:32768
	ds_write_b16_d16_hi v0, v2 offset:32912
	ds_write_b16 v0, v3 offset:33056
	ds_write_b16_d16_hi v0, v3 offset:33200
	ds_write_b16 v0, v4 offset:33344
	ds_write_b16_d16_hi v0, v4 offset:33488
	ds_write_b16 v0, v5 offset:33632
	ds_write_b16_d16_hi v0, v5 offset:33776
	ds_write_b16 v0, v112 offset:33920
	ds_write_b16_d16_hi v0, v112 offset:34064
	ds_write_b16 v0, v113 offset:34208
	ds_write_b16_d16_hi v0, v113 offset:34352
	ds_write_b16 v0, v114 offset:34496
	ds_write_b16_d16_hi v0, v114 offset:34640
	ds_write_b16 v0, v115 offset:34784
	ds_write_b16_d16_hi v0, v115 offset:34928
	ds_write_b16 v0, v116 offset:35072
	ds_write_b16_d16_hi v0, v116 offset:35216
	ds_write_b16 v0, v117 offset:35360
	ds_write_b16_d16_hi v0, v117 offset:35504
	ds_write_b16 v0, v118 offset:35648
	ds_write_b16_d16_hi v0, v118 offset:35792
	ds_write_b16 v0, v119 offset:35936
	ds_write_b16_d16_hi v0, v119 offset:36080
	ds_write_b16 v0, v120 offset:36224
	ds_write_b16_d16_hi v0, v120 offset:36368
	ds_write_b16 v0, v121 offset:36512
	ds_write_b16_d16_hi v0, v121 offset:36656
	ds_write_b16 v0, v122 offset:36800
	ds_write_b16_d16_hi v0, v122 offset:36944
	ds_write_b16 v0, v123 offset:37088
	ds_write_b16_d16_hi v0, v123 offset:37232
.LBB0_174:
	s_andn2_saveexec_b64 s[0:1], s[0:1]
	s_cbranch_execz .LBB0_178
	s_lshl_b32 s24, s14, 6
	s_and_b64 s[8:9], s[8:9], exec
	v_bfe_u32 v2, v34, 2, 6
	s_movk_i32 s8, 0xd00
	s_cselect_b32 s8, s8, 0x1200
	v_or_b32_e32 v0, s10, v2
	v_mov_b64_e32 v[4:5], s[22:23]
	s_add_i32 s24, s8, s24
	s_mul_i32 s10, s11, 0x3200
	v_mad_u64_u32 v[4:5], s[8:9], v0, s79, v[4:5]
	v_lshlrev_b32_e32 v0, 3, v34
	v_add_u32_e32 v5, s10, v5
	s_lshl_b32 s24, s24, 1
	v_and_b32_e32 v29, 24, v0
	v_lshl_add_u64 v[4:5], v[4:5], 0, s[24:25]
	v_lshlrev_b32_e32 v0, 1, v29
	v_lshl_add_u64 v[8:9], v[4:5], 0, v[0:1]
	global_load_dwordx4 v[4:7], v[8:9], off
	s_waitcnt vmcnt(0)
	global_load_dwordx4 v[14:17], v[8:9], off offset:64
	s_cmp_lt_u32 s14, 4
	s_waitcnt vmcnt(0) lgkmcnt(0)
	v_lshlrev_b32_e32 v10, 16, v7
	v_lshlrev_b32_e32 v26, 16, v4
	v_and_b32_e32 v27, 0xffff0000, v4
	v_lshlrev_b32_e32 v24, 16, v14
	v_and_b32_e32 v25, 0xffff0000, v14
	v_lshlrev_b32_e32 v22, 16, v5
	v_and_b32_e32 v23, 0xffff0000, v5
	v_lshlrev_b32_e32 v20, 16, v15
	v_and_b32_e32 v21, 0xffff0000, v15
	v_lshlrev_b32_e32 v18, 16, v6
	v_and_b32_e32 v19, 0xffff0000, v6
	v_lshlrev_b32_e32 v12, 16, v16
	v_and_b32_e32 v13, 0xffff0000, v16
	v_lshlrev_b32_e32 v16, 16, v17
	v_and_b32_e32 v15, 0xffff0000, v7
	v_and_b32_e32 v14, 0xffff0000, v17
	s_cbranch_scc1 .LBB0_177
	v_or_b32_e32 v0, s5, v2
	v_readlane_b32 s8, v254, 28
	v_lshlrev_b32_e32 v0, 8, v0
	v_readlane_b32 s9, v254, 29
	s_nop 1
	v_lshl_add_u64 v[4:5], s[8:9], 0, v[0:1]
	v_lshlrev_b32_e32 v0, 3, v29
	v_lshl_add_u64 v[8:9], v[4:5], 0, v[0:1]
	global_load_dwordx4 v[4:7], v[8:9], off
	global_load_dwordx4 v[30:33], v[8:9], off offset:16
	global_load_dwordx4 v[36:39], v[8:9], off offset:32
	global_load_dwordx4 v[40:43], v[8:9], off offset:48
	s_waitcnt vmcnt(0) lgkmcnt(0)
	v_mov_b32_e32 v8, v4
	v_mov_b32_e32 v9, v6
	v_mov_b32_e32 v6, v5
	v_mov_b32_e32 v4, v30
	v_mov_b32_e32 v5, v32
	v_mov_b32_e32 v32, v31
	v_mov_b32_e32 v30, v36
	v_mov_b32_e32 v31, v38
	v_mov_b32_e32 v38, v37
	v_mul_f32_e32 v36, v40, v10
	v_mul_f32_e32 v46, v41, v10
	v_pk_mul_f32 v[10:11], v[42:43], v[14:15] op_sel:[0,1] op_sel_hi:[1,0]
	v_pk_mul_f32 v[14:15], v[42:43], v[14:15]
	v_mul_f32_e32 v44, v41, v16
	v_mul_f32_e32 v16, v40, v16
	v_pk_mul_f32 v[40:41], v[6:7], v[24:25]
	v_pk_mul_f32 v[42:43], v[32:33], v[20:21]
	v_pk_mul_f32 v[48:49], v[38:39], v[12:13]
	v_mov_b32_e32 v37, v10
	v_mov_b32_e32 v45, v11
	v_mov_b32_e32 v47, v15
	v_mov_b32_e32 v17, v14
	v_pk_mul_f32 v[24:25], v[8:9], v[24:25]
	v_pk_mul_f32 v[20:21], v[4:5], v[20:21]
	v_pk_mul_f32 v[12:13], v[30:31], v[12:13]
	v_pk_fma_f32 v[8:9], v[8:9], v[26:27], v[40:41] neg_lo:[0,0,1] neg_hi:[0,0,1]
	v_pk_fma_f32 v[4:5], v[4:5], v[22:23], v[42:43] neg_lo:[0,0,1] neg_hi:[0,0,1]
	v_pk_fma_f32 v[30:31], v[30:31], v[18:19], v[48:49] neg_lo:[0,0,1] neg_hi:[0,0,1]
	v_pk_add_f32 v[10:11], v[36:37], v[44:45] neg_lo:[0,1] neg_hi:[0,1]
	v_pk_add_f32 v[16:17], v[46:47], v[16:17]
	v_pk_fma_f32 v[24:25], v[6:7], v[26:27], v[24:25]
	v_pk_fma_f32 v[20:21], v[32:33], v[22:23], v[20:21]
	v_pk_fma_f32 v[12:13], v[38:39], v[18:19], v[12:13]
	v_mov_b32_e32 v14, v17
	v_mov_b32_e32 v26, v8
	v_mov_b32_e32 v27, v9
	v_mov_b32_e32 v22, v4
	v_mov_b32_e32 v23, v5
	v_mov_b32_e32 v18, v30
	v_mov_b32_e32 v19, v31
	v_mov_b32_e32 v15, v11

; #define LAS __attribute__((address_space(3)))
; __device__ __forceinline__ unsigned f2bf(float f) { unsigned u = __builtin_bit_cast(unsigned, f); return (u + 0x7fffu + ((u >> 16) & 1u)) >> 16; }
; __device__ __forceinline__ int crow(int r, int hi) { return (r & 3) + 8 * (r >> 2) + 4 * hi; }
; __device__ __forceinline__ int crow(int r, int hi) { return (r & 3) + 8 * (r >> 2) + 4 * hi; }
; __device__ __forceinline__ int seqidx(int b, int hl, int dir, int c) { return ((b * 8 + hl) * 2 + dir) * 64 + c; }
; __device__ __forceinline__ void r1_item(const Args& a, int L, int item, LAS unsigned char* lds) {
;     ...
;     { const int dir = wid >> 2, mt = wid & 3; f32x16 acc0 = f32x16{}, acc1 = f32x16{};
; #pragma unroll
;         for (int ks = 0; ks < 4; ++ks) { const bf16x8 av = *(const LAS bf16x8*)(VT + (mt * 32 + r32) * PT + ks * 16 + hi * 8);
;             const bf16x8 b0 = *(const LAS bf16x8*)(KeT + (dir * 64 + r32) * PT + ks * 16 + hi * 8), b1 = *(const LAS bf16x8*)(KeT + (dir * 64 + 32 + r32) * PT + ks * 16 + hi * 8);
;             acc0 = __builtin_amdgcn_mfma_f32_32x32x16_bf16(av, b0, acc0, 0, 0, 0); acc1 = __builtin_amdgcn_mfma_f32_32x32x16_bf16(av, b1, acc1, 0, 0, 0); }
;         bf16_t* kvt = (bf16_t*)(a.ws + WS_KVT) + (size_t)seqidx(b, hl, dir, c) * 8192;
; #pragma unroll
;         for (int r = 0; r < 16; ++r) { const int v = mt * 32 + crow(r, hi); kvt[v * 64 + r32] = (bf16_t)f2bf(acc0[r]); kvt[v * 64 + 32 + r32] = (bf16_t)f2bf(acc1[r]); } }
;     if (tid < 128) { const int dir = tid >> 6, k = tid & 63; ((float*)(a.ws + WS_DEC))[(size_t)seqidx(b, hl, dir, c) * 64 + k] = __expf(cum[(dir == 0 ? 63 : 64) * 64 + k]); }
; __global__ void __launch_bounds__(NTHR, 2) mega_fwd(Args a0) {
;     ...
;                 const float lam = ((const float*)(a.ws + WS_LAM))[L]; const float li = 0.8f - 0.6f * __expf(-0.3f * (float)L);
.LBB0_178:
	s_or_b64 exec, exec, s[0:1]
	v_and_b32_e32 v0, 31, v34
	v_bfe_u32 v49, v34, 6, 2
	v_bfe_u32 v35, v34, 5, 1
	v_lshl_or_b32 v2, v49, 5, v0
	v_ashrrev_i32_e32 v48, 8, v34
	v_mul_u32_u24_e32 v2, 0x90, v2
	v_lshlrev_b32_e32 v3, 4, v35
	v_add3_u32 v50, 0, v2, v3
	v_lshl_or_b32 v2, v48, 6, v0
	v_mul_lo_u32 v2, v2, s81
	s_waitcnt vmcnt(0)
	v_add3_u32 v51, 0, v2, v3
	s_waitcnt lgkmcnt(0)
	s_barrier
	ds_read_b128 v[2:5], v51 offset:55808
	ds_read_b128 v[6:9], v50 offset:32768
	ds_read_b128 v[36:39], v50 offset:32800
	ds_read_b128 v[10:13], v51 offset:51200
	ds_read_b128 v[40:43], v51 offset:51232
	s_waitcnt lgkmcnt(0)
	v_mfma_f32_32x32x16_bf16 v[18:33], v[6:9], v[10:13], 0
	ds_read_b128 v[44:47], v51 offset:55840
	s_lshl_b32 s0, s4, 4
	s_lshl_b32 s1, s14, 1
	s_or_b32 s4, s1, s0
	v_lshlrev_b32_e32 v35, 8, v35
	s_movk_i32 s0, 0x80
	v_cmp_gt_i32_e32 vcc, s0, v34
	v_mfma_f32_32x32x16_bf16 v[2:17], v[6:9], v[2:5], 0
	s_waitcnt lgkmcnt(0)
	v_mfma_f32_32x32x16_bf16 v[2:17], v[36:39], v[44:47], v[2:17]
	v_mfma_f32_32x32x16_bf16 v[18:33], v[36:39], v[40:43], v[18:33]
	ds_read_b128 v[36:39], v50 offset:32832
	ds_read_b128 v[40:43], v51 offset:51264
	ds_read_b128 v[44:47], v51 offset:55872
	s_waitcnt lgkmcnt(0)
	v_mfma_f32_32x32x16_bf16 v[2:17], v[36:39], v[44:47], v[2:17]
	v_mfma_f32_32x32x16_bf16 v[18:33], v[36:39], v[40:43], v[18:33]
	ds_read_b128 v[36:39], v50 offset:32864
	ds_read_b128 v[40:43], v51 offset:51296
	ds_read_b128 v[44:47], v51 offset:55904
	s_waitcnt lgkmcnt(0)
	v_mfma_f32_32x32x16_bf16 v[2:17], v[36:39], v[44:47], v[2:17]
	v_mfma_f32_32x32x16_bf16 v[18:33], v[36:39], v[40:43], v[18:33]
	v_add_u32_e32 v36, s4, v48
	v_lshl_or_b32 v36, v36, 6, s15
	v_ashrrev_i32_e32 v37, 31, v36
	v_lshlrev_b32_e32 v38, 11, v49
	v_lshlrev_b64 v[36:37], 14, v[36:37]
	v_or3_b32 v0, v35, v38, v0
	v_lshl_add_u64 v[36:37], s[2:3], 0, v[36:37]
	v_lshlrev_b32_e32 v0, 1, v0
	v_lshl_add_u64 v[36:37], v[36:37], 0, v[0:1]
	s_nop 1
	v_bfe_u32 v0, v2, 16, 1
	v_add3_u32 v0, v2, v0, s91
	global_store_short_d16_hi v[36:37], v0, off offset:64
	v_bfe_u32 v0, v19, 16, 1
	v_add3_u32 v0, v19, v0, s91
	global_store_short_d16_hi v[36:37], v0, off offset:128
	v_bfe_u32 v0, v3, 16, 1
	v_add3_u32 v0, v3, v0, s91
	global_store_short_d16_hi v[36:37], v0, off offset:192
	v_bfe_u32 v0, v20, 16, 1
	v_add3_u32 v0, v20, v0, s91
	global_store_short_d16_hi v[36:37], v0, off offset:256
	v_bfe_u32 v0, v4, 16, 1
	v_add3_u32 v0, v4, v0, s91
	global_store_short_d16_hi v[36:37], v0, off offset:320
	v_bfe_u32 v0, v21, 16, 1
	v_add3_u32 v0, v21, v0, s91
	global_store_short_d16_hi v[36:37], v0, off offset:384
	v_bfe_u32 v0, v5, 16, 1
	v_add3_u32 v0, v5, v0, s91
	global_store_short_d16_hi v[36:37], v0, off offset:448
	v_bfe_u32 v0, v22, 16, 1
	v_add3_u32 v0, v22, v0, s91
	global_store_short_d16_hi v[36:37], v0, off offset:1024
	v_bfe_u32 v0, v6, 16, 1
	v_add3_u32 v0, v6, v0, s91
	global_store_short_d16_hi v[36:37], v0, off offset:1088
	v_bfe_u32 v0, v23, 16, 1
	v_add3_u32 v0, v23, v0, s91
	global_store_short_d16_hi v[36:37], v0, off offset:1152
	v_bfe_u32 v0, v7, 16, 1
	v_add3_u32 v0, v7, v0, s91
	global_store_short_d16_hi v[36:37], v0, off offset:1216
	v_bfe_u32 v0, v24, 16, 1
	v_add3_u32 v0, v24, v0, s91
	global_store_short_d16_hi v[36:37], v0, off offset:1280
	v_bfe_u32 v0, v8, 16, 1
	v_add3_u32 v0, v8, v0, s91
	global_store_short_d16_hi v[36:37], v0, off offset:1344
	v_bfe_u32 v0, v25, 16, 1
	v_add3_u32 v0, v25, v0, s91
	global_store_short_d16_hi v[36:37], v0, off offset:1408
	v_bfe_u32 v0, v9, 16, 1
	v_add3_u32 v0, v9, v0, s91
	global_store_short_d16_hi v[36:37], v0, off offset:1472
	v_bfe_u32 v0, v26, 16, 1
	v_add3_u32 v0, v26, v0, s91
	global_store_short_d16_hi v[36:37], v0, off offset:2048
	v_bfe_u32 v0, v10, 16, 1
	v_add3_u32 v0, v10, v0, s91
	global_store_short_d16_hi v[36:37], v0, off offset:2112
	v_bfe_u32 v0, v27, 16, 1
	v_add3_u32 v0, v27, v0, s91
	global_store_short_d16_hi v[36:37], v0, off offset:2176
	v_bfe_u32 v0, v11, 16, 1
	v_add3_u32 v0, v11, v0, s91
	global_store_short_d16_hi v[36:37], v0, off offset:2240
	v_bfe_u32 v0, v28, 16, 1
	v_add3_u32 v0, v28, v0, s91
	global_store_short_d16_hi v[36:37], v0, off offset:2304
	v_bfe_u32 v0, v12, 16, 1
	v_add3_u32 v0, v12, v0, s91
	global_store_short_d16_hi v[36:37], v0, off offset:2368
	v_bfe_u32 v0, v29, 16, 1
	v_add3_u32 v0, v29, v0, s91
	global_store_short_d16_hi v[36:37], v0, off offset:2432
	v_bfe_u32 v0, v13, 16, 1
	v_add3_u32 v0, v13, v0, s91
	global_store_short_d16_hi v[36:37], v0, off offset:2496
	v_bfe_u32 v0, v30, 16, 1
	v_add3_u32 v0, v30, v0, s91
	global_store_short_d16_hi v[36:37], v0, off offset:3072
	v_bfe_u32 v0, v14, 16, 1
	v_add3_u32 v0, v14, v0, s91
	global_store_short_d16_hi v[36:37], v0, off offset:3136
	v_bfe_u32 v0, v31, 16, 1
	v_add3_u32 v0, v31, v0, s91
	global_store_short_d16_hi v[36:37], v0, off offset:3200
	v_bfe_u32 v0, v15, 16, 1
	v_add3_u32 v0, v15, v0, s91
	global_store_short_d16_hi v[36:37], v0, off offset:3264
	v_bfe_u32 v0, v32, 16, 1
	v_add3_u32 v0, v32, v0, s91
	global_store_short_d16_hi v[36:37], v0, off offset:3328
	v_bfe_u32 v0, v16, 16, 1
	v_add3_u32 v0, v16, v0, s91
	global_store_short_d16_hi v[36:37], v0, off offset:3392
	v_bfe_u32 v0, v33, 16, 1
	v_add3_u32 v0, v33, v0, s91
	v_bfe_u32 v39, v18, 16, 1
	global_store_short_d16_hi v[36:37], v0, off offset:3456
	v_bfe_u32 v0, v17, 16, 1
	v_add3_u32 v18, v18, v39, s91
	v_add3_u32 v0, v17, v0, s91
	global_store_short_d16_hi v[36:37], v18, off
	global_store_short_d16_hi v[36:37], v0, off offset:3520
	s_and_saveexec_b64 s[0:1], vcc
	s_cbranch_execz .LBB0_157
	v_and_b32_e32 v0, 63, v34
	v_cmp_gt_u32_e32 vcc, 64, v34
	v_mov_b32_e32 v2, 0x4000
	v_lshlrev_b32_e32 v0, 2, v0
	v_cndmask_b32_e32 v2, v2, v213, vcc
	v_add3_u32 v2, 0, v2, v0
	ds_read_b32 v2, v2
	v_lshrrev_b32_e32 v3, 6, v34
	v_add_u32_e32 v3, s4, v3
	s_waitcnt lgkmcnt(0)
	v_mul_f32_e32 v2, 0x3fb8aa3b, v2
	v_exp_f32_e32 v4, v2
	v_lshl_or_b32 v2, v3, 6, s15
	v_ashrrev_i32_e32 v3, 31, v2
	v_lshlrev_b64 v[2:3], 8, v[2:3]
	v_lshl_add_u64 v[2:3], s[6:7], 0, v[2:3]
	v_lshl_add_u64 v[2:3], v[2:3], 0, v[0:1]
	global_store_dword v[2:3], v4, off
	s_branch .LBB0_157
.LBB0_180:
	s_cmpk_gt_i32 s16, 0xff
	s_cbranch_scc1 .LBB0_224
	v_readlane_b32 s4, v254, 45
	v_readlane_b32 s5, v254, 46
	s_lshl_b64 s[0:1], s[4:5], 2
	v_readlane_b32 s2, v254, 30
	v_readlane_b32 s3, v254, 31
	s_add_u32 s0, s2, s0
	s_addc_u32 s1, s3, s1
	s_waitcnt lgkmcnt(0)
	v_mov_b64_e32 v[2:3], s[0:1]
	global_load_dword v179, v[2:3], off
	v_cvt_f32_i32_e32 v0, s4
	s_lshl_b64 s[0:1], s[18:19], 17
	s_add_u32 s0, s98, s0
	v_mov_b32_e32 v2, 0xbf4ccccd
	v_mul_f32_e32 v0, 0xbe99999a, v0
	v_mul_f32_e32 v0, 0x3fb8aa3b, v0
	v_exp_f32_e32 v0, v0
	s_addc_u32 s1, s99, s1
	s_add_u32 s4, s0, 0x39c00000
	s_addc_u32 s5, s1, 0
	v_fmamk_f32 v0, v0, 0x3f19999a, v2
	v_add_f32_e32 v221, 1.0, v0
	s_lshl_b32 s28, s16, 8
	s_lshl_b32 s29, s87, 8
	s_branch .LBB0_183

; __device__ __forceinline__ void attn_unit(int b, int h, int qb, const bf16_t* __restrict__ proj, const float* __restrict__ btab, float lam, float outscale,
;                                           const float* __restrict__ gain, float* o1scr, bf16_t* merged, LAS char* lds) {
;     ...
;     __syncthreads();
;     if (tid < BTAB_N) tabL[tid] = btab[h * BTAB_N + tid];
;     __syncthreads();
;     const float cL = tabL[0], cR = tabL[BTAB_N - 1];
.LBB0_183:
	v_mov_b32_e32 v222, v206
	s_movk_i32 s0, 0x1c0
	s_bfe_u32 s2, s16, 0x30004
	s_waitcnt lgkmcnt(0)
	v_readfirstlane_b32 s3, v222
	v_cmp_gt_i32_e32 vcc, s0, v222
	s_barrier
	s_and_saveexec_b64 s[0:1], vcc
	s_cbranch_execz .LBB0_185
	s_mul_i32 s6, s2, 0x1c0
	v_add_u32_e32 v2, s6, v222
	v_ashrrev_i32_e32 v3, 31, v2
	v_lshl_add_u64 v[2:3], v[2:3], 2, s[52:53]
	global_load_dword v0, v[2:3], off
	v_lshl_add_u32 v2, v222, 2, 0
	v_add_u32_e32 v2, 0x12800, v2
	s_waitcnt vmcnt(0) lgkmcnt(0)
	ds_write_b32 v2, v0

; #define WAITBAR(N) asm volatile("s_waitcnt vmcnt(" #N ") lgkmcnt(0)\n\ts_barrier" ::: "memory")
; __device__ __forceinline__ void attn_unit(int b, int h, int qb, const bf16_t* __restrict__ proj, const float* __restrict__ btab, float lam, float outscale,
;                                           const float* __restrict__ gain, float* o1scr, bf16_t* merged, LAS char* lds) {
;     ...
;         const int hq = 2 * h + s;
;         const bf16_t* Kh = proj + rowbase * LD + OKK + hq * 64;
;         const bf16_t* Qw = proj + (rowbase + qw + r32) * LD + OQ + hq * 64 + hi * 8;
;         float m_reg = -1e30f, l_reg = 0; f32x16 o[4]; bf16x8 qr[4];
; #pragma unroll
;         for (int d0 = 0; d0 < 4; ++d0) { o[d0] = f32x16{}; qr[d0] = *(const bf16x8*)(Qw + d0 * 16); }
;     ...
;         f32x16 pA0, pA1, pB0, pB1; float mnA, mnB, alA, alB, bo; bf16x8 pa0, pa1, pa2, pa3; constexpr int NT = T / 64;
;         asm volatile("s_waitcnt vmcnt(0) lgkmcnt(0)" ::: "memory"); __syncthreads();
;         DMA_TILE(0, 0); DMA_TILE(1, 1);
;         WAITBAR(3);
.LBB0_187:
	s_or_b32 s24, s6, s48
	s_lshl_b64 s[2:3], s[24:25], 1
	v_lshl_add_u64 v[2:3], v[190:191], 0, s[2:3]
	s_add_u32 s2, s36, s2
	s_addc_u32 s3, s37, s3
	global_load_dwordx4 v[142:145], v[2:3], off
	global_load_dwordx4 v[138:141], v[2:3], off offset:32
	global_load_dwordx4 v[134:137], v[2:3], off offset:64
	global_load_dwordx4 v[130:133], v[2:3], off offset:96
	v_lshl_add_u64 v[204:205], s[2:3], 0, v[186:187]
	s_xor_b64 s[2:3], s[0:1], -1
	s_mov_b64 s[6:7], 0x800
	v_lshl_add_u64 v[204:205], v[204:205], 0, s[6:7]
	v_mov_b64_e32 v[250:251], v[192:193]
	v_mov_b64_e32 v[246:247], v[194:195]
	s_mov_b32 s6, 0xc8000
	s_mov_b32 s7, 0
	v_readfirstlane_b32 s67, v222
	v_add_u32_e32 v239, v226, v227
	v_add_u32_e32 v240, v226, v228
	v_add_u32_e32 v241, v226, v229
	v_add_u32_e32 v242, v226, v230
	s_lshr_b32 s67, s67, 8
	v_add_u32_e32 v239, 0x14000, v239
	v_add_u32_e32 v240, 0x14000, v240
	v_add_u32_e32 v241, 0x14000, v241
	v_add_u32_e32 v242, 0x14000, v242
	v_mov_b32_e32 v2, 0
	v_mov_b32_e32 v3, 0
	v_mov_b32_e32 v4, 0
	v_mov_b32_e32 v5, 0
	v_mov_b32_e32 v6, 0
	v_mov_b32_e32 v7, 0
	v_mov_b32_e32 v8, 0
	v_mov_b32_e32 v9, 0
	v_mov_b32_e32 v10, 0
	v_mov_b32_e32 v11, 0
	v_mov_b32_e32 v12, 0
	v_mov_b32_e32 v13, 0
	v_mov_b32_e32 v14, 0
	v_mov_b32_e32 v15, 0
	v_mov_b32_e32 v16, 0
	v_mov_b32_e32 v17, 0
	v_mov_b32_e32 v18, 0
	v_mov_b32_e32 v19, 0
	v_mov_b32_e32 v20, 0
	v_mov_b32_e32 v21, 0
	v_mov_b32_e32 v22, 0
	v_mov_b32_e32 v23, 0
	v_mov_b32_e32 v24, 0
	v_mov_b32_e32 v25, 0
	v_mov_b32_e32 v26, 0
	v_mov_b32_e32 v27, 0
	v_mov_b32_e32 v28, 0
	v_mov_b32_e32 v29, 0
	v_mov_b32_e32 v30, 0
	v_mov_b32_e32 v31, 0
	v_mov_b32_e32 v32, 0
	v_mov_b32_e32 v33, 0
	v_mov_b32_e32 v34, 0
	v_mov_b32_e32 v35, 0
	v_mov_b32_e32 v36, 0
	v_mov_b32_e32 v37, 0
	v_mov_b32_e32 v38, 0
	v_mov_b32_e32 v39, 0
	v_mov_b32_e32 v40, 0
	v_mov_b32_e32 v41, 0
	v_mov_b32_e32 v42, 0
	v_mov_b32_e32 v43, 0
	v_mov_b32_e32 v44, 0
	v_mov_b32_e32 v45, 0
	v_mov_b32_e32 v46, 0
	v_mov_b32_e32 v47, 0
	v_mov_b32_e32 v48, 0
	v_mov_b32_e32 v49, 0
	v_mov_b32_e32 v50, 0
	v_mov_b32_e32 v51, 0
	v_mov_b32_e32 v52, 0
	v_mov_b32_e32 v53, 0
	v_mov_b32_e32 v54, 0
	v_mov_b32_e32 v55, 0
	v_mov_b32_e32 v56, 0
	v_mov_b32_e32 v57, 0
	v_mov_b32_e32 v58, 0
	v_mov_b32_e32 v59, 0
	v_mov_b32_e32 v60, 0
	v_mov_b32_e32 v61, 0
	v_mov_b32_e32 v62, 0
	v_mov_b32_e32 v63, 0
	v_mov_b32_e32 v64, 0
	v_mov_b32_e32 v65, 0
	v_mov_b32_e32 v243, v215
	v_mov_b32_e32 v238, 0
	v_add_u32_e32 v245, 0xffffff00, v235
	s_sub_i32 s65, s78, 0x80
	s_mov_b32 s40, 0
	s_waitcnt vmcnt(0) lgkmcnt(0)
	s_barrier
	s_mov_b32 s24, 0
	s_lshl_b32 s12, s24, 13
	s_add_i32 s12, s12, s66
	s_lshl_b32 s13, s24, 14
	s_add_i32 s13, s13, s74
	s_add_i32 m0, s12, 0x14000
	s_nop 0
	global_load_lds_dwordx4 v[204:205], off
	s_mov_b32 m0, s13
	v_lshl_add_u64 v[204:205], v[204:205], 0, s[6:7]
	global_load_lds_dwordx4 v[250:251], off
	s_add_i32 m0, s13, 0x400
	v_lshl_add_u64 v[250:251], v[250:251], 0, s[6:7]
	global_load_lds_dwordx4 v[246:247], off
	v_lshl_add_u64 v[246:247], v[246:247], 0, s[6:7]
	s_mov_b32 s24, 1
	s_lshl_b32 s12, s24, 13
	s_add_i32 s12, s12, s66
	s_lshl_b32 s13, s24, 14
	s_add_i32 s13, s13, s74
	s_add_i32 m0, s12, 0x14000
	s_nop 0
	global_load_lds_dwordx4 v[204:205], off
	s_mov_b32 m0, s13
	v_lshl_add_u64 v[204:205], v[204:205], 0, s[6:7]
	global_load_lds_dwordx4 v[250:251], off
	s_add_i32 m0, s13, 0x400
	v_lshl_add_u64 v[250:251], v[250:251], 0, s[6:7]
	global_load_lds_dwordx4 v[246:247], off
	v_lshl_add_u64 v[246:247], v[246:247], 0, s[6:7]
	s_waitcnt vmcnt(3)
	s_barrier
	s_cmp_eq_u32 s67, 0
	s_cbranch_scc1 .Lat_enter
	s_barrier

; __device__ __forceinline__ void attn_unit(int b, int h, int qb, const bf16_t* __restrict__ proj, const float* __restrict__ btab, float lam, float outscale,
;                                           const float* __restrict__ gain, float* o1scr, bf16_t* merged, LAS char* lds) {
;     ...
;         } else {
; #pragma unroll
;             for (int d0 = 0; d0 < 4; ++d0)
; #pragma unroll
;                 for (int r4 = 0; r4 < 4; ++r4) { const f32x4 p = o1p[d0 * 4 + r4];
; #pragma unroll
;                     for (int e = 0; e < 4; ++e) o[d0][4 * r4 + e] = p[e] - lam * (o[d0][4 * r4 + e] * rli[4 * r4 + e]); }
.LBB0_222:
	global_load_dwordx4 v[66:69], v[74:75], off
	global_load_dwordx4 v[224:227], v[74:75], off offset:16
	global_load_dwordx4 v[228:231], v[74:75], off offset:32
	global_load_dwordx4 v[232:235], v[74:75], off offset:48
	global_load_dwordx4 v[236:239], v[74:75], off offset:64
	global_load_dwordx4 v[240:243], v[74:75], off offset:80
	global_load_dwordx4 v[244:247], v[74:75], off offset:96
	global_load_dwordx4 v[248:251], v[74:75], off offset:112
	v_mul_f32_e32 v0, v50, v86
	v_xor_b32_e32 v152, 8, v208
	v_and_b32_e32 v171, 31, v88
	s_mov_b32 s0, 0x8000
	s_waitcnt vmcnt(0) lgkmcnt(0)
	v_fma_f32 v110, -v179, v0, v66
	v_mul_f32_e32 v0, v51, v87
	v_fma_f32 v107, -v179, v0, v67
	v_mul_f32_e32 v0, v52, v84
	v_fma_f32 v104, -v179, v0, v68
	v_mul_f32_e32 v0, v53, v85
	v_fma_f32 v101, -v179, v0, v69
	v_mov_b32_e32 v66, v224
	v_mov_b32_e32 v67, v225
	v_mov_b32_e32 v68, v226
	v_mov_b32_e32 v69, v227
	v_mul_f32_e32 v0, v54, v76
	v_fma_f32 v103, -v179, v0, v66
	v_mul_f32_e32 v0, v55, v77
	v_fma_f32 v100, -v179, v0, v67
	v_mul_f32_e32 v0, v56, v82
	v_fma_f32 v98, -v179, v0, v68
	v_mul_f32_e32 v0, v57, v83
	v_fma_f32 v96, -v179, v0, v69
	v_mov_b32_e32 v66, v228
	v_mov_b32_e32 v67, v229
	v_mov_b32_e32 v68, v230
	v_mov_b32_e32 v69, v231
	v_mul_f32_e32 v0, v58, v80
	v_fma_f32 v97, -v179, v0, v66
	v_mul_f32_e32 v0, v59, v81
	v_fma_f32 v95, -v179, v0, v67
	v_mul_f32_e32 v0, v60, v78
	v_fma_f32 v94, -v179, v0, v68
	v_mul_f32_e32 v0, v61, v79
	v_fma_f32 v92, -v179, v0, v69
	v_mov_b32_e32 v66, v232
	v_mov_b32_e32 v67, v233
	v_mov_b32_e32 v68, v234
	v_mov_b32_e32 v69, v235
	v_mul_f32_e32 v0, v62, v72
	v_fma_f32 v93, -v179, v0, v66
	v_mul_f32_e32 v0, v63, v73
	v_fma_f32 v91, -v179, v0, v67
	v_mul_f32_e32 v0, v64, v70
	v_fma_f32 v90, -v179, v0, v68
	v_mul_f32_e32 v0, v65, v71
	v_fma_f32 v89, -v179, v0, v69
	v_mov_b32_e32 v66, v236
	v_mov_b32_e32 v67, v237
	v_mov_b32_e32 v68, v238
	v_mov_b32_e32 v69, v239
	v_mul_f32_e32 v0, v34, v86
	v_fma_f32 v122, -v179, v0, v66
	v_mul_f32_e32 v0, v35, v87
	v_fma_f32 v120, -v179, v0, v67
	v_mul_f32_e32 v0, v36, v84
	v_fma_f32 v118, -v179, v0, v68
	v_mul_f32_e32 v0, v37, v85
	v_fma_f32 v116, -v179, v0, v69
	v_mov_b32_e32 v66, v240
	v_mov_b32_e32 v67, v241
	v_mov_b32_e32 v68, v242
	v_mov_b32_e32 v69, v243
	v_mul_f32_e32 v0, v38, v76
	v_fma_f32 v117, -v179, v0, v66
	v_mul_f32_e32 v0, v39, v77
	v_fma_f32 v115, -v179, v0, v67
	v_mul_f32_e32 v0, v40, v82
	v_fma_f32 v114, -v179, v0, v68
	v_mul_f32_e32 v0, v41, v83
	v_fma_f32 v112, -v179, v0, v69
	v_mov_b32_e32 v66, v244
	v_mov_b32_e32 v67, v245
	v_mov_b32_e32 v68, v246
	v_mov_b32_e32 v69, v247
	v_mul_f32_e32 v0, v42, v80
	v_fma_f32 v113, -v179, v0, v66
	v_mul_f32_e32 v0, v43, v81
	v_fma_f32 v111, -v179, v0, v67
	v_mul_f32_e32 v0, v44, v78
	v_fma_f32 v109, -v179, v0, v68
	v_mul_f32_e32 v0, v45, v79
	v_fma_f32 v106, -v179, v0, v69
	v_mov_b32_e32 v66, v248
	v_mov_b32_e32 v67, v249
	v_mov_b32_e32 v68, v250
	v_mov_b32_e32 v69, v251
	v_mul_f32_e32 v0, v46, v72
	v_fma_f32 v108, -v179, v0, v66
	v_mul_f32_e32 v0, v47, v73
	v_fma_f32 v105, -v179, v0, v67
	v_mul_f32_e32 v0, v48, v70
	v_fma_f32 v102, -v179, v0, v68
	v_mul_f32_e32 v0, v49, v71
	v_fma_f32 v99, -v179, v0, v69
	global_load_dwordx4 v[66:69], v[74:75], off offset:128
	global_load_dwordx4 v[224:227], v[74:75], off offset:144
	global_load_dwordx4 v[228:231], v[74:75], off offset:160
	global_load_dwordx4 v[232:235], v[74:75], off offset:176
	global_load_dwordx4 v[236:239], v[74:75], off offset:192
	global_load_dwordx4 v[240:243], v[74:75], off offset:208
	global_load_dwordx4 v[244:247], v[74:75], off offset:224
	global_load_dwordx4 v[248:251], v[74:75], off offset:240
	v_mul_f32_e32 v0, v18, v86
	s_waitcnt vmcnt(0) lgkmcnt(0)
	v_fma_f32 v136, -v179, v0, v66
	v_mul_f32_e32 v0, v19, v87
	v_fma_f32 v135, -v179, v0, v67
	v_mul_f32_e32 v0, v20, v84
	v_fma_f32 v134, -v179, v0, v68
	v_mul_f32_e32 v0, v21, v85
	v_fma_f32 v132, -v179, v0, v69
	v_mov_b32_e32 v66, v224
	v_mov_b32_e32 v67, v225
	v_mov_b32_e32 v68, v226
	v_mov_b32_e32 v69, v227
	v_mul_f32_e32 v0, v22, v76
	v_fma_f32 v133, -v179, v0, v66
	v_mul_f32_e32 v0, v23, v77
	v_fma_f32 v131, -v179, v0, v67
	v_mul_f32_e32 v0, v24, v82
	v_fma_f32 v129, -v179, v0, v68
	v_mul_f32_e32 v0, v25, v83
	v_fma_f32 v126, -v179, v0, v69
	v_mov_b32_e32 v66, v228
	v_mov_b32_e32 v67, v229
	v_mov_b32_e32 v68, v230
	v_mov_b32_e32 v69, v231
	v_mul_f32_e32 v0, v26, v80
	v_fma_f32 v130, -v179, v0, v66
	v_mul_f32_e32 v0, v27, v81
	v_fma_f32 v128, -v179, v0, v67
	v_mul_f32_e32 v0, v28, v78
	v_fma_f32 v125, -v179, v0, v68
	v_mul_f32_e32 v0, v29, v79
	v_fma_f32 v123, -v179, v0, v69
	v_mov_b32_e32 v66, v232
	v_mov_b32_e32 v67, v233
	v_mov_b32_e32 v68, v234
	v_mov_b32_e32 v69, v235
	v_mul_f32_e32 v0, v30, v72
	v_fma_f32 v127, -v179, v0, v66
	v_mul_f32_e32 v0, v31, v73
	v_fma_f32 v124, -v179, v0, v67
	v_mul_f32_e32 v0, v32, v70
	v_fma_f32 v121, -v179, v0, v68
	v_mul_f32_e32 v0, v33, v71
	v_fma_f32 v119, -v179, v0, v69
	v_mov_b32_e32 v66, v236
	v_mov_b32_e32 v67, v237
	v_mov_b32_e32 v68, v238
	v_mov_b32_e32 v69, v239
	v_mul_f32_e32 v0, v2, v86
	v_fma_f32 v148, -v179, v0, v66
	v_mul_f32_e32 v0, v3, v87
	v_fma_f32 v147, -v179, v0, v67
	v_mul_f32_e32 v0, v4, v84
	v_fma_f32 v145, -v179, v0, v68
	v_mul_f32_e32 v0, v5, v85
	v_fma_f32 v142, -v179, v0, v69
	v_mov_b32_e32 v66, v240
	v_mov_b32_e32 v67, v241
	v_mov_b32_e32 v68, v242
	v_mov_b32_e32 v69, v243
	v_mul_f32_e32 v0, v6, v76
	v_fma_f32 v146, -v179, v0, v66
	v_mul_f32_e32 v0, v7, v77
	v_fma_f32 v144, -v179, v0, v67
	v_mul_f32_e32 v0, v8, v82
	v_fma_f32 v141, -v179, v0, v68
	v_mul_f32_e32 v0, v9, v83
	v_fma_f32 v139, -v179, v0, v69
	v_mov_b32_e32 v66, v244
	v_mov_b32_e32 v67, v245
; __device__ __forceinline__ void attn_unit(int b, int h, int qb, const bf16_t* __restrict__ proj, const float* __restrict__ btab, float lam, float outscale,
;                                           const float* __restrict__ gain, float* o1scr, bf16_t* merged, LAS char* lds) {
;     ...
;             float ssq[16];
; #pragma unroll
;             for (int r = 0; r < 16; ++r) { float a2 = 0.f;
; #pragma unroll
;                 for (int d0 = 0; d0 < 4; ++d0) a2 += o[d0][r] * o[d0][r];
;                 a2 += __shfl_xor(a2, 1); a2 += __shfl_xor(a2, 2); a2 += __shfl_xor(a2, 4); a2 += __shfl_xor(a2, 8); a2 += __shfl_xor(a2, 16);
;                 ssq[r] = __builtin_amdgcn_rsqf(a2 * (1.0f / 128.0f) + EPS) * outscale; }
	v_mov_b32_e32 v68, v246
	v_mov_b32_e32 v69, v247
	v_mul_f32_e32 v0, v10, v80
	v_fma_f32 v143, -v179, v0, v66
	v_mul_f32_e32 v0, v11, v81
	v_fma_f32 v140, -v179, v0, v67
	v_mul_f32_e32 v0, v12, v78
	v_fma_f32 v138, -v179, v0, v68
	v_mul_f32_e32 v0, v13, v79
	v_fma_f32 v137, -v179, v0, v69
	v_mov_b32_e32 v66, v248
	v_mov_b32_e32 v67, v249
	v_mov_b32_e32 v68, v250
	v_mov_b32_e32 v69, v251
	v_mul_f32_e32 v0, v14, v72
	v_fma_f32 v151, -v179, v0, v66
	v_mul_f32_e32 v0, v15, v73
	v_fma_f32 v150, -v179, v0, v67
	v_mul_f32_e32 v0, v16, v70
	v_fma_f32 v149, -v179, v0, v68
	v_mul_f32_e32 v0, v17, v71
	v_and_b32_e32 v66, 64, v208
	v_fma_f32 v68, -v179, v0, v69
	v_xor_b32_e32 v0, 1, v208
	v_add_u32_e32 v69, 64, v66
	v_cmp_lt_i32_e32 vcc, v0, v69
	v_xor_b32_e32 v66, 2, v208
	v_xor_b32_e32 v67, 4, v208
	v_cndmask_b32_e32 v0, v208, v0, vcc
	v_cmp_lt_i32_e32 vcc, v66, v69
	v_lshlrev_b32_e32 v0, 2, v0
	s_nop 0
	v_cndmask_b32_e32 v66, v208, v66, vcc
	v_cmp_lt_i32_e32 vcc, v67, v69
	v_lshlrev_b32_e32 v66, 2, v66
	s_nop 0
	v_cndmask_b32_e32 v67, v208, v67, vcc
	v_cmp_lt_i32_e32 vcc, v152, v69
	v_lshlrev_b32_e32 v67, 2, v67
	s_nop 0
	v_cndmask_b32_e32 v152, v208, v152, vcc
	v_lshlrev_b32_e32 v159, 2, v152
	v_xor_b32_e32 v152, 16, v208
	v_cmp_lt_i32_e32 vcc, v152, v69
	s_nop 1
	v_cndmask_b32_e32 v69, v208, v152, vcc
	v_lshlrev_b32_e32 v160, 2, v69
	v_mul_f32_e32 v69, v122, v122
	v_fmac_f32_e32 v69, v110, v110
	v_fmac_f32_e32 v69, v136, v136
	v_fmac_f32_e32 v69, v148, v148
	ds_bpermute_b32 v152, v0, v69
	s_waitcnt lgkmcnt(0)
	v_add_f32_e32 v69, v69, v152
	ds_bpermute_b32 v152, v66, v69
	s_waitcnt lgkmcnt(0)
	v_add_f32_e32 v69, v69, v152
	ds_bpermute_b32 v152, v67, v69
	s_waitcnt lgkmcnt(0)
	v_add_f32_e32 v69, v69, v152
	ds_bpermute_b32 v152, v159, v69
	s_waitcnt lgkmcnt(0)
	v_add_f32_e32 v69, v69, v152
	ds_bpermute_b32 v152, v160, v69
	s_waitcnt lgkmcnt(0)
	v_add_f32_e32 v69, v69, v152
	v_mul_f32_e32 v152, v120, v120
	v_fmac_f32_e32 v152, v107, v107
	v_fmac_f32_e32 v152, v135, v135
	v_fmac_f32_e32 v152, v147, v147
	ds_bpermute_b32 v153, v0, v152
	v_fmamk_f32 v69, v69, 0x3c000000, v207
	v_rsq_f32_e32 v69, v69
	s_waitcnt lgkmcnt(0)
	v_add_f32_e32 v152, v152, v153
	ds_bpermute_b32 v153, v66, v152
	v_mul_f32_e32 v69, v221, v69
	s_waitcnt lgkmcnt(0)
	v_add_f32_e32 v152, v152, v153
	ds_bpermute_b32 v153, v67, v152
	s_waitcnt lgkmcnt(0)
	v_add_f32_e32 v152, v152, v153
	ds_bpermute_b32 v153, v159, v152
	s_waitcnt lgkmcnt(0)
	v_add_f32_e32 v152, v152, v153
	ds_bpermute_b32 v153, v160, v152
	s_waitcnt lgkmcnt(0)
	v_add_f32_e32 v152, v152, v153
	v_mul_f32_e32 v153, v118, v118
	v_fmac_f32_e32 v153, v104, v104
	v_fmac_f32_e32 v153, v134, v134
	v_fmac_f32_e32 v153, v145, v145
	ds_bpermute_b32 v154, v0, v153
	v_fmamk_f32 v152, v152, 0x3c000000, v207
	v_rsq_f32_e32 v152, v152
	s_waitcnt lgkmcnt(0)
	v_add_f32_e32 v153, v153, v154
	ds_bpermute_b32 v154, v66, v153
	v_mul_f32_e32 v152, v221, v152
	s_waitcnt lgkmcnt(0)
	v_add_f32_e32 v153, v153, v154
	ds_bpermute_b32 v154, v67, v153
	s_waitcnt lgkmcnt(0)
	v_add_f32_e32 v153, v153, v154
	ds_bpermute_b32 v154, v159, v153
	s_waitcnt lgkmcnt(0)
	v_add_f32_e32 v153, v153, v154
	ds_bpermute_b32 v154, v160, v153
	s_waitcnt lgkmcnt(0)
	v_add_f32_e32 v153, v153, v154
	v_mul_f32_e32 v154, v116, v116
	v_fmac_f32_e32 v154, v101, v101
	v_fmac_f32_e32 v154, v132, v132
	v_fmac_f32_e32 v154, v142, v142
	ds_bpermute_b32 v155, v0, v154
	v_fmamk_f32 v153, v153, 0x3c000000, v207
	v_rsq_f32_e32 v153, v153
	s_waitcnt lgkmcnt(0)
	v_add_f32_e32 v154, v154, v155
	ds_bpermute_b32 v155, v66, v154
	v_mul_f32_e32 v153, v221, v153
	s_waitcnt lgkmcnt(0)
	v_add_f32_e32 v154, v154, v155
	ds_bpermute_b32 v155, v67, v154
	s_waitcnt lgkmcnt(0)
	v_add_f32_e32 v154, v154, v155
	ds_bpermute_b32 v155, v159, v154
	s_waitcnt lgkmcnt(0)
	v_add_f32_e32 v154, v154, v155
	ds_bpermute_b32 v155, v160, v154
	s_waitcnt lgkmcnt(0)
	v_add_f32_e32 v154, v154, v155
	v_mul_f32_e32 v155, v117, v117
	v_fmac_f32_e32 v155, v103, v103
	v_fmac_f32_e32 v155, v133, v133
	v_fmac_f32_e32 v155, v146, v146
	ds_bpermute_b32 v156, v0, v155
	v_fmamk_f32 v154, v154, 0x3c000000, v207
	v_rsq_f32_e32 v154, v154
	s_waitcnt lgkmcnt(0)
	v_add_f32_e32 v155, v155, v156
	ds_bpermute_b32 v156, v66, v155
	v_mul_f32_e32 v154, v221, v154
	s_waitcnt lgkmcnt(0)
	v_add_f32_e32 v155, v155, v156
	ds_bpermute_b32 v156, v67, v155
	s_waitcnt lgkmcnt(0)
	v_add_f32_e32 v155, v155, v156
	ds_bpermute_b32 v156, v159, v155
	s_waitcnt lgkmcnt(0)
	v_add_f32_e32 v155, v155, v156
	ds_bpermute_b32 v156, v160, v155
	s_waitcnt lgkmcnt(0)
	v_add_f32_e32 v155, v155, v156
	v_mul_f32_e32 v156, v115, v115
	v_fmac_f32_e32 v156, v100, v100
	v_fmac_f32_e32 v156, v131, v131
	v_fmac_f32_e32 v156, v144, v144
	ds_bpermute_b32 v157, v0, v156
	v_fmamk_f32 v155, v155, 0x3c000000, v207
	v_rsq_f32_e32 v155, v155
	s_waitcnt lgkmcnt(0)
	v_add_f32_e32 v156, v156, v157
	ds_bpermute_b32 v157, v66, v156
	v_mul_f32_e32 v155, v221, v155
	s_waitcnt lgkmcnt(0)
	v_add_f32_e32 v156, v156, v157
	ds_bpermute_b32 v157, v67, v156
	s_waitcnt lgkmcnt(0)
	v_add_f32_e32 v156, v156, v157
	ds_bpermute_b32 v157, v159, v156
	s_waitcnt lgkmcnt(0)
	v_add_f32_e32 v156, v156, v157
	ds_bpermute_b32 v157, v160, v156
	s_waitcnt lgkmcnt(0)
	v_add_f32_e32 v156, v156, v157
	v_mul_f32_e32 v157, v114, v114
	v_fmac_f32_e32 v157, v98, v98
	v_fmac_f32_e32 v157, v129, v129
	v_fmac_f32_e32 v157, v141, v141
	ds_bpermute_b32 v158, v0, v157
	v_fmamk_f32 v156, v156, 0x3c000000, v207
	v_rsq_f32_e32 v156, v156
	s_waitcnt lgkmcnt(0)
	v_add_f32_e32 v157, v157, v158
	ds_bpermute_b32 v158, v66, v157
	v_mul_f32_e32 v156, v221, v156
	s_waitcnt lgkmcnt(0)
	v_add_f32_e32 v157, v157, v158
	ds_bpermute_b32 v158, v67, v157
	s_waitcnt lgkmcnt(0)
; __device__ __forceinline__ void attn_unit(int b, int h, int qb, const bf16_t* __restrict__ proj, const float* __restrict__ btab, float lam, float outscale,
;                                           const float* __restrict__ gain, float* o1scr, bf16_t* merged, LAS char* lds) {
;     ...
;             for (int r = 0; r < 16; ++r) { float a2 = 0.f;
; #pragma unroll
;                 for (int d0 = 0; d0 < 4; ++d0) a2 += o[d0][r] * o[d0][r];
;                 a2 += __shfl_xor(a2, 1); a2 += __shfl_xor(a2, 2); a2 += __shfl_xor(a2, 4); a2 += __shfl_xor(a2, 8); a2 += __shfl_xor(a2, 16);
;                 ssq[r] = __builtin_amdgcn_rsqf(a2 * (1.0f / 128.0f) + EPS) * outscale; }
	v_add_f32_e32 v157, v157, v158
	ds_bpermute_b32 v158, v159, v157
	s_waitcnt lgkmcnt(0)
	v_add_f32_e32 v157, v157, v158
	ds_bpermute_b32 v158, v160, v157
	s_waitcnt lgkmcnt(0)
	v_add_f32_e32 v157, v157, v158
	v_mul_f32_e32 v158, v112, v112
	v_fmac_f32_e32 v158, v96, v96
	v_fmac_f32_e32 v158, v126, v126
	v_fmac_f32_e32 v158, v139, v139
	ds_bpermute_b32 v161, v0, v158
	v_fmamk_f32 v157, v157, 0x3c000000, v207
	v_rsq_f32_e32 v157, v157
	s_waitcnt lgkmcnt(0)
	v_add_f32_e32 v158, v158, v161
	ds_bpermute_b32 v161, v66, v158
	v_mul_f32_e32 v157, v221, v157
	s_waitcnt lgkmcnt(0)
	v_add_f32_e32 v158, v158, v161
	ds_bpermute_b32 v161, v67, v158
	s_waitcnt lgkmcnt(0)
	v_add_f32_e32 v158, v158, v161
	ds_bpermute_b32 v161, v159, v158
	s_waitcnt lgkmcnt(0)
	v_add_f32_e32 v158, v158, v161
	ds_bpermute_b32 v161, v160, v158
	s_waitcnt lgkmcnt(0)
	v_add_f32_e32 v158, v158, v161
	v_mul_f32_e32 v161, v113, v113
	v_fmac_f32_e32 v161, v97, v97
	v_fmac_f32_e32 v161, v130, v130
	v_fmac_f32_e32 v161, v143, v143
	ds_bpermute_b32 v162, v0, v161
	v_fmamk_f32 v158, v158, 0x3c000000, v207
	v_rsq_f32_e32 v158, v158
	s_waitcnt lgkmcnt(0)
	v_add_f32_e32 v161, v161, v162
	ds_bpermute_b32 v162, v66, v161
	v_mul_f32_e32 v158, v221, v158
	s_waitcnt lgkmcnt(0)
	v_add_f32_e32 v161, v161, v162
	ds_bpermute_b32 v162, v67, v161
	s_waitcnt lgkmcnt(0)
	v_add_f32_e32 v161, v161, v162
	ds_bpermute_b32 v162, v159, v161
	s_waitcnt lgkmcnt(0)
	v_add_f32_e32 v161, v161, v162
	ds_bpermute_b32 v162, v160, v161
	s_waitcnt lgkmcnt(0)
	v_add_f32_e32 v161, v161, v162
	v_mul_f32_e32 v162, v111, v111
	v_fmac_f32_e32 v162, v95, v95
	v_fmac_f32_e32 v162, v128, v128
	v_fmac_f32_e32 v162, v140, v140
	ds_bpermute_b32 v163, v0, v162
	v_fmamk_f32 v161, v161, 0x3c000000, v207
	v_rsq_f32_e32 v161, v161
	s_waitcnt lgkmcnt(0)
	v_add_f32_e32 v162, v162, v163
	ds_bpermute_b32 v163, v66, v162
	v_mul_f32_e32 v161, v221, v161
	s_waitcnt lgkmcnt(0)
	v_add_f32_e32 v162, v162, v163
	ds_bpermute_b32 v163, v67, v162
	s_waitcnt lgkmcnt(0)
	v_add_f32_e32 v162, v162, v163
	ds_bpermute_b32 v163, v159, v162
	s_waitcnt lgkmcnt(0)
	v_add_f32_e32 v162, v162, v163
	ds_bpermute_b32 v163, v160, v162
	s_waitcnt lgkmcnt(0)
	v_add_f32_e32 v162, v162, v163
	v_mul_f32_e32 v163, v109, v109
	v_fmac_f32_e32 v163, v94, v94
	v_fmac_f32_e32 v163, v125, v125
	v_fmac_f32_e32 v163, v138, v138
	ds_bpermute_b32 v164, v0, v163
	v_fmamk_f32 v162, v162, 0x3c000000, v207
	v_rsq_f32_e32 v162, v162
	s_waitcnt lgkmcnt(0)
	v_add_f32_e32 v163, v163, v164
	ds_bpermute_b32 v164, v66, v163
	v_mul_f32_e32 v162, v221, v162
	s_waitcnt lgkmcnt(0)
	v_add_f32_e32 v163, v163, v164
	ds_bpermute_b32 v164, v67, v163
	s_waitcnt lgkmcnt(0)
	v_add_f32_e32 v163, v163, v164
	ds_bpermute_b32 v164, v159, v163
	s_waitcnt lgkmcnt(0)
	v_add_f32_e32 v163, v163, v164
	ds_bpermute_b32 v164, v160, v163
	s_waitcnt lgkmcnt(0)
	v_add_f32_e32 v163, v163, v164
	v_mul_f32_e32 v164, v106, v106
	v_fmac_f32_e32 v164, v92, v92
	v_fmac_f32_e32 v164, v123, v123
	v_fmac_f32_e32 v164, v137, v137
	ds_bpermute_b32 v165, v0, v164
	v_fmamk_f32 v163, v163, 0x3c000000, v207
	v_rsq_f32_e32 v163, v163
	s_waitcnt lgkmcnt(0)
	v_add_f32_e32 v164, v164, v165
	ds_bpermute_b32 v165, v66, v164
	v_mul_f32_e32 v163, v221, v163
	s_waitcnt lgkmcnt(0)
	v_add_f32_e32 v164, v164, v165
	ds_bpermute_b32 v165, v67, v164
	s_waitcnt lgkmcnt(0)
	v_add_f32_e32 v164, v164, v165
	ds_bpermute_b32 v165, v159, v164
	s_waitcnt lgkmcnt(0)
	v_add_f32_e32 v164, v164, v165
	ds_bpermute_b32 v165, v160, v164
	s_waitcnt lgkmcnt(0)
	v_add_f32_e32 v164, v164, v165
	v_mul_f32_e32 v165, v108, v108
	v_fmac_f32_e32 v165, v93, v93
	v_fmac_f32_e32 v165, v127, v127
	v_fmac_f32_e32 v165, v151, v151
	ds_bpermute_b32 v166, v0, v165
	v_fmamk_f32 v164, v164, 0x3c000000, v207
	v_rsq_f32_e32 v164, v164
	s_waitcnt lgkmcnt(0)
	v_add_f32_e32 v165, v165, v166
	ds_bpermute_b32 v166, v66, v165
	v_mul_f32_e32 v164, v221, v164
	s_waitcnt lgkmcnt(0)
	v_add_f32_e32 v165, v165, v166
	ds_bpermute_b32 v166, v67, v165
	s_waitcnt lgkmcnt(0)
	v_add_f32_e32 v165, v165, v166
	ds_bpermute_b32 v166, v159, v165
	s_waitcnt lgkmcnt(0)
	v_add_f32_e32 v165, v165, v166
	ds_bpermute_b32 v166, v160, v165
	s_waitcnt lgkmcnt(0)
	v_add_f32_e32 v165, v165, v166
	v_fmamk_f32 v165, v165, 0x3c000000, v207
	v_rsq_f32_e32 v165, v165
	s_nop 0
	v_mul_f32_e32 v167, v221, v165
	v_mul_f32_e32 v165, v105, v105
	v_fmac_f32_e32 v165, v91, v91
	v_fmac_f32_e32 v165, v124, v124
	v_fmac_f32_e32 v165, v150, v150
	ds_bpermute_b32 v166, v0, v165
	s_waitcnt lgkmcnt(0)
	v_add_f32_e32 v165, v165, v166
	ds_bpermute_b32 v166, v66, v165
	s_waitcnt lgkmcnt(0)
	v_add_f32_e32 v165, v165, v166
	ds_bpermute_b32 v166, v67, v165
	s_waitcnt lgkmcnt(0)
	v_add_f32_e32 v165, v165, v166
	ds_bpermute_b32 v166, v159, v165
	s_waitcnt lgkmcnt(0)
	v_add_f32_e32 v165, v165, v166
	ds_bpermute_b32 v166, v160, v165
	s_waitcnt lgkmcnt(0)
	v_add_f32_e32 v165, v165, v166
	v_fmamk_f32 v165, v165, 0x3c000000, v207
	v_rsq_f32_e32 v165, v165
	s_nop 0
	v_mul_f32_e32 v166, v221, v165
	v_mul_f32_e32 v165, v102, v102
	v_fmac_f32_e32 v165, v90, v90
	v_fmac_f32_e32 v165, v121, v121
	v_fmac_f32_e32 v165, v149, v149
	ds_bpermute_b32 v168, v0, v165
	s_waitcnt lgkmcnt(0)
	v_add_f32_e32 v165, v165, v168
	ds_bpermute_b32 v168, v66, v165
	s_waitcnt lgkmcnt(0)
	v_add_f32_e32 v165, v165, v168
	ds_bpermute_b32 v168, v67, v165
	s_waitcnt lgkmcnt(0)
	v_add_f32_e32 v165, v165, v168
	ds_bpermute_b32 v168, v159, v165
	s_waitcnt lgkmcnt(0)
	v_add_f32_e32 v165, v165, v168
	ds_bpermute_b32 v168, v160, v165
	s_waitcnt lgkmcnt(0)
; __device__ __forceinline__ unsigned f2bf(float f) { unsigned u = __builtin_bit_cast(unsigned, f); return (u + 0x7fffu + ((u >> 16) & 1u)) >> 16; }
; __device__ __forceinline__ void attn_unit(int b, int h, int qb, const bf16_t* __restrict__ proj, const float* __restrict__ btab, float lam, float outscale,
;                                           const float* __restrict__ gain, float* o1scr, bf16_t* merged, LAS char* lds) {
;     ...
;                 ssq[r] = __builtin_amdgcn_rsqf(a2 * (1.0f / 128.0f) + EPS) * outscale; }
;             const int r32l = tl & 31, hil = (tl >> 5) & 1;
;             float gn[4];
; #pragma unroll
;             for (int d0 = 0; d0 < 4; ++d0) gn[d0] = gain[h * 128 + d0 * 32 + r32l];
;             bf16_t* Ow = merged + (rowbase + qw + 4 * hil) * D + h * 128 + r32l;
; #pragma unroll
;             for (int r = 0; r < 16; ++r) { bf16_t* orp = Ow + (long)((r & 3) + 8 * (r >> 2)) * D;
; #pragma unroll
;                 for (int d0 = 0; d0 < 4; ++d0) orp[d0 * 32] = (bf16_t)f2bf(o[d0][r] * ssq[r] * gn[d0]); }
	v_add_f32_e32 v165, v165, v168
	v_mul_f32_e32 v168, v99, v99
	v_fmac_f32_e32 v168, v89, v89
	v_fmac_f32_e32 v168, v119, v119
	v_fmac_f32_e32 v168, v68, v68
	ds_bpermute_b32 v0, v0, v168
	v_fmamk_f32 v165, v165, 0x3c000000, v207
	v_rsq_f32_e32 v165, v165
	s_waitcnt lgkmcnt(0)
	v_add_f32_e32 v0, v168, v0
	ds_bpermute_b32 v66, v66, v0
	v_mul_f32_e32 v165, v221, v165
	s_waitcnt lgkmcnt(0)
	v_add_f32_e32 v0, v0, v66
	ds_bpermute_b32 v66, v67, v0
	s_waitcnt lgkmcnt(0)
	v_add_f32_e32 v0, v0, v66
	ds_bpermute_b32 v66, v159, v0
	s_waitcnt lgkmcnt(0)
	v_add_f32_e32 v0, v0, v66
	ds_bpermute_b32 v66, v160, v0
	s_waitcnt lgkmcnt(0)
	v_add_f32_e32 v0, v0, v66
	v_fmamk_f32 v0, v0, 0x3c000000, v207
	v_rsq_f32_e32 v0, v0
	s_nop 0
	v_mul_f32_e32 v159, v221, v0
	v_or_b32_e32 v0, s48, v171
	v_lshlrev_b32_e32 v0, 2, v0
	v_lshl_add_u64 v[66:67], s[42:43], 0, v[0:1]
	global_load_dword v160, v[66:67], off
	global_load_dword v168, v[66:67], off offset:128
	global_load_dword v169, v[66:67], off offset:256
	global_load_dword v170, v[66:67], off offset:384
	v_lshrrev_b32_e32 v0, 3, v88
	v_and_or_b32 v66, v0, 4, s49
	v_mov_b32_e32 v67, s50
	v_lshlrev_b64 v[66:67], 12, v[66:67]
	v_lshl_add_u64 v[66:67], s[8:9], 0, v[66:67]
	v_lshlrev_b32_e32 v0, 1, v171
	v_lshl_add_u64 v[66:67], v[66:67], 0, v[0:1]
	v_mul_f32_e32 v0, v110, v69
	v_add_co_u32_e32 v172, vcc, s94, v66
	s_waitcnt vmcnt(0) lgkmcnt(0)
	v_mul_f32_e32 v0, v0, v160
	v_bfe_u32 v88, v0, 16, 1
	v_add3_u32 v0, v0, v88, s91
	global_store_short_d16_hi v[66:67], v0, off
	v_mul_f32_e32 v0, v122, v69
	v_mul_f32_e32 v0, v0, v168
	v_bfe_u32 v88, v0, 16, 1
	v_add3_u32 v0, v0, v88, s91
	global_store_short_d16_hi v[66:67], v0, off offset:64
	v_mul_f32_e32 v0, v136, v69
	v_mul_f32_e32 v0, v0, v169
	v_bfe_u32 v88, v0, 16, 1
	v_add3_u32 v0, v0, v88, s91
	global_store_short_d16_hi v[66:67], v0, off offset:128
	v_mul_f32_e32 v0, v148, v69
	v_mul_f32_e32 v0, v0, v170
	v_bfe_u32 v69, v0, 16, 1
	v_add3_u32 v0, v0, v69, s91
	global_store_short_d16_hi v[66:67], v0, off offset:192
	v_mul_f32_e32 v0, v107, v152
	v_mul_f32_e32 v0, v0, v160
	v_bfe_u32 v69, v0, 16, 1
	v_add3_u32 v0, v0, v69, s91
	v_addc_co_u32_e32 v173, vcc, 0, v67, vcc
	global_store_short_d16_hi v[172:173], v0, off
	v_mul_f32_e32 v0, v120, v152
	v_mul_f32_e32 v0, v0, v168
	v_bfe_u32 v69, v0, 16, 1
	v_add3_u32 v0, v0, v69, s91
	global_store_short_d16_hi v[172:173], v0, off offset:64
	v_mul_f32_e32 v0, v135, v152
	v_mul_f32_e32 v0, v0, v169
	v_bfe_u32 v69, v0, 16, 1
	v_add3_u32 v0, v0, v69, s91
	global_store_short_d16_hi v[172:173], v0, off offset:128
	v_mul_f32_e32 v0, v147, v152
	v_mul_f32_e32 v0, v0, v170
	v_bfe_u32 v69, v0, 16, 1
	v_add3_u32 v0, v0, v69, s91
	global_store_short_d16_hi v[172:173], v0, off offset:192
	v_mul_f32_e32 v0, v104, v153
	v_mul_f32_e32 v0, v0, v160
	v_bfe_u32 v69, v0, 16, 1
	v_add_co_u32_e32 v172, vcc, s17, v66
	v_add3_u32 v0, v0, v69, s91
	s_nop 0
	v_addc_co_u32_e32 v173, vcc, 0, v67, vcc
	global_store_short_d16_hi v[172:173], v0, off
	v_mul_f32_e32 v0, v118, v153
	v_mul_f32_e32 v0, v0, v168
	v_bfe_u32 v69, v0, 16, 1
	v_add3_u32 v0, v0, v69, s91
	global_store_short_d16_hi v[172:173], v0, off offset:64
	v_mul_f32_e32 v0, v134, v153
	v_mul_f32_e32 v0, v0, v169
	v_bfe_u32 v69, v0, 16, 1
	v_add3_u32 v0, v0, v69, s91
	global_store_short_d16_hi v[172:173], v0, off offset:128
	v_mul_f32_e32 v0, v145, v153
	v_mul_f32_e32 v0, v0, v170
	v_bfe_u32 v69, v0, 16, 1
	v_add3_u32 v0, v0, v69, s91
	global_store_short_d16_hi v[172:173], v0, off offset:192
	v_mul_f32_e32 v0, v101, v154
	v_mul_f32_e32 v0, v0, v160
	v_bfe_u32 v69, v0, 16, 1
	v_add_co_u32_e32 v134, vcc, s59, v66
	v_add3_u32 v0, v0, v69, s91
	s_nop 0
	v_addc_co_u32_e32 v135, vcc, 0, v67, vcc
	global_store_short_d16_hi v[134:135], v0, off
	v_mul_f32_e32 v0, v116, v154
	v_mul_f32_e32 v0, v0, v168
	v_bfe_u32 v69, v0, 16, 1
	v_add3_u32 v0, v0, v69, s91
	global_store_short_d16_hi v[134:135], v0, off offset:64
	v_mul_f32_e32 v0, v132, v154
	v_mul_f32_e32 v0, v0, v169
	v_bfe_u32 v69, v0, 16, 1
	v_add3_u32 v0, v0, v69, s91
	global_store_short_d16_hi v[134:135], v0, off offset:128
	v_mul_f32_e32 v0, v142, v154
	v_mul_f32_e32 v0, v0, v170
	v_bfe_u32 v69, v0, 16, 1
	v_add3_u32 v0, v0, v69, s91
	global_store_short_d16_hi v[134:135], v0, off offset:192
	v_mul_f32_e32 v0, v103, v155
	v_mul_f32_e32 v0, v0, v160
	v_bfe_u32 v69, v0, 16, 1
	v_add_co_u32_e32 v134, vcc, s0, v66
	v_add3_u32 v0, v0, v69, s91
	s_nop 0
	v_addc_co_u32_e32 v135, vcc, 0, v67, vcc
	global_store_short_d16_hi v[134:135], v0, off
	v_mul_f32_e32 v0, v117, v155
	v_mul_f32_e32 v0, v0, v168
	v_bfe_u32 v69, v0, 16, 1
	v_add3_u32 v0, v0, v69, s91
	global_store_short_d16_hi v[134:135], v0, off offset:64
	v_mul_f32_e32 v0, v133, v155
	v_mul_f32_e32 v0, v0, v169
	v_bfe_u32 v69, v0, 16, 1
	v_add3_u32 v0, v0, v69, s91
	global_store_short_d16_hi v[134:135], v0, off offset:128
	v_mul_f32_e32 v0, v146, v155
	v_mul_f32_e32 v0, v0, v170
	v_bfe_u32 v69, v0, 16, 1
	v_add3_u32 v0, v0, v69, s91
	global_store_short_d16_hi v[134:135], v0, off offset:192
	v_mul_f32_e32 v0, v100, v156
	v_mul_f32_e32 v0, v0, v160
	s_mov_b32 s0, 0x9000
	v_bfe_u32 v69, v0, 16, 1
	v_add_co_u32_e32 v100, vcc, s0, v66
	v_add3_u32 v0, v0, v69, s91
	s_nop 0
	v_addc_co_u32_e32 v101, vcc, 0, v67, vcc
	global_store_short_d16_hi v[100:101], v0, off
	v_mul_f32_e32 v0, v115, v156
	v_mul_f32_e32 v0, v0, v168
	v_bfe_u32 v69, v0, 16, 1
	v_add3_u32 v0, v0, v69, s91
	global_store_short_d16_hi v[100:101], v0, off offset:64
	v_mul_f32_e32 v0, v131, v156
	v_mul_f32_e32 v0, v0, v169
	v_bfe_u32 v69, v0, 16, 1
	v_add3_u32 v0, v0, v69, s91
	global_store_short_d16_hi v[100:101], v0, off offset:128
; __device__ __forceinline__ unsigned f2bf(float f) { unsigned u = __builtin_bit_cast(unsigned, f); return (u + 0x7fffu + ((u >> 16) & 1u)) >> 16; }
; __device__ __forceinline__ void attn_unit(int b, int h, int qb, const bf16_t* __restrict__ proj, const float* __restrict__ btab, float lam, float outscale,
;                                           const float* __restrict__ gain, float* o1scr, bf16_t* merged, LAS char* lds) {
;     ...
;             for (int r = 0; r < 16; ++r) { bf16_t* orp = Ow + (long)((r & 3) + 8 * (r >> 2)) * D;
; #pragma unroll
;                 for (int d0 = 0; d0 < 4; ++d0) orp[d0 * 32] = (bf16_t)f2bf(o[d0][r] * ssq[r] * gn[d0]); }
	v_mul_f32_e32 v0, v144, v156
	v_mul_f32_e32 v0, v0, v170
	v_bfe_u32 v69, v0, 16, 1
	v_add3_u32 v0, v0, v69, s91
	global_store_short_d16_hi v[100:101], v0, off offset:192
	v_mul_f32_e32 v0, v98, v157
	v_mul_f32_e32 v0, v0, v160
	s_mov_b32 s0, 0xa000
	v_bfe_u32 v69, v0, 16, 1
	v_add_co_u32_e32 v100, vcc, s0, v66
	v_add3_u32 v0, v0, v69, s91
	s_nop 0
	v_addc_co_u32_e32 v101, vcc, 0, v67, vcc
	global_store_short_d16_hi v[100:101], v0, off
	v_mul_f32_e32 v0, v114, v157
	v_mul_f32_e32 v0, v0, v168
	v_bfe_u32 v69, v0, 16, 1
	v_add3_u32 v0, v0, v69, s91
	global_store_short_d16_hi v[100:101], v0, off offset:64
	v_mul_f32_e32 v0, v129, v157
	v_mul_f32_e32 v0, v0, v169
	v_bfe_u32 v69, v0, 16, 1
	v_add3_u32 v0, v0, v69, s91
	global_store_short_d16_hi v[100:101], v0, off offset:128
	v_mul_f32_e32 v0, v141, v157
	v_mul_f32_e32 v0, v0, v170
	v_bfe_u32 v69, v0, 16, 1
	v_add3_u32 v0, v0, v69, s91
	global_store_short_d16_hi v[100:101], v0, off offset:192
	v_mul_f32_e32 v0, v96, v158
	v_mul_f32_e32 v0, v0, v160
	v_bfe_u32 v69, v0, 16, 1
	v_add_co_u32_e32 v100, vcc, s55, v66
	v_add3_u32 v0, v0, v69, s91
	s_nop 0
	v_addc_co_u32_e32 v101, vcc, 0, v67, vcc
	global_store_short_d16_hi v[100:101], v0, off
	v_mul_f32_e32 v0, v112, v158
	v_mul_f32_e32 v0, v0, v168
	v_bfe_u32 v69, v0, 16, 1
	v_add3_u32 v0, v0, v69, s91
	global_store_short_d16_hi v[100:101], v0, off offset:64
	v_mul_f32_e32 v0, v126, v158
	v_mul_f32_e32 v0, v0, v169
	v_bfe_u32 v69, v0, 16, 1
	v_add3_u32 v0, v0, v69, s91
	global_store_short_d16_hi v[100:101], v0, off offset:128
	v_mul_f32_e32 v0, v139, v158
	v_mul_f32_e32 v0, v0, v170
	v_bfe_u32 v69, v0, 16, 1
	v_add3_u32 v0, v0, v69, s91
	global_store_short_d16_hi v[100:101], v0, off offset:192
	v_mul_f32_e32 v0, v97, v161
	v_mul_f32_e32 v0, v0, v160
	s_mov_b32 s0, 0x10000
	v_bfe_u32 v69, v0, 16, 1
	v_add_co_u32_e32 v96, vcc, s0, v66
	v_add3_u32 v0, v0, v69, s91
	s_nop 0
	v_addc_co_u32_e32 v97, vcc, 0, v67, vcc
	global_store_short_d16_hi v[96:97], v0, off
	v_mul_f32_e32 v0, v113, v161
	v_mul_f32_e32 v0, v0, v168
	v_bfe_u32 v69, v0, 16, 1
	v_add3_u32 v0, v0, v69, s91
	global_store_short_d16_hi v[96:97], v0, off offset:64
	v_mul_f32_e32 v0, v130, v161
	v_mul_f32_e32 v0, v0, v169
	v_bfe_u32 v69, v0, 16, 1
	v_add3_u32 v0, v0, v69, s91
	global_store_short_d16_hi v[96:97], v0, off offset:128
	v_mul_f32_e32 v0, v143, v161
	v_mul_f32_e32 v0, v0, v170
	v_bfe_u32 v69, v0, 16, 1
	v_add3_u32 v0, v0, v69, s91
	global_store_short_d16_hi v[96:97], v0, off offset:192
	v_mul_f32_e32 v0, v95, v162
	v_mul_f32_e32 v0, v0, v160
	s_mov_b32 s0, 0x11000
	v_bfe_u32 v69, v0, 16, 1
	v_add_co_u32_e32 v96, vcc, s0, v66
	v_add3_u32 v0, v0, v69, s91
	s_nop 0
	v_addc_co_u32_e32 v97, vcc, 0, v67, vcc
	global_store_short_d16_hi v[96:97], v0, off
	v_mul_f32_e32 v0, v111, v162
	v_mul_f32_e32 v0, v0, v168
	v_bfe_u32 v69, v0, 16, 1
	v_add3_u32 v0, v0, v69, s91
	global_store_short_d16_hi v[96:97], v0, off offset:64
	v_mul_f32_e32 v0, v128, v162
	v_mul_f32_e32 v0, v0, v169
	v_bfe_u32 v69, v0, 16, 1
	v_add3_u32 v0, v0, v69, s91
	global_store_short_d16_hi v[96:97], v0, off offset:128
	v_mul_f32_e32 v0, v140, v162
	v_mul_f32_e32 v0, v0, v170
	v_bfe_u32 v69, v0, 16, 1
	v_add3_u32 v0, v0, v69, s91
	global_store_short_d16_hi v[96:97], v0, off offset:192
	v_mul_f32_e32 v0, v94, v163
	v_mul_f32_e32 v0, v0, v160
	s_mov_b32 s0, 0x12000
	v_bfe_u32 v69, v0, 16, 1
	v_add_co_u32_e32 v94, vcc, s0, v66
	v_add3_u32 v0, v0, v69, s91
	s_nop 0
	v_addc_co_u32_e32 v95, vcc, 0, v67, vcc
	global_store_short_d16_hi v[94:95], v0, off
	v_mul_f32_e32 v0, v109, v163
	v_mul_f32_e32 v0, v0, v168
	v_bfe_u32 v69, v0, 16, 1
	v_add3_u32 v0, v0, v69, s91
	global_store_short_d16_hi v[94:95], v0, off offset:64
	v_mul_f32_e32 v0, v125, v163
	v_mul_f32_e32 v0, v0, v169
	v_bfe_u32 v69, v0, 16, 1
	v_add3_u32 v0, v0, v69, s91
	global_store_short_d16_hi v[94:95], v0, off offset:128
	v_mul_f32_e32 v0, v138, v163
	v_mul_f32_e32 v0, v0, v170
	v_bfe_u32 v69, v0, 16, 1
	v_add3_u32 v0, v0, v69, s91
	global_store_short_d16_hi v[94:95], v0, off offset:192
	v_mul_f32_e32 v0, v92, v164
	v_mul_f32_e32 v0, v0, v160
	s_mov_b32 s0, 0x13000
	v_bfe_u32 v69, v0, 16, 1
	v_add_co_u32_e32 v94, vcc, s0, v66
	v_add3_u32 v0, v0, v69, s91
	s_nop 0
	v_addc_co_u32_e32 v95, vcc, 0, v67, vcc
	global_store_short_d16_hi v[94:95], v0, off
	v_mul_f32_e32 v0, v106, v164
	v_mul_f32_e32 v0, v0, v168
	v_bfe_u32 v69, v0, 16, 1
	v_add3_u32 v0, v0, v69, s91
	global_store_short_d16_hi v[94:95], v0, off offset:64
	v_mul_f32_e32 v0, v123, v164
	v_mul_f32_e32 v0, v0, v169
	v_bfe_u32 v69, v0, 16, 1
	v_add3_u32 v0, v0, v69, s91
	global_store_short_d16_hi v[94:95], v0, off offset:128
	v_mul_f32_e32 v0, v137, v164
	v_mul_f32_e32 v0, v0, v170
	v_bfe_u32 v69, v0, 16, 1
	v_add3_u32 v0, v0, v69, s91
	global_store_short_d16_hi v[94:95], v0, off offset:192
	v_mul_f32_e32 v0, v93, v167
	v_mul_f32_e32 v0, v0, v160
	s_mov_b32 s0, 0x18000
	v_bfe_u32 v69, v0, 16, 1
	v_add_co_u32_e32 v92, vcc, s0, v66
	v_add3_u32 v0, v0, v69, s91
	s_nop 0
	v_addc_co_u32_e32 v93, vcc, 0, v67, vcc
	global_store_short_d16_hi v[92:93], v0, off
	v_mul_f32_e32 v0, v108, v167
; __device__ __forceinline__ unsigned f2bf(float f) { unsigned u = __builtin_bit_cast(unsigned, f); return (u + 0x7fffu + ((u >> 16) & 1u)) >> 16; }
; __device__ __forceinline__ void attn_unit(int b, int h, int qb, const bf16_t* __restrict__ proj, const float* __restrict__ btab, float lam, float outscale,
;                                           const float* __restrict__ gain, float* o1scr, bf16_t* merged, LAS char* lds) {
;     ...
; #pragma unroll
;             for (int d0 = 0; d0 < 4; ++d0)
; #pragma unroll
;                 for (int r4 = 0; r4 < 4; ++r4)
;                     o1p[d0 * 4 + r4] = (f32x4){o[d0][4 * r4] * rli[4 * r4], o[d0][4 * r4 + 1] * rli[4 * r4 + 1], o[d0][4 * r4 + 2] * rli[4 * r4 + 2], o[d0][4 * r4 + 3] * rli[4 * r4 + 3]};
;     ...
;             for (int r = 0; r < 16; ++r) { bf16_t* orp = Ow + (long)((r & 3) + 8 * (r >> 2)) * D;
; #pragma unroll
;                 for (int d0 = 0; d0 < 4; ++d0) orp[d0 * 32] = (bf16_t)f2bf(o[d0][r] * ssq[r] * gn[d0]); }
	v_mul_f32_e32 v0, v0, v168
	v_bfe_u32 v69, v0, 16, 1
	v_add3_u32 v0, v0, v69, s91
	global_store_short_d16_hi v[92:93], v0, off offset:64
	v_mul_f32_e32 v0, v127, v167
	v_mul_f32_e32 v0, v0, v169
	v_bfe_u32 v69, v0, 16, 1
	v_add3_u32 v0, v0, v69, s91
	global_store_short_d16_hi v[92:93], v0, off offset:128
	v_mul_f32_e32 v0, v151, v167
	v_mul_f32_e32 v0, v0, v170
	v_bfe_u32 v69, v0, 16, 1
	v_add3_u32 v0, v0, v69, s91
	global_store_short_d16_hi v[92:93], v0, off offset:192
	v_mul_f32_e32 v0, v91, v166
	v_mul_f32_e32 v0, v0, v160
	s_mov_b32 s0, 0x19000
	v_bfe_u32 v69, v0, 16, 1
	v_add_co_u32_e32 v92, vcc, s0, v66
	v_add3_u32 v0, v0, v69, s91
	s_nop 0
	v_addc_co_u32_e32 v93, vcc, 0, v67, vcc
	global_store_short_d16_hi v[92:93], v0, off
	v_mul_f32_e32 v0, v105, v166
	v_mul_f32_e32 v0, v0, v168
	v_bfe_u32 v69, v0, 16, 1
	v_add3_u32 v0, v0, v69, s91
	global_store_short_d16_hi v[92:93], v0, off offset:64
	v_mul_f32_e32 v0, v124, v166
	v_mul_f32_e32 v0, v0, v169
	v_bfe_u32 v69, v0, 16, 1
	v_add3_u32 v0, v0, v69, s91
	global_store_short_d16_hi v[92:93], v0, off offset:128
	v_mul_f32_e32 v0, v150, v166
	v_mul_f32_e32 v0, v0, v170
	v_bfe_u32 v69, v0, 16, 1
	v_add3_u32 v0, v0, v69, s91
	global_store_short_d16_hi v[92:93], v0, off offset:192
	v_mul_f32_e32 v0, v90, v165
	v_mul_f32_e32 v0, v160, v0
	s_mov_b32 s0, 0x1a000
	v_bfe_u32 v69, v0, 16, 1
	v_add_co_u32_e32 v90, vcc, s0, v66
	v_add3_u32 v0, v0, v69, s91
	s_nop 0
	v_addc_co_u32_e32 v91, vcc, 0, v67, vcc
	global_store_short_d16_hi v[90:91], v0, off
	v_mul_f32_e32 v0, v102, v165
	v_mul_f32_e32 v0, v0, v168
	v_bfe_u32 v69, v0, 16, 1
	v_add3_u32 v0, v0, v69, s91
	global_store_short_d16_hi v[90:91], v0, off offset:64
	v_mul_f32_e32 v0, v121, v165
	v_mul_f32_e32 v0, v0, v169
	v_bfe_u32 v69, v0, 16, 1
	v_add3_u32 v0, v0, v69, s91
	global_store_short_d16_hi v[90:91], v0, off offset:128
	v_mul_f32_e32 v0, v149, v165
	v_mul_f32_e32 v0, v0, v170
	v_bfe_u32 v69, v0, 16, 1
	v_add3_u32 v0, v0, v69, s91
	global_store_short_d16_hi v[90:91], v0, off offset:192
	v_mul_f32_e32 v0, v89, v159
	v_mul_f32_e32 v0, v160, v0
	s_mov_b32 s0, 0x1b000
	v_bfe_u32 v69, v0, 16, 1
	v_add_co_u32_e32 v66, vcc, s0, v66
	v_add3_u32 v0, v0, v69, s91
	s_nop 0
	v_addc_co_u32_e32 v67, vcc, 0, v67, vcc
	global_store_short_d16_hi v[66:67], v0, off
	v_mul_f32_e32 v0, v99, v159
	v_mul_f32_e32 v0, v168, v0
	v_bfe_u32 v69, v0, 16, 1
	v_add3_u32 v0, v0, v69, s91
	global_store_short_d16_hi v[66:67], v0, off offset:64
	v_mul_f32_e32 v0, v119, v159
	v_mul_f32_e32 v0, v169, v0
	v_bfe_u32 v69, v0, 16, 1
	v_add3_u32 v0, v0, v69, s91
	global_store_short_d16_hi v[66:67], v0, off offset:128
	v_mul_f32_e32 v0, v68, v159
	v_mul_f32_e32 v0, v170, v0
	v_bfe_u32 v68, v0, 16, 1
	v_add3_u32 v0, v0, v68, s91
	global_store_short_d16_hi v[66:67], v0, off offset:192
	s_cbranch_execnz .LBB0_186
.LBB0_223:
	v_pk_mul_f32 v[50:51], v[50:51], v[86:87]
	v_pk_mul_f32 v[52:53], v[52:53], v[84:85]
	v_pk_mul_f32 v[34:35], v[34:35], v[86:87]
	v_pk_mul_f32 v[36:37], v[36:37], v[84:85]
	v_pk_mul_f32 v[18:19], v[18:19], v[86:87]
	v_pk_mul_f32 v[20:21], v[20:21], v[84:85]
	v_pk_mul_f32 v[2:3], v[2:3], v[86:87]
	v_pk_mul_f32 v[4:5], v[4:5], v[84:85]
	global_store_dwordx4 v[74:75], v[50:53], off
	global_store_dwordx4 v[74:75], v[34:37], off offset:64
	global_store_dwordx4 v[74:75], v[18:21], off offset:128
	v_pk_mul_f32 v[50:51], v[54:55], v[76:77]
	v_pk_mul_f32 v[52:53], v[56:57], v[82:83]
	v_pk_mul_f32 v[34:35], v[38:39], v[76:77]
	v_pk_mul_f32 v[36:37], v[40:41], v[82:83]
	v_pk_mul_f32 v[18:19], v[22:23], v[76:77]
	v_pk_mul_f32 v[20:21], v[24:25], v[82:83]
	global_store_dwordx4 v[74:75], v[2:5], off offset:192
	global_store_dwordx4 v[74:75], v[50:53], off offset:16
	global_store_dwordx4 v[74:75], v[34:37], off offset:80
	v_pk_mul_f32 v[2:3], v[6:7], v[76:77]
	v_pk_mul_f32 v[4:5], v[8:9], v[82:83]
	v_pk_mul_f32 v[50:51], v[58:59], v[80:81]
	v_pk_mul_f32 v[52:53], v[60:61], v[78:79]
	v_pk_mul_f32 v[34:35], v[42:43], v[80:81]
	v_pk_mul_f32 v[36:37], v[44:45], v[78:79]
	global_store_dwordx4 v[74:75], v[18:21], off offset:144
	global_store_dwordx4 v[74:75], v[2:5], off offset:208
	global_store_dwordx4 v[74:75], v[50:53], off offset:32
	v_pk_mul_f32 v[18:19], v[26:27], v[80:81]
	v_pk_mul_f32 v[20:21], v[28:29], v[78:79]
	v_pk_mul_f32 v[2:3], v[10:11], v[80:81]
	v_pk_mul_f32 v[4:5], v[12:13], v[78:79]
	v_pk_mul_f32 v[50:51], v[62:63], v[72:73]
	v_pk_mul_f32 v[52:53], v[64:65], v[70:71]
	global_store_dwordx4 v[74:75], v[34:37], off offset:96
	global_store_dwordx4 v[74:75], v[18:21], off offset:160
	global_store_dwordx4 v[74:75], v[2:5], off offset:224
	v_pk_mul_f32 v[34:35], v[46:47], v[72:73]
	v_pk_mul_f32 v[36:37], v[48:49], v[70:71]
	v_pk_mul_f32 v[18:19], v[30:31], v[72:73]
	v_pk_mul_f32 v[20:21], v[32:33], v[70:71]
	v_pk_mul_f32 v[2:3], v[14:15], v[72:73]
	v_pk_mul_f32 v[4:5], v[16:17], v[70:71]
	global_store_dwordx4 v[74:75], v[50:53], off offset:48
	global_store_dwordx4 v[74:75], v[34:37], off offset:112
	global_store_dwordx4 v[74:75], v[18:21], off offset:176
	global_store_dwordx4 v[74:75], v[2:5], off offset:240
	s_branch .LBB0_186

; #define LAS __attribute__((address_space(3)))
; __device__ __forceinline__ int otid() { int t = threadIdx.x; asm volatile("" : "+v"(t)); return t; }
; __device__ __forceinline__ void inproj_strip(const bf16_t* __restrict__ xb, const bf16_t* __restrict__ wt, const u64_t* ss, bf16_t* proj, int G, int bx, LAS unsigned char* lds) {
;     const int tid = otid(), wid = tid >> 6, lane = tid & 63, r32 = lane & 31, hi = lane >> 5;
;     LAS float* red = (LAS float*)lds;
;     for (int rb = bx; rb < M / 32; rb += G) {
;         const bf16_t* ap = xb + (size_t)(rb * 32 + r32) * D + wid * 256 + hi * 8;
;         const bf16_t* bp = wt + (size_t)(GAF + r32) * D + wid * 256 + hi * 8;
;         f32x16 acc = f32x16{};
; #pragma unroll
;         for (int ks = 0; ks < 16; ++ks) { const bf16x8 av = *(const bf16x8*)(ap + ks * 16), bv = *(const bf16x8*)(bp + ks * 16);
.LBB0_225:
	s_andn2_b64 vcc, exec, s[0:1]
	s_cbranch_vccnz .LBB0_248
	v_readlane_b32 s0, v254, 47
	v_readlane_b32 s1, v254, 48
	v_mov_b32_e32 v83, v206
	s_andn2_b64 vcc, exec, s[0:1]
	s_cbranch_vccnz .LBB0_232
	v_ashrrev_i32_e32 v9, 6, v83
	v_and_b32_e32 v82, 31, v83
	v_lshlrev_b32_e32 v2, 8, v9
	v_readlane_b32 s0, v254, 38
	s_waitcnt lgkmcnt(0)
	v_ashrrev_i32_e32 v3, 31, v2
	v_lshlrev_b32_e32 v4, 12, v82
	v_mov_b32_e32 v5, v1
	v_readlane_b32 s1, v254, 39
	v_bfe_u32 v8, v83, 5, 1
	v_lshlrev_b64 v[2:3], 1, v[2:3]
	v_lshl_add_u64 v[4:5], s[0:1], 0, v[4:5]
	v_lshlrev_b32_e32 v0, 4, v8
	v_lshl_add_u64 v[4:5], v[4:5], 0, v[2:3]
	v_lshl_add_u64 v[4:5], v[4:5], 0, v[0:1]
	s_mov_b64 s[0:1], 0x1800000
	v_lshl_add_u64 v[6:7], v[4:5], 0, s[0:1]
	s_mov_b32 s0, 0x1800000
	v_add_co_u32_e32 v4, vcc, s0, v4
	global_load_dwordx4 v[18:21], v[6:7], off offset:416
	global_load_dwordx4 v[22:25], v[6:7], off offset:448
	v_addc_co_u32_e32 v5, vcc, 0, v5, vcc
	global_load_dwordx4 v[26:29], v[6:7], off offset:480
	global_load_dwordx4 v[30:33], v[4:5], off
	global_load_dwordx4 v[34:37], v[6:7], off offset:32
	global_load_dwordx4 v[38:41], v[6:7], off offset:64
	s_waitcnt vmcnt(0)
	global_load_dwordx4 v[42:45], v[6:7], off offset:96
	global_load_dwordx4 v[46:49], v[6:7], off offset:128
	global_load_dwordx4 v[50:53], v[6:7], off offset:160
	global_load_dwordx4 v[54:57], v[6:7], off offset:192
	global_load_dwordx4 v[58:61], v[6:7], off offset:224
	global_load_dwordx4 v[62:65], v[6:7], off offset:256
	global_load_dwordx4 v[66:69], v[6:7], off offset:288
	global_load_dwordx4 v[70:73], v[6:7], off offset:320
	global_load_dwordx4 v[74:77], v[6:7], off offset:352
	global_load_dwordx4 v[78:81], v[6:7], off offset:384
	v_lshl_add_u64 v[2:3], s[20:21], 0, v[2:3]
	v_lshl_add_u64 v[84:85], v[2:3], 0, v[0:1]
	v_lshlrev_b32_e32 v0, 5, v9
	v_lshl_or_b32 v0, v8, 2, v0
	v_lshl_add_u32 v86, v82, 2, 0
	s_movk_i32 s0, 0x400
	v_mul_lo_u32 v0, v0, s93
	v_cmp_gt_i32_e64 s[0:1], s0, v83
	v_add_u32_e32 v87, v86, v0
	v_lshlrev_b32_e32 v0, 1, v82
	s_mov_b32 s6, s18
	s_branch .LBB0_229

; __device__ __forceinline__ unsigned f2bf(float f) { unsigned u = __builtin_bit_cast(unsigned, f); return (u + 0x7fffu + ((u >> 16) & 1u)) >> 16; }
; __device__ __forceinline__ float ss_rstd(const u64_t* ss, int row) { return __builtin_amdgcn_rsqf((float)ss[row] * (SS_IFX / (float)2048) + 1e-6f); }
; __device__ __forceinline__ void inproj_strip(const bf16_t* __restrict__ xb, const bf16_t* __restrict__ wt, const u64_t* ss, bf16_t* proj, int G, int bx, LAS unsigned char* lds) {
;     ...
;     for (int rb = bx; rb < M / 32; rb += G) {
;         const bf16_t* ap = xb + (size_t)(rb * 32 + r32) * D + wid * 256 + hi * 8;
;         const bf16_t* bp = wt + (size_t)(GAF + r32) * D + wid * 256 + hi * 8;
;         f32x16 acc = f32x16{};
; #pragma unroll
;         for (int ks = 0; ks < 16; ++ks) { const bf16x8 av = *(const bf16x8*)(ap + ks * 16), bv = *(const bf16x8*)(bp + ks * 16);
;             acc = __builtin_amdgcn_mfma_f32_32x32x16_bf16(av, bv, acc, 0, 0, 0); }
;         __syncthreads();
; #pragma unroll
;         for (int r = 0; r < 16; ++r) red[(wid * 32 + ((r & 3) + 8 * (r >> 2) + 4 * hi)) * 33 + r32] = acc[r];
;         __syncthreads();
;         for (int o = tid; o < 1024; o += NTHR) { const int row = o >> 5, col = o & 31; float v = 0.f;
; #pragma unroll
;             for (int w = 0; w < 8; ++w) v += red[(w * 32 + row) * 33 + col];
;             proj[(size_t)(rb * 32 + row) * INP + GAF + col] = (bf16_t)f2bf(v * ss_rstd(ss, rb * 32 + row)); }
.LBB0_229:
	s_lshl_b32 s7, s6, 5
	v_or_b32_e32 v2, s7, v82
	v_ashrrev_i32_e32 v3, 31, v2
	v_lshlrev_b64 v[2:3], 12, v[2:3]
	v_lshl_add_u64 v[92:93], v[84:85], 0, v[2:3]
	global_load_dwordx4 v[2:5], v[92:93], off
	global_load_dwordx4 v[88:91], v[92:93], off offset:32
	global_load_dwordx4 v[100:103], v[92:93], off offset:64
	global_load_dwordx4 v[104:107], v[92:93], off offset:96
	global_load_dwordx4 v[108:111], v[92:93], off offset:128
	global_load_dwordx4 v[112:115], v[92:93], off offset:160
	global_load_dwordx4 v[116:119], v[92:93], off offset:192
	global_load_dwordx4 v[120:123], v[92:93], off offset:224
	global_load_dwordx4 v[124:127], v[92:93], off offset:256
	global_load_dwordx4 v[128:131], v[92:93], off offset:288
	global_load_dwordx4 v[132:135], v[92:93], off offset:320
	global_load_dwordx4 v[136:139], v[92:93], off offset:352
	global_load_dwordx4 v[140:143], v[92:93], off offset:384
	global_load_dwordx4 v[144:147], v[92:93], off offset:416
	global_load_dwordx4 v[148:151], v[92:93], off offset:448
	global_load_dwordx4 v[152:155], v[92:93], off offset:480
	v_add_u32_e32 v94, 0xc00, v87
	s_waitcnt vmcnt(0) lgkmcnt(0)
	v_mfma_f32_32x32x16_bf16 v[2:17], v[2:5], v[30:33], 0
	v_mfma_f32_32x32x16_bf16 v[2:17], v[88:91], v[34:37], v[2:17]
	v_mfma_f32_32x32x16_bf16 v[2:17], v[100:103], v[38:41], v[2:17]
	v_mfma_f32_32x32x16_bf16 v[2:17], v[104:107], v[42:45], v[2:17]
	v_mfma_f32_32x32x16_bf16 v[2:17], v[108:111], v[46:49], v[2:17]
	v_mfma_f32_32x32x16_bf16 v[2:17], v[112:115], v[50:53], v[2:17]
	v_mfma_f32_32x32x16_bf16 v[2:17], v[116:119], v[54:57], v[2:17]
	v_mfma_f32_32x32x16_bf16 v[2:17], v[120:123], v[58:61], v[2:17]
	v_mfma_f32_32x32x16_bf16 v[2:17], v[124:127], v[62:65], v[2:17]
	v_mfma_f32_32x32x16_bf16 v[2:17], v[128:131], v[66:69], v[2:17]
	v_mfma_f32_32x32x16_bf16 v[2:17], v[132:135], v[70:73], v[2:17]
	v_mfma_f32_32x32x16_bf16 v[2:17], v[136:139], v[74:77], v[2:17]
	v_mfma_f32_32x32x16_bf16 v[2:17], v[140:143], v[78:81], v[2:17]
	v_mfma_f32_32x32x16_bf16 v[2:17], v[144:147], v[18:21], v[2:17]
	v_mfma_f32_32x32x16_bf16 v[2:17], v[148:151], v[22:25], v[2:17]
	v_add_u32_e32 v92, 0x400, v87
	v_add_u32_e32 v93, 0x800, v87
	s_waitcnt lgkmcnt(0)
	s_barrier
	s_waitcnt vmcnt(0)
	v_mfma_f32_32x32x16_bf16 v[2:17], v[152:155], v[26:29], v[2:17]
	s_nop 11
	ds_write2_b32 v87, v2, v3 offset1:33
	ds_write2_b32 v87, v4, v5 offset0:66 offset1:99
	ds_write2_b32 v92, v6, v7 offset0:8 offset1:41
	ds_write2_b32 v92, v8, v9 offset0:74 offset1:107
	ds_write2_b32 v93, v10, v11 offset0:16 offset1:49
	ds_write2_b32 v93, v12, v13 offset0:82 offset1:115
	ds_write2_b32 v94, v14, v15 offset0:24 offset1:57
	ds_write2_b32 v94, v16, v17 offset0:90 offset1:123
	s_waitcnt lgkmcnt(0)
	s_barrier
	s_and_saveexec_b64 s[2:3], s[0:1]
	s_cbranch_execz .LBB0_228
	s_mov_b64 s[4:5], 0
	v_mov_b32_e32 v2, v83
.LBB0_231:
	v_ashrrev_i32_e32 v3, 5, v2
	v_add_u32_e32 v4, s7, v3
	v_ashrrev_i32_e32 v5, 31, v4
	v_lshl_add_u64 v[6:7], v[4:5], 3, s[84:85]
	global_load_dwordx2 v[6:7], v[6:7], off
	v_mov_b64_e32 v[8:9], s[22:23]
	v_add_u32_e32 v5, 0x200, v2
	s_movk_i32 s8, 0x1ff
	v_cmp_lt_i32_e32 vcc, s8, v2
	v_mov_b32_e32 v2, v5
	v_mad_i64_i32 v[4:5], s[8:9], v4, s79, v[8:9]
	v_mad_u64_u32 v[10:11], s[8:9], v3, s93, v[86:87]
	ds_read_b32 v3, v10
	ds_read_b32 v11, v10 offset:4224
	ds_read_b32 v12, v10 offset:8448
	ds_read_b32 v13, v10 offset:12672
	ds_read_b32 v14, v10 offset:16896
	ds_read_b32 v15, v10 offset:21120
	ds_read_b32 v16, v10 offset:25344
	ds_read_b32 v10, v10 offset:29568
	s_waitcnt lgkmcnt(0)
	v_add_f32_e32 v3, 0, v3
	v_add_f32_e32 v3, v3, v11
	v_add_f32_e32 v3, v3, v12
	v_add_f32_e32 v3, v3, v13
	v_add_f32_e32 v3, v3, v14
	v_add_f32_e32 v3, v3, v15
	v_add_f32_e32 v3, v3, v16
	v_add_f32_e32 v3, v3, v10
	v_lshl_add_u64 v[4:5], v[4:5], 0, v[0:1]
	s_or_b64 s[4:5], vcc, s[4:5]
	v_add_co_u32_e32 v4, vcc, 0x3000, v4
	s_waitcnt vmcnt(0)
	v_ffbh_u32_e32 v8, v7
	v_min_u32_e32 v8, 32, v8
	v_lshlrev_b64 v[6:7], v8, v[6:7]
	v_min_u32_e32 v6, 1, v6
	v_or_b32_e32 v6, v7, v6
	v_cvt_f32_u32_e32 v6, v6
	v_sub_u32_e32 v7, 32, v8
	v_addc_co_u32_e32 v5, vcc, 0, v5, vcc
	v_ldexp_f32 v6, v6, v7
	v_fmamk_f32 v6, v6, 0x2e000000, v207
	v_rsq_f32_e32 v6, v6
	s_nop 0
	v_mul_f32_e32 v3, v3, v6
	v_bfe_u32 v6, v3, 16, 1
	v_add3_u32 v3, v3, v6, s91
	global_store_short_d16_hi v[4:5], v3, off
	s_andn2_b64 exec, exec, s[4:5]
	s_cbranch_execnz .LBB0_231
	s_branch .LBB0_228

; __device__ __forceinline__ unsigned cvt_pk_bf16(float lo, float hi) { unsigned r; asm volatile("v_cvt_pk_bf16_f32 %0, %1, %2" : "=v"(r) : "v"(lo), "v"(hi)); return r; }
; __device__ __forceinline__ float ss_rstd(const u64_t* ss, int row) { return __builtin_amdgcn_rsqf((float)ss[row] * (SS_IFX / (float)2048) + 1e-6f); }
;     __device__ __forceinline__ void operator()(const f32x4 (&acc)[2][2][4][2], const Unit& u, int wr, int wc, int fr, int fq) const {
;         const int row0 = u.pm * BM + wr * 64 + fr, col0 = u.pn * BM + wc * 32 + 8 * fq;
; #pragma unroll
;         for (int ai = 0; ai < 2; ++ai)
; #pragma unroll
;             for (int m = 0; m < 4; ++m) {
;                 const int row = row0 + ai * HALF + m * 16;
;                 const float sc = ss_rstd(ss, row);
;                 bf16_t* rowp = O + (size_t)row * ldc + col0;
; #pragma unroll
;                 for (int bj = 0; bj < 2; ++bj) { const f32x4 v0 = acc[ai][bj][m][0] * sc, v1 = acc[ai][bj][m][1] * sc;
;                     u32x4 w; w.x = cvt_pk_bf16(v0[0], v0[1]); w.y = cvt_pk_bf16(v0[2], v0[3]); w.z = cvt_pk_bf16(v1[0], v1[1]); w.w = cvt_pk_bf16(v1[2], v1[3]);
;                     *(u32x4*)(rowp + bj * HALF) = w; }
;                 asm volatile("" ::: "memory");
;             }
.LBB0_244:
	v_lshl_add_u32 v140, s12, 8, v148
	v_ashrrev_i32_e32 v141, 31, v140
	v_lshl_add_u64 v[142:143], v[140:141], 3, s[84:85]
	global_load_dwordx2 v[144:145], v[142:143], off
	global_load_dwordx2 v[162:163], v[142:143], off offset:128
	global_load_dwordx2 v[164:165], v[142:143], off offset:256
	global_load_dwordx2 v[166:167], v[142:143], off offset:384
	global_load_dwordx2 v[168:169], v[142:143], off offset:1024
	global_load_dwordx2 v[170:171], v[142:143], off offset:1152
	global_load_dwordx2 v[172:173], v[142:143], off offset:1280
	global_load_dwordx2 v[174:175], v[142:143], off offset:1408
	v_lshl_or_b32 v146, s13, 8, v150
	v_ashrrev_i32_e32 v147, 31, v146
	v_lshlrev_b64 v[146:147], 1, v[146:147]
	s_andn2_b64 vcc, exec, s[38:39]
	s_waitcnt vmcnt(0) lgkmcnt(0)
	v_ffbh_u32_e32 v141, v145
	v_min_u32_e32 v141, 32, v141
	v_lshlrev_b64 v[144:145], v141, v[144:145]
	v_min_u32_e32 v144, 1, v144
	v_or_b32_e32 v144, v145, v144
	v_cvt_f32_u32_e32 v152, v144
	v_sub_u32_e32 v141, 32, v141
	v_mov_b64_e32 v[144:145], s[22:23]
	v_mad_i64_i32 v[154:155], s[12:13], v140, s79, v[144:145]
	v_ldexp_f32 v141, v152, v141
	v_fmamk_f32 v141, v141, 0x2e000000, v207
	v_rsq_f32_e32 v152, v141
	v_lshl_add_u64 v[154:155], v[154:155], 0, v[146:147]
	v_pk_mul_f32 v[128:129], v[128:129], v[152:153] op_sel_hi:[1,0]
	v_pk_mul_f32 v[126:127], v[126:127], v[152:153] op_sel_hi:[1,0]
	v_pk_mul_f32 v[124:125], v[124:125], v[152:153] op_sel_hi:[1,0]
	v_pk_mul_f32 v[122:123], v[122:123], v[152:153] op_sel_hi:[1,0]
	v_pk_mul_f32 v[120:121], v[120:121], v[152:153] op_sel_hi:[1,0]
	v_pk_mul_f32 v[118:119], v[118:119], v[152:153] op_sel_hi:[1,0]
	v_pk_mul_f32 v[156:157], v[116:117], v[152:153] op_sel_hi:[1,0]
	v_pk_mul_f32 v[152:153], v[114:115], v[152:153] op_sel_hi:[1,0]
	v_cvt_pk_bf16_f32 v114, v126, v127
	v_cvt_pk_bf16_f32 v115, v128, v129
	v_cvt_pk_bf16_f32 v116, v122, v123
	v_cvt_pk_bf16_f32 v117, v124, v125
	global_store_dwordx4 v[154:155], v[114:117], off
	s_nop 1
	v_cvt_pk_bf16_f32 v114, v118, v119
	v_cvt_pk_bf16_f32 v115, v120, v121
	v_cvt_pk_bf16_f32 v116, v152, v153
	v_cvt_pk_bf16_f32 v117, v156, v157
	global_store_dwordx4 v[154:155], v[114:117], off offset:256
	s_nop 1
	v_mov_b32_e32 v114, v162
	v_mov_b32_e32 v115, v163
	v_ffbh_u32_e32 v116, v115
	v_min_u32_e32 v116, 32, v116
	v_lshlrev_b64 v[114:115], v116, v[114:115]
	v_min_u32_e32 v114, 1, v114
	v_or_b32_e32 v114, v115, v114
	v_cvt_f32_u32_e32 v114, v114
	v_sub_u32_e32 v116, 32, v116
	v_or_b32_e32 v115, 16, v140
	v_ldexp_f32 v114, v114, v116
	v_fmamk_f32 v114, v114, 0x2e000000, v207
	v_rsq_f32_e32 v114, v114
	v_mad_i64_i32 v[116:117], s[12:13], v115, s79, v[144:145]
	v_lshl_add_u64 v[116:117], v[116:117], 0, v[146:147]
	v_pk_mul_f32 v[112:113], v[112:113], v[114:115] op_sel_hi:[1,0]
	v_pk_mul_f32 v[110:111], v[110:111], v[114:115] op_sel_hi:[1,0]
	v_pk_mul_f32 v[108:109], v[108:109], v[114:115] op_sel_hi:[1,0]
	v_pk_mul_f32 v[106:107], v[106:107], v[114:115] op_sel_hi:[1,0]
	v_pk_mul_f32 v[104:105], v[104:105], v[114:115] op_sel_hi:[1,0]
	v_pk_mul_f32 v[102:103], v[102:103], v[114:115] op_sel_hi:[1,0]
	v_pk_mul_f32 v[118:119], v[100:101], v[114:115] op_sel_hi:[1,0]
	v_pk_mul_f32 v[114:115], v[98:99], v[114:115] op_sel_hi:[1,0]
	v_cvt_pk_bf16_f32 v98, v110, v111
	v_cvt_pk_bf16_f32 v99, v112, v113
	v_cvt_pk_bf16_f32 v100, v106, v107
	v_cvt_pk_bf16_f32 v101, v108, v109
	global_store_dwordx4 v[116:117], v[98:101], off
	s_nop 1
	v_cvt_pk_bf16_f32 v98, v102, v103
	v_cvt_pk_bf16_f32 v99, v104, v105
	v_cvt_pk_bf16_f32 v100, v114, v115
	v_cvt_pk_bf16_f32 v101, v118, v119
	global_store_dwordx4 v[116:117], v[98:101], off offset:256
	s_nop 1
	v_mov_b32_e32 v98, v164
	v_mov_b32_e32 v99, v165
	v_ffbh_u32_e32 v100, v99
	v_min_u32_e32 v100, 32, v100
	v_lshlrev_b64 v[98:99], v100, v[98:99]
	v_min_u32_e32 v98, 1, v98
	v_or_b32_e32 v98, v99, v98
	v_cvt_f32_u32_e32 v98, v98
	v_sub_u32_e32 v100, 32, v100
	v_or_b32_e32 v99, 32, v140
	v_ldexp_f32 v98, v98, v100
	v_fmamk_f32 v98, v98, 0x2e000000, v207
	v_rsq_f32_e32 v98, v98
	v_mad_i64_i32 v[100:101], s[12:13], v99, s79, v[144:145]
	v_lshl_add_u64 v[100:101], v[100:101], 0, v[146:147]
	v_pk_mul_f32 v[96:97], v[96:97], v[98:99] op_sel_hi:[1,0]
	v_pk_mul_f32 v[94:95], v[94:95], v[98:99] op_sel_hi:[1,0]
	v_pk_mul_f32 v[92:93], v[92:93], v[98:99] op_sel_hi:[1,0]
	v_pk_mul_f32 v[90:91], v[90:91], v[98:99] op_sel_hi:[1,0]
	v_pk_mul_f32 v[88:89], v[88:89], v[98:99] op_sel_hi:[1,0]
	v_pk_mul_f32 v[86:87], v[86:87], v[98:99] op_sel_hi:[1,0]
	v_pk_mul_f32 v[102:103], v[84:85], v[98:99] op_sel_hi:[1,0]
	v_pk_mul_f32 v[98:99], v[82:83], v[98:99] op_sel_hi:[1,0]
	v_cvt_pk_bf16_f32 v82, v94, v95
	v_cvt_pk_bf16_f32 v83, v96, v97
	v_cvt_pk_bf16_f32 v84, v90, v91
	v_cvt_pk_bf16_f32 v85, v92, v93
	global_store_dwordx4 v[100:101], v[82:85], off
	s_nop 1
	v_cvt_pk_bf16_f32 v82, v86, v87
	v_cvt_pk_bf16_f32 v83, v88, v89
	v_cvt_pk_bf16_f32 v84, v98, v99
	v_cvt_pk_bf16_f32 v85, v102, v103
	global_store_dwordx4 v[100:101], v[82:85], off offset:256
	s_nop 1
	v_mov_b32_e32 v82, v166
	v_mov_b32_e32 v83, v167
	v_ffbh_u32_e32 v84, v83
	v_min_u32_e32 v84, 32, v84
	v_lshlrev_b64 v[82:83], v84, v[82:83]
	v_min_u32_e32 v82, 1, v82
	v_or_b32_e32 v82, v83, v82
	v_cvt_f32_u32_e32 v82, v82
	v_sub_u32_e32 v84, 32, v84
	v_or_b32_e32 v83, 48, v140
	v_ldexp_f32 v82, v82, v84
	v_fmamk_f32 v82, v82, 0x2e000000, v207
	v_rsq_f32_e32 v82, v82
	v_mad_i64_i32 v[84:85], s[12:13], v83, s79, v[144:145]
	v_lshl_add_u64 v[84:85], v[84:85], 0, v[146:147]
	v_pk_mul_f32 v[80:81], v[80:81], v[82:83] op_sel_hi:[1,0]
	v_pk_mul_f32 v[78:79], v[78:79], v[82:83] op_sel_hi:[1,0]
	v_pk_mul_f32 v[76:77], v[76:77], v[82:83] op_sel_hi:[1,0]
; __device__ __forceinline__ unsigned cvt_pk_bf16(float lo, float hi) { unsigned r; asm volatile("v_cvt_pk_bf16_f32 %0, %1, %2" : "=v"(r) : "v"(lo), "v"(hi)); return r; }
; __device__ __forceinline__ float ss_rstd(const u64_t* ss, int row) { return __builtin_amdgcn_rsqf((float)ss[row] * (SS_IFX / (float)2048) + 1e-6f); }
;     __device__ __forceinline__ void operator()(const f32x4 (&acc)[2][2][4][2], const Unit& u, int wr, int wc, int fr, int fq) const {
;     ...
;                 const int row = row0 + ai * HALF + m * 16;
;                 const float sc = ss_rstd(ss, row);
;                 bf16_t* rowp = O + (size_t)row * ldc + col0;
; #pragma unroll
;                 for (int bj = 0; bj < 2; ++bj) { const f32x4 v0 = acc[ai][bj][m][0] * sc, v1 = acc[ai][bj][m][1] * sc;
;                     u32x4 w; w.x = cvt_pk_bf16(v0[0], v0[1]); w.y = cvt_pk_bf16(v0[2], v0[3]); w.z = cvt_pk_bf16(v1[0], v1[1]); w.w = cvt_pk_bf16(v1[2], v1[3]);
;                     *(u32x4*)(rowp + bj * HALF) = w; }
;                 asm volatile("" ::: "memory");
	v_pk_mul_f32 v[74:75], v[74:75], v[82:83] op_sel_hi:[1,0]
	v_pk_mul_f32 v[72:73], v[72:73], v[82:83] op_sel_hi:[1,0]
	v_pk_mul_f32 v[70:71], v[70:71], v[82:83] op_sel_hi:[1,0]
	v_pk_mul_f32 v[86:87], v[68:69], v[82:83] op_sel_hi:[1,0]
	v_pk_mul_f32 v[82:83], v[66:67], v[82:83] op_sel_hi:[1,0]
	v_cvt_pk_bf16_f32 v66, v78, v79
	v_cvt_pk_bf16_f32 v67, v80, v81
	v_cvt_pk_bf16_f32 v68, v74, v75
	v_cvt_pk_bf16_f32 v69, v76, v77
	global_store_dwordx4 v[84:85], v[66:69], off
	s_nop 1
	v_cvt_pk_bf16_f32 v66, v70, v71
	v_cvt_pk_bf16_f32 v67, v72, v73
	v_cvt_pk_bf16_f32 v68, v82, v83
	v_cvt_pk_bf16_f32 v69, v86, v87
	global_store_dwordx4 v[84:85], v[66:69], off offset:256
	s_nop 1
	v_mov_b32_e32 v66, v168
	v_mov_b32_e32 v67, v169
	v_ffbh_u32_e32 v68, v67
	v_min_u32_e32 v68, 32, v68
	v_lshlrev_b64 v[66:67], v68, v[66:67]
	v_min_u32_e32 v66, 1, v66
	v_or_b32_e32 v66, v67, v66
	v_cvt_f32_u32_e32 v66, v66
	v_sub_u32_e32 v68, 32, v68
	v_add_u32_e32 v67, 0x80, v140
	v_ldexp_f32 v66, v66, v68
	v_fmamk_f32 v66, v66, 0x2e000000, v207
	v_rsq_f32_e32 v66, v66
	v_mad_i64_i32 v[68:69], s[12:13], v67, s79, v[144:145]
	v_lshl_add_u64 v[68:69], v[68:69], 0, v[146:147]
	v_pk_mul_f32 v[64:65], v[64:65], v[66:67] op_sel_hi:[1,0]
	v_pk_mul_f32 v[62:63], v[62:63], v[66:67] op_sel_hi:[1,0]
	v_pk_mul_f32 v[60:61], v[60:61], v[66:67] op_sel_hi:[1,0]
	v_pk_mul_f32 v[58:59], v[58:59], v[66:67] op_sel_hi:[1,0]
	v_pk_mul_f32 v[56:57], v[56:57], v[66:67] op_sel_hi:[1,0]
	v_pk_mul_f32 v[54:55], v[54:55], v[66:67] op_sel_hi:[1,0]
	v_pk_mul_f32 v[70:71], v[52:53], v[66:67] op_sel_hi:[1,0]
	v_pk_mul_f32 v[66:67], v[50:51], v[66:67] op_sel_hi:[1,0]
	v_cvt_pk_bf16_f32 v50, v62, v63
	v_cvt_pk_bf16_f32 v51, v64, v65
	v_cvt_pk_bf16_f32 v52, v58, v59
	v_cvt_pk_bf16_f32 v53, v60, v61
	global_store_dwordx4 v[68:69], v[50:53], off
	s_nop 1
	v_cvt_pk_bf16_f32 v50, v54, v55
	v_cvt_pk_bf16_f32 v51, v56, v57
	v_cvt_pk_bf16_f32 v52, v66, v67
	v_cvt_pk_bf16_f32 v53, v70, v71
	global_store_dwordx4 v[68:69], v[50:53], off offset:256
	s_nop 1
	v_mov_b32_e32 v50, v170
	v_mov_b32_e32 v51, v171
	v_ffbh_u32_e32 v52, v51
	v_min_u32_e32 v52, 32, v52
	v_lshlrev_b64 v[50:51], v52, v[50:51]
	v_min_u32_e32 v50, 1, v50
	v_or_b32_e32 v50, v51, v50
	v_cvt_f32_u32_e32 v50, v50
	v_sub_u32_e32 v52, 32, v52
	v_add_u32_e32 v51, 0x90, v140
	v_ldexp_f32 v50, v50, v52
	v_fmamk_f32 v50, v50, 0x2e000000, v207
	v_rsq_f32_e32 v50, v50
	v_mad_i64_i32 v[52:53], s[12:13], v51, s79, v[144:145]
	v_lshl_add_u64 v[52:53], v[52:53], 0, v[146:147]
	v_pk_mul_f32 v[48:49], v[48:49], v[50:51] op_sel_hi:[1,0]
	v_pk_mul_f32 v[46:47], v[46:47], v[50:51] op_sel_hi:[1,0]
	v_pk_mul_f32 v[44:45], v[44:45], v[50:51] op_sel_hi:[1,0]
	v_pk_mul_f32 v[42:43], v[42:43], v[50:51] op_sel_hi:[1,0]
	v_pk_mul_f32 v[40:41], v[40:41], v[50:51] op_sel_hi:[1,0]
	v_pk_mul_f32 v[38:39], v[38:39], v[50:51] op_sel_hi:[1,0]
	v_pk_mul_f32 v[54:55], v[36:37], v[50:51] op_sel_hi:[1,0]
	v_pk_mul_f32 v[50:51], v[34:35], v[50:51] op_sel_hi:[1,0]
	v_cvt_pk_bf16_f32 v34, v46, v47
	v_cvt_pk_bf16_f32 v35, v48, v49
	v_cvt_pk_bf16_f32 v36, v42, v43
	v_cvt_pk_bf16_f32 v37, v44, v45
	global_store_dwordx4 v[52:53], v[34:37], off
	s_nop 1
	v_cvt_pk_bf16_f32 v34, v38, v39
	v_cvt_pk_bf16_f32 v35, v40, v41
	v_cvt_pk_bf16_f32 v36, v50, v51
	v_cvt_pk_bf16_f32 v37, v54, v55
	global_store_dwordx4 v[52:53], v[34:37], off offset:256
	s_nop 1
	v_mov_b32_e32 v34, v172
	v_mov_b32_e32 v35, v173
	v_ffbh_u32_e32 v36, v35
	v_min_u32_e32 v36, 32, v36
	v_lshlrev_b64 v[34:35], v36, v[34:35]
	v_min_u32_e32 v34, 1, v34
	v_or_b32_e32 v34, v35, v34
	v_cvt_f32_u32_e32 v34, v34
	v_sub_u32_e32 v36, 32, v36
	v_add_u32_e32 v35, 0xa0, v140
	v_ldexp_f32 v34, v34, v36
	v_fmamk_f32 v34, v34, 0x2e000000, v207
	v_rsq_f32_e32 v34, v34
	v_mad_i64_i32 v[36:37], s[12:13], v35, s79, v[144:145]
	v_lshl_add_u64 v[36:37], v[36:37], 0, v[146:147]
	v_pk_mul_f32 v[32:33], v[32:33], v[34:35] op_sel_hi:[1,0]
	v_pk_mul_f32 v[30:31], v[30:31], v[34:35] op_sel_hi:[1,0]
	v_pk_mul_f32 v[28:29], v[28:29], v[34:35] op_sel_hi:[1,0]
	v_pk_mul_f32 v[26:27], v[26:27], v[34:35] op_sel_hi:[1,0]
	v_pk_mul_f32 v[24:25], v[24:25], v[34:35] op_sel_hi:[1,0]
	v_pk_mul_f32 v[22:23], v[22:23], v[34:35] op_sel_hi:[1,0]
	v_pk_mul_f32 v[38:39], v[20:21], v[34:35] op_sel_hi:[1,0]
	v_pk_mul_f32 v[34:35], v[18:19], v[34:35] op_sel_hi:[1,0]
	v_cvt_pk_bf16_f32 v18, v30, v31
	v_cvt_pk_bf16_f32 v19, v32, v33
	v_cvt_pk_bf16_f32 v20, v26, v27
	v_cvt_pk_bf16_f32 v21, v28, v29
	global_store_dwordx4 v[36:37], v[18:21], off
	s_nop 1
	v_cvt_pk_bf16_f32 v18, v22, v23
	v_cvt_pk_bf16_f32 v19, v24, v25
	v_cvt_pk_bf16_f32 v20, v34, v35
	v_cvt_pk_bf16_f32 v21, v38, v39
	global_store_dwordx4 v[36:37], v[18:21], off offset:256
	s_nop 1
	v_mov_b32_e32 v18, v174
	v_mov_b32_e32 v19, v175
	v_ffbh_u32_e32 v20, v19
	v_min_u32_e32 v20, 32, v20
	v_lshlrev_b64 v[18:19], v20, v[18:19]
	v_min_u32_e32 v18, 1, v18
	v_or_b32_e32 v18, v19, v18
	v_cvt_f32_u32_e32 v18, v18
	v_sub_u32_e32 v20, 32, v20
	v_add_u32_e32 v19, 0xb0, v140
	v_ldexp_f32 v18, v18, v20
	v_fmamk_f32 v18, v18, 0x2e000000, v207
	v_rsq_f32_e32 v18, v18
	v_mad_i64_i32 v[20:21], s[12:13], v19, s79, v[144:145]
	v_lshl_add_u64 v[20:21], v[20:21], 0, v[146:147]
	v_pk_mul_f32 v[16:17], v[16:17], v[18:19] op_sel_hi:[1,0]
	v_pk_mul_f32 v[14:15], v[14:15], v[18:19] op_sel_hi:[1,0]
	v_pk_mul_f32 v[12:13], v[12:13], v[18:19] op_sel_hi:[1,0]
	v_pk_mul_f32 v[10:11], v[10:11], v[18:19] op_sel_hi:[1,0]
	v_pk_mul_f32 v[8:9], v[8:9], v[18:19] op_sel_hi:[1,0]
	v_pk_mul_f32 v[6:7], v[6:7], v[18:19] op_sel_hi:[1,0]
	v_pk_mul_f32 v[22:23], v[4:5], v[18:19] op_sel_hi:[1,0]
	v_pk_mul_f32 v[18:19], v[2:3], v[18:19] op_sel_hi:[1,0]
	v_cvt_pk_bf16_f32 v2, v14, v15
	v_cvt_pk_bf16_f32 v3, v16, v17
	v_cvt_pk_bf16_f32 v4, v10, v11
	v_cvt_pk_bf16_f32 v5, v12, v13
	global_store_dwordx4 v[20:21], v[2:5], off
	s_mov_b64 s[12:13], -1
	s_nop 0
	v_cvt_pk_bf16_f32 v2, v6, v7
	v_cvt_pk_bf16_f32 v3, v8, v9
	v_cvt_pk_bf16_f32 v4, v18, v19
	v_cvt_pk_bf16_f32 v5, v22, v23
	global_store_dwordx4 v[20:21], v[2:5], off offset:256
	s_cbranch_vccnz .LBB0_237
	s_andn2_b64 vcc, exec, s[0:1]
	s_cbranch_vccnz .LBB0_236
	s_barrier
	s_branch .LBB0_236

.LBB0_262:
	s_or_b64 exec, exec, s[4:5]
	v_lshrrev_b32_e32 v0, 5, v19
	v_mul_u32_u24_e32 v0, v9, v0
	v_lshlrev_b32_e32 v0, 2, v0
	v_lshl_add_u64 v[10:11], v[12:13], 0, v[0:1]
	v_and_b32_e32 v0, 31, v17
	v_lshlrev_b32_e32 v0, 2, v0
	v_lshl_add_u64 v[22:23], v[10:11], 0, v[0:1]
	v_lshlrev_b32_e32 v0, 1, v9
	v_lshl_add_u64 v[12:13], v[0:1], 2, v[22:23]
	v_lshlrev_b32_e32 v0, 2, v9
	v_lshl_add_u64 v[14:15], v[0:1], 2, v[22:23]
	v_mul_u32_u24_e32 v0, 6, v9
	v_lshlrev_b32_e32 v0, 2, v0
	v_lshl_add_u64 v[24:25], v[22:23], 0, v[0:1]
	v_lshlrev_b32_e32 v0, 3, v9
	v_lshl_add_u64 v[26:27], v[0:1], 2, v[22:23]
	v_mul_u32_u24_e32 v0, 10, v9
	v_lshlrev_b32_e32 v0, 2, v0
	v_lshl_add_u64 v[28:29], v[22:23], 0, v[0:1]
	v_mul_u32_u24_e32 v0, 12, v9
	v_lshlrev_b32_e32 v0, 2, v0
	v_lshl_add_u64 v[30:31], v[22:23], 0, v[0:1]
	v_mul_u32_u24_e32 v0, 14, v9
	v_lshlrev_b32_e32 v0, 2, v0
	v_lshl_add_u64 v[32:33], v[22:23], 0, v[0:1]
	v_lshlrev_b32_e32 v0, 4, v9
	global_load_dword v11, v[22:23], off
	s_nop 0
	global_load_dword v13, v[12:13], off
	s_nop 0
	global_load_dword v15, v[14:15], off
	s_nop 0
	global_load_dword v42, v[24:25], off
	global_load_dword v43, v[26:27], off
	global_load_dword v45, v[28:29], off
	global_load_dword v46, v[30:31], off
	global_load_dword v47, v[32:33], off
	v_lshl_add_u64 v[24:25], v[0:1], 2, v[22:23]
	v_mul_u32_u24_e32 v0, 18, v9
	v_lshlrev_b32_e32 v0, 2, v0
	v_lshl_add_u64 v[26:27], v[22:23], 0, v[0:1]
	v_mul_u32_u24_e32 v0, 20, v9
	v_lshlrev_b32_e32 v0, 2, v0
	v_lshl_add_u64 v[28:29], v[22:23], 0, v[0:1]
	v_mul_u32_u24_e32 v0, 22, v9
	v_lshlrev_b32_e32 v0, 2, v0
	v_lshl_add_u64 v[30:31], v[22:23], 0, v[0:1]
	v_mul_u32_u24_e32 v0, 24, v9
	v_lshlrev_b32_e32 v0, 2, v0
	v_lshl_add_u64 v[32:33], v[22:23], 0, v[0:1]
	v_mul_u32_u24_e32 v0, 26, v9
	v_lshlrev_b32_e32 v0, 2, v0
	v_lshl_add_u64 v[34:35], v[22:23], 0, v[0:1]
	v_mul_u32_u24_e32 v0, 28, v9
	v_lshlrev_b32_e32 v0, 2, v0
	v_lshl_add_u64 v[36:37], v[22:23], 0, v[0:1]
	v_mul_u32_u24_e32 v0, 30, v9
	v_lshlrev_b32_e32 v0, 2, v0
	v_lshl_add_u64 v[38:39], v[22:23], 0, v[0:1]
	v_lshlrev_b32_e32 v0, 5, v9
	global_load_dword v51, v[24:25], off
	global_load_dword v52, v[26:27], off
	global_load_dword v53, v[28:29], off
	global_load_dword v54, v[30:31], off
	global_load_dword v55, v[32:33], off
	global_load_dword v56, v[34:35], off
	global_load_dword v57, v[36:37], off
	global_load_dword v58, v[38:39], off
	v_lshl_add_u64 v[24:25], v[0:1], 2, v[22:23]
	v_mul_u32_u24_e32 v0, 34, v9
	v_lshlrev_b32_e32 v0, 2, v0
	v_lshl_add_u64 v[26:27], v[22:23], 0, v[0:1]
	v_mul_u32_u24_e32 v0, 36, v9
	v_lshlrev_b32_e32 v0, 2, v0
	v_lshl_add_u64 v[28:29], v[22:23], 0, v[0:1]
	v_mul_u32_u24_e32 v0, 38, v9
	v_lshlrev_b32_e32 v0, 2, v0
	v_lshl_add_u64 v[30:31], v[22:23], 0, v[0:1]
	v_mul_u32_u24_e32 v0, 40, v9
	v_lshlrev_b32_e32 v0, 2, v0
	v_lshl_add_u64 v[32:33], v[22:23], 0, v[0:1]
	v_mul_u32_u24_e32 v0, 42, v9
	v_lshlrev_b32_e32 v0, 2, v0
	v_lshl_add_u64 v[34:35], v[22:23], 0, v[0:1]
	v_mul_u32_u24_e32 v0, 44, v9
	v_lshlrev_b32_e32 v0, 2, v0
	v_lshl_add_u64 v[36:37], v[22:23], 0, v[0:1]
	v_mul_u32_u24_e32 v0, 46, v9
	v_lshlrev_b32_e32 v0, 2, v0
	v_lshl_add_u64 v[38:39], v[22:23], 0, v[0:1]
	v_mul_u32_u24_e32 v0, 48, v9
	v_lshlrev_b32_e32 v0, 2, v0
	global_load_dword v59, v[24:25], off
	global_load_dword v60, v[26:27], off
	global_load_dword v61, v[28:29], off
	global_load_dword v62, v[30:31], off
	global_load_dword v63, v[32:33], off
	global_load_dword v64, v[34:35], off
	global_load_dword v65, v[36:37], off
	global_load_dword v66, v[38:39], off
	v_lshl_add_u64 v[24:25], v[22:23], 0, v[0:1]
	v_mul_u32_u24_e32 v0, 50, v9
	v_lshlrev_b32_e32 v0, 2, v0
	v_lshl_add_u64 v[26:27], v[22:23], 0, v[0:1]
	v_mul_u32_u24_e32 v0, 52, v9
	v_lshlrev_b32_e32 v0, 2, v0
	v_lshl_add_u64 v[28:29], v[22:23], 0, v[0:1]
	v_mul_u32_u24_e32 v0, 54, v9
	v_lshlrev_b32_e32 v0, 2, v0
	v_lshl_add_u64 v[30:31], v[22:23], 0, v[0:1]
	v_mul_u32_u24_e32 v0, 56, v9
	v_lshlrev_b32_e32 v0, 2, v0
	v_lshl_add_u64 v[32:33], v[22:23], 0, v[0:1]
	v_mul_u32_u24_e32 v0, 58, v9
	v_lshlrev_b32_e32 v0, 2, v0
	v_lshl_add_u64 v[34:35], v[22:23], 0, v[0:1]
	v_mul_u32_u24_e32 v0, 60, v9
	v_lshlrev_b32_e32 v0, 2, v0
	v_lshl_add_u64 v[36:37], v[22:23], 0, v[0:1]
	v_mul_u32_u24_e32 v0, 62, v9
	v_lshlrev_b32_e32 v0, 2, v0
	v_lshl_add_u64 v[22:23], v[22:23], 0, v[0:1]
	global_load_dword v68, v[24:25], off
	global_load_dword v69, v[26:27], off
	global_load_dword v70, v[28:29], off
	global_load_dword v71, v[30:31], off
	global_load_dword v72, v[32:33], off
	global_load_dword v73, v[34:35], off
	global_load_dword v74, v[36:37], off
	global_load_dword v75, v[22:23], off
	v_cmp_ne_u64_e64 s[0:1], 0, v[4:5]
	s_and_saveexec_b64 s[4:5], s[0:1]
	s_xor_b64 s[0:1], exec, s[4:5]
	s_cbranch_execz .LBB0_264
	v_lshlrev_b32_e32 v0, 5, v17
	v_and_b32_e32 v0, 0xe0, v0
	v_lshl_add_u64 v[4:5], v[4:5], 0, v[0:1]
	global_load_dwordx4 v[22:25], v[4:5], off offset:16
	global_load_dwordx4 v[32:35], v[4:5], off
	s_waitcnt vmcnt(0) lgkmcnt(0)
	v_pk_mul_f32 v[26:27], v[8:9], v[24:25] op_sel_hi:[0,1]
	v_pk_mul_f32 v[28:29], v[8:9], v[22:23] op_sel_hi:[0,1]
	v_pk_mul_f32 v[30:31], v[8:9], v[34:35] op_sel_hi:[0,1]
	v_pk_mul_f32 v[8:9], v[8:9], v[32:33] op_sel_hi:[0,1]

; __device__ __forceinline__ TItem titem_decode(const Args& a, int it) {
;     constexpr int I_IN = (D / 64) * (INW / 32), I_O = (D / 64) * (D / 32), I_UP = (D / 64) * (UPW / 32), I_DN = (DFF / 64) * (D / 32), I_L = I_IN + I_O + I_UP + I_DN;
;     const int L = it / I_L; int r = it % I_L; unsigned char* wl = a.ws + WS_W + (size_t)L * W_LAYER; TItem t;
;     if (r < I_IN) { const int nblk = INW / 32, kb = r / nblk, n0 = (r % nblk) * 32, k0 = kb * 64;
;         t.cs = ((n0 >= GQ && n0 < GK) || (n0 >= SRC_RK && n0 < SRC_RV)) ? 0.125f : 1.f; t.N = INW; t.K = D; t.src = a.w_in + (size_t)L * D * INW + (size_t)k0 * INW + n0; t.gk = a.ln1_g + L * D + k0;
;         const int dn = n0 < SRC_GA ? n0 : (n0 < SRC_GA + 32 ? GAF + (n0 - SRC_GA) : n0 - 32);
;         t.dst = (bf16_t*)(wl + W_IN) + (size_t)dn * D + k0; return t; }
;     r -= I_IN;
;     if (r < I_O) { const int nblk = D / 32, kb = r / nblk, n0 = (r % nblk) * 32, k0 = kb * 64;
;         t.cs = 1.f; t.N = D; t.K = D; t.src = a.w_o + (size_t)L * D * D + (size_t)k0 * D + n0; t.gk = nullptr; t.dst = (bf16_t*)(wl + W_O) + (size_t)n0 * D + k0; return t; }
;     r -= I_O;
;     if (r < I_UP) { const int nblk = UPW / 32, kb = r / nblk, n0 = (r % nblk) * 32, k0 = kb * 64;
;         const int c = n0 < DFF ? n0 : n0 - DFF; const int dst = (c >> 7) * 256 + (c & 127) + (n0 < DFF ? 0 : 128);
;         t.cs = 1.f; t.N = UPW; t.K = D; t.src = a.w_up + (size_t)L * D * UPW + (size_t)k0 * UPW + n0; t.gk = a.ln2_g + L * D + k0; t.dst = (bf16_t*)(wl + W_UP) + (size_t)dst * D + k0; return t; }
;     r -= I_UP;
;     { const int nblk = D / 32, kb = r / nblk, n0 = (r % nblk) * 32, k0 = kb * 64;
;         t.cs = 1.f; t.N = D; t.K = DFF; t.src = a.w_down + (size_t)L * DFF * D + (size_t)k0 * D + n0; t.gk = nullptr; t.dst = (bf16_t*)(wl + W_DN) + (size_t)n0 * DFF + k0; return t; }
; }
.Lti_wd_a:
	ds_write2_b32 v49, v11, v13 offset1:66
	ds_write2_b32 v49, v15, v42 offset0:132 offset1:198
	ds_write2_b32 v21, v43, v45 offset0:8 offset1:74
	ds_write2_b32 v21, v46, v47 offset0:140 offset1:206
	ds_write2_b32 v108, v51, v52 offset0:16 offset1:82
	ds_write2_b32 v108, v53, v54 offset0:148 offset1:214
	ds_write2_b32 v109, v55, v56 offset0:24 offset1:90
	ds_write2_b32 v109, v57, v58 offset0:156 offset1:222
	ds_write2_b32 v110, v59, v60 offset0:32 offset1:98
	ds_write2_b32 v110, v61, v62 offset0:164 offset1:230
	ds_write2_b32 v111, v63, v64 offset0:40 offset1:106
	ds_write2_b32 v111, v65, v66 offset0:172 offset1:238
	ds_write2_b32 v112, v68, v69 offset0:48 offset1:114
	ds_write2_b32 v112, v70, v71 offset0:180 offset1:246
	ds_write2_b32 v113, v72, v73 offset0:56 offset1:122
	ds_write2_b32 v113, v74, v75 offset0:188 offset1:254
	s_waitcnt lgkmcnt(0)
	ds_read2_b32 v[38:39], v44 offset1:33
	v_mad_i64_i32 v[120:121], s[0:1], v3, v18, 0
	v_add_u32_e32 v50, s70, v50
	s_mov_b32 s6, 0x1887f
	s_waitcnt lgkmcnt(0)
	v_mul_f32_e32 v0, v8, v38
	v_mul_f32_e32 v38, v9, v39
	v_cvt_pk_bf16_f32 v114, v0, v38
	ds_read2_b32 v[38:39], v44 offset0:66 offset1:99
	v_cmp_lt_i32_e64 s[38:39], s6, v50
	s_waitcnt lgkmcnt(0)
	v_mul_f32_e32 v0, v30, v38
	v_mul_f32_e32 v38, v31, v39
	v_cvt_pk_bf16_f32 v115, v0, v38
	ds_read2_b32 v[38:39], v44 offset0:132 offset1:165
	s_waitcnt lgkmcnt(0)
	v_mul_f32_e32 v0, v28, v38
	v_mul_f32_e32 v38, v29, v39
	v_cvt_pk_bf16_f32 v116, v0, v38
	ds_read2_b32 v[40:41], v44 offset0:198 offset1:231
	v_lshlrev_b32_e32 v38, 1, v12
	v_mov_b32_e32 v39, v1
	v_lshl_add_u64 v[118:119], v[6:7], 0, v[38:39]
	s_waitcnt lgkmcnt(0)
	v_mul_f32_e32 v0, v26, v40
	v_mul_f32_e32 v39, v27, v41
	v_mad_i64_i32 v[40:41], s[0:1], v3, v10, 0
	v_lshl_add_u64 v[40:41], v[40:41], 1, v[118:119]
	v_cvt_pk_bf16_f32 v117, v0, v39
	global_store_dwordx4 v[40:41], v[114:117], off
	ds_read2_b32 v[40:41], v44 offset0:8 offset1:41
	s_waitcnt lgkmcnt(0)
	v_mul_f32_e32 v0, v8, v40
	v_mul_f32_e32 v39, v9, v41
	v_cvt_pk_bf16_f32 v114, v0, v39
	ds_read2_b32 v[40:41], v44 offset0:74 offset1:107
	s_waitcnt lgkmcnt(0)
	v_mul_f32_e32 v0, v30, v40
	v_mul_f32_e32 v39, v31, v41
	v_cvt_pk_bf16_f32 v115, v0, v39
	ds_read2_b32 v[40:41], v44 offset0:140 offset1:173
	s_waitcnt lgkmcnt(0)
	v_mul_f32_e32 v0, v28, v40
	v_mul_f32_e32 v39, v29, v41
	v_cvt_pk_bf16_f32 v116, v0, v39
	ds_read2_b32 v[40:41], v44 offset0:206 offset1:239
	s_waitcnt lgkmcnt(0)
	v_mul_f32_e32 v0, v26, v40
	v_mul_f32_e32 v39, v27, v41
	v_mad_i64_i32 v[40:41], s[0:1], v3, v14, 0
	v_lshl_add_u64 v[40:41], v[40:41], 1, v[118:119]
	v_cvt_pk_bf16_f32 v117, v0, v39
	global_store_dwordx4 v[40:41], v[114:117], off
	ds_read2_b32 v[40:41], v44 offset0:16 offset1:49
	s_waitcnt lgkmcnt(0)
	v_mul_f32_e32 v0, v8, v40
	v_mul_f32_e32 v39, v9, v41
	v_cvt_pk_bf16_f32 v114, v0, v39
	ds_read2_b32 v[40:41], v44 offset0:82 offset1:115
	s_waitcnt lgkmcnt(0)
	v_mul_f32_e32 v0, v30, v40
	v_mul_f32_e32 v39, v31, v41
	v_cvt_pk_bf16_f32 v115, v0, v39
	ds_read2_b32 v[40:41], v44 offset0:148 offset1:181
	s_waitcnt lgkmcnt(0)
	v_mul_f32_e32 v0, v28, v40
	v_mul_f32_e32 v39, v29, v41
	v_cvt_pk_bf16_f32 v116, v0, v39
	ds_read2_b32 v[40:41], v44 offset0:214 offset1:247
	s_waitcnt lgkmcnt(0)
	v_mul_f32_e32 v0, v26, v40
	v_mul_f32_e32 v39, v27, v41
	v_mad_i64_i32 v[40:41], s[0:1], v3, v16, 0
	v_lshl_add_u64 v[40:41], v[40:41], 1, v[118:119]
	v_cvt_pk_bf16_f32 v117, v0, v39
	global_store_dwordx4 v[40:41], v[114:117], off
	ds_read2_b32 v[40:41], v44 offset0:24 offset1:57
	s_mov_b32 s0, 0x18880
	v_cmp_gt_i32_e64 s[0:1], s0, v50
	s_waitcnt lgkmcnt(0)
	v_mul_f32_e32 v0, v8, v40
	v_mul_f32_e32 v39, v9, v41
	v_cvt_pk_bf16_f32 v114, v0, v39
	ds_read2_b32 v[40:41], v44 offset0:90 offset1:123
	s_waitcnt lgkmcnt(0)
	v_mul_f32_e32 v0, v30, v40
	v_mul_f32_e32 v39, v31, v41
	v_cvt_pk_bf16_f32 v115, v0, v39
	ds_read2_b32 v[40:41], v44 offset0:156 offset1:189
	s_waitcnt lgkmcnt(0)
	v_mul_f32_e32 v0, v28, v40
	v_mul_f32_e32 v39, v29, v41
	v_cvt_pk_bf16_f32 v116, v0, v39
	ds_read2_b32 v[40:41], v44 offset0:222 offset1:255
	s_waitcnt lgkmcnt(0)
	v_mul_f32_e32 v0, v26, v40
	v_mul_f32_e32 v39, v27, v41
	v_lshl_add_u64 v[40:41], v[120:121], 1, v[118:119]
	v_cvt_pk_bf16_f32 v117, v0, v39
	global_store_dwordx4 v[40:41], v[114:117], off
	s_waitcnt lgkmcnt(0)
	s_and_saveexec_b64 s[6:7], s[0:1]
	s_cbranch_execz .LBB0_306
	s_mov_b32 s0, 0xa6f87fd7
	v_mul_hi_i32 v0, v50, s0
	v_add_u32_e32 v0, v0, v50
	v_lshrrev_b32_e32 v3, 31, v0
	v_ashrrev_i32_e32 v0, 14, v0
	v_add_u32_e32 v30, v0, v3
	v_mov_b64_e32 v[6:7], s[56:57]
	v_mul_i32_i24_e32 v8, 0x6220, v30
	v_mad_i64_i32 v[26:27], s[0:1], v30, s77, v[6:7]
	v_sub_u32_e32 v0, v50, v8
	s_movk_i32 s0, 0x181f
	v_ashrrev_i32_e32 v31, 31, v30
	v_cmp_lt_i32_e64 s[0:1], s0, v0
	s_and_saveexec_b64 s[8:9], s[0:1]
	s_xor_b64 s[8:9], exec, s[8:9]
	s_cbranch_execz .LBB0_299
	s_movk_i32 s0, 0x201f
	v_cmp_lt_u32_e64 s[0:1], s0, v0
	s_and_saveexec_b64 s[10:11], s[0:1]
	s_xor_b64 s[10:11], exec, s[10:11]
	s_cbranch_execz .LBB0_296
	s_movk_i32 s0, 0x4c1f
	v_cmp_lt_u32_e64 s[0:1], s0, v0
	s_and_saveexec_b64 s[12:13], s[0:1]
	s_xor_b64 s[0:1], exec, s[12:13]
	s_cbranch_execz .LBB0_293
	v_lshlrev_b32_e32 v3, 5, v8
	v_readlane_b32 s12, v254, 22
	v_add_u32_e32 v0, 0xffffb3e0, v0
	v_sub_u32_e32 v3, v48, v3
	v_readlane_b32 s13, v254, 23
	v_and_b32_e32 v0, 0xffffffc0, v0
	v_add_u32_e32 v3, 0xfff67c00, v3
	v_mov_b64_e32 v[6:7], s[12:13]
	s_mov_b32 s12, 0x2c00000
	v_and_b32_e32 v3, 0x7e0, v3
	v_mad_i64_i32 v[6:7], s[12:13], v30, s12, v[6:7]
	v_lshlrev_b64 v[8:9], 13, v[0:1]
	v_lshl_add_u64 v[6:7], v[6:7], 0, v[8:9]
	v_lshlrev_b32_e32 v8, 2, v3
	v_mov_b32_e32 v9, v1
	s_movk_i32 s12, 0x2c00
	v_lshl_add_u64 v[28:29], v[6:7], 0, v[8:9]
	v_mad_u64_u32 v[6:7], s[12:13], v3, s12, v[26:27]
	v_lshl_add_u64 v[6:7], v[0:1], 1, v[6:7]
	s_mov_b64 s[12:13], 0x4d00000
	v_lshl_add_u64 v[6:7], v[6:7], 0, s[12:13]

.Lti_wd_b2:
	s_and_b64 s[0:1], exec, s[38:39]
	s_or_b64 s[4:5], s[0:1], s[4:5]
	s_and_saveexec_b64 s[0:1], vcc
	s_cbranch_execz .LBB0_269
	ds_write2_b32 v49, v83, v82 offset1:66
	ds_write2_b32 v49, v81, v80 offset0:132 offset1:198
	ds_write2_b32 v21, v79, v78 offset0:8 offset1:74
	ds_write2_b32 v21, v77, v76 offset0:140 offset1:206
	ds_write2_b32 v108, v91, v90 offset0:16 offset1:82
	ds_write2_b32 v108, v89, v88 offset0:148 offset1:214
	ds_write2_b32 v109, v87, v86 offset0:24 offset1:90
	ds_write2_b32 v109, v85, v84 offset0:156 offset1:222
	ds_write2_b32 v110, v99, v98 offset0:32 offset1:98
	ds_write2_b32 v110, v97, v96 offset0:164 offset1:230
	ds_write2_b32 v111, v95, v94 offset0:40 offset1:106
	ds_write2_b32 v111, v93, v92 offset0:172 offset1:238
	ds_write2_b32 v112, v107, v106 offset0:48 offset1:114
	ds_write2_b32 v112, v105, v104 offset0:180 offset1:246
	ds_write2_b32 v113, v103, v102 offset0:56 offset1:122
	ds_write2_b32 v113, v101, v100 offset0:188 offset1:254
	s_waitcnt lgkmcnt(0)
	ds_read2_b32 v[40:41], v44 offset1:33
	v_mov_b32_e32 v39, v1
	v_lshl_add_u64 v[112:113], v[22:23], 0, v[38:39]
	v_mad_i64_i32 v[38:39], s[6:7], v67, v10, 0
	s_waitcnt lgkmcnt(0)
	v_mul_f32_e32 v0, v24, v40
	v_mul_f32_e32 v21, v25, v41
	v_cvt_pk_bf16_f32 v108, v0, v21
	ds_read2_b32 v[40:41], v44 offset0:66 offset1:99
	v_lshl_add_u64 v[38:39], v[38:39], 1, v[112:113]
	s_waitcnt lgkmcnt(0)
	v_mul_f32_e32 v0, v36, v40
	v_mul_f32_e32 v21, v37, v41
	v_cvt_pk_bf16_f32 v109, v0, v21
	ds_read2_b32 v[40:41], v44 offset0:132 offset1:165
	s_waitcnt lgkmcnt(0)
	v_mul_f32_e32 v0, v34, v40
	v_mul_f32_e32 v21, v35, v41
	v_cvt_pk_bf16_f32 v110, v0, v21
	ds_read2_b32 v[40:41], v44 offset0:198 offset1:231
	s_waitcnt lgkmcnt(0)
	v_mul_f32_e32 v0, v32, v40
	v_mul_f32_e32 v21, v33, v41
	v_cvt_pk_bf16_f32 v111, v0, v21
	global_store_dwordx4 v[38:39], v[108:111], off
	ds_read2_b32 v[38:39], v44 offset0:8 offset1:41
	s_waitcnt lgkmcnt(0)
	v_mul_f32_e32 v0, v24, v38
	v_mul_f32_e32 v21, v25, v39
	v_cvt_pk_bf16_f32 v38, v0, v21
	ds_read2_b32 v[40:41], v44 offset0:74 offset1:107
	v_mad_i64_i32 v[110:111], s[6:7], v67, v16, 0
	v_lshl_add_u64 v[110:111], v[110:111], 1, v[112:113]
	s_waitcnt lgkmcnt(0)
	v_mul_f32_e32 v0, v36, v40
	v_mul_f32_e32 v21, v37, v41
	v_cvt_pk_bf16_f32 v39, v0, v21
	ds_read2_b32 v[40:41], v44 offset0:140 offset1:173
	s_waitcnt lgkmcnt(0)
	v_mul_f32_e32 v0, v34, v40
	v_mul_f32_e32 v21, v35, v41
	v_cvt_pk_bf16_f32 v40, v0, v21
	ds_read2_b32 v[108:109], v44 offset0:206 offset1:239
	s_waitcnt lgkmcnt(0)
	v_mul_f32_e32 v0, v32, v108
	v_mul_f32_e32 v21, v33, v109
	v_mad_i64_i32 v[108:109], s[6:7], v67, v14, 0
	v_lshl_add_u64 v[108:109], v[108:109], 1, v[112:113]
	v_cvt_pk_bf16_f32 v41, v0, v21
	global_store_dwordx4 v[108:109], v[38:41], off
	ds_read2_b32 v[38:39], v44 offset0:16 offset1:49
	s_waitcnt lgkmcnt(0)
	v_mul_f32_e32 v0, v24, v38
	v_mul_f32_e32 v21, v25, v39
	v_cvt_pk_bf16_f32 v38, v0, v21
	ds_read2_b32 v[40:41], v44 offset0:82 offset1:115
	s_waitcnt lgkmcnt(0)
	v_mul_f32_e32 v0, v36, v40
	v_mul_f32_e32 v21, v37, v41
	v_cvt_pk_bf16_f32 v39, v0, v21
	ds_read2_b32 v[40:41], v44 offset0:148 offset1:181
	s_waitcnt lgkmcnt(0)
	v_mul_f32_e32 v0, v34, v40
	v_mul_f32_e32 v21, v35, v41
	v_cvt_pk_bf16_f32 v40, v0, v21
	ds_read2_b32 v[108:109], v44 offset0:214 offset1:247
	s_waitcnt lgkmcnt(0)
	v_mul_f32_e32 v0, v32, v108
	v_mul_f32_e32 v21, v33, v109
	v_cvt_pk_bf16_f32 v41, v0, v21
	global_store_dwordx4 v[110:111], v[38:41], off
	ds_read2_b32 v[38:39], v44 offset0:24 offset1:57
	v_mad_i64_i32 v[110:111], s[6:7], v67, v18, 0
	s_waitcnt lgkmcnt(0)
	v_mul_f32_e32 v0, v24, v38
	v_mul_f32_e32 v21, v25, v39
	v_cvt_pk_bf16_f32 v38, v0, v21
	ds_read2_b32 v[40:41], v44 offset0:90 offset1:123
	s_waitcnt lgkmcnt(0)
	v_mul_f32_e32 v0, v36, v40
	v_mul_f32_e32 v21, v37, v41
	v_cvt_pk_bf16_f32 v39, v0, v21
	ds_read2_b32 v[40:41], v44 offset0:156 offset1:189
	s_waitcnt lgkmcnt(0)
	v_mul_f32_e32 v0, v34, v40
	v_mul_f32_e32 v21, v35, v41
	v_cvt_pk_bf16_f32 v40, v0, v21
	ds_read2_b32 v[108:109], v44 offset0:222 offset1:255
	s_waitcnt lgkmcnt(0)
	v_mul_f32_e32 v0, v32, v108
	v_mul_f32_e32 v21, v33, v109
	v_lshl_add_u64 v[108:109], v[110:111], 1, v[112:113]
	v_cvt_pk_bf16_f32 v41, v0, v21
	global_store_dwordx4 v[108:109], v[38:41], off
	s_waitcnt lgkmcnt(0)
	s_branch .LBB0_269

; __device__ __forceinline__ void phase_prologue(const Args& a, LAS unsigned char* lds) {
;     ...
;     { const int gt = blockIdx.x * NTHR + tid, NT_ = G * NTHR; constexpr int PER = (INP - INW) * D * 2 / 16;
;         for (int i = gt; i < DEPTH * PER; i += NT_) { const int L = i / PER, j = i % PER;
;             *(u32x4*)(a.ws + WS_W + (size_t)L * W_LAYER + W_IN + (size_t)INW * D * 2 + (size_t)j * 16) = (u32x4){0u, 0u, 0u, 0u}; } }
.LBB0_310:
	s_waitcnt lgkmcnt(0)
	v_mul_hi_i32 v3, v0, s6
	v_add_u32_e32 v3, v3, v0
	v_lshrrev_b32_e32 v5, 31, v3
	v_ashrrev_i32_e32 v3, 15, v3
	v_add_u32_e32 v3, v3, v5
	v_mov_b64_e32 v[8:9], s[98:99]
	v_mul_i32_i24_e32 v5, 0xe000, v3
	v_mad_i64_i32 v[8:9], s[4:5], v3, s77, v[8:9]
	v_sub_u32_e32 v10, v0, v5
	v_add_u32_e32 v0, s88, v0
	v_ashrrev_i32_e32 v11, 31, v10
	s_mov_b32 s4, 0x37fff
	v_cmp_lt_i32_e32 vcc, s4, v0
	v_lshl_add_u64 v[8:9], v[10:11], 4, v[8:9]
	s_or_b64 s[2:3], vcc, s[2:3]
	v_add_co_u32_e32 v8, vcc, 0x1b20000, v8
	s_nop 1
	v_addc_co_u32_e32 v9, vcc, 0, v9, vcc
	global_store_dwordx4 v[8:9], v[180:183], off
	s_andn2_b64 exec, exec, s[2:3]
	s_cbranch_execnz .LBB0_310

; __device__ __forceinline__ unsigned cvt_pk_bf16(float lo, float hi) { unsigned r; asm volatile("v_cvt_pk_bf16_f32 %0, %1, %2" : "=v"(r) : "v"(lo), "v"(hi)); return r; }
; __device__ __forceinline__ void phase_prologue(const Args& a, LAS unsigned char* lds) {
;     ...
;     { u64_t* ss0 = (u64_t*)(a.ws + WS_SS); bf16_t* xb = (bf16_t*)(a.ws + WS_XB);
;         for (int m = gw; m < M; m += NGW) { const f32x4* xr = (const f32x4*)(a.x + (size_t)m * D) + lane; f32x4* orow = (f32x4*)(a.out + (size_t)m * D) + lane; u32x2* brow = (u32x2*)(xb + (size_t)m * D) + lane; float s = 0.f;
; #pragma unroll
;             for (int j = 0; j < 8; ++j) { const f32x4 v = xr[64 * j]; orow[64 * j] = v; s += (v[0] * v[0] + v[1] * v[1]) + (v[2] * v[2] + v[3] * v[3]);
;                 u32x2 w; w.x = cvt_pk_bf16(v[0], v[1]); w.y = cvt_pk_bf16(v[2], v[3]); brow[64 * j] = w; }
;             s = wave_sum(s); if (lane == 0) ss0[m] = (u64_t)(s * SS_FX + 0.5f); } }
.LBB0_314:
	v_lshl_add_u64 v[34:35], v[14:15], 0, v[0:1]
	global_load_dwordx4 v[18:21], v[34:35], off
	v_lshl_add_u64 v[22:23], s[98:99], 0, v[12:13]
	s_mov_b32 s0, 0x18f00000
	v_add_co_u32_e64 v50, s[0:1], s0, v22
	v_lshl_add_u64 v[38:39], v[10:11], 0, v[0:1]
	s_nop 0
	v_addc_co_u32_e64 v51, s[0:1], 0, v23, s[0:1]
	v_add_co_u32_e64 v46, s[0:1], s94, v34
	v_and_b32_e32 v3, 64, v208
	s_nop 0
	v_addc_co_u32_e64 v47, s[0:1], 0, v35, s[0:1]
	v_add_co_u32_e64 v52, s[0:1], s94, v38
	s_waitcnt lgkmcnt(0)
	v_xor_b32_e32 v5, 1, v208
	v_addc_co_u32_e64 v53, s[0:1], 0, v39, s[0:1]
	v_add_u32_e32 v3, 64, v3
	v_cmp_lt_i32_e64 s[0:1], v5, v3
	global_load_dwordx4 v[100:103], v[34:35], off offset:1024
	global_load_dwordx4 v[104:107], v[34:35], off offset:2048
	global_load_dwordx4 v[108:111], v[34:35], off offset:3072
	global_load_dwordx4 v[112:115], v[46:47], off
	global_load_dwordx4 v[116:119], v[46:47], off offset:1024
	global_load_dwordx4 v[120:123], v[46:47], off offset:2048
	global_load_dwordx4 v[124:127], v[46:47], off offset:3072
	s_waitcnt vmcnt(0) lgkmcnt(0)
	global_store_dwordx4 v[38:39], v[18:21], off
	v_cvt_pk_bf16_f32 v22, v18, v19
	v_cvt_pk_bf16_f32 v23, v20, v21
	global_store_dwordx2 v[50:51], v[22:23], off
	s_nop 1
	v_mov_b32_e32 v22, v100
	v_mov_b32_e32 v23, v101
	v_mov_b32_e32 v24, v102
	v_mov_b32_e32 v25, v103
	v_mul_f32_e32 v7, v19, v19
	v_mul_f32_e32 v16, v21, v21
	v_fmac_f32_e32 v7, v18, v18
	v_fmac_f32_e32 v16, v20, v20
	v_add_f32_e32 v7, v7, v16
	v_cndmask_b32_e64 v5, v208, v5, s[0:1]
	v_lshlrev_b32_e32 v5, 2, v5
	s_waitcnt lgkmcnt(0)
	global_store_dwordx4 v[38:39], v[22:25], off offset:1024
	v_cvt_pk_bf16_f32 v26, v22, v23
	v_cvt_pk_bf16_f32 v27, v24, v25
	global_store_dwordx2 v[50:51], v[26:27], off offset:512
	s_nop 1
	v_mov_b32_e32 v26, v104
	v_mov_b32_e32 v27, v105
	v_mov_b32_e32 v28, v106
	v_mov_b32_e32 v29, v107
	v_mul_f32_e32 v16, v23, v23
	v_mul_f32_e32 v18, v25, v25
	v_fmac_f32_e32 v16, v22, v22
	v_fmac_f32_e32 v18, v24, v24
	v_add_f32_e32 v16, v16, v18
	v_add_f32_e32 v7, v7, v16
	s_waitcnt lgkmcnt(0)
	global_store_dwordx4 v[38:39], v[26:29], off offset:2048
	v_cvt_pk_bf16_f32 v30, v26, v27
	v_cvt_pk_bf16_f32 v31, v28, v29
	global_store_dwordx2 v[50:51], v[30:31], off offset:1024
	s_nop 1
	v_mov_b32_e32 v30, v108
	v_mov_b32_e32 v31, v109
	v_mov_b32_e32 v32, v110
	v_mov_b32_e32 v33, v111
	v_mul_f32_e32 v16, v27, v27
	v_mul_f32_e32 v18, v29, v29
	v_fmac_f32_e32 v16, v26, v26
	v_fmac_f32_e32 v18, v28, v28
	v_add_f32_e32 v16, v16, v18
	v_add_f32_e32 v7, v7, v16
	s_waitcnt lgkmcnt(0)
	global_store_dwordx4 v[38:39], v[30:33], off offset:3072
	v_cvt_pk_bf16_f32 v34, v30, v31
	v_cvt_pk_bf16_f32 v35, v32, v33
	global_store_dwordx2 v[50:51], v[34:35], off offset:1536
	s_nop 1
	v_mov_b32_e32 v34, v112
	v_mov_b32_e32 v35, v113
	v_mov_b32_e32 v36, v114
	v_mov_b32_e32 v37, v115
	v_mul_f32_e32 v16, v31, v31
	v_mul_f32_e32 v18, v33, v33
	v_fmac_f32_e32 v16, v30, v30
	v_fmac_f32_e32 v18, v32, v32
	v_add_f32_e32 v16, v16, v18
	v_add_f32_e32 v7, v7, v16
	s_waitcnt lgkmcnt(0)
	global_store_dwordx4 v[52:53], v[34:37], off
	v_cvt_pk_bf16_f32 v38, v34, v35
	v_cvt_pk_bf16_f32 v39, v36, v37
	global_store_dwordx2 v[50:51], v[38:39], off offset:2048
	s_nop 1
	v_mov_b32_e32 v38, v116
	v_mov_b32_e32 v39, v117
	v_mov_b32_e32 v40, v118
	v_mov_b32_e32 v41, v119
	v_mul_f32_e32 v16, v35, v35
	v_mul_f32_e32 v18, v37, v37
	v_fmac_f32_e32 v16, v34, v34
	v_fmac_f32_e32 v18, v36, v36
	v_add_f32_e32 v16, v16, v18
	v_add_f32_e32 v7, v7, v16
	s_waitcnt lgkmcnt(0)
	global_store_dwordx4 v[52:53], v[38:41], off offset:1024
	v_cvt_pk_bf16_f32 v42, v38, v39
	v_cvt_pk_bf16_f32 v43, v40, v41
	global_store_dwordx2 v[50:51], v[42:43], off offset:2560
	s_nop 1
	v_mov_b32_e32 v42, v120
	v_mov_b32_e32 v43, v121
	v_mov_b32_e32 v44, v122
	v_mov_b32_e32 v45, v123
	v_mul_f32_e32 v16, v39, v39
	v_mul_f32_e32 v18, v41, v41
	v_fmac_f32_e32 v16, v38, v38
	v_fmac_f32_e32 v18, v40, v40
	v_add_f32_e32 v16, v16, v18
	v_add_f32_e32 v7, v7, v16
	s_waitcnt lgkmcnt(0)
	global_store_dwordx4 v[52:53], v[42:45], off offset:2048
	v_cvt_pk_bf16_f32 v48, v42, v43
	v_cvt_pk_bf16_f32 v49, v44, v45
	global_store_dwordx2 v[50:51], v[48:49], off offset:3072
	s_nop 1
	v_mov_b32_e32 v46, v124
	v_mov_b32_e32 v47, v125
	v_mov_b32_e32 v48, v126
	v_mov_b32_e32 v49, v127
	v_mul_f32_e32 v16, v43, v43
	v_mul_f32_e32 v18, v45, v45
	v_fmac_f32_e32 v16, v42, v42
	v_fmac_f32_e32 v18, v44, v44
	v_add_f32_e32 v16, v16, v18
	v_add_f32_e32 v7, v7, v16
	s_waitcnt lgkmcnt(0)
	v_mul_f32_e32 v16, v47, v47
	v_mul_f32_e32 v18, v49, v49
	v_fmac_f32_e32 v16, v46, v46
	v_fmac_f32_e32 v18, v48, v48
	v_add_f32_e32 v16, v16, v18
	v_add_f32_e32 v7, v7, v16
	ds_bpermute_b32 v5, v5, v7
	v_xor_b32_e32 v16, 2, v208
	v_cmp_lt_i32_e64 s[0:1], v16, v3
	global_store_dwordx4 v[52:53], v[46:49], off offset:3072
	v_cvt_pk_bf16_f32 v18, v46, v47
	s_waitcnt lgkmcnt(0)
	v_add_f32_e32 v5, v7, v5
	v_cndmask_b32_e64 v16, v208, v16, s[0:1]
	v_lshlrev_b32_e32 v16, 2, v16
	ds_bpermute_b32 v7, v16, v5
	v_xor_b32_e32 v16, 4, v208
	v_cmp_lt_i32_e64 s[0:1], v16, v3
	v_cvt_pk_bf16_f32 v19, v48, v49
	global_store_dwordx2 v[50:51], v[18:19], off offset:3584
	s_waitcnt lgkmcnt(0)
	v_add_f32_e32 v5, v5, v7
	v_cndmask_b32_e64 v16, v208, v16, s[0:1]
	v_lshlrev_b32_e32 v16, 2, v16
	ds_bpermute_b32 v7, v16, v5
	v_xor_b32_e32 v16, 8, v208
	v_cmp_lt_i32_e64 s[0:1], v16, v3
	s_waitcnt lgkmcnt(0)
	v_add_f32_e32 v5, v5, v7
	v_cndmask_b32_e64 v16, v208, v16, s[0:1]
	v_lshlrev_b32_e32 v16, 2, v16
	ds_bpermute_b32 v7, v16, v5
	v_xor_b32_e32 v16, 16, v208
	v_cmp_lt_i32_e64 s[0:1], v16, v3
	s_waitcnt lgkmcnt(0)
	v_add_f32_e32 v5, v5, v7
	v_cndmask_b32_e64 v16, v208, v16, s[0:1]
	v_lshlrev_b32_e32 v16, 2, v16
	ds_bpermute_b32 v7, v16, v5
	v_xor_b32_e32 v16, 32, v208
	v_cmp_lt_i32_e64 s[0:1], v16, v3
	s_waitcnt lgkmcnt(0)
	v_add_f32_e32 v3, v5, v7
	v_cndmask_b32_e64 v16, v208, v16, s[0:1]
	v_lshlrev_b32_e32 v5, 2, v16
	ds_bpermute_b32 v5, v5, v3
	s_and_saveexec_b64 s[0:1], vcc
	s_cbranch_execz .LBB0_313
	s_waitcnt lgkmcnt(0)
	v_add_f32_e32 v3, v3, v5
	s_mov_b32 s6, 0x4b800000
	v_fma_f32 v3, v3, s6, 0.5
	v_trunc_f32_e32 v3, v3
	v_mul_f32_e32 v5, 0x2f800000, v3
	v_floor_f32_e32 v5, v5
	v_fmac_f32_e32 v3, 0xcf800000, v5
	v_cvt_u32_f32_e32 v18, v3
	v_cvt_u32_f32_e32 v19, v5
	v_lshl_add_u64 v[20:21], s[98:99], 0, v[8:9]
	global_store_dwordx2 v[20:21], v[18:19], off
	s_branch .LBB0_313

; __device__ __forceinline__ void phase_prologue(const Args& a, LAS unsigned char* lds) {
;     ...
;         for (int i = gt; i < T * 32; i += NT_) { const int pos = i >> 5, f = i & 31;
;             const float ex = (float)f * (1.0f / 31.0f); const float inv = 1.0f / __builtin_amdgcn_exp2f(ex * 13.287712379549449f);
;             const float ang = (float)pos * inv; const double rev = (double)ang * 0.15915494309189535; const float fr = (float)(rev - __builtin_rint(rev));
;             rope[i] = (f32x2){__builtin_amdgcn_cosf(fr), __builtin_amdgcn_sinf(fr)}; }
.LBB0_318:
	v_ashrrev_i32_e32 v5, 5, v4
	v_cvt_f32_i32_e32 v5, v5
	v_add_u32_e32 v4, s88, v4
	v_cmp_lt_i32_e32 vcc, s6, v4
	s_or_b64 s[2:3], vcc, s[2:3]
	v_mul_f32_e32 v5, v0, v5
	v_cvt_f64_f32_e32 v[8:9], v5
	v_mul_f64 v[10:11], v[8:9], s[4:5]
	v_rndne_f64_e32 v[10:11], v[10:11]
	v_fma_f64 v[8:9], v[8:9], s[4:5], -v[10:11]
	v_cvt_f32_f64_e32 v5, v[8:9]
	v_cos_f32_e32 v8, v5
	v_sin_f32_e32 v9, v5
	global_store_dwordx2 v[2:3], v[8:9], off
	v_lshl_add_u64 v[2:3], v[2:3], 0, s[12:13]
	s_andn2_b64 exec, exec, s[2:3]
	s_cbranch_execnz .LBB0_318

; __device__ __forceinline__ void phase_prologue(const Args& a, LAS unsigned char* lds) {
;     ...
;         for (int i = gt; i < 8 * BTAB_N; i += NT_) { const int h = i / BTAB_N, rel = i % BTAB_N - BTAB_OFF; const int n = rel < 0 ? -rel : rel;
;             int bk = n; if (n >= 8) { bk = 8 + (n >= 12) + (n >= 16) + (n >= 23) + (n >= 32) + (n >= 46) + (n >= 64) + (n >= 91); }
;             if (rel > 0) bk += 16; btab[i] = a.rel_bias[bk * 8 + h] * 8.0f; }
.LBB0_321:
	s_or_b64 exec, exec, s[4:5]
	v_lshlrev_b32_e32 v5, 3, v5
	v_add_u32_e32 v8, 0x80, v5
	v_cmp_lt_i32_e32 vcc, s8, v4
	s_movk_i32 s4, 0xdff
	v_subrev_u32_e32 v0, s88, v0
	v_cndmask_b32_e32 v4, v5, v8, vcc
	v_add_u32_e32 v4, v4, v3
	v_ashrrev_i32_e32 v5, 31, v4
	v_lshl_add_u64 v[4:5], v[4:5], 2, s[44:45]
	global_load_dword v8, v[4:5], off
	v_ashrrev_i32_e32 v3, 31, v2
	v_lshl_add_u64 v[4:5], v[2:3], 2, s[52:53]
	v_add_u32_e32 v2, s88, v2
	v_cmp_lt_i32_e32 vcc, s4, v2
	s_or_b64 s[2:3], vcc, s[2:3]
	s_waitcnt vmcnt(0) lgkmcnt(0)
	v_mul_f32_e32 v3, 0x41000000, v8
	global_store_dword v[4:5], v3, off
	s_andn2_b64 exec, exec, s[2:3]
	s_cbranch_execz .LBB0_324

; __device__ __forceinline__ void phase_prologue(const Args& a, LAS unsigned char* lds) {
;     ...
;         if (gt < DEPTH) { const float* lp = a.diff_lambda + gt * 256; float s1 = 0.f, s2 = 0.f; for (int j = 0; j < 64; ++j) { s1 += lp[j] * lp[64 + j]; s2 += lp[128 + j] * lp[192 + j]; }
;             float e1 = __expf(s1), e2 = __expf(s2); asm volatile("" : "+v"(e1), "+v"(e2));
;             const float li = 0.8f - 0.6f * __expf(-0.3f * (float)gt); ((float*)(a.ws + WS_LAM))[gt] = (e1 - e2) + li; } }
.LBB0_326:
	s_waitcnt vmcnt(0)
	v_lshl_add_u64 v[68:69], v[2:3], 0, s[2:3]
	global_load_dwordx4 v[8:11], v[68:69], off offset:512
	global_load_dwordx4 v[12:15], v[68:69], off
	global_load_dwordx4 v[16:19], v[68:69], off offset:768
	global_load_dwordx4 v[20:23], v[68:69], off offset:256
	global_load_dwordx4 v[24:27], v[68:69], off offset:528
	global_load_dwordx4 v[28:31], v[68:69], off offset:16
	global_load_dwordx4 v[32:35], v[68:69], off offset:784
	global_load_dwordx4 v[36:39], v[68:69], off offset:272
	global_load_dwordx4 v[40:43], v[68:69], off offset:544
	global_load_dwordx4 v[44:47], v[68:69], off offset:32
	global_load_dwordx4 v[48:51], v[68:69], off offset:800
	global_load_dwordx4 v[52:55], v[68:69], off offset:288
	global_load_dwordx4 v[56:59], v[68:69], off offset:560
	global_load_dwordx4 v[60:63], v[68:69], off offset:48
	global_load_dwordx4 v[64:67], v[68:69], off offset:816
	s_nop 0
	global_load_dwordx4 v[68:71], v[68:69], off offset:304
	s_add_u32 s2, s2, 64
	s_addc_u32 s3, s3, 0
	s_cmpk_eq_i32 s2, 0x100
	s_waitcnt vmcnt(0) lgkmcnt(0)
	v_mov_b32_e32 v72, v8
	v_mov_b32_e32 v73, v12
	v_mov_b32_e32 v74, v16
	v_mov_b32_e32 v75, v20
	v_mov_b32_e32 v12, v9
	v_mov_b32_e32 v20, v17
	v_pk_fma_f32 v[4:5], v[72:73], v[74:75], v[4:5]
	v_mov_b32_e32 v8, v10
	v_mov_b32_e32 v9, v14
	v_mov_b32_e32 v16, v18
	v_mov_b32_e32 v17, v22
	v_pk_fma_f32 v[4:5], v[12:13], v[20:21], v[4:5]
	v_mov_b32_e32 v14, v11
	v_mov_b32_e32 v22, v19
	v_pk_fma_f32 v[4:5], v[8:9], v[16:17], v[4:5]
	v_mov_b32_e32 v10, v24
	v_mov_b32_e32 v11, v28
	v_mov_b32_e32 v18, v32
	v_mov_b32_e32 v19, v36
	v_pk_fma_f32 v[4:5], v[14:15], v[22:23], v[4:5]
	v_mov_b32_e32 v28, v25
	v_mov_b32_e32 v36, v33
	v_pk_fma_f32 v[4:5], v[10:11], v[18:19], v[4:5]
	v_mov_b32_e32 v24, v26
	v_mov_b32_e32 v25, v30
	v_mov_b32_e32 v32, v34
	v_mov_b32_e32 v33, v38
	v_pk_fma_f32 v[4:5], v[28:29], v[36:37], v[4:5]
	v_mov_b32_e32 v30, v27
	v_mov_b32_e32 v38, v35
	v_pk_fma_f32 v[4:5], v[24:25], v[32:33], v[4:5]
	v_mov_b32_e32 v26, v40
	v_mov_b32_e32 v27, v44
	v_mov_b32_e32 v34, v48
	v_mov_b32_e32 v35, v52
	v_pk_fma_f32 v[4:5], v[30:31], v[38:39], v[4:5]
	v_mov_b32_e32 v44, v41
	v_mov_b32_e32 v52, v49
	v_pk_fma_f32 v[4:5], v[26:27], v[34:35], v[4:5]
	v_mov_b32_e32 v40, v42
	v_mov_b32_e32 v41, v46
	v_mov_b32_e32 v48, v50
	v_mov_b32_e32 v49, v54
	v_pk_fma_f32 v[4:5], v[44:45], v[52:53], v[4:5]
	v_mov_b32_e32 v46, v43
	v_mov_b32_e32 v54, v51
	v_pk_fma_f32 v[4:5], v[40:41], v[48:49], v[4:5]
	v_mov_b32_e32 v42, v56
	v_mov_b32_e32 v43, v60
	v_mov_b32_e32 v50, v64
	v_mov_b32_e32 v51, v68
	v_pk_fma_f32 v[4:5], v[46:47], v[54:55], v[4:5]
	v_mov_b32_e32 v60, v57
	v_mov_b32_e32 v68, v65
	v_pk_fma_f32 v[4:5], v[42:43], v[50:51], v[4:5]
	v_mov_b32_e32 v56, v58
	v_mov_b32_e32 v57, v62
	v_mov_b32_e32 v64, v66
	v_mov_b32_e32 v65, v70
	v_pk_fma_f32 v[4:5], v[60:61], v[68:69], v[4:5]
	v_mov_b32_e32 v62, v59
	v_mov_b32_e32 v70, v67
	v_pk_fma_f32 v[4:5], v[56:57], v[64:65], v[4:5]
	s_nop 0
	v_pk_fma_f32 v[4:5], v[62:63], v[70:71], v[4:5]
	s_cbranch_scc0 .LBB0_326
	v_cvt_f32_i32_e32 v2, v6
	v_mul_f32_e32 v0, 0x3fb8aa3b, v5
	v_exp_f32_e32 v179, v0
	v_mul_f32_e32 v0, 0x3fb8aa3b, v4
	v_exp_f32_e32 v3, v0
	v_mul_f32_e32 v0, 0xbe99999a, v2
	v_mul_f32_e32 v0, 0x3fb8aa3b, v0
	v_exp_f32_e32 v0, v0
	v_readlane_b32 s2, v254, 30
	v_readlane_b32 s3, v254, 31
	v_mul_f32_e32 v2, 0x3f19999a, v0
	v_pk_add_f32 v[2:3], v[178:179], v[2:3] neg_lo:[0,1] neg_hi:[0,1]
	s_nop 0
	v_add_f32_e32 v0, v2, v3
	v_lshl_add_u64 v[2:3], v[6:7], 2, s[2:3]
	global_store_dword v[2:3], v0, off
